# K-loops: loop-invariant LDS read addresses of buffer 1 hoisted to the unit preheader (2 VALU per iteration off the head of the SP1(t+1) load segment); on top of v40
# speedup vs baseline: 1.0069x; 1.0069x over previous
; #define PG8_STAGE(bufoff, gbase, voff) do { _Pragma("unroll") for (int _i = 0; _i < 2; ++_i) \
;         __builtin_amdgcn_global_load_lds((const unsigned*)((const char*)(gbase) + (voff)[_i]), (PG8_LAS unsigned*)(lds + (bufoff) + ldsw + _i * 8192), 16, 0, 0); } while (0)
; #define PG8_LDA(dst, b, h) do { _Pragma("unroll") for (int m = 0; m < 4; ++m) _Pragma("unroll") for (int k = 0; k < 2; ++k) dst[m][k] = *(const PG8_LAS bf16x8*)(lds + PG8_SA(b, h) + aoff + m * 2048 + k * 1024); } while (0)
; #define PG8_LDB(dst, b, h) do { _Pragma("unroll") for (int n = 0; n < 2; ++n) _Pragma("unroll") for (int k = 0; k < 2; ++k) dst[n][k] = *(const PG8_LAS bf16x8*)(lds + PG8_SB(b, h) + boff + n * 2048 + k * 1024); } while (0)
; #define PG8_SCHED __builtin_amdgcn_sched_barrier(0)
; template <class Epi, class Sched, bool ALIGN_EPI = false, bool SP2 = false>
; __device__ __forceinline__ void gemm_phase(PG8_LAS unsigned char* lds, const Gemm g, const Sched& S, const Epi& E) {
;     ...
; #pragma unroll
;     for (int a = 0; a < 2; ++a)
; #pragma unroll
;         for (int b = 0; b < 2; ++b)
; #pragma unroll
;             for (int m = 0; m < 4; ++m)
; #pragma unroll
;                 for (int n = 0; n < 2; ++n) acc[a][b][m][n] = (f32x4){0.f, 0.f, 0.f, 0.f};
;     ...
;         const bool has_next = S.next(ui + 1, nxt);
;         const char* nA = has_next ? (const char*)g.A + (size_t)nxt.pm * tstep : cA; const char* nB = has_next ? (const char*)g.Bt + (size_t)nxt.pn * tstep : cB;
;         for (int t = 0; t < nt; t += 2) {
;             const bool last = (t == nt - 2);
;             const char* a1 = cA + (size_t)(t + 1) * kstep;
;             const char* a2 = last ? nA : cA + (size_t)(t + 2) * kstep; const char* b2 = last ? nB : cB + (size_t)(t + 2) * kstep;
;             const char* a3 = a2 + kstep; const char* b3 = b2 + kstep;
;             if (last && has_next) S.a_ready(nxt);
;             if constexpr (SP2) {
;             PG8_LDB(B0, 0, 0); PG8_LDB(B1, 0, 1); PG8_SCHED; PG8_LDA(At, 0, 0); PG8_STAGE(PG8_SA(1, 1), a1 + hstep, voffA);
.LBB0_65:
	s_ashr_i32 s35, s34, 31
	s_lshl_b64 s[36:37], s[34:35], 20
	s_add_u32 s36, s24, s36
	s_addc_u32 s37, s25, s37
	s_and_b64 s[38:39], s[4:5], exec
	s_cselect_b32 s35, s37, s41
	s_cselect_b32 s63, s36, s40
	s_ashr_i32 s31, s30, 31
	s_lshl_b64 s[38:39], s[30:31], 20
	s_add_u32 s38, s46, s38
	s_addc_u32 s39, s47, s39
	s_and_b64 s[44:45], s[4:5], exec
	s_cselect_b32 s31, s39, s43
	s_cselect_b32 s64, s38, s42
	s_add_u32 s40, s40, 0x80080
	s_addc_u32 s41, s41, 0
	s_add_u32 s65, s42, 0x100
	v_mov_b32_e32 v0, 0
	s_addc_u32 s67, s43, 0
	s_mov_b32 s68, -2
	v_mov_b32_e32 v1, v0
	v_mov_b32_e32 v2, v0
	v_mov_b32_e32 v3, v0
	v_mov_b32_e32 v4, v0
	v_mov_b32_e32 v5, v0
	v_mov_b32_e32 v6, v0
	v_mov_b32_e32 v7, v0
	v_mov_b32_e32 v8, v0
	v_mov_b32_e32 v9, v0
	v_mov_b32_e32 v10, v0
	v_mov_b32_e32 v11, v0
	v_mov_b32_e32 v12, v0
	v_mov_b32_e32 v13, v0
	v_mov_b32_e32 v14, v0
	v_mov_b32_e32 v15, v0
	v_mov_b32_e32 v24, v0
	v_mov_b32_e32 v25, v0
	v_mov_b32_e32 v26, v0
	v_mov_b32_e32 v27, v0
	v_mov_b32_e32 v28, v0
	v_mov_b32_e32 v29, v0
	v_mov_b32_e32 v30, v0
	v_mov_b32_e32 v31, v0
	v_mov_b32_e32 v40, v0
	v_mov_b32_e32 v41, v0
	v_mov_b32_e32 v42, v0
	v_mov_b32_e32 v43, v0
	v_mov_b32_e32 v44, v0
	v_mov_b32_e32 v45, v0
	v_mov_b32_e32 v46, v0
	v_mov_b32_e32 v47, v0
	v_mov_b32_e32 v16, v0
	v_mov_b32_e32 v17, v0
	v_mov_b32_e32 v18, v0
	v_mov_b32_e32 v19, v0
	v_mov_b32_e32 v20, v0
	v_mov_b32_e32 v21, v0
	v_mov_b32_e32 v22, v0
	v_mov_b32_e32 v23, v0
	v_mov_b32_e32 v32, v0
	v_mov_b32_e32 v33, v0
	v_mov_b32_e32 v34, v0
	v_mov_b32_e32 v35, v0
	v_mov_b32_e32 v36, v0
	v_mov_b32_e32 v37, v0
	v_mov_b32_e32 v38, v0
	v_mov_b32_e32 v39, v0
	v_mov_b32_e32 v48, v0
	v_mov_b32_e32 v49, v0
	v_mov_b32_e32 v50, v0
	v_mov_b32_e32 v51, v0
	v_mov_b32_e32 v52, v0
	v_mov_b32_e32 v53, v0
	v_mov_b32_e32 v54, v0
	v_mov_b32_e32 v55, v0
	v_mov_b32_e32 v56, v0
	v_mov_b32_e32 v57, v0
	v_mov_b32_e32 v58, v0
	v_mov_b32_e32 v59, v0
	v_mov_b32_e32 v60, v0
	v_mov_b32_e32 v61, v0
	v_mov_b32_e32 v62, v0
	v_mov_b32_e32 v63, v0
	v_mov_b32_e32 v64, v0
	v_mov_b32_e32 v65, v0
	v_mov_b32_e32 v66, v0
	v_mov_b32_e32 v67, v0
	v_mov_b32_e32 v68, v0
	v_mov_b32_e32 v69, v0
	v_mov_b32_e32 v70, v0
	v_mov_b32_e32 v71, v0
	v_mov_b32_e32 v72, v0
	v_mov_b32_e32 v73, v0
	v_mov_b32_e32 v74, v0
	v_mov_b32_e32 v75, v0
	v_mov_b32_e32 v76, v0
	v_mov_b32_e32 v77, v0
	v_mov_b32_e32 v78, v0
	v_mov_b32_e32 v79, v0
	v_mov_b32_e32 v88, v0
	v_mov_b32_e32 v89, v0
	v_mov_b32_e32 v90, v0
	v_mov_b32_e32 v91, v0
	v_mov_b32_e32 v92, v0
	v_mov_b32_e32 v93, v0
	v_mov_b32_e32 v94, v0
	v_mov_b32_e32 v95, v0
	v_mov_b32_e32 v104, v0
	v_mov_b32_e32 v105, v0
	v_mov_b32_e32 v106, v0
	v_mov_b32_e32 v107, v0
	v_mov_b32_e32 v108, v0
	v_mov_b32_e32 v109, v0
	v_mov_b32_e32 v110, v0
	v_mov_b32_e32 v111, v0
	v_mov_b32_e32 v80, v0
	v_mov_b32_e32 v81, v0
	v_mov_b32_e32 v82, v0
	v_mov_b32_e32 v83, v0
	v_mov_b32_e32 v84, v0
	v_mov_b32_e32 v85, v0
	v_mov_b32_e32 v86, v0
	v_mov_b32_e32 v87, v0
	v_mov_b32_e32 v96, v0
	v_mov_b32_e32 v97, v0
	v_mov_b32_e32 v98, v0
	v_mov_b32_e32 v99, v0
	v_mov_b32_e32 v100, v0
	v_mov_b32_e32 v101, v0
	v_mov_b32_e32 v102, v0
	v_mov_b32_e32 v103, v0
	v_mov_b32_e32 v112, v0
	v_mov_b32_e32 v113, v0
	v_mov_b32_e32 v114, v0
	v_mov_b32_e32 v115, v0
	v_mov_b32_e32 v116, v0
	v_mov_b32_e32 v117, v0
	v_mov_b32_e32 v118, v0
	v_mov_b32_e32 v119, v0
	v_mov_b32_e32 v120, v0
	v_mov_b32_e32 v121, v0
	v_mov_b32_e32 v122, v0
	v_mov_b32_e32 v123, v0
	v_mov_b32_e32 v124, v0
	v_mov_b32_e32 v125, v0
	v_mov_b32_e32 v126, v0
	v_mov_b32_e32 v127, v0
	v_add_u32_e32 v255, 0x1c000, v147
	v_add_u32_e32 v254, 0x18000, v147
	v_add_u32_e32 v253, 0x80, v130
	v_add_u32_e32 v252, 0x80, v134
	v_add_u32_e32 v251, 0x80, v128
	v_add_u32_e32 v250, 0x80, v132
.LBB0_66:
	ds_read_b128 v[152:155], v149
	ds_read_b128 v[156:159], v149 offset:1024
	ds_read_b128 v[160:163], v149 offset:2048
	ds_read_b128 v[164:167], v149 offset:3072
	ds_read_b128 v[168:171], v150
	ds_read_b128 v[172:175], v150 offset:1024
	ds_read_b128 v[176:179], v150 offset:2048
	ds_read_b128 v[180:183], v150 offset:3072
	s_add_u32 s42, s40, 0xfff80080
	s_addc_u32 s43, s41, -1
	s_cmp_eq_u32 s68, 28
	s_cselect_b32 s45, s35, s43
	s_cselect_b32 s44, s63, s42
	s_cselect_b32 s43, s31, s67
	s_cselect_b32 s42, s64, s65

; #define PG8_STAGE(bufoff, gbase, voff) do { _Pragma("unroll") for (int _i = 0; _i < 2; ++_i) \
;         __builtin_amdgcn_global_load_lds((const unsigned*)((const char*)(gbase) + (voff)[_i]), (PG8_LAS unsigned*)(lds + (bufoff) + ldsw + _i * 8192), 16, 0, 0); } while (0)
; #define PG8_LDA(dst, b, h) do { _Pragma("unroll") for (int m = 0; m < 4; ++m) _Pragma("unroll") for (int k = 0; k < 2; ++k) dst[m][k] = *(const PG8_LAS bf16x8*)(lds + PG8_SA(b, h) + aoff + m * 2048 + k * 1024); } while (0)
; #define PG8_LDB(dst, b, h) do { _Pragma("unroll") for (int n = 0; n < 2; ++n) _Pragma("unroll") for (int k = 0; k < 2; ++k) dst[n][k] = *(const PG8_LAS bf16x8*)(lds + PG8_SB(b, h) + boff + n * 2048 + k * 1024); } while (0)
; #define PG8_SCHED __builtin_amdgcn_sched_barrier(0)
; template <class Epi, class Sched, bool ALIGN_EPI = false, bool SP2 = false>
; __device__ __forceinline__ void gemm_phase(PG8_LAS unsigned char* lds, const Gemm g, const Sched& S, const Epi& E) {
;     ...
;             PG8_LDB(B0, 0, 0); PG8_LDB(B1, 0, 1); PG8_SCHED; PG8_LDA(At, 0, 0); PG8_STAGE(PG8_SA(1, 1), a1 + hstep, voffA);
	s_add_i32 m0, s29, 0xc000
	ds_read_b128 v[184:187], v151
	ds_read_b128 v[188:191], v151 offset:1024
	ds_read_b128 v[192:195], v151 offset:2048
	ds_read_b128 v[196:199], v151 offset:3072
	ds_read_b128 v[200:203], v151 offset:4096
	ds_read_b128 v[204:207], v151 offset:5120
	ds_read_b128 v[208:211], v151 offset:6144
	ds_read_b128 v[212:215], v151 offset:7168
	global_load_lds_dwordx4 v136, s[40:41]

; #define PG8_STAGE(bufoff, gbase, voff) do { _Pragma("unroll") for (int _i = 0; _i < 2; ++_i) \
;         __builtin_amdgcn_global_load_lds((const unsigned*)((const char*)(gbase) + (voff)[_i]), (PG8_LAS unsigned*)(lds + (bufoff) + ldsw + _i * 8192), 16, 0, 0); } while (0)
; #define PG8_LDA(dst, b, h) do { _Pragma("unroll") for (int m = 0; m < 4; ++m) _Pragma("unroll") for (int k = 0; k < 2; ++k) dst[m][k] = *(const PG8_LAS bf16x8*)(lds + PG8_SA(b, h) + aoff + m * 2048 + k * 1024); } while (0)
; #define PG8_LDB(dst, b, h) do { _Pragma("unroll") for (int n = 0; n < 2; ++n) _Pragma("unroll") for (int k = 0; k < 2; ++k) dst[n][k] = *(const PG8_LAS bf16x8*)(lds + PG8_SB(b, h) + boff + n * 2048 + k * 1024); } while (0)
; #define PG8_MMA(ai, bj, At, Bt) do { __builtin_amdgcn_s_setprio(1); _Pragma("unroll") for (int m = 0; m < 4; ++m) _Pragma("unroll") for (int n = 0; n < 2; ++n) _Pragma("unroll") for (int k = 0; k < 2; ++k) \
;         acc[ai][bj][m][n] = __builtin_amdgcn_mfma_f32_16x16x32_bf16(Bt[n][k], At[m][k], acc[ai][bj][m][n], 0, 0, 0); __builtin_amdgcn_s_setprio(0); } while (0)
; #define PG8_WAIT_V(n) asm volatile("s_waitcnt vmcnt(" #n ")" ::: "memory")
; #define PG8_WAIT_L(n) asm volatile("s_waitcnt lgkmcnt(" #n ")" ::: "memory")
; #define PG8_BAR __builtin_amdgcn_s_barrier()
; #define PG8_SCHED __builtin_amdgcn_sched_barrier(0)
; template <class Epi, class Sched, bool ALIGN_EPI = false, bool SP2 = false>
; __device__ __forceinline__ void gemm_phase(PG8_LAS unsigned char* lds, const Gemm g, const Sched& S, const Epi& E) {
;     ...
;             PG8_LDB(B0, 0, 0); PG8_LDB(B1, 0, 1); PG8_SCHED; PG8_LDA(At, 0, 0); PG8_STAGE(PG8_SA(1, 1), a1 + hstep, voffA);
;             PG8_WAIT_V(8); PG8_WAIT_L(0); PG8_BAR; PG8_MMA(0, 0, At, B0); PG8_MMA(0, 1, At, B1); PG8_BAR; PG8_SCHED;
	s_add_i32 m0, s29, 0xe000
	s_nop 0
	global_load_lds_dwordx4 v138, s[40:41]
	s_waitcnt vmcnt(8)
	s_waitcnt lgkmcnt(0)
	s_barrier
	s_setprio 1
	s_waitcnt lgkmcnt(0)
	v_mfma_f32_16x16x32_bf16 v[124:127], v[152:155], v[184:187], v[124:127]
	v_mfma_f32_16x16x32_bf16 v[120:123], v[160:163], v[184:187], v[120:123]
	v_mfma_f32_16x16x32_bf16 v[116:119], v[152:155], v[192:195], v[116:119]
	v_mfma_f32_16x16x32_bf16 v[112:115], v[160:163], v[192:195], v[112:115]
	v_mfma_f32_16x16x32_bf16 v[100:103], v[152:155], v[200:203], v[100:103]
	v_mfma_f32_16x16x32_bf16 v[96:99], v[160:163], v[200:203], v[96:99]
	v_mfma_f32_16x16x32_bf16 v[84:87], v[152:155], v[208:211], v[84:87]
	v_mfma_f32_16x16x32_bf16 v[80:83], v[160:163], v[208:211], v[80:83]
	v_mfma_f32_16x16x32_bf16 v[124:127], v[156:159], v[188:191], v[124:127]
	v_mfma_f32_16x16x32_bf16 v[120:123], v[164:167], v[188:191], v[120:123]
	v_mfma_f32_16x16x32_bf16 v[116:119], v[156:159], v[196:199], v[116:119]
	v_mfma_f32_16x16x32_bf16 v[112:115], v[164:167], v[196:199], v[112:115]
	v_mfma_f32_16x16x32_bf16 v[100:103], v[156:159], v[204:207], v[100:103]
	v_mfma_f32_16x16x32_bf16 v[96:99], v[164:167], v[204:207], v[96:99]
	v_mfma_f32_16x16x32_bf16 v[84:87], v[156:159], v[212:215], v[84:87]
	v_mfma_f32_16x16x32_bf16 v[80:83], v[164:167], v[212:215], v[80:83]


; #define PG8_STAGE(bufoff, gbase, voff) do { _Pragma("unroll") for (int _i = 0; _i < 2; ++_i) \
;         __builtin_amdgcn_global_load_lds((const unsigned*)((const char*)(gbase) + (voff)[_i]), (PG8_LAS unsigned*)(lds + (bufoff) + ldsw + _i * 8192), 16, 0, 0); } while (0)
; #define PG8_LDA(dst, b, h) do { _Pragma("unroll") for (int m = 0; m < 4; ++m) _Pragma("unroll") for (int k = 0; k < 2; ++k) dst[m][k] = *(const PG8_LAS bf16x8*)(lds + PG8_SA(b, h) + aoff + m * 2048 + k * 1024); } while (0)
; #define PG8_MMA(ai, bj, At, Bt) do { __builtin_amdgcn_s_setprio(1); _Pragma("unroll") for (int m = 0; m < 4; ++m) _Pragma("unroll") for (int n = 0; n < 2; ++n) _Pragma("unroll") for (int k = 0; k < 2; ++k) \
;         acc[ai][bj][m][n] = __builtin_amdgcn_mfma_f32_16x16x32_bf16(Bt[n][k], At[m][k], acc[ai][bj][m][n], 0, 0, 0); __builtin_amdgcn_s_setprio(0); } while (0)
; #define PG8_WAIT_V(n) asm volatile("s_waitcnt vmcnt(" #n ")" ::: "memory")
; #define PG8_WAIT_L(n) asm volatile("s_waitcnt lgkmcnt(" #n ")" ::: "memory")
; #define PG8_BAR __builtin_amdgcn_s_barrier()
; #define PG8_SCHED __builtin_amdgcn_sched_barrier(0)
; template <class Epi, class Sched, bool ALIGN_EPI = false, bool SP2 = false>
; __device__ __forceinline__ void gemm_phase(PG8_LAS unsigned char* lds, const Gemm g, const Sched& S, const Epi& E) {
;     ...
;             PG8_WAIT_V(8); PG8_WAIT_L(0); PG8_BAR; PG8_MMA(0, 0, At, B0); PG8_MMA(0, 1, At, B1); PG8_BAR; PG8_SCHED;
;             PG8_LDA(At, 0, 1); PG8_STAGE(PG8_SB(0, 0), b2, voffB); PG8_STAGE(PG8_SB(0, 1), b2 + hstep, voffB); PG8_STAGE(PG8_SA(0, 0), a2, voffA);
	v_mfma_f32_16x16x32_bf16 v[108:111], v[168:171], v[184:187], v[108:111]
	v_mfma_f32_16x16x32_bf16 v[104:107], v[176:179], v[184:187], v[104:107]
	v_mfma_f32_16x16x32_bf16 v[92:95], v[168:171], v[192:195], v[92:95]
	v_mfma_f32_16x16x32_bf16 v[88:91], v[176:179], v[192:195], v[88:91]
	v_mfma_f32_16x16x32_bf16 v[76:79], v[168:171], v[200:203], v[76:79]
	v_mfma_f32_16x16x32_bf16 v[72:75], v[176:179], v[200:203], v[72:75]
	v_mfma_f32_16x16x32_bf16 v[68:71], v[168:171], v[208:211], v[68:71]
	v_mfma_f32_16x16x32_bf16 v[64:67], v[176:179], v[208:211], v[64:67]
	v_mfma_f32_16x16x32_bf16 v[108:111], v[172:175], v[188:191], v[108:111]
	v_mfma_f32_16x16x32_bf16 v[104:107], v[180:183], v[188:191], v[104:107]
	v_mfma_f32_16x16x32_bf16 v[92:95], v[172:175], v[196:199], v[92:95]
	v_mfma_f32_16x16x32_bf16 v[88:91], v[180:183], v[196:199], v[88:91]
	v_mfma_f32_16x16x32_bf16 v[76:79], v[172:175], v[204:207], v[76:79]
	v_mfma_f32_16x16x32_bf16 v[72:75], v[180:183], v[204:207], v[72:75]
	v_mfma_f32_16x16x32_bf16 v[68:71], v[172:175], v[212:215], v[68:71]
	v_mfma_f32_16x16x32_bf16 v[64:67], v[180:183], v[212:215], v[64:67]
	s_setprio 0
	s_barrier
	s_add_i32 s69, s59, s48
	s_mov_b64 s[96:97], s[42:43]

; #define PG8_STAGE(bufoff, gbase, voff) do { _Pragma("unroll") for (int _i = 0; _i < 2; ++_i) \
;         __builtin_amdgcn_global_load_lds((const unsigned*)((const char*)(gbase) + (voff)[_i]), (PG8_LAS unsigned*)(lds + (bufoff) + ldsw + _i * 8192), 16, 0, 0); } while (0)
; #define PG8_LDA(dst, b, h) do { _Pragma("unroll") for (int m = 0; m < 4; ++m) _Pragma("unroll") for (int k = 0; k < 2; ++k) dst[m][k] = *(const PG8_LAS bf16x8*)(lds + PG8_SA(b, h) + aoff + m * 2048 + k * 1024); } while (0)
; template <class Epi, class Sched, bool ALIGN_EPI = false, bool SP2 = false>
; __device__ __forceinline__ void gemm_phase(PG8_LAS unsigned char* lds, const Gemm g, const Sched& S, const Epi& E) {
;     ...
;             PG8_LDA(At, 0, 1); PG8_STAGE(PG8_SB(0, 0), b2, voffB); PG8_STAGE(PG8_SB(0, 1), b2 + hstep, voffB); PG8_STAGE(PG8_SA(0, 0), a2, voffA);
	s_mov_b32 m0, s69
	ds_read_b128 v[184:187], v151 offset:16384
	ds_read_b128 v[188:191], v151 offset:17408
	ds_read_b128 v[192:195], v151 offset:18432
	ds_read_b128 v[196:199], v151 offset:19456
	ds_read_b128 v[200:203], v151 offset:20480
	ds_read_b128 v[204:207], v151 offset:21504
	ds_read_b128 v[208:211], v151 offset:22528
	ds_read_b128 v[212:215], v151 offset:23552
	global_load_lds_dwordx4 v132, s[42:43]
	s_add_i32 m0, s69, 0x2000
	s_add_u32 s70, s42, 0x80000

; #define PG8_STAGE(bufoff, gbase, voff) do { _Pragma("unroll") for (int _i = 0; _i < 2; ++_i) \
;         __builtin_amdgcn_global_load_lds((const unsigned*)((const char*)(gbase) + (voff)[_i]), (PG8_LAS unsigned*)(lds + (bufoff) + ldsw + _i * 8192), 16, 0, 0); } while (0)
; #define PG8_LDA(dst, b, h) do { _Pragma("unroll") for (int m = 0; m < 4; ++m) _Pragma("unroll") for (int k = 0; k < 2; ++k) dst[m][k] = *(const PG8_LAS bf16x8*)(lds + PG8_SA(b, h) + aoff + m * 2048 + k * 1024); } while (0)
; template <class Epi, class Sched, bool ALIGN_EPI = false, bool SP2 = false>
; __device__ __forceinline__ void gemm_phase(PG8_LAS unsigned char* lds, const Gemm g, const Sched& S, const Epi& E) {
;     ...
;             PG8_LDA(At, 0, 1); PG8_STAGE(PG8_SB(0, 0), b2, voffB); PG8_STAGE(PG8_SB(0, 1), b2 + hstep, voffB); PG8_STAGE(PG8_SA(0, 0), a2, voffA);
	s_addc_u32 s71, s43, 0
	s_add_i32 s69, s60, s48
	global_load_lds_dwordx4 v128, s[42:43]

; #define PG8_STAGE(bufoff, gbase, voff) do { _Pragma("unroll") for (int _i = 0; _i < 2; ++_i) \
;         __builtin_amdgcn_global_load_lds((const unsigned*)((const char*)(gbase) + (voff)[_i]), (PG8_LAS unsigned*)(lds + (bufoff) + ldsw + _i * 8192), 16, 0, 0); } while (0)
; #define PG8_LDA(dst, b, h) do { _Pragma("unroll") for (int m = 0; m < 4; ++m) _Pragma("unroll") for (int k = 0; k < 2; ++k) dst[m][k] = *(const PG8_LAS bf16x8*)(lds + PG8_SA(b, h) + aoff + m * 2048 + k * 1024); } while (0)
; template <class Epi, class Sched, bool ALIGN_EPI = false, bool SP2 = false>
; __device__ __forceinline__ void gemm_phase(PG8_LAS unsigned char* lds, const Gemm g, const Sched& S, const Epi& E) {
;     ...
;             PG8_LDA(At, 0, 1); PG8_STAGE(PG8_SB(0, 0), b2, voffB); PG8_STAGE(PG8_SB(0, 1), b2 + hstep, voffB); PG8_STAGE(PG8_SA(0, 0), a2, voffA);
	s_mov_b32 m0, s69
	s_nop 0
	global_load_lds_dwordx4 v132, s[70:71]

; #define PG8_STAGE(bufoff, gbase, voff) do { _Pragma("unroll") for (int _i = 0; _i < 2; ++_i) \
;         __builtin_amdgcn_global_load_lds((const unsigned*)((const char*)(gbase) + (voff)[_i]), (PG8_LAS unsigned*)(lds + (bufoff) + ldsw + _i * 8192), 16, 0, 0); } while (0)
; #define PG8_LDA(dst, b, h) do { _Pragma("unroll") for (int m = 0; m < 4; ++m) _Pragma("unroll") for (int k = 0; k < 2; ++k) dst[m][k] = *(const PG8_LAS bf16x8*)(lds + PG8_SA(b, h) + aoff + m * 2048 + k * 1024); } while (0)
; template <class Epi, class Sched, bool ALIGN_EPI = false, bool SP2 = false>
; __device__ __forceinline__ void gemm_phase(PG8_LAS unsigned char* lds, const Gemm g, const Sched& S, const Epi& E) {
;     ...
;             PG8_LDA(At, 0, 1); PG8_STAGE(PG8_SB(0, 0), b2, voffB); PG8_STAGE(PG8_SB(0, 1), b2 + hstep, voffB); PG8_STAGE(PG8_SA(0, 0), a2, voffA);
	s_add_i32 m0, s69, 0x2000
	s_nop 0
	global_load_lds_dwordx4 v128, s[70:71]
	s_mov_b64 s[98:99], s[44:45]

; #define PG8_STAGE(bufoff, gbase, voff) do { _Pragma("unroll") for (int _i = 0; _i < 2; ++_i) \
;         __builtin_amdgcn_global_load_lds((const unsigned*)((const char*)(gbase) + (voff)[_i]), (PG8_LAS unsigned*)(lds + (bufoff) + ldsw + _i * 8192), 16, 0, 0); } while (0)
; #define PG8_LDA(dst, b, h) do { _Pragma("unroll") for (int m = 0; m < 4; ++m) _Pragma("unroll") for (int k = 0; k < 2; ++k) dst[m][k] = *(const PG8_LAS bf16x8*)(lds + PG8_SA(b, h) + aoff + m * 2048 + k * 1024); } while (0)
; #define PG8_MMA(ai, bj, At, Bt) do { __builtin_amdgcn_s_setprio(1); _Pragma("unroll") for (int m = 0; m < 4; ++m) _Pragma("unroll") for (int n = 0; n < 2; ++n) _Pragma("unroll") for (int k = 0; k < 2; ++k) \
;         acc[ai][bj][m][n] = __builtin_amdgcn_mfma_f32_16x16x32_bf16(Bt[n][k], At[m][k], acc[ai][bj][m][n], 0, 0, 0); __builtin_amdgcn_s_setprio(0); } while (0)
; #define PG8_WAIT_V(n) asm volatile("s_waitcnt vmcnt(" #n ")" ::: "memory")
; #define PG8_WAIT_L(n) asm volatile("s_waitcnt lgkmcnt(" #n ")" ::: "memory")
; #define PG8_BAR __builtin_amdgcn_s_barrier()
; #define PG8_SCHED __builtin_amdgcn_sched_barrier(0)
; template <class Epi, class Sched, bool ALIGN_EPI = false, bool SP2 = false>
; __device__ __forceinline__ void gemm_phase(PG8_LAS unsigned char* lds, const Gemm g, const Sched& S, const Epi& E) {
;     ...
;             PG8_LDA(At, 0, 1); PG8_STAGE(PG8_SB(0, 0), b2, voffB); PG8_STAGE(PG8_SB(0, 1), b2 + hstep, voffB); PG8_STAGE(PG8_SA(0, 0), a2, voffA);
;             PG8_WAIT_V(8); PG8_WAIT_L(0); PG8_BAR; PG8_MMA(1, 0, At, B0); PG8_MMA(1, 1, At, B1); PG8_BAR; PG8_SCHED;
	s_mov_b32 m0, s29
	s_nop 0
	global_load_lds_dwordx4 v134, s[44:45]
	s_mov_b32 m0, s51
	s_nop 0
	global_load_lds_dwordx4 v130, s[44:45]
	s_waitcnt vmcnt(8)
	s_waitcnt lgkmcnt(0)
	s_barrier
	s_setprio 1
	s_waitcnt lgkmcnt(0)
	v_mfma_f32_16x16x32_bf16 v[60:63], v[152:155], v[184:187], v[60:63]
	v_mfma_f32_16x16x32_bf16 v[56:59], v[160:163], v[184:187], v[56:59]
	v_mfma_f32_16x16x32_bf16 v[52:55], v[152:155], v[192:195], v[52:55]
	v_mfma_f32_16x16x32_bf16 v[48:51], v[160:163], v[192:195], v[48:51]
	v_mfma_f32_16x16x32_bf16 v[36:39], v[152:155], v[200:203], v[36:39]
	v_mfma_f32_16x16x32_bf16 v[32:35], v[160:163], v[200:203], v[32:35]
	v_mfma_f32_16x16x32_bf16 v[20:23], v[152:155], v[208:211], v[20:23]
	v_mfma_f32_16x16x32_bf16 v[16:19], v[160:163], v[208:211], v[16:19]
	v_mfma_f32_16x16x32_bf16 v[60:63], v[156:159], v[188:191], v[60:63]
	v_mfma_f32_16x16x32_bf16 v[56:59], v[164:167], v[188:191], v[56:59]
	v_mfma_f32_16x16x32_bf16 v[52:55], v[156:159], v[196:199], v[52:55]
	v_mfma_f32_16x16x32_bf16 v[48:51], v[164:167], v[196:199], v[48:51]
	v_mfma_f32_16x16x32_bf16 v[36:39], v[156:159], v[204:207], v[36:39]
	v_mfma_f32_16x16x32_bf16 v[32:35], v[164:167], v[204:207], v[32:35]
	v_mfma_f32_16x16x32_bf16 v[20:23], v[156:159], v[212:215], v[20:23]
	v_mfma_f32_16x16x32_bf16 v[16:19], v[164:167], v[212:215], v[16:19]


; #define PG8_STAGE(bufoff, gbase, voff) do { _Pragma("unroll") for (int _i = 0; _i < 2; ++_i) \
;         __builtin_amdgcn_global_load_lds((const unsigned*)((const char*)(gbase) + (voff)[_i]), (PG8_LAS unsigned*)(lds + (bufoff) + ldsw + _i * 8192), 16, 0, 0); } while (0)
; #define PG8_LDA(dst, b, h) do { _Pragma("unroll") for (int m = 0; m < 4; ++m) _Pragma("unroll") for (int k = 0; k < 2; ++k) dst[m][k] = *(const PG8_LAS bf16x8*)(lds + PG8_SA(b, h) + aoff + m * 2048 + k * 1024); } while (0)
; #define PG8_LDB(dst, b, h) do { _Pragma("unroll") for (int n = 0; n < 2; ++n) _Pragma("unroll") for (int k = 0; k < 2; ++k) dst[n][k] = *(const PG8_LAS bf16x8*)(lds + PG8_SB(b, h) + boff + n * 2048 + k * 1024); } while (0)
; #define PG8_MMA(ai, bj, At, Bt) do { __builtin_amdgcn_s_setprio(1); _Pragma("unroll") for (int m = 0; m < 4; ++m) _Pragma("unroll") for (int n = 0; n < 2; ++n) _Pragma("unroll") for (int k = 0; k < 2; ++k) \
;         acc[ai][bj][m][n] = __builtin_amdgcn_mfma_f32_16x16x32_bf16(Bt[n][k], At[m][k], acc[ai][bj][m][n], 0, 0, 0); __builtin_amdgcn_s_setprio(0); } while (0)
; #define PG8_WAIT_V(n) asm volatile("s_waitcnt vmcnt(" #n ")" ::: "memory")
; #define PG8_WAIT_L(n) asm volatile("s_waitcnt lgkmcnt(" #n ")" ::: "memory")
; #define PG8_BAR __builtin_amdgcn_s_barrier()
; #define PG8_SCHED __builtin_amdgcn_sched_barrier(0)
; template <class Epi, class Sched, bool ALIGN_EPI = false, bool SP2 = false>
; __device__ __forceinline__ void gemm_phase(PG8_LAS unsigned char* lds, const Gemm g, const Sched& S, const Epi& E) {
;     ...
;             PG8_WAIT_V(8); PG8_WAIT_L(0); PG8_BAR; PG8_MMA(1, 0, At, B0); PG8_MMA(1, 1, At, B1); PG8_BAR; PG8_SCHED;
;             PG8_LDB(B0, 1, 0); PG8_LDB(B1, 1, 1); PG8_SCHED; PG8_LDA(At, 1, 0); PG8_STAGE(PG8_SA(0, 1), a2 + hstep, voffA);
	v_mfma_f32_16x16x32_bf16 v[44:47], v[168:171], v[184:187], v[44:47]
	v_mfma_f32_16x16x32_bf16 v[40:43], v[176:179], v[184:187], v[40:43]
	v_mfma_f32_16x16x32_bf16 v[28:31], v[168:171], v[192:195], v[28:31]
	v_mfma_f32_16x16x32_bf16 v[24:27], v[176:179], v[192:195], v[24:27]
	v_mfma_f32_16x16x32_bf16 v[12:15], v[168:171], v[200:203], v[12:15]
	v_mfma_f32_16x16x32_bf16 v[8:11], v[176:179], v[200:203], v[8:11]
	v_mfma_f32_16x16x32_bf16 v[4:7], v[168:171], v[208:211], v[4:7]
	v_mfma_f32_16x16x32_bf16 v[0:3], v[176:179], v[208:211], v[0:3]
	v_mfma_f32_16x16x32_bf16 v[44:47], v[172:175], v[188:191], v[44:47]
	v_mfma_f32_16x16x32_bf16 v[40:43], v[180:183], v[188:191], v[40:43]
	v_mfma_f32_16x16x32_bf16 v[28:31], v[172:175], v[196:199], v[28:31]
	v_mfma_f32_16x16x32_bf16 v[24:27], v[180:183], v[196:199], v[24:27]
	v_mfma_f32_16x16x32_bf16 v[12:15], v[172:175], v[204:207], v[12:15]
	v_mfma_f32_16x16x32_bf16 v[8:11], v[180:183], v[204:207], v[8:11]
	v_mfma_f32_16x16x32_bf16 v[4:7], v[172:175], v[212:215], v[4:7]
	v_mfma_f32_16x16x32_bf16 v[0:3], v[180:183], v[212:215], v[0:3]
	s_setprio 0
	s_barrier
	s_add_i32 s69, 0, 0x18000
	s_add_i32 s70, 0, 0x1c000


; #define PG8_STAGE(bufoff, gbase, voff) do { _Pragma("unroll") for (int _i = 0; _i < 2; ++_i) \
;         __builtin_amdgcn_global_load_lds((const unsigned*)((const char*)(gbase) + (voff)[_i]), (PG8_LAS unsigned*)(lds + (bufoff) + ldsw + _i * 8192), 16, 0, 0); } while (0)
; #define PG8_LDA(dst, b, h) do { _Pragma("unroll") for (int m = 0; m < 4; ++m) _Pragma("unroll") for (int k = 0; k < 2; ++k) dst[m][k] = *(const PG8_LAS bf16x8*)(lds + PG8_SA(b, h) + aoff + m * 2048 + k * 1024); } while (0)
; #define PG8_LDB(dst, b, h) do { _Pragma("unroll") for (int n = 0; n < 2; ++n) _Pragma("unroll") for (int k = 0; k < 2; ++k) dst[n][k] = *(const PG8_LAS bf16x8*)(lds + PG8_SB(b, h) + boff + n * 2048 + k * 1024); } while (0)
; #define PG8_SCHED __builtin_amdgcn_sched_barrier(0)
; template <class Epi, class Sched, bool ALIGN_EPI = false, bool SP2 = false>
; __device__ __forceinline__ void gemm_phase(PG8_LAS unsigned char* lds, const Gemm g, const Sched& S, const Epi& E) {
;     ...
;             PG8_LDB(B0, 1, 0); PG8_LDB(B1, 1, 1); PG8_SCHED; PG8_LDA(At, 1, 0); PG8_STAGE(PG8_SA(0, 1), a2 + hstep, voffA);
	ds_read_b128 v[152:155], v254
	ds_read_b128 v[156:159], v254 offset:1024
	ds_read_b128 v[160:163], v254 offset:2048
	ds_read_b128 v[164:167], v254 offset:3072
	ds_read_b128 v[168:171], v255
	ds_read_b128 v[172:175], v255 offset:1024
	ds_read_b128 v[176:179], v255 offset:2048
	ds_read_b128 v[180:183], v255 offset:3072
	s_add_u32 s44, s44, 0x80000
	s_addc_u32 s45, s45, 0
	s_mov_b32 m0, s52

; #define PG8_STAGE(bufoff, gbase, voff) do { _Pragma("unroll") for (int _i = 0; _i < 2; ++_i) \
;         __builtin_amdgcn_global_load_lds((const unsigned*)((const char*)(gbase) + (voff)[_i]), (PG8_LAS unsigned*)(lds + (bufoff) + ldsw + _i * 8192), 16, 0, 0); } while (0)
; #define PG8_LDA(dst, b, h) do { _Pragma("unroll") for (int m = 0; m < 4; ++m) _Pragma("unroll") for (int k = 0; k < 2; ++k) dst[m][k] = *(const PG8_LAS bf16x8*)(lds + PG8_SA(b, h) + aoff + m * 2048 + k * 1024); } while (0)
; #define PG8_LDB(dst, b, h) do { _Pragma("unroll") for (int n = 0; n < 2; ++n) _Pragma("unroll") for (int k = 0; k < 2; ++k) dst[n][k] = *(const PG8_LAS bf16x8*)(lds + PG8_SB(b, h) + boff + n * 2048 + k * 1024); } while (0)
; #define PG8_SCHED __builtin_amdgcn_sched_barrier(0)
; template <class Epi, class Sched, bool ALIGN_EPI = false, bool SP2 = false>
; __device__ __forceinline__ void gemm_phase(PG8_LAS unsigned char* lds, const Gemm g, const Sched& S, const Epi& E) {
;     ...
;             PG8_LDB(B0, 1, 0); PG8_LDB(B1, 1, 1); PG8_SCHED; PG8_LDA(At, 1, 0); PG8_STAGE(PG8_SA(0, 1), a2 + hstep, voffA);
	ds_read_b128 v[184:187], v151 offset:32768
	ds_read_b128 v[188:191], v151 offset:33792
	ds_read_b128 v[192:195], v151 offset:34816
	ds_read_b128 v[196:199], v151 offset:35840
	ds_read_b128 v[200:203], v151 offset:36864
	ds_read_b128 v[204:207], v151 offset:37888
	ds_read_b128 v[208:211], v151 offset:38912
	ds_read_b128 v[212:215], v151 offset:39936
	global_load_lds_dwordx4 v134, s[44:45]

; #define PG8_STAGE(bufoff, gbase, voff) do { _Pragma("unroll") for (int _i = 0; _i < 2; ++_i) \
;         __builtin_amdgcn_global_load_lds((const unsigned*)((const char*)(gbase) + (voff)[_i]), (PG8_LAS unsigned*)(lds + (bufoff) + ldsw + _i * 8192), 16, 0, 0); } while (0)
; #define PG8_LDA(dst, b, h) do { _Pragma("unroll") for (int m = 0; m < 4; ++m) _Pragma("unroll") for (int k = 0; k < 2; ++k) dst[m][k] = *(const PG8_LAS bf16x8*)(lds + PG8_SA(b, h) + aoff + m * 2048 + k * 1024); } while (0)
; #define PG8_LDB(dst, b, h) do { _Pragma("unroll") for (int n = 0; n < 2; ++n) _Pragma("unroll") for (int k = 0; k < 2; ++k) dst[n][k] = *(const PG8_LAS bf16x8*)(lds + PG8_SB(b, h) + boff + n * 2048 + k * 1024); } while (0)
; #define PG8_MMA(ai, bj, At, Bt) do { __builtin_amdgcn_s_setprio(1); _Pragma("unroll") for (int m = 0; m < 4; ++m) _Pragma("unroll") for (int n = 0; n < 2; ++n) _Pragma("unroll") for (int k = 0; k < 2; ++k) \
;         acc[ai][bj][m][n] = __builtin_amdgcn_mfma_f32_16x16x32_bf16(Bt[n][k], At[m][k], acc[ai][bj][m][n], 0, 0, 0); __builtin_amdgcn_s_setprio(0); } while (0)
; #define PG8_WAIT_V(n) asm volatile("s_waitcnt vmcnt(" #n ")" ::: "memory")
; #define PG8_WAIT_L(n) asm volatile("s_waitcnt lgkmcnt(" #n ")" ::: "memory")
; #define PG8_BAR __builtin_amdgcn_s_barrier()
; #define PG8_SCHED __builtin_amdgcn_sched_barrier(0)
; template <class Epi, class Sched, bool ALIGN_EPI = false, bool SP2 = false>
; __device__ __forceinline__ void gemm_phase(PG8_LAS unsigned char* lds, const Gemm g, const Sched& S, const Epi& E) {
;     ...
;             PG8_LDB(B0, 1, 0); PG8_LDB(B1, 1, 1); PG8_SCHED; PG8_LDA(At, 1, 0); PG8_STAGE(PG8_SA(0, 1), a2 + hstep, voffA);
;             PG8_WAIT_V(8); PG8_WAIT_L(0); PG8_BAR; PG8_MMA(0, 0, At, B0); PG8_MMA(0, 1, At, B1); PG8_BAR; PG8_SCHED;
	s_mov_b32 m0, s53
	s_nop 0
	global_load_lds_dwordx4 v130, s[44:45]
	s_waitcnt vmcnt(8)
	s_waitcnt lgkmcnt(0)
	s_barrier
	s_setprio 1
	s_waitcnt lgkmcnt(0)
	v_mfma_f32_16x16x32_bf16 v[124:127], v[152:155], v[184:187], v[124:127]
	v_mfma_f32_16x16x32_bf16 v[120:123], v[160:163], v[184:187], v[120:123]
	v_mfma_f32_16x16x32_bf16 v[116:119], v[152:155], v[192:195], v[116:119]
	v_mfma_f32_16x16x32_bf16 v[112:115], v[160:163], v[192:195], v[112:115]
	v_mfma_f32_16x16x32_bf16 v[100:103], v[152:155], v[200:203], v[100:103]
	v_mfma_f32_16x16x32_bf16 v[96:99], v[160:163], v[200:203], v[96:99]
	v_mfma_f32_16x16x32_bf16 v[84:87], v[152:155], v[208:211], v[84:87]
	v_mfma_f32_16x16x32_bf16 v[80:83], v[160:163], v[208:211], v[80:83]
	v_mfma_f32_16x16x32_bf16 v[124:127], v[156:159], v[188:191], v[124:127]
	v_mfma_f32_16x16x32_bf16 v[120:123], v[164:167], v[188:191], v[120:123]
	v_mfma_f32_16x16x32_bf16 v[116:119], v[156:159], v[196:199], v[116:119]
	v_mfma_f32_16x16x32_bf16 v[112:115], v[164:167], v[196:199], v[112:115]
	v_mfma_f32_16x16x32_bf16 v[100:103], v[156:159], v[204:207], v[100:103]
	v_mfma_f32_16x16x32_bf16 v[96:99], v[164:167], v[204:207], v[96:99]
	v_mfma_f32_16x16x32_bf16 v[84:87], v[156:159], v[212:215], v[84:87]
	v_mfma_f32_16x16x32_bf16 v[80:83], v[164:167], v[212:215], v[80:83]


; #define PG8_STAGE(bufoff, gbase, voff) do { _Pragma("unroll") for (int _i = 0; _i < 2; ++_i) \
;         __builtin_amdgcn_global_load_lds((const unsigned*)((const char*)(gbase) + (voff)[_i]), (PG8_LAS unsigned*)(lds + (bufoff) + ldsw + _i * 8192), 16, 0, 0); } while (0)
; #define PG8_LDA(dst, b, h) do { _Pragma("unroll") for (int m = 0; m < 4; ++m) _Pragma("unroll") for (int k = 0; k < 2; ++k) dst[m][k] = *(const PG8_LAS bf16x8*)(lds + PG8_SA(b, h) + aoff + m * 2048 + k * 1024); } while (0)
; #define PG8_MMA(ai, bj, At, Bt) do { __builtin_amdgcn_s_setprio(1); _Pragma("unroll") for (int m = 0; m < 4; ++m) _Pragma("unroll") for (int n = 0; n < 2; ++n) _Pragma("unroll") for (int k = 0; k < 2; ++k) \
;         acc[ai][bj][m][n] = __builtin_amdgcn_mfma_f32_16x16x32_bf16(Bt[n][k], At[m][k], acc[ai][bj][m][n], 0, 0, 0); __builtin_amdgcn_s_setprio(0); } while (0)
; #define PG8_WAIT_V(n) asm volatile("s_waitcnt vmcnt(" #n ")" ::: "memory")
; #define PG8_WAIT_L(n) asm volatile("s_waitcnt lgkmcnt(" #n ")" ::: "memory")
; #define PG8_BAR __builtin_amdgcn_s_barrier()
; #define PG8_SCHED __builtin_amdgcn_sched_barrier(0)
; template <class Epi, class Sched, bool ALIGN_EPI = false, bool SP2 = false>
; __device__ __forceinline__ void gemm_phase(PG8_LAS unsigned char* lds, const Gemm g, const Sched& S, const Epi& E) {
;     ...
;             PG8_WAIT_V(8); PG8_WAIT_L(0); PG8_BAR; PG8_MMA(0, 0, At, B0); PG8_MMA(0, 1, At, B1); PG8_BAR; PG8_SCHED;
;             PG8_LDA(At, 1, 1); PG8_STAGE(PG8_SB(1, 0), b3, voffB); PG8_STAGE(PG8_SB(1, 1), b3 + hstep, voffB); PG8_STAGE(PG8_SA(1, 0), a3, voffA);
	v_mfma_f32_16x16x32_bf16 v[108:111], v[168:171], v[184:187], v[108:111]
	v_mfma_f32_16x16x32_bf16 v[104:107], v[176:179], v[184:187], v[104:107]
	v_mfma_f32_16x16x32_bf16 v[92:95], v[168:171], v[192:195], v[92:95]
	v_mfma_f32_16x16x32_bf16 v[88:91], v[176:179], v[192:195], v[88:91]
	v_mfma_f32_16x16x32_bf16 v[76:79], v[168:171], v[200:203], v[76:79]
	v_mfma_f32_16x16x32_bf16 v[72:75], v[176:179], v[200:203], v[72:75]
	v_mfma_f32_16x16x32_bf16 v[68:71], v[168:171], v[208:211], v[68:71]
	v_mfma_f32_16x16x32_bf16 v[64:67], v[176:179], v[208:211], v[64:67]
	v_mfma_f32_16x16x32_bf16 v[108:111], v[172:175], v[188:191], v[108:111]
	v_mfma_f32_16x16x32_bf16 v[104:107], v[180:183], v[188:191], v[104:107]
	v_mfma_f32_16x16x32_bf16 v[92:95], v[172:175], v[196:199], v[92:95]
	v_mfma_f32_16x16x32_bf16 v[88:91], v[180:183], v[196:199], v[88:91]
	v_mfma_f32_16x16x32_bf16 v[76:79], v[172:175], v[204:207], v[76:79]
	v_mfma_f32_16x16x32_bf16 v[72:75], v[180:183], v[204:207], v[72:75]
	v_mfma_f32_16x16x32_bf16 v[68:71], v[172:175], v[212:215], v[68:71]
	v_mfma_f32_16x16x32_bf16 v[64:67], v[180:183], v[212:215], v[64:67]
	s_setprio 0
	s_barrier
	s_add_i32 s44, s69, s48

; #define PG8_STAGE(bufoff, gbase, voff) do { _Pragma("unroll") for (int _i = 0; _i < 2; ++_i) \
;         __builtin_amdgcn_global_load_lds((const unsigned*)((const char*)(gbase) + (voff)[_i]), (PG8_LAS unsigned*)(lds + (bufoff) + ldsw + _i * 8192), 16, 0, 0); } while (0)
; #define PG8_LDA(dst, b, h) do { _Pragma("unroll") for (int m = 0; m < 4; ++m) _Pragma("unroll") for (int k = 0; k < 2; ++k) dst[m][k] = *(const PG8_LAS bf16x8*)(lds + PG8_SA(b, h) + aoff + m * 2048 + k * 1024); } while (0)
; template <class Epi, class Sched, bool ALIGN_EPI = false, bool SP2 = false>
; __device__ __forceinline__ void gemm_phase(PG8_LAS unsigned char* lds, const Gemm g, const Sched& S, const Epi& E) {
;     ...
;             PG8_LDA(At, 1, 1); PG8_STAGE(PG8_SB(1, 0), b3, voffB); PG8_STAGE(PG8_SB(1, 1), b3 + hstep, voffB); PG8_STAGE(PG8_SA(1, 0), a3, voffA);
	s_mov_b32 m0, s44
	ds_read_b128 v[184:187], v151 offset:49152
	ds_read_b128 v[188:191], v151 offset:50176
	ds_read_b128 v[192:195], v151 offset:51200
	ds_read_b128 v[196:199], v151 offset:52224
	ds_read_b128 v[200:203], v151 offset:53248
	ds_read_b128 v[204:207], v151 offset:54272
	ds_read_b128 v[208:211], v151 offset:55296
	ds_read_b128 v[212:215], v151 offset:56320
	global_load_lds_dwordx4 v250, s[96:97]
	s_add_i32 m0, s44, 0x2000
	s_add_u32 s42, s42, 0x80080

; #define PG8_STAGE(bufoff, gbase, voff) do { _Pragma("unroll") for (int _i = 0; _i < 2; ++_i) \
;         __builtin_amdgcn_global_load_lds((const unsigned*)((const char*)(gbase) + (voff)[_i]), (PG8_LAS unsigned*)(lds + (bufoff) + ldsw + _i * 8192), 16, 0, 0); } while (0)
; #define PG8_LDA(dst, b, h) do { _Pragma("unroll") for (int m = 0; m < 4; ++m) _Pragma("unroll") for (int k = 0; k < 2; ++k) dst[m][k] = *(const PG8_LAS bf16x8*)(lds + PG8_SA(b, h) + aoff + m * 2048 + k * 1024); } while (0)
; template <class Epi, class Sched, bool ALIGN_EPI = false, bool SP2 = false>
; __device__ __forceinline__ void gemm_phase(PG8_LAS unsigned char* lds, const Gemm g, const Sched& S, const Epi& E) {
;     ...
;             PG8_LDA(At, 1, 1); PG8_STAGE(PG8_SB(1, 0), b3, voffB); PG8_STAGE(PG8_SB(1, 1), b3 + hstep, voffB); PG8_STAGE(PG8_SA(1, 0), a3, voffA);
	s_addc_u32 s43, s43, 0
	s_add_i32 s44, s70, s48
	global_load_lds_dwordx4 v251, s[96:97]

; #define PG8_STAGE(bufoff, gbase, voff) do { _Pragma("unroll") for (int _i = 0; _i < 2; ++_i) \
;         __builtin_amdgcn_global_load_lds((const unsigned*)((const char*)(gbase) + (voff)[_i]), (PG8_LAS unsigned*)(lds + (bufoff) + ldsw + _i * 8192), 16, 0, 0); } while (0)
; #define PG8_LDA(dst, b, h) do { _Pragma("unroll") for (int m = 0; m < 4; ++m) _Pragma("unroll") for (int k = 0; k < 2; ++k) dst[m][k] = *(const PG8_LAS bf16x8*)(lds + PG8_SA(b, h) + aoff + m * 2048 + k * 1024); } while (0)
; template <class Epi, class Sched, bool ALIGN_EPI = false, bool SP2 = false>
; __device__ __forceinline__ void gemm_phase(PG8_LAS unsigned char* lds, const Gemm g, const Sched& S, const Epi& E) {
;     ...
;             PG8_LDA(At, 1, 1); PG8_STAGE(PG8_SB(1, 0), b3, voffB); PG8_STAGE(PG8_SB(1, 1), b3 + hstep, voffB); PG8_STAGE(PG8_SA(1, 0), a3, voffA);
	s_mov_b32 m0, s44
	s_nop 0
	global_load_lds_dwordx4 v132, s[42:43]

; #define PG8_STAGE(bufoff, gbase, voff) do { _Pragma("unroll") for (int _i = 0; _i < 2; ++_i) \
;         __builtin_amdgcn_global_load_lds((const unsigned*)((const char*)(gbase) + (voff)[_i]), (PG8_LAS unsigned*)(lds + (bufoff) + ldsw + _i * 8192), 16, 0, 0); } while (0)
; #define PG8_LDA(dst, b, h) do { _Pragma("unroll") for (int m = 0; m < 4; ++m) _Pragma("unroll") for (int k = 0; k < 2; ++k) dst[m][k] = *(const PG8_LAS bf16x8*)(lds + PG8_SA(b, h) + aoff + m * 2048 + k * 1024); } while (0)
; template <class Epi, class Sched, bool ALIGN_EPI = false, bool SP2 = false>
; __device__ __forceinline__ void gemm_phase(PG8_LAS unsigned char* lds, const Gemm g, const Sched& S, const Epi& E) {
;     ...
;             PG8_LDA(At, 1, 1); PG8_STAGE(PG8_SB(1, 0), b3, voffB); PG8_STAGE(PG8_SB(1, 1), b3 + hstep, voffB); PG8_STAGE(PG8_SA(1, 0), a3, voffA);
	s_add_i32 m0, s44, 0x2000
	s_nop 0
	global_load_lds_dwordx4 v128, s[42:43]

; #define PG8_STAGE(bufoff, gbase, voff) do { _Pragma("unroll") for (int _i = 0; _i < 2; ++_i) \
;         __builtin_amdgcn_global_load_lds((const unsigned*)((const char*)(gbase) + (voff)[_i]), (PG8_LAS unsigned*)(lds + (bufoff) + ldsw + _i * 8192), 16, 0, 0); } while (0)
; #define PG8_LDA(dst, b, h) do { _Pragma("unroll") for (int m = 0; m < 4; ++m) _Pragma("unroll") for (int k = 0; k < 2; ++k) dst[m][k] = *(const PG8_LAS bf16x8*)(lds + PG8_SA(b, h) + aoff + m * 2048 + k * 1024); } while (0)
; template <class Epi, class Sched, bool ALIGN_EPI = false, bool SP2 = false>
; __device__ __forceinline__ void gemm_phase(PG8_LAS unsigned char* lds, const Gemm g, const Sched& S, const Epi& E) {
;     ...
;             PG8_LDA(At, 1, 1); PG8_STAGE(PG8_SB(1, 0), b3, voffB); PG8_STAGE(PG8_SB(1, 1), b3 + hstep, voffB); PG8_STAGE(PG8_SA(1, 0), a3, voffA);
	s_mov_b32 m0, s55
	s_nop 0
	global_load_lds_dwordx4 v252, s[98:99]

; #define PG8_STAGE(bufoff, gbase, voff) do { _Pragma("unroll") for (int _i = 0; _i < 2; ++_i) \
;         __builtin_amdgcn_global_load_lds((const unsigned*)((const char*)(gbase) + (voff)[_i]), (PG8_LAS unsigned*)(lds + (bufoff) + ldsw + _i * 8192), 16, 0, 0); } while (0)
; #define PG8_LDA(dst, b, h) do { _Pragma("unroll") for (int m = 0; m < 4; ++m) _Pragma("unroll") for (int k = 0; k < 2; ++k) dst[m][k] = *(const PG8_LAS bf16x8*)(lds + PG8_SA(b, h) + aoff + m * 2048 + k * 1024); } while (0)
; #define PG8_MMA(ai, bj, At, Bt) do { __builtin_amdgcn_s_setprio(1); _Pragma("unroll") for (int m = 0; m < 4; ++m) _Pragma("unroll") for (int n = 0; n < 2; ++n) _Pragma("unroll") for (int k = 0; k < 2; ++k) \
;         acc[ai][bj][m][n] = __builtin_amdgcn_mfma_f32_16x16x32_bf16(Bt[n][k], At[m][k], acc[ai][bj][m][n], 0, 0, 0); __builtin_amdgcn_s_setprio(0); } while (0)
; #define PG8_WAIT_V(n) asm volatile("s_waitcnt vmcnt(" #n ")" ::: "memory")
; #define PG8_WAIT_L(n) asm volatile("s_waitcnt lgkmcnt(" #n ")" ::: "memory")
; #define PG8_BAR __builtin_amdgcn_s_barrier()
; #define PG8_SCHED __builtin_amdgcn_sched_barrier(0)
; template <class Epi, class Sched, bool ALIGN_EPI = false, bool SP2 = false>
; __device__ __forceinline__ void gemm_phase(PG8_LAS unsigned char* lds, const Gemm g, const Sched& S, const Epi& E) {
;     ...
;             PG8_LDA(At, 1, 1); PG8_STAGE(PG8_SB(1, 0), b3, voffB); PG8_STAGE(PG8_SB(1, 1), b3 + hstep, voffB); PG8_STAGE(PG8_SA(1, 0), a3, voffA);
;             PG8_WAIT_V(8); PG8_WAIT_L(0); PG8_BAR; PG8_MMA(1, 0, At, B0); PG8_MMA(1, 1, At, B1); PG8_BAR; PG8_SCHED;
	s_mov_b32 m0, s56
	s_nop 0
	global_load_lds_dwordx4 v253, s[98:99]
	s_waitcnt vmcnt(8)
	s_waitcnt lgkmcnt(0)
	s_barrier
	s_setprio 1
	s_waitcnt lgkmcnt(0)
	v_mfma_f32_16x16x32_bf16 v[60:63], v[152:155], v[184:187], v[60:63]
	v_mfma_f32_16x16x32_bf16 v[56:59], v[160:163], v[184:187], v[56:59]
	v_mfma_f32_16x16x32_bf16 v[52:55], v[152:155], v[192:195], v[52:55]
	v_mfma_f32_16x16x32_bf16 v[48:51], v[160:163], v[192:195], v[48:51]
	v_mfma_f32_16x16x32_bf16 v[36:39], v[152:155], v[200:203], v[36:39]
	v_mfma_f32_16x16x32_bf16 v[32:35], v[160:163], v[200:203], v[32:35]
	v_mfma_f32_16x16x32_bf16 v[20:23], v[152:155], v[208:211], v[20:23]
	v_mfma_f32_16x16x32_bf16 v[16:19], v[160:163], v[208:211], v[16:19]
	v_mfma_f32_16x16x32_bf16 v[60:63], v[156:159], v[188:191], v[60:63]
	v_mfma_f32_16x16x32_bf16 v[56:59], v[164:167], v[188:191], v[56:59]
	v_mfma_f32_16x16x32_bf16 v[52:55], v[156:159], v[196:199], v[52:55]
	v_mfma_f32_16x16x32_bf16 v[48:51], v[164:167], v[196:199], v[48:51]
	v_mfma_f32_16x16x32_bf16 v[36:39], v[156:159], v[204:207], v[36:39]
	v_mfma_f32_16x16x32_bf16 v[32:35], v[164:167], v[204:207], v[32:35]
	v_mfma_f32_16x16x32_bf16 v[20:23], v[156:159], v[212:215], v[20:23]
	v_mfma_f32_16x16x32_bf16 v[16:19], v[164:167], v[212:215], v[16:19]


; #define PG8_MMA(ai, bj, At, Bt) do { __builtin_amdgcn_s_setprio(1); _Pragma("unroll") for (int m = 0; m < 4; ++m) _Pragma("unroll") for (int n = 0; n < 2; ++n) _Pragma("unroll") for (int k = 0; k < 2; ++k) \
;         acc[ai][bj][m][n] = __builtin_amdgcn_mfma_f32_16x16x32_bf16(Bt[n][k], At[m][k], acc[ai][bj][m][n], 0, 0, 0); __builtin_amdgcn_s_setprio(0); } while (0)
; #define PG8_WAIT_V(n) asm volatile("s_waitcnt vmcnt(" #n ")" ::: "memory")
; #define PG8_WAIT_L(n) asm volatile("s_waitcnt lgkmcnt(" #n ")" ::: "memory")
; #define PG8_BAR __builtin_amdgcn_s_barrier()
; #define PG8_SCHED __builtin_amdgcn_sched_barrier(0)
; template <class Epi, class Sched, bool ALIGN_EPI = false, bool SP2 = false>
; __device__ __forceinline__ void gemm_phase(PG8_LAS unsigned char* lds, const Gemm g, const Sched& S, const Epi& E) {
;     ...
;             PG8_WAIT_V(8); PG8_WAIT_L(0); PG8_BAR; PG8_MMA(1, 0, At, B0); PG8_MMA(1, 1, At, B1); PG8_BAR; PG8_SCHED;
;     ...
;         if constexpr (ALIGN_EPI) { if (wr == 0) PG8_BAR; }
	v_mfma_f32_16x16x32_bf16 v[44:47], v[168:171], v[184:187], v[44:47]
	v_mfma_f32_16x16x32_bf16 v[40:43], v[176:179], v[184:187], v[40:43]
	v_mfma_f32_16x16x32_bf16 v[28:31], v[168:171], v[192:195], v[28:31]
	v_mfma_f32_16x16x32_bf16 v[24:27], v[176:179], v[192:195], v[24:27]
	v_mfma_f32_16x16x32_bf16 v[12:15], v[168:171], v[200:203], v[12:15]
	v_mfma_f32_16x16x32_bf16 v[8:11], v[176:179], v[200:203], v[8:11]
	v_mfma_f32_16x16x32_bf16 v[4:7], v[168:171], v[208:211], v[4:7]
	v_mfma_f32_16x16x32_bf16 v[0:3], v[176:179], v[208:211], v[0:3]
	v_mfma_f32_16x16x32_bf16 v[44:47], v[172:175], v[188:191], v[44:47]
	v_mfma_f32_16x16x32_bf16 v[40:43], v[180:183], v[188:191], v[40:43]
	v_mfma_f32_16x16x32_bf16 v[28:31], v[172:175], v[196:199], v[28:31]
	v_mfma_f32_16x16x32_bf16 v[24:27], v[180:183], v[196:199], v[24:27]
	v_mfma_f32_16x16x32_bf16 v[12:15], v[172:175], v[204:207], v[12:15]
	v_mfma_f32_16x16x32_bf16 v[8:11], v[180:183], v[204:207], v[8:11]
	v_mfma_f32_16x16x32_bf16 v[4:7], v[172:175], v[212:215], v[4:7]
	v_mfma_f32_16x16x32_bf16 v[0:3], v[180:183], v[212:215], v[0:3]
	s_setprio 0
	s_barrier
	s_add_i32 s68, s68, 2
	s_add_u32 s40, s40, 0x100
	s_addc_u32 s41, s41, 0
	s_add_u32 s65, s65, 0x100
	s_addc_u32 s67, s67, 0
	s_cmp_gt_u32 s68, 29
	s_cbranch_scc0 .LBB0_66
	s_and_b64 vcc, exec, s[26:27]
	s_cbranch_vccz .LBB0_69
	s_barrier

; #define PG8_STAGE(bufoff, gbase, voff) do { _Pragma("unroll") for (int _i = 0; _i < 2; ++_i) \
;         __builtin_amdgcn_global_load_lds((const unsigned*)((const char*)(gbase) + (voff)[_i]), (PG8_LAS unsigned*)(lds + (bufoff) + ldsw + _i * 8192), 16, 0, 0); } while (0)
; #define PG8_LDA(dst, b, h) do { _Pragma("unroll") for (int m = 0; m < 4; ++m) _Pragma("unroll") for (int k = 0; k < 2; ++k) dst[m][k] = *(const PG8_LAS bf16x8*)(lds + PG8_SA(b, h) + aoff + m * 2048 + k * 1024); } while (0)
; #define PG8_LDB(dst, b, h) do { _Pragma("unroll") for (int n = 0; n < 2; ++n) _Pragma("unroll") for (int k = 0; k < 2; ++k) dst[n][k] = *(const PG8_LAS bf16x8*)(lds + PG8_SB(b, h) + boff + n * 2048 + k * 1024); } while (0)
; #define PG8_SCHED __builtin_amdgcn_sched_barrier(0)
; template <class Epi, class Sched, bool ALIGN_EPI = false, bool SP2 = false>
; __device__ __forceinline__ void gemm_phase(PG8_LAS unsigned char* lds, const Gemm g, const Sched& S, const Epi& E) {
;     ...
; #pragma unroll
;     for (int a = 0; a < 2; ++a)
; #pragma unroll
;         for (int b = 0; b < 2; ++b)
; #pragma unroll
;             for (int m = 0; m < 4; ++m)
; #pragma unroll
;                 for (int n = 0; n < 2; ++n) acc[a][b][m][n] = (f32x4){0.f, 0.f, 0.f, 0.f};
;     ...
;         const bool has_next = S.next(ui + 1, nxt);
;         const char* nA = has_next ? (const char*)g.A + (size_t)nxt.pm * tstep : cA; const char* nB = has_next ? (const char*)g.Bt + (size_t)nxt.pn * tstep : cB;
;         for (int t = 0; t < nt; t += 2) {
;             const bool last = (t == nt - 2);
;             const char* a1 = cA + (size_t)(t + 1) * kstep;
;             const char* a2 = last ? nA : cA + (size_t)(t + 2) * kstep; const char* b2 = last ? nB : cB + (size_t)(t + 2) * kstep;
;             const char* a3 = a2 + kstep; const char* b3 = b2 + kstep;
;             if (last && has_next) S.a_ready(nxt);
;             if constexpr (SP2) {
;             PG8_LDB(B0, 0, 0); PG8_LDB(B1, 0, 1); PG8_SCHED; PG8_LDA(At, 0, 0); PG8_STAGE(PG8_SA(1, 1), a1 + hstep, voffA);
.LBB0_332:
	s_ashr_i32 s51, s50, 31
	s_lshl_b64 s[52:53], s[50:51], 20
	s_add_u32 s52, s26, s52
	s_addc_u32 s53, s27, s53
	s_and_b64 s[54:55], s[6:7], exec
	s_cselect_b32 s11, s53, s59
	s_cselect_b32 s51, s52, s58
	s_ashr_i32 s49, s48, 31
	s_lshl_b64 s[54:55], s[48:49], 20
	s_add_u32 s54, s45, s54
	s_addc_u32 s55, s47, s55
	s_and_b64 s[62:63], s[6:7], exec
	s_cselect_b32 s49, s55, s61
	s_cselect_b32 s78, s54, s60
	s_add_u32 s58, s58, 0x80080
	s_addc_u32 s59, s59, 0
	s_add_u32 s79, s60, 0x100
	v_mov_b32_e32 v0, 0
	s_addc_u32 s80, s61, 0
	s_mov_b32 s81, -2
	v_mov_b32_e32 v1, v0
	s_waitcnt lgkmcnt(0)
	v_mov_b32_e32 v2, v0
	v_mov_b32_e32 v3, v0
	v_mov_b32_e32 v4, v0
	v_mov_b32_e32 v5, v0
	v_mov_b32_e32 v6, v0
	v_mov_b32_e32 v7, v0
	v_mov_b32_e32 v16, v0
	v_mov_b32_e32 v17, v0
	v_mov_b32_e32 v18, v0
	v_mov_b32_e32 v19, v0
	v_mov_b32_e32 v20, v0
	v_mov_b32_e32 v21, v0
	v_mov_b32_e32 v22, v0
	v_mov_b32_e32 v23, v0
	v_mov_b32_e32 v32, v0
	v_mov_b32_e32 v33, v0
	v_mov_b32_e32 v34, v0
	v_mov_b32_e32 v35, v0
	v_mov_b32_e32 v36, v0
	v_mov_b32_e32 v37, v0
	v_mov_b32_e32 v38, v0
	v_mov_b32_e32 v39, v0
	v_mov_b32_e32 v48, v0
	v_mov_b32_e32 v49, v0
	v_mov_b32_e32 v50, v0
	v_mov_b32_e32 v51, v0
	v_mov_b32_e32 v52, v0
	v_mov_b32_e32 v53, v0
	v_mov_b32_e32 v54, v0
	v_mov_b32_e32 v55, v0
	v_mov_b32_e32 v8, v0
	v_mov_b32_e32 v9, v0
	v_mov_b32_e32 v10, v0
	v_mov_b32_e32 v11, v0
	v_mov_b32_e32 v12, v0
	v_mov_b32_e32 v13, v0
	v_mov_b32_e32 v14, v0
	v_mov_b32_e32 v15, v0
	v_mov_b32_e32 v24, v0
	v_mov_b32_e32 v25, v0
	v_mov_b32_e32 v26, v0
	v_mov_b32_e32 v27, v0
	v_mov_b32_e32 v28, v0
	v_mov_b32_e32 v29, v0
	v_mov_b32_e32 v30, v0
	v_mov_b32_e32 v31, v0
	v_mov_b32_e32 v40, v0
	v_mov_b32_e32 v41, v0
	v_mov_b32_e32 v42, v0
	v_mov_b32_e32 v43, v0
	v_mov_b32_e32 v44, v0
	v_mov_b32_e32 v45, v0
	v_mov_b32_e32 v46, v0
	v_mov_b32_e32 v47, v0
	v_mov_b32_e32 v56, v0
	v_mov_b32_e32 v57, v0
	v_mov_b32_e32 v58, v0
	v_mov_b32_e32 v59, v0
	v_mov_b32_e32 v60, v0
	v_mov_b32_e32 v61, v0
	v_mov_b32_e32 v62, v0
	v_mov_b32_e32 v63, v0
	v_mov_b32_e32 v80, v0
	v_mov_b32_e32 v81, v0
	v_mov_b32_e32 v82, v0
	v_mov_b32_e32 v83, v0
	v_mov_b32_e32 v84, v0
	v_mov_b32_e32 v85, v0
	v_mov_b32_e32 v86, v0
	v_mov_b32_e32 v87, v0
	v_mov_b32_e32 v96, v0
	v_mov_b32_e32 v97, v0
	v_mov_b32_e32 v98, v0
	v_mov_b32_e32 v99, v0
	v_mov_b32_e32 v100, v0
	v_mov_b32_e32 v101, v0
	v_mov_b32_e32 v102, v0
	v_mov_b32_e32 v103, v0
	v_mov_b32_e32 v112, v0
	v_mov_b32_e32 v113, v0
	v_mov_b32_e32 v114, v0
	v_mov_b32_e32 v115, v0
	v_mov_b32_e32 v116, v0
	v_mov_b32_e32 v117, v0
	v_mov_b32_e32 v118, v0
	v_mov_b32_e32 v119, v0
	v_mov_b32_e32 v128, v0
	v_mov_b32_e32 v129, v0
	v_mov_b32_e32 v130, v0
	v_mov_b32_e32 v131, v0
	v_mov_b32_e32 v132, v0
	v_mov_b32_e32 v133, v0
	v_mov_b32_e32 v134, v0
	v_mov_b32_e32 v135, v0
	v_mov_b32_e32 v88, v0
	v_mov_b32_e32 v89, v0
	v_mov_b32_e32 v90, v0
	v_mov_b32_e32 v91, v0
	v_mov_b32_e32 v92, v0
	v_mov_b32_e32 v93, v0
	v_mov_b32_e32 v94, v0
	v_mov_b32_e32 v95, v0
	v_mov_b32_e32 v104, v0
	v_mov_b32_e32 v105, v0
	v_mov_b32_e32 v106, v0
	v_mov_b32_e32 v107, v0
	v_mov_b32_e32 v108, v0
	v_mov_b32_e32 v109, v0
	v_mov_b32_e32 v110, v0
	v_mov_b32_e32 v111, v0
	v_mov_b32_e32 v120, v0
	v_mov_b32_e32 v121, v0
	v_mov_b32_e32 v122, v0
	v_mov_b32_e32 v123, v0
	v_mov_b32_e32 v124, v0
	v_mov_b32_e32 v125, v0
	v_mov_b32_e32 v126, v0
	v_mov_b32_e32 v127, v0
	v_mov_b32_e32 v136, v0
	v_mov_b32_e32 v137, v0
	v_mov_b32_e32 v138, v0
	v_mov_b32_e32 v139, v0
	v_mov_b32_e32 v140, v0
	v_mov_b32_e32 v141, v0
	v_mov_b32_e32 v142, v0
	v_mov_b32_e32 v143, v0
	v_add_u32_e32 v255, 0x1c000, v209
	v_add_u32_e32 v254, 0x18000, v209
	v_add_u32_e32 v253, 0x80, v164
	v_add_u32_e32 v252, 0x80, v160
	v_add_u32_e32 v251, 0x80, v166
	v_add_u32_e32 v250, 0x80, v162
.LBB0_333:
	ds_read_b128 v[64:67], v211
	ds_read_b128 v[68:71], v211 offset:1024
	ds_read_b128 v[72:75], v211 offset:2048
	ds_read_b128 v[76:79], v211 offset:3072
	ds_read_b128 v[144:147], v212
	ds_read_b128 v[148:151], v212 offset:1024
	ds_read_b128 v[152:155], v212 offset:2048
	ds_read_b128 v[156:159], v212 offset:3072
	s_add_u32 s60, s58, 0xfff80080
	s_addc_u32 s61, s59, -1
	s_cmp_eq_u32 s81, 28
	s_cselect_b32 s63, s11, s61
	s_cselect_b32 s62, s51, s60
	s_cselect_b32 s61, s49, s80
	s_cselect_b32 s60, s78, s79

; #define PG8_STAGE(bufoff, gbase, voff) do { _Pragma("unroll") for (int _i = 0; _i < 2; ++_i) \
;         __builtin_amdgcn_global_load_lds((const unsigned*)((const char*)(gbase) + (voff)[_i]), (PG8_LAS unsigned*)(lds + (bufoff) + ldsw + _i * 8192), 16, 0, 0); } while (0)
; #define PG8_LDA(dst, b, h) do { _Pragma("unroll") for (int m = 0; m < 4; ++m) _Pragma("unroll") for (int k = 0; k < 2; ++k) dst[m][k] = *(const PG8_LAS bf16x8*)(lds + PG8_SA(b, h) + aoff + m * 2048 + k * 1024); } while (0)
; #define PG8_LDB(dst, b, h) do { _Pragma("unroll") for (int n = 0; n < 2; ++n) _Pragma("unroll") for (int k = 0; k < 2; ++k) dst[n][k] = *(const PG8_LAS bf16x8*)(lds + PG8_SB(b, h) + boff + n * 2048 + k * 1024); } while (0)
; #define PG8_SCHED __builtin_amdgcn_sched_barrier(0)
; template <class Epi, class Sched, bool ALIGN_EPI = false, bool SP2 = false>
; __device__ __forceinline__ void gemm_phase(PG8_LAS unsigned char* lds, const Gemm g, const Sched& S, const Epi& E) {
;     ...
;             PG8_LDB(B0, 0, 0); PG8_LDB(B1, 0, 1); PG8_SCHED; PG8_LDA(At, 0, 0); PG8_STAGE(PG8_SA(1, 1), a1 + hstep, voffA);
	s_add_i32 m0, s57, 0xc000
	ds_read_b128 v[176:179], v213
	ds_read_b128 v[180:183], v213 offset:1024
	ds_read_b128 v[184:187], v213 offset:2048
	ds_read_b128 v[188:191], v213 offset:3072
	ds_read_b128 v[192:195], v213 offset:4096
	ds_read_b128 v[196:199], v213 offset:5120
	ds_read_b128 v[200:203], v213 offset:6144
	ds_read_b128 v[204:207], v213 offset:7168
	global_load_lds_dwordx4 v168, s[58:59]

; #define PG8_STAGE(bufoff, gbase, voff) do { _Pragma("unroll") for (int _i = 0; _i < 2; ++_i) \
;         __builtin_amdgcn_global_load_lds((const unsigned*)((const char*)(gbase) + (voff)[_i]), (PG8_LAS unsigned*)(lds + (bufoff) + ldsw + _i * 8192), 16, 0, 0); } while (0)
; #define PG8_LDA(dst, b, h) do { _Pragma("unroll") for (int m = 0; m < 4; ++m) _Pragma("unroll") for (int k = 0; k < 2; ++k) dst[m][k] = *(const PG8_LAS bf16x8*)(lds + PG8_SA(b, h) + aoff + m * 2048 + k * 1024); } while (0)
; #define PG8_LDB(dst, b, h) do { _Pragma("unroll") for (int n = 0; n < 2; ++n) _Pragma("unroll") for (int k = 0; k < 2; ++k) dst[n][k] = *(const PG8_LAS bf16x8*)(lds + PG8_SB(b, h) + boff + n * 2048 + k * 1024); } while (0)
; #define PG8_MMA(ai, bj, At, Bt) do { __builtin_amdgcn_s_setprio(1); _Pragma("unroll") for (int m = 0; m < 4; ++m) _Pragma("unroll") for (int n = 0; n < 2; ++n) _Pragma("unroll") for (int k = 0; k < 2; ++k) \
;         acc[ai][bj][m][n] = __builtin_amdgcn_mfma_f32_16x16x32_bf16(Bt[n][k], At[m][k], acc[ai][bj][m][n], 0, 0, 0); __builtin_amdgcn_s_setprio(0); } while (0)
; #define PG8_WAIT_V(n) asm volatile("s_waitcnt vmcnt(" #n ")" ::: "memory")
; #define PG8_WAIT_L(n) asm volatile("s_waitcnt lgkmcnt(" #n ")" ::: "memory")
; #define PG8_BAR __builtin_amdgcn_s_barrier()
; #define PG8_SCHED __builtin_amdgcn_sched_barrier(0)
; template <class Epi, class Sched, bool ALIGN_EPI = false, bool SP2 = false>
; __device__ __forceinline__ void gemm_phase(PG8_LAS unsigned char* lds, const Gemm g, const Sched& S, const Epi& E) {
;     ...
;             PG8_LDB(B0, 0, 0); PG8_LDB(B1, 0, 1); PG8_SCHED; PG8_LDA(At, 0, 0); PG8_STAGE(PG8_SA(1, 1), a1 + hstep, voffA);
;             PG8_WAIT_V(8); PG8_WAIT_L(0); PG8_BAR; PG8_MMA(0, 0, At, B0); PG8_MMA(0, 1, At, B1); PG8_BAR; PG8_SCHED;
	s_add_i32 m0, s57, 0xe000
	s_nop 0
	global_load_lds_dwordx4 v170, s[58:59]
	s_waitcnt vmcnt(8)
	s_waitcnt lgkmcnt(0)
	s_barrier
	s_setprio 1
	s_waitcnt lgkmcnt(0)
	v_mfma_f32_16x16x32_bf16 v[140:143], v[64:67], v[176:179], v[140:143]
	v_mfma_f32_16x16x32_bf16 v[136:139], v[72:75], v[176:179], v[136:139]
	v_mfma_f32_16x16x32_bf16 v[124:127], v[64:67], v[184:187], v[124:127]
	v_mfma_f32_16x16x32_bf16 v[120:123], v[72:75], v[184:187], v[120:123]
	v_mfma_f32_16x16x32_bf16 v[108:111], v[64:67], v[192:195], v[108:111]
	v_mfma_f32_16x16x32_bf16 v[104:107], v[72:75], v[192:195], v[104:107]
	v_mfma_f32_16x16x32_bf16 v[92:95], v[64:67], v[200:203], v[92:95]
	v_mfma_f32_16x16x32_bf16 v[88:91], v[72:75], v[200:203], v[88:91]
	v_mfma_f32_16x16x32_bf16 v[140:143], v[68:71], v[180:183], v[140:143]
	v_mfma_f32_16x16x32_bf16 v[136:139], v[76:79], v[180:183], v[136:139]
	v_mfma_f32_16x16x32_bf16 v[124:127], v[68:71], v[188:191], v[124:127]
	v_mfma_f32_16x16x32_bf16 v[120:123], v[76:79], v[188:191], v[120:123]
	v_mfma_f32_16x16x32_bf16 v[108:111], v[68:71], v[196:199], v[108:111]
	v_mfma_f32_16x16x32_bf16 v[104:107], v[76:79], v[196:199], v[104:107]
	v_mfma_f32_16x16x32_bf16 v[92:95], v[68:71], v[204:207], v[92:95]
	v_mfma_f32_16x16x32_bf16 v[88:91], v[76:79], v[204:207], v[88:91]


; #define PG8_STAGE(bufoff, gbase, voff) do { _Pragma("unroll") for (int _i = 0; _i < 2; ++_i) \
;         __builtin_amdgcn_global_load_lds((const unsigned*)((const char*)(gbase) + (voff)[_i]), (PG8_LAS unsigned*)(lds + (bufoff) + ldsw + _i * 8192), 16, 0, 0); } while (0)
; #define PG8_LDA(dst, b, h) do { _Pragma("unroll") for (int m = 0; m < 4; ++m) _Pragma("unroll") for (int k = 0; k < 2; ++k) dst[m][k] = *(const PG8_LAS bf16x8*)(lds + PG8_SA(b, h) + aoff + m * 2048 + k * 1024); } while (0)
; #define PG8_MMA(ai, bj, At, Bt) do { __builtin_amdgcn_s_setprio(1); _Pragma("unroll") for (int m = 0; m < 4; ++m) _Pragma("unroll") for (int n = 0; n < 2; ++n) _Pragma("unroll") for (int k = 0; k < 2; ++k) \
;         acc[ai][bj][m][n] = __builtin_amdgcn_mfma_f32_16x16x32_bf16(Bt[n][k], At[m][k], acc[ai][bj][m][n], 0, 0, 0); __builtin_amdgcn_s_setprio(0); } while (0)
; #define PG8_WAIT_V(n) asm volatile("s_waitcnt vmcnt(" #n ")" ::: "memory")
; #define PG8_WAIT_L(n) asm volatile("s_waitcnt lgkmcnt(" #n ")" ::: "memory")
; #define PG8_BAR __builtin_amdgcn_s_barrier()
; #define PG8_SCHED __builtin_amdgcn_sched_barrier(0)
; template <class Epi, class Sched, bool ALIGN_EPI = false, bool SP2 = false>
; __device__ __forceinline__ void gemm_phase(PG8_LAS unsigned char* lds, const Gemm g, const Sched& S, const Epi& E) {
;     ...
;             PG8_WAIT_V(8); PG8_WAIT_L(0); PG8_BAR; PG8_MMA(0, 0, At, B0); PG8_MMA(0, 1, At, B1); PG8_BAR; PG8_SCHED;
;             PG8_LDA(At, 0, 1); PG8_STAGE(PG8_SB(0, 0), b2, voffB); PG8_STAGE(PG8_SB(0, 1), b2 + hstep, voffB); PG8_STAGE(PG8_SA(0, 0), a2, voffA);
	v_mfma_f32_16x16x32_bf16 v[132:135], v[144:147], v[176:179], v[132:135]
	v_mfma_f32_16x16x32_bf16 v[128:131], v[152:155], v[176:179], v[128:131]
	v_mfma_f32_16x16x32_bf16 v[116:119], v[144:147], v[184:187], v[116:119]
	v_mfma_f32_16x16x32_bf16 v[112:115], v[152:155], v[184:187], v[112:115]
	v_mfma_f32_16x16x32_bf16 v[100:103], v[144:147], v[192:195], v[100:103]
	v_mfma_f32_16x16x32_bf16 v[96:99], v[152:155], v[192:195], v[96:99]
	v_mfma_f32_16x16x32_bf16 v[84:87], v[144:147], v[200:203], v[84:87]
	v_mfma_f32_16x16x32_bf16 v[80:83], v[152:155], v[200:203], v[80:83]
	v_mfma_f32_16x16x32_bf16 v[132:135], v[148:151], v[180:183], v[132:135]
	v_mfma_f32_16x16x32_bf16 v[128:131], v[156:159], v[180:183], v[128:131]
	v_mfma_f32_16x16x32_bf16 v[116:119], v[148:151], v[188:191], v[116:119]
	v_mfma_f32_16x16x32_bf16 v[112:115], v[156:159], v[188:191], v[112:115]
	v_mfma_f32_16x16x32_bf16 v[100:103], v[148:151], v[196:199], v[100:103]
	v_mfma_f32_16x16x32_bf16 v[96:99], v[156:159], v[196:199], v[96:99]
	v_mfma_f32_16x16x32_bf16 v[84:87], v[148:151], v[204:207], v[84:87]
	v_mfma_f32_16x16x32_bf16 v[80:83], v[156:159], v[204:207], v[80:83]
	s_setprio 0
	s_barrier
	s_add_i32 s82, s75, s64
	s_mov_b64 s[96:97], s[60:61]

; #define PG8_STAGE(bufoff, gbase, voff) do { _Pragma("unroll") for (int _i = 0; _i < 2; ++_i) \
;         __builtin_amdgcn_global_load_lds((const unsigned*)((const char*)(gbase) + (voff)[_i]), (PG8_LAS unsigned*)(lds + (bufoff) + ldsw + _i * 8192), 16, 0, 0); } while (0)
; #define PG8_LDA(dst, b, h) do { _Pragma("unroll") for (int m = 0; m < 4; ++m) _Pragma("unroll") for (int k = 0; k < 2; ++k) dst[m][k] = *(const PG8_LAS bf16x8*)(lds + PG8_SA(b, h) + aoff + m * 2048 + k * 1024); } while (0)
; template <class Epi, class Sched, bool ALIGN_EPI = false, bool SP2 = false>
; __device__ __forceinline__ void gemm_phase(PG8_LAS unsigned char* lds, const Gemm g, const Sched& S, const Epi& E) {
;     ...
;             PG8_LDA(At, 0, 1); PG8_STAGE(PG8_SB(0, 0), b2, voffB); PG8_STAGE(PG8_SB(0, 1), b2 + hstep, voffB); PG8_STAGE(PG8_SA(0, 0), a2, voffA);
	s_mov_b32 m0, s82
	ds_read_b128 v[176:179], v213 offset:16384
	ds_read_b128 v[180:183], v213 offset:17408
	ds_read_b128 v[184:187], v213 offset:18432
	ds_read_b128 v[188:191], v213 offset:19456
	ds_read_b128 v[192:195], v213 offset:20480
	ds_read_b128 v[196:199], v213 offset:21504
	ds_read_b128 v[200:203], v213 offset:22528
	ds_read_b128 v[204:207], v213 offset:23552
	global_load_lds_dwordx4 v162, s[60:61]
	s_add_i32 m0, s82, 0x2000
	s_add_u32 s82, s60, 0x80000

; #define PG8_STAGE(bufoff, gbase, voff) do { _Pragma("unroll") for (int _i = 0; _i < 2; ++_i) \
;         __builtin_amdgcn_global_load_lds((const unsigned*)((const char*)(gbase) + (voff)[_i]), (PG8_LAS unsigned*)(lds + (bufoff) + ldsw + _i * 8192), 16, 0, 0); } while (0)
; #define PG8_LDA(dst, b, h) do { _Pragma("unroll") for (int m = 0; m < 4; ++m) _Pragma("unroll") for (int k = 0; k < 2; ++k) dst[m][k] = *(const PG8_LAS bf16x8*)(lds + PG8_SA(b, h) + aoff + m * 2048 + k * 1024); } while (0)
; template <class Epi, class Sched, bool ALIGN_EPI = false, bool SP2 = false>
; __device__ __forceinline__ void gemm_phase(PG8_LAS unsigned char* lds, const Gemm g, const Sched& S, const Epi& E) {
;     ...
;             PG8_LDA(At, 0, 1); PG8_STAGE(PG8_SB(0, 0), b2, voffB); PG8_STAGE(PG8_SB(0, 1), b2 + hstep, voffB); PG8_STAGE(PG8_SA(0, 0), a2, voffA);
	s_addc_u32 s83, s61, 0
	s_add_i32 s84, s76, s64
	global_load_lds_dwordx4 v166, s[60:61]

; #define PG8_STAGE(bufoff, gbase, voff) do { _Pragma("unroll") for (int _i = 0; _i < 2; ++_i) \
;         __builtin_amdgcn_global_load_lds((const unsigned*)((const char*)(gbase) + (voff)[_i]), (PG8_LAS unsigned*)(lds + (bufoff) + ldsw + _i * 8192), 16, 0, 0); } while (0)
; #define PG8_LDA(dst, b, h) do { _Pragma("unroll") for (int m = 0; m < 4; ++m) _Pragma("unroll") for (int k = 0; k < 2; ++k) dst[m][k] = *(const PG8_LAS bf16x8*)(lds + PG8_SA(b, h) + aoff + m * 2048 + k * 1024); } while (0)
; template <class Epi, class Sched, bool ALIGN_EPI = false, bool SP2 = false>
; __device__ __forceinline__ void gemm_phase(PG8_LAS unsigned char* lds, const Gemm g, const Sched& S, const Epi& E) {
;     ...
;             PG8_LDA(At, 0, 1); PG8_STAGE(PG8_SB(0, 0), b2, voffB); PG8_STAGE(PG8_SB(0, 1), b2 + hstep, voffB); PG8_STAGE(PG8_SA(0, 0), a2, voffA);
	s_mov_b32 m0, s84
	s_nop 0
	global_load_lds_dwordx4 v162, s[82:83]

; #define PG8_STAGE(bufoff, gbase, voff) do { _Pragma("unroll") for (int _i = 0; _i < 2; ++_i) \
;         __builtin_amdgcn_global_load_lds((const unsigned*)((const char*)(gbase) + (voff)[_i]), (PG8_LAS unsigned*)(lds + (bufoff) + ldsw + _i * 8192), 16, 0, 0); } while (0)
; #define PG8_LDA(dst, b, h) do { _Pragma("unroll") for (int m = 0; m < 4; ++m) _Pragma("unroll") for (int k = 0; k < 2; ++k) dst[m][k] = *(const PG8_LAS bf16x8*)(lds + PG8_SA(b, h) + aoff + m * 2048 + k * 1024); } while (0)
; template <class Epi, class Sched, bool ALIGN_EPI = false, bool SP2 = false>
; __device__ __forceinline__ void gemm_phase(PG8_LAS unsigned char* lds, const Gemm g, const Sched& S, const Epi& E) {
;     ...
;             PG8_LDA(At, 0, 1); PG8_STAGE(PG8_SB(0, 0), b2, voffB); PG8_STAGE(PG8_SB(0, 1), b2 + hstep, voffB); PG8_STAGE(PG8_SA(0, 0), a2, voffA);
	s_add_i32 m0, s84, 0x2000
	s_nop 0
	global_load_lds_dwordx4 v166, s[82:83]
	s_mov_b64 s[98:99], s[62:63]

; #define PG8_STAGE(bufoff, gbase, voff) do { _Pragma("unroll") for (int _i = 0; _i < 2; ++_i) \
;         __builtin_amdgcn_global_load_lds((const unsigned*)((const char*)(gbase) + (voff)[_i]), (PG8_LAS unsigned*)(lds + (bufoff) + ldsw + _i * 8192), 16, 0, 0); } while (0)
; #define PG8_LDA(dst, b, h) do { _Pragma("unroll") for (int m = 0; m < 4; ++m) _Pragma("unroll") for (int k = 0; k < 2; ++k) dst[m][k] = *(const PG8_LAS bf16x8*)(lds + PG8_SA(b, h) + aoff + m * 2048 + k * 1024); } while (0)
; #define PG8_MMA(ai, bj, At, Bt) do { __builtin_amdgcn_s_setprio(1); _Pragma("unroll") for (int m = 0; m < 4; ++m) _Pragma("unroll") for (int n = 0; n < 2; ++n) _Pragma("unroll") for (int k = 0; k < 2; ++k) \
;         acc[ai][bj][m][n] = __builtin_amdgcn_mfma_f32_16x16x32_bf16(Bt[n][k], At[m][k], acc[ai][bj][m][n], 0, 0, 0); __builtin_amdgcn_s_setprio(0); } while (0)
; #define PG8_WAIT_V(n) asm volatile("s_waitcnt vmcnt(" #n ")" ::: "memory")
; #define PG8_WAIT_L(n) asm volatile("s_waitcnt lgkmcnt(" #n ")" ::: "memory")
; #define PG8_BAR __builtin_amdgcn_s_barrier()
; #define PG8_SCHED __builtin_amdgcn_sched_barrier(0)
; template <class Epi, class Sched, bool ALIGN_EPI = false, bool SP2 = false>
; __device__ __forceinline__ void gemm_phase(PG8_LAS unsigned char* lds, const Gemm g, const Sched& S, const Epi& E) {
;     ...
;             PG8_LDA(At, 0, 1); PG8_STAGE(PG8_SB(0, 0), b2, voffB); PG8_STAGE(PG8_SB(0, 1), b2 + hstep, voffB); PG8_STAGE(PG8_SA(0, 0), a2, voffA);
;             PG8_WAIT_V(8); PG8_WAIT_L(0); PG8_BAR; PG8_MMA(1, 0, At, B0); PG8_MMA(1, 1, At, B1); PG8_BAR; PG8_SCHED;
	s_mov_b32 m0, s57
	s_nop 0
	global_load_lds_dwordx4 v160, s[62:63]
	s_mov_b32 m0, s65
	s_nop 0
	global_load_lds_dwordx4 v164, s[62:63]
	s_waitcnt vmcnt(8)
	s_waitcnt lgkmcnt(0)
	s_barrier
	s_setprio 1
	s_waitcnt lgkmcnt(0)
	v_mfma_f32_16x16x32_bf16 v[60:63], v[64:67], v[176:179], v[60:63]
	v_mfma_f32_16x16x32_bf16 v[56:59], v[72:75], v[176:179], v[56:59]
	v_mfma_f32_16x16x32_bf16 v[44:47], v[64:67], v[184:187], v[44:47]
	v_mfma_f32_16x16x32_bf16 v[40:43], v[72:75], v[184:187], v[40:43]
	v_mfma_f32_16x16x32_bf16 v[28:31], v[64:67], v[192:195], v[28:31]
	v_mfma_f32_16x16x32_bf16 v[24:27], v[72:75], v[192:195], v[24:27]
	v_mfma_f32_16x16x32_bf16 v[12:15], v[64:67], v[200:203], v[12:15]
	v_mfma_f32_16x16x32_bf16 v[8:11], v[72:75], v[200:203], v[8:11]
	v_mfma_f32_16x16x32_bf16 v[60:63], v[68:71], v[180:183], v[60:63]
	v_mfma_f32_16x16x32_bf16 v[56:59], v[76:79], v[180:183], v[56:59]
	v_mfma_f32_16x16x32_bf16 v[44:47], v[68:71], v[188:191], v[44:47]
	v_mfma_f32_16x16x32_bf16 v[40:43], v[76:79], v[188:191], v[40:43]
	v_mfma_f32_16x16x32_bf16 v[28:31], v[68:71], v[196:199], v[28:31]
	v_mfma_f32_16x16x32_bf16 v[24:27], v[76:79], v[196:199], v[24:27]
	v_mfma_f32_16x16x32_bf16 v[12:15], v[68:71], v[204:207], v[12:15]
	v_mfma_f32_16x16x32_bf16 v[8:11], v[76:79], v[204:207], v[8:11]


; #define PG8_STAGE(bufoff, gbase, voff) do { _Pragma("unroll") for (int _i = 0; _i < 2; ++_i) \
;         __builtin_amdgcn_global_load_lds((const unsigned*)((const char*)(gbase) + (voff)[_i]), (PG8_LAS unsigned*)(lds + (bufoff) + ldsw + _i * 8192), 16, 0, 0); } while (0)
; #define PG8_LDA(dst, b, h) do { _Pragma("unroll") for (int m = 0; m < 4; ++m) _Pragma("unroll") for (int k = 0; k < 2; ++k) dst[m][k] = *(const PG8_LAS bf16x8*)(lds + PG8_SA(b, h) + aoff + m * 2048 + k * 1024); } while (0)
; #define PG8_LDB(dst, b, h) do { _Pragma("unroll") for (int n = 0; n < 2; ++n) _Pragma("unroll") for (int k = 0; k < 2; ++k) dst[n][k] = *(const PG8_LAS bf16x8*)(lds + PG8_SB(b, h) + boff + n * 2048 + k * 1024); } while (0)
; #define PG8_MMA(ai, bj, At, Bt) do { __builtin_amdgcn_s_setprio(1); _Pragma("unroll") for (int m = 0; m < 4; ++m) _Pragma("unroll") for (int n = 0; n < 2; ++n) _Pragma("unroll") for (int k = 0; k < 2; ++k) \
;         acc[ai][bj][m][n] = __builtin_amdgcn_mfma_f32_16x16x32_bf16(Bt[n][k], At[m][k], acc[ai][bj][m][n], 0, 0, 0); __builtin_amdgcn_s_setprio(0); } while (0)
; #define PG8_WAIT_V(n) asm volatile("s_waitcnt vmcnt(" #n ")" ::: "memory")
; #define PG8_WAIT_L(n) asm volatile("s_waitcnt lgkmcnt(" #n ")" ::: "memory")
; #define PG8_BAR __builtin_amdgcn_s_barrier()
; #define PG8_SCHED __builtin_amdgcn_sched_barrier(0)
; template <class Epi, class Sched, bool ALIGN_EPI = false, bool SP2 = false>
; __device__ __forceinline__ void gemm_phase(PG8_LAS unsigned char* lds, const Gemm g, const Sched& S, const Epi& E) {
;     ...
;             PG8_WAIT_V(8); PG8_WAIT_L(0); PG8_BAR; PG8_MMA(1, 0, At, B0); PG8_MMA(1, 1, At, B1); PG8_BAR; PG8_SCHED;
;             PG8_LDB(B0, 1, 0); PG8_LDB(B1, 1, 1); PG8_SCHED; PG8_LDA(At, 1, 0); PG8_STAGE(PG8_SA(0, 1), a2 + hstep, voffA);
	v_mfma_f32_16x16x32_bf16 v[52:55], v[144:147], v[176:179], v[52:55]
	v_mfma_f32_16x16x32_bf16 v[48:51], v[152:155], v[176:179], v[48:51]
	v_mfma_f32_16x16x32_bf16 v[36:39], v[144:147], v[184:187], v[36:39]
	v_mfma_f32_16x16x32_bf16 v[32:35], v[152:155], v[184:187], v[32:35]
	v_mfma_f32_16x16x32_bf16 v[20:23], v[144:147], v[192:195], v[20:23]
	v_mfma_f32_16x16x32_bf16 v[16:19], v[152:155], v[192:195], v[16:19]
	v_mfma_f32_16x16x32_bf16 v[4:7], v[144:147], v[200:203], v[4:7]
	v_mfma_f32_16x16x32_bf16 v[0:3], v[152:155], v[200:203], v[0:3]
	v_mfma_f32_16x16x32_bf16 v[52:55], v[148:151], v[180:183], v[52:55]
	v_mfma_f32_16x16x32_bf16 v[48:51], v[156:159], v[180:183], v[48:51]
	v_mfma_f32_16x16x32_bf16 v[36:39], v[148:151], v[188:191], v[36:39]
	v_mfma_f32_16x16x32_bf16 v[32:35], v[156:159], v[188:191], v[32:35]
	v_mfma_f32_16x16x32_bf16 v[20:23], v[148:151], v[196:199], v[20:23]
	v_mfma_f32_16x16x32_bf16 v[16:19], v[156:159], v[196:199], v[16:19]
	v_mfma_f32_16x16x32_bf16 v[4:7], v[148:151], v[204:207], v[4:7]
	v_mfma_f32_16x16x32_bf16 v[0:3], v[156:159], v[204:207], v[0:3]
	s_setprio 0
	s_barrier
	s_add_i32 s82, 0, 0x18000
	s_add_i32 s83, 0, 0x1c000


; #define PG8_STAGE(bufoff, gbase, voff) do { _Pragma("unroll") for (int _i = 0; _i < 2; ++_i) \
;         __builtin_amdgcn_global_load_lds((const unsigned*)((const char*)(gbase) + (voff)[_i]), (PG8_LAS unsigned*)(lds + (bufoff) + ldsw + _i * 8192), 16, 0, 0); } while (0)
; #define PG8_LDA(dst, b, h) do { _Pragma("unroll") for (int m = 0; m < 4; ++m) _Pragma("unroll") for (int k = 0; k < 2; ++k) dst[m][k] = *(const PG8_LAS bf16x8*)(lds + PG8_SA(b, h) + aoff + m * 2048 + k * 1024); } while (0)
; #define PG8_LDB(dst, b, h) do { _Pragma("unroll") for (int n = 0; n < 2; ++n) _Pragma("unroll") for (int k = 0; k < 2; ++k) dst[n][k] = *(const PG8_LAS bf16x8*)(lds + PG8_SB(b, h) + boff + n * 2048 + k * 1024); } while (0)
; #define PG8_SCHED __builtin_amdgcn_sched_barrier(0)
; template <class Epi, class Sched, bool ALIGN_EPI = false, bool SP2 = false>
; __device__ __forceinline__ void gemm_phase(PG8_LAS unsigned char* lds, const Gemm g, const Sched& S, const Epi& E) {
;     ...
;             PG8_LDB(B0, 1, 0); PG8_LDB(B1, 1, 1); PG8_SCHED; PG8_LDA(At, 1, 0); PG8_STAGE(PG8_SA(0, 1), a2 + hstep, voffA);
	ds_read_b128 v[64:67], v254
	ds_read_b128 v[68:71], v254 offset:1024
	ds_read_b128 v[72:75], v254 offset:2048
	ds_read_b128 v[76:79], v254 offset:3072
	ds_read_b128 v[144:147], v255
	ds_read_b128 v[148:151], v255 offset:1024
	ds_read_b128 v[152:155], v255 offset:2048
	ds_read_b128 v[156:159], v255 offset:3072
	s_add_u32 s62, s62, 0x80000
	s_addc_u32 s63, s63, 0
	s_mov_b32 m0, s67

; #define PG8_STAGE(bufoff, gbase, voff) do { _Pragma("unroll") for (int _i = 0; _i < 2; ++_i) \
;         __builtin_amdgcn_global_load_lds((const unsigned*)((const char*)(gbase) + (voff)[_i]), (PG8_LAS unsigned*)(lds + (bufoff) + ldsw + _i * 8192), 16, 0, 0); } while (0)
; #define PG8_LDA(dst, b, h) do { _Pragma("unroll") for (int m = 0; m < 4; ++m) _Pragma("unroll") for (int k = 0; k < 2; ++k) dst[m][k] = *(const PG8_LAS bf16x8*)(lds + PG8_SA(b, h) + aoff + m * 2048 + k * 1024); } while (0)
; #define PG8_LDB(dst, b, h) do { _Pragma("unroll") for (int n = 0; n < 2; ++n) _Pragma("unroll") for (int k = 0; k < 2; ++k) dst[n][k] = *(const PG8_LAS bf16x8*)(lds + PG8_SB(b, h) + boff + n * 2048 + k * 1024); } while (0)
; #define PG8_SCHED __builtin_amdgcn_sched_barrier(0)
; template <class Epi, class Sched, bool ALIGN_EPI = false, bool SP2 = false>
; __device__ __forceinline__ void gemm_phase(PG8_LAS unsigned char* lds, const Gemm g, const Sched& S, const Epi& E) {
;     ...
;             PG8_LDB(B0, 1, 0); PG8_LDB(B1, 1, 1); PG8_SCHED; PG8_LDA(At, 1, 0); PG8_STAGE(PG8_SA(0, 1), a2 + hstep, voffA);
	ds_read_b128 v[176:179], v213 offset:32768
	ds_read_b128 v[180:183], v213 offset:33792
	ds_read_b128 v[184:187], v213 offset:34816
	ds_read_b128 v[188:191], v213 offset:35840
	ds_read_b128 v[192:195], v213 offset:36864
	ds_read_b128 v[196:199], v213 offset:37888
	ds_read_b128 v[200:203], v213 offset:38912
	ds_read_b128 v[204:207], v213 offset:39936
	global_load_lds_dwordx4 v160, s[62:63]

; #define PG8_STAGE(bufoff, gbase, voff) do { _Pragma("unroll") for (int _i = 0; _i < 2; ++_i) \
;         __builtin_amdgcn_global_load_lds((const unsigned*)((const char*)(gbase) + (voff)[_i]), (PG8_LAS unsigned*)(lds + (bufoff) + ldsw + _i * 8192), 16, 0, 0); } while (0)
; #define PG8_LDA(dst, b, h) do { _Pragma("unroll") for (int m = 0; m < 4; ++m) _Pragma("unroll") for (int k = 0; k < 2; ++k) dst[m][k] = *(const PG8_LAS bf16x8*)(lds + PG8_SA(b, h) + aoff + m * 2048 + k * 1024); } while (0)
; #define PG8_LDB(dst, b, h) do { _Pragma("unroll") for (int n = 0; n < 2; ++n) _Pragma("unroll") for (int k = 0; k < 2; ++k) dst[n][k] = *(const PG8_LAS bf16x8*)(lds + PG8_SB(b, h) + boff + n * 2048 + k * 1024); } while (0)
; #define PG8_MMA(ai, bj, At, Bt) do { __builtin_amdgcn_s_setprio(1); _Pragma("unroll") for (int m = 0; m < 4; ++m) _Pragma("unroll") for (int n = 0; n < 2; ++n) _Pragma("unroll") for (int k = 0; k < 2; ++k) \
;         acc[ai][bj][m][n] = __builtin_amdgcn_mfma_f32_16x16x32_bf16(Bt[n][k], At[m][k], acc[ai][bj][m][n], 0, 0, 0); __builtin_amdgcn_s_setprio(0); } while (0)
; #define PG8_WAIT_V(n) asm volatile("s_waitcnt vmcnt(" #n ")" ::: "memory")
; #define PG8_WAIT_L(n) asm volatile("s_waitcnt lgkmcnt(" #n ")" ::: "memory")
; #define PG8_BAR __builtin_amdgcn_s_barrier()
; #define PG8_SCHED __builtin_amdgcn_sched_barrier(0)
; template <class Epi, class Sched, bool ALIGN_EPI = false, bool SP2 = false>
; __device__ __forceinline__ void gemm_phase(PG8_LAS unsigned char* lds, const Gemm g, const Sched& S, const Epi& E) {
;     ...
;             PG8_LDB(B0, 1, 0); PG8_LDB(B1, 1, 1); PG8_SCHED; PG8_LDA(At, 1, 0); PG8_STAGE(PG8_SA(0, 1), a2 + hstep, voffA);
;             PG8_WAIT_V(8); PG8_WAIT_L(0); PG8_BAR; PG8_MMA(0, 0, At, B0); PG8_MMA(0, 1, At, B1); PG8_BAR; PG8_SCHED;
	s_mov_b32 m0, s68
	s_nop 0
	global_load_lds_dwordx4 v164, s[62:63]
	s_waitcnt vmcnt(8)
	s_waitcnt lgkmcnt(0)
	s_barrier
	s_setprio 1
	s_waitcnt lgkmcnt(0)
	v_mfma_f32_16x16x32_bf16 v[140:143], v[64:67], v[176:179], v[140:143]
	v_mfma_f32_16x16x32_bf16 v[136:139], v[72:75], v[176:179], v[136:139]
	v_mfma_f32_16x16x32_bf16 v[124:127], v[64:67], v[184:187], v[124:127]
	v_mfma_f32_16x16x32_bf16 v[120:123], v[72:75], v[184:187], v[120:123]
	v_mfma_f32_16x16x32_bf16 v[108:111], v[64:67], v[192:195], v[108:111]
	v_mfma_f32_16x16x32_bf16 v[104:107], v[72:75], v[192:195], v[104:107]
	v_mfma_f32_16x16x32_bf16 v[92:95], v[64:67], v[200:203], v[92:95]
	v_mfma_f32_16x16x32_bf16 v[88:91], v[72:75], v[200:203], v[88:91]
	v_mfma_f32_16x16x32_bf16 v[140:143], v[68:71], v[180:183], v[140:143]
	v_mfma_f32_16x16x32_bf16 v[136:139], v[76:79], v[180:183], v[136:139]
	v_mfma_f32_16x16x32_bf16 v[124:127], v[68:71], v[188:191], v[124:127]
	v_mfma_f32_16x16x32_bf16 v[120:123], v[76:79], v[188:191], v[120:123]
	v_mfma_f32_16x16x32_bf16 v[108:111], v[68:71], v[196:199], v[108:111]
	v_mfma_f32_16x16x32_bf16 v[104:107], v[76:79], v[196:199], v[104:107]
	v_mfma_f32_16x16x32_bf16 v[92:95], v[68:71], v[204:207], v[92:95]
	v_mfma_f32_16x16x32_bf16 v[88:91], v[76:79], v[204:207], v[88:91]


; #define PG8_STAGE(bufoff, gbase, voff) do { _Pragma("unroll") for (int _i = 0; _i < 2; ++_i) \
;         __builtin_amdgcn_global_load_lds((const unsigned*)((const char*)(gbase) + (voff)[_i]), (PG8_LAS unsigned*)(lds + (bufoff) + ldsw + _i * 8192), 16, 0, 0); } while (0)
; #define PG8_LDA(dst, b, h) do { _Pragma("unroll") for (int m = 0; m < 4; ++m) _Pragma("unroll") for (int k = 0; k < 2; ++k) dst[m][k] = *(const PG8_LAS bf16x8*)(lds + PG8_SA(b, h) + aoff + m * 2048 + k * 1024); } while (0)
; #define PG8_MMA(ai, bj, At, Bt) do { __builtin_amdgcn_s_setprio(1); _Pragma("unroll") for (int m = 0; m < 4; ++m) _Pragma("unroll") for (int n = 0; n < 2; ++n) _Pragma("unroll") for (int k = 0; k < 2; ++k) \
;         acc[ai][bj][m][n] = __builtin_amdgcn_mfma_f32_16x16x32_bf16(Bt[n][k], At[m][k], acc[ai][bj][m][n], 0, 0, 0); __builtin_amdgcn_s_setprio(0); } while (0)
; #define PG8_WAIT_V(n) asm volatile("s_waitcnt vmcnt(" #n ")" ::: "memory")
; #define PG8_WAIT_L(n) asm volatile("s_waitcnt lgkmcnt(" #n ")" ::: "memory")
; #define PG8_BAR __builtin_amdgcn_s_barrier()
; #define PG8_SCHED __builtin_amdgcn_sched_barrier(0)
; template <class Epi, class Sched, bool ALIGN_EPI = false, bool SP2 = false>
; __device__ __forceinline__ void gemm_phase(PG8_LAS unsigned char* lds, const Gemm g, const Sched& S, const Epi& E) {
;     ...
;             PG8_WAIT_V(8); PG8_WAIT_L(0); PG8_BAR; PG8_MMA(0, 0, At, B0); PG8_MMA(0, 1, At, B1); PG8_BAR; PG8_SCHED;
;             PG8_LDA(At, 1, 1); PG8_STAGE(PG8_SB(1, 0), b3, voffB); PG8_STAGE(PG8_SB(1, 1), b3 + hstep, voffB); PG8_STAGE(PG8_SA(1, 0), a3, voffA);
	v_mfma_f32_16x16x32_bf16 v[132:135], v[144:147], v[176:179], v[132:135]
	v_mfma_f32_16x16x32_bf16 v[128:131], v[152:155], v[176:179], v[128:131]
	v_mfma_f32_16x16x32_bf16 v[116:119], v[144:147], v[184:187], v[116:119]
	v_mfma_f32_16x16x32_bf16 v[112:115], v[152:155], v[184:187], v[112:115]
	v_mfma_f32_16x16x32_bf16 v[100:103], v[144:147], v[192:195], v[100:103]
	v_mfma_f32_16x16x32_bf16 v[96:99], v[152:155], v[192:195], v[96:99]
	v_mfma_f32_16x16x32_bf16 v[84:87], v[144:147], v[200:203], v[84:87]
	v_mfma_f32_16x16x32_bf16 v[80:83], v[152:155], v[200:203], v[80:83]
	v_mfma_f32_16x16x32_bf16 v[132:135], v[148:151], v[180:183], v[132:135]
	v_mfma_f32_16x16x32_bf16 v[128:131], v[156:159], v[180:183], v[128:131]
	v_mfma_f32_16x16x32_bf16 v[116:119], v[148:151], v[188:191], v[116:119]
	v_mfma_f32_16x16x32_bf16 v[112:115], v[156:159], v[188:191], v[112:115]
	v_mfma_f32_16x16x32_bf16 v[100:103], v[148:151], v[196:199], v[100:103]
	v_mfma_f32_16x16x32_bf16 v[96:99], v[156:159], v[196:199], v[96:99]
	v_mfma_f32_16x16x32_bf16 v[84:87], v[148:151], v[204:207], v[84:87]
	v_mfma_f32_16x16x32_bf16 v[80:83], v[156:159], v[204:207], v[80:83]
	s_setprio 0
	s_barrier
	s_add_i32 s62, s82, s64

; #define PG8_STAGE(bufoff, gbase, voff) do { _Pragma("unroll") for (int _i = 0; _i < 2; ++_i) \
;         __builtin_amdgcn_global_load_lds((const unsigned*)((const char*)(gbase) + (voff)[_i]), (PG8_LAS unsigned*)(lds + (bufoff) + ldsw + _i * 8192), 16, 0, 0); } while (0)
; #define PG8_LDA(dst, b, h) do { _Pragma("unroll") for (int m = 0; m < 4; ++m) _Pragma("unroll") for (int k = 0; k < 2; ++k) dst[m][k] = *(const PG8_LAS bf16x8*)(lds + PG8_SA(b, h) + aoff + m * 2048 + k * 1024); } while (0)
; template <class Epi, class Sched, bool ALIGN_EPI = false, bool SP2 = false>
; __device__ __forceinline__ void gemm_phase(PG8_LAS unsigned char* lds, const Gemm g, const Sched& S, const Epi& E) {
;     ...
;             PG8_LDA(At, 1, 1); PG8_STAGE(PG8_SB(1, 0), b3, voffB); PG8_STAGE(PG8_SB(1, 1), b3 + hstep, voffB); PG8_STAGE(PG8_SA(1, 0), a3, voffA);
	s_mov_b32 m0, s62
	ds_read_b128 v[176:179], v213 offset:49152
	ds_read_b128 v[180:183], v213 offset:50176
	ds_read_b128 v[184:187], v213 offset:51200
	ds_read_b128 v[188:191], v213 offset:52224
	ds_read_b128 v[192:195], v213 offset:53248
	ds_read_b128 v[196:199], v213 offset:54272
	ds_read_b128 v[200:203], v213 offset:55296
	ds_read_b128 v[204:207], v213 offset:56320
	global_load_lds_dwordx4 v250, s[96:97]
	s_add_i32 m0, s62, 0x2000
	s_add_u32 s60, s60, 0x80080

; #define PG8_STAGE(bufoff, gbase, voff) do { _Pragma("unroll") for (int _i = 0; _i < 2; ++_i) \
;         __builtin_amdgcn_global_load_lds((const unsigned*)((const char*)(gbase) + (voff)[_i]), (PG8_LAS unsigned*)(lds + (bufoff) + ldsw + _i * 8192), 16, 0, 0); } while (0)
; #define PG8_LDA(dst, b, h) do { _Pragma("unroll") for (int m = 0; m < 4; ++m) _Pragma("unroll") for (int k = 0; k < 2; ++k) dst[m][k] = *(const PG8_LAS bf16x8*)(lds + PG8_SA(b, h) + aoff + m * 2048 + k * 1024); } while (0)
; template <class Epi, class Sched, bool ALIGN_EPI = false, bool SP2 = false>
; __device__ __forceinline__ void gemm_phase(PG8_LAS unsigned char* lds, const Gemm g, const Sched& S, const Epi& E) {
;     ...
;             PG8_LDA(At, 1, 1); PG8_STAGE(PG8_SB(1, 0), b3, voffB); PG8_STAGE(PG8_SB(1, 1), b3 + hstep, voffB); PG8_STAGE(PG8_SA(1, 0), a3, voffA);
	s_addc_u32 s61, s61, 0
	s_add_i32 s62, s83, s64
	global_load_lds_dwordx4 v251, s[96:97]

; #define PG8_STAGE(bufoff, gbase, voff) do { _Pragma("unroll") for (int _i = 0; _i < 2; ++_i) \
;         __builtin_amdgcn_global_load_lds((const unsigned*)((const char*)(gbase) + (voff)[_i]), (PG8_LAS unsigned*)(lds + (bufoff) + ldsw + _i * 8192), 16, 0, 0); } while (0)
; #define PG8_LDA(dst, b, h) do { _Pragma("unroll") for (int m = 0; m < 4; ++m) _Pragma("unroll") for (int k = 0; k < 2; ++k) dst[m][k] = *(const PG8_LAS bf16x8*)(lds + PG8_SA(b, h) + aoff + m * 2048 + k * 1024); } while (0)
; template <class Epi, class Sched, bool ALIGN_EPI = false, bool SP2 = false>
; __device__ __forceinline__ void gemm_phase(PG8_LAS unsigned char* lds, const Gemm g, const Sched& S, const Epi& E) {
;     ...
;             PG8_LDA(At, 1, 1); PG8_STAGE(PG8_SB(1, 0), b3, voffB); PG8_STAGE(PG8_SB(1, 1), b3 + hstep, voffB); PG8_STAGE(PG8_SA(1, 0), a3, voffA);
	s_mov_b32 m0, s62
	s_nop 0
	global_load_lds_dwordx4 v162, s[60:61]

; #define PG8_STAGE(bufoff, gbase, voff) do { _Pragma("unroll") for (int _i = 0; _i < 2; ++_i) \
;         __builtin_amdgcn_global_load_lds((const unsigned*)((const char*)(gbase) + (voff)[_i]), (PG8_LAS unsigned*)(lds + (bufoff) + ldsw + _i * 8192), 16, 0, 0); } while (0)
; #define PG8_LDA(dst, b, h) do { _Pragma("unroll") for (int m = 0; m < 4; ++m) _Pragma("unroll") for (int k = 0; k < 2; ++k) dst[m][k] = *(const PG8_LAS bf16x8*)(lds + PG8_SA(b, h) + aoff + m * 2048 + k * 1024); } while (0)
; template <class Epi, class Sched, bool ALIGN_EPI = false, bool SP2 = false>
; __device__ __forceinline__ void gemm_phase(PG8_LAS unsigned char* lds, const Gemm g, const Sched& S, const Epi& E) {
;     ...
;             PG8_LDA(At, 1, 1); PG8_STAGE(PG8_SB(1, 0), b3, voffB); PG8_STAGE(PG8_SB(1, 1), b3 + hstep, voffB); PG8_STAGE(PG8_SA(1, 0), a3, voffA);
	s_add_i32 m0, s62, 0x2000
	s_nop 0
	global_load_lds_dwordx4 v166, s[60:61]

; #define PG8_STAGE(bufoff, gbase, voff) do { _Pragma("unroll") for (int _i = 0; _i < 2; ++_i) \
;         __builtin_amdgcn_global_load_lds((const unsigned*)((const char*)(gbase) + (voff)[_i]), (PG8_LAS unsigned*)(lds + (bufoff) + ldsw + _i * 8192), 16, 0, 0); } while (0)
; #define PG8_LDA(dst, b, h) do { _Pragma("unroll") for (int m = 0; m < 4; ++m) _Pragma("unroll") for (int k = 0; k < 2; ++k) dst[m][k] = *(const PG8_LAS bf16x8*)(lds + PG8_SA(b, h) + aoff + m * 2048 + k * 1024); } while (0)
; template <class Epi, class Sched, bool ALIGN_EPI = false, bool SP2 = false>
; __device__ __forceinline__ void gemm_phase(PG8_LAS unsigned char* lds, const Gemm g, const Sched& S, const Epi& E) {
;     ...
;             PG8_LDA(At, 1, 1); PG8_STAGE(PG8_SB(1, 0), b3, voffB); PG8_STAGE(PG8_SB(1, 1), b3 + hstep, voffB); PG8_STAGE(PG8_SA(1, 0), a3, voffA);
	s_mov_b32 m0, s70
	s_nop 0
	global_load_lds_dwordx4 v252, s[98:99]

; #define PG8_STAGE(bufoff, gbase, voff) do { _Pragma("unroll") for (int _i = 0; _i < 2; ++_i) \
;         __builtin_amdgcn_global_load_lds((const unsigned*)((const char*)(gbase) + (voff)[_i]), (PG8_LAS unsigned*)(lds + (bufoff) + ldsw + _i * 8192), 16, 0, 0); } while (0)
; #define PG8_LDA(dst, b, h) do { _Pragma("unroll") for (int m = 0; m < 4; ++m) _Pragma("unroll") for (int k = 0; k < 2; ++k) dst[m][k] = *(const PG8_LAS bf16x8*)(lds + PG8_SA(b, h) + aoff + m * 2048 + k * 1024); } while (0)
; #define PG8_MMA(ai, bj, At, Bt) do { __builtin_amdgcn_s_setprio(1); _Pragma("unroll") for (int m = 0; m < 4; ++m) _Pragma("unroll") for (int n = 0; n < 2; ++n) _Pragma("unroll") for (int k = 0; k < 2; ++k) \
;         acc[ai][bj][m][n] = __builtin_amdgcn_mfma_f32_16x16x32_bf16(Bt[n][k], At[m][k], acc[ai][bj][m][n], 0, 0, 0); __builtin_amdgcn_s_setprio(0); } while (0)
; #define PG8_WAIT_V(n) asm volatile("s_waitcnt vmcnt(" #n ")" ::: "memory")
; #define PG8_WAIT_L(n) asm volatile("s_waitcnt lgkmcnt(" #n ")" ::: "memory")
; #define PG8_BAR __builtin_amdgcn_s_barrier()
; #define PG8_SCHED __builtin_amdgcn_sched_barrier(0)
; template <class Epi, class Sched, bool ALIGN_EPI = false, bool SP2 = false>
; __device__ __forceinline__ void gemm_phase(PG8_LAS unsigned char* lds, const Gemm g, const Sched& S, const Epi& E) {
;     ...
;             PG8_LDA(At, 1, 1); PG8_STAGE(PG8_SB(1, 0), b3, voffB); PG8_STAGE(PG8_SB(1, 1), b3 + hstep, voffB); PG8_STAGE(PG8_SA(1, 0), a3, voffA);
;             PG8_WAIT_V(8); PG8_WAIT_L(0); PG8_BAR; PG8_MMA(1, 0, At, B0); PG8_MMA(1, 1, At, B1); PG8_BAR; PG8_SCHED;
	s_mov_b32 m0, s71
	s_nop 0
	global_load_lds_dwordx4 v253, s[98:99]
	s_waitcnt vmcnt(8)
	s_waitcnt lgkmcnt(0)
	s_barrier
	s_setprio 1
	s_waitcnt lgkmcnt(0)
	v_mfma_f32_16x16x32_bf16 v[60:63], v[64:67], v[176:179], v[60:63]
	v_mfma_f32_16x16x32_bf16 v[56:59], v[72:75], v[176:179], v[56:59]
	v_mfma_f32_16x16x32_bf16 v[44:47], v[64:67], v[184:187], v[44:47]
	v_mfma_f32_16x16x32_bf16 v[40:43], v[72:75], v[184:187], v[40:43]
	v_mfma_f32_16x16x32_bf16 v[28:31], v[64:67], v[192:195], v[28:31]
	v_mfma_f32_16x16x32_bf16 v[24:27], v[72:75], v[192:195], v[24:27]
	v_mfma_f32_16x16x32_bf16 v[12:15], v[64:67], v[200:203], v[12:15]
	v_mfma_f32_16x16x32_bf16 v[8:11], v[72:75], v[200:203], v[8:11]
	v_mfma_f32_16x16x32_bf16 v[60:63], v[68:71], v[180:183], v[60:63]
	v_mfma_f32_16x16x32_bf16 v[56:59], v[76:79], v[180:183], v[56:59]
	v_mfma_f32_16x16x32_bf16 v[44:47], v[68:71], v[188:191], v[44:47]
	v_mfma_f32_16x16x32_bf16 v[40:43], v[76:79], v[188:191], v[40:43]
	v_mfma_f32_16x16x32_bf16 v[28:31], v[68:71], v[196:199], v[28:31]
	v_mfma_f32_16x16x32_bf16 v[24:27], v[76:79], v[196:199], v[24:27]
	v_mfma_f32_16x16x32_bf16 v[12:15], v[68:71], v[204:207], v[12:15]
	v_mfma_f32_16x16x32_bf16 v[8:11], v[76:79], v[204:207], v[8:11]


; #define PG8_MMA(ai, bj, At, Bt) do { __builtin_amdgcn_s_setprio(1); _Pragma("unroll") for (int m = 0; m < 4; ++m) _Pragma("unroll") for (int n = 0; n < 2; ++n) _Pragma("unroll") for (int k = 0; k < 2; ++k) \
;         acc[ai][bj][m][n] = __builtin_amdgcn_mfma_f32_16x16x32_bf16(Bt[n][k], At[m][k], acc[ai][bj][m][n], 0, 0, 0); __builtin_amdgcn_s_setprio(0); } while (0)
; #define PG8_WAIT_V(n) asm volatile("s_waitcnt vmcnt(" #n ")" ::: "memory")
; #define PG8_WAIT_L(n) asm volatile("s_waitcnt lgkmcnt(" #n ")" ::: "memory")
; #define PG8_BAR __builtin_amdgcn_s_barrier()
; #define PG8_SCHED __builtin_amdgcn_sched_barrier(0)
; template <class Epi, class Sched, bool ALIGN_EPI = false, bool SP2 = false>
; __device__ __forceinline__ void gemm_phase(PG8_LAS unsigned char* lds, const Gemm g, const Sched& S, const Epi& E) {
;     ...
;             PG8_WAIT_V(8); PG8_WAIT_L(0); PG8_BAR; PG8_MMA(1, 0, At, B0); PG8_MMA(1, 1, At, B1); PG8_BAR; PG8_SCHED;
;     ...
;         if constexpr (ALIGN_EPI) { if (wr == 0) PG8_BAR; }
	v_mfma_f32_16x16x32_bf16 v[52:55], v[144:147], v[176:179], v[52:55]
	v_mfma_f32_16x16x32_bf16 v[48:51], v[152:155], v[176:179], v[48:51]
	v_mfma_f32_16x16x32_bf16 v[36:39], v[144:147], v[184:187], v[36:39]
	v_mfma_f32_16x16x32_bf16 v[32:35], v[152:155], v[184:187], v[32:35]
	v_mfma_f32_16x16x32_bf16 v[20:23], v[144:147], v[192:195], v[20:23]
	v_mfma_f32_16x16x32_bf16 v[16:19], v[152:155], v[192:195], v[16:19]
	v_mfma_f32_16x16x32_bf16 v[4:7], v[144:147], v[200:203], v[4:7]
	v_mfma_f32_16x16x32_bf16 v[0:3], v[152:155], v[200:203], v[0:3]
	v_mfma_f32_16x16x32_bf16 v[52:55], v[148:151], v[180:183], v[52:55]
	v_mfma_f32_16x16x32_bf16 v[48:51], v[156:159], v[180:183], v[48:51]
	v_mfma_f32_16x16x32_bf16 v[36:39], v[148:151], v[188:191], v[36:39]
	v_mfma_f32_16x16x32_bf16 v[32:35], v[156:159], v[188:191], v[32:35]
	v_mfma_f32_16x16x32_bf16 v[20:23], v[148:151], v[196:199], v[20:23]
	v_mfma_f32_16x16x32_bf16 v[16:19], v[156:159], v[196:199], v[16:19]
	v_mfma_f32_16x16x32_bf16 v[4:7], v[148:151], v[204:207], v[4:7]
	v_mfma_f32_16x16x32_bf16 v[0:3], v[156:159], v[204:207], v[0:3]
	s_setprio 0
	s_barrier
	s_add_i32 s81, s81, 2
	s_add_u32 s58, s58, 0x100
	s_addc_u32 s59, s59, 0
	s_add_u32 s79, s79, 0x100
	s_addc_u32 s80, s80, 0
	s_cmp_gt_u32 s81, 29
	s_cbranch_scc0 .LBB0_333
	s_and_b64 vcc, exec, s[42:43]
	s_cbranch_vccz .LBB0_336
	s_barrier

; #define PG8_STAGE(bufoff, gbase, voff) do { _Pragma("unroll") for (int _i = 0; _i < 2; ++_i) \
;         __builtin_amdgcn_global_load_lds((const unsigned*)((const char*)(gbase) + (voff)[_i]), (PG8_LAS unsigned*)(lds + (bufoff) + ldsw + _i * 8192), 16, 0, 0); } while (0)
; #define PG8_LDA(dst, b, h) do { _Pragma("unroll") for (int m = 0; m < 4; ++m) _Pragma("unroll") for (int k = 0; k < 2; ++k) dst[m][k] = *(const PG8_LAS bf16x8*)(lds + PG8_SA(b, h) + aoff + m * 2048 + k * 1024); } while (0)
; #define PG8_LDB(dst, b, h) do { _Pragma("unroll") for (int n = 0; n < 2; ++n) _Pragma("unroll") for (int k = 0; k < 2; ++k) dst[n][k] = *(const PG8_LAS bf16x8*)(lds + PG8_SB(b, h) + boff + n * 2048 + k * 1024); } while (0)
; #define PG8_SCHED __builtin_amdgcn_sched_barrier(0)
; template <class Epi, class Sched, bool ALIGN_EPI = false, bool SP2 = false>
; __device__ __forceinline__ void gemm_phase(PG8_LAS unsigned char* lds, const Gemm g, const Sched& S, const Epi& E) {
;     ...
; #pragma unroll
;     for (int a = 0; a < 2; ++a)
; #pragma unroll
;         for (int b = 0; b < 2; ++b)
; #pragma unroll
;             for (int m = 0; m < 4; ++m)
; #pragma unroll
;                 for (int n = 0; n < 2; ++n) acc[a][b][m][n] = (f32x4){0.f, 0.f, 0.f, 0.f};
;     ...
;         const bool has_next = S.next(ui + 1, nxt);
;         const char* nA = has_next ? (const char*)g.A + (size_t)nxt.pm * tstep : cA; const char* nB = has_next ? (const char*)g.Bt + (size_t)nxt.pn * tstep : cB;
;         for (int t = 0; t < nt; t += 2) {
;             const bool last = (t == nt - 2);
;             const char* a1 = cA + (size_t)(t + 1) * kstep;
;             const char* a2 = last ? nA : cA + (size_t)(t + 2) * kstep; const char* b2 = last ? nB : cB + (size_t)(t + 2) * kstep;
;             const char* a3 = a2 + kstep; const char* b3 = b2 + kstep;
;             if (last && has_next) S.a_ready(nxt);
;             if constexpr (SP2) {
;             PG8_LDB(B0, 0, 0); PG8_LDB(B1, 0, 1); PG8_SCHED; PG8_LDA(At, 0, 0); PG8_STAGE(PG8_SA(1, 1), a1 + hstep, voffA);
.LBB0_427:
	s_ashr_i32 s55, s54, 31
	s_lshl_b64 s[56:57], s[54:55], 20
	s_add_u32 s56, s24, s56
	s_addc_u32 s57, s25, s57
	s_and_b64 s[58:59], s[4:5], exec
	s_cselect_b32 s55, s57, s11
	s_cselect_b32 s81, s56, s10
	s_ashr_i32 s53, s52, 31
	s_lshl_b64 s[58:59], s[52:53], 20
	s_add_u32 s58, s62, s58
	s_addc_u32 s59, s63, s59
	s_and_b64 s[60:61], s[4:5], exec
	s_cselect_b32 s53, s59, s13
	s_cselect_b32 s82, s58, s12
	s_add_u32 s10, s10, 0x80080
	s_addc_u32 s11, s11, 0
	s_add_u32 s83, s12, 0x100
	v_mov_b32_e32 v0, 0
	s_addc_u32 s84, s13, 0
	s_mov_b32 s85, -2
	v_mov_b32_e32 v1, v0
	v_mov_b32_e32 v2, v0
	v_mov_b32_e32 v3, v0
	v_mov_b32_e32 v4, v0
	v_mov_b32_e32 v5, v0
	v_mov_b32_e32 v6, v0
	v_mov_b32_e32 v7, v0
	v_mov_b32_e32 v16, v0
	v_mov_b32_e32 v17, v0
	v_mov_b32_e32 v18, v0
	v_mov_b32_e32 v19, v0
	v_mov_b32_e32 v20, v0
	v_mov_b32_e32 v21, v0
	v_mov_b32_e32 v22, v0
	v_mov_b32_e32 v23, v0
	v_mov_b32_e32 v32, v0
	v_mov_b32_e32 v33, v0
	v_mov_b32_e32 v34, v0
	v_mov_b32_e32 v35, v0
	v_mov_b32_e32 v36, v0
	v_mov_b32_e32 v37, v0
	v_mov_b32_e32 v38, v0
	v_mov_b32_e32 v39, v0
	v_mov_b32_e32 v48, v0
	v_mov_b32_e32 v49, v0
	v_mov_b32_e32 v50, v0
	v_mov_b32_e32 v51, v0
	v_mov_b32_e32 v52, v0
	v_mov_b32_e32 v53, v0
	v_mov_b32_e32 v54, v0
	v_mov_b32_e32 v55, v0
	v_mov_b32_e32 v8, v0
	v_mov_b32_e32 v9, v0
	v_mov_b32_e32 v10, v0
	v_mov_b32_e32 v11, v0
	v_mov_b32_e32 v12, v0
	v_mov_b32_e32 v13, v0
	v_mov_b32_e32 v14, v0
	v_mov_b32_e32 v15, v0
	v_mov_b32_e32 v24, v0
	v_mov_b32_e32 v25, v0
	v_mov_b32_e32 v26, v0
	v_mov_b32_e32 v27, v0
	v_mov_b32_e32 v28, v0
	v_mov_b32_e32 v29, v0
	v_mov_b32_e32 v30, v0
	v_mov_b32_e32 v31, v0
	v_mov_b32_e32 v40, v0
	v_mov_b32_e32 v41, v0
	v_mov_b32_e32 v42, v0
	v_mov_b32_e32 v43, v0
	v_mov_b32_e32 v44, v0
	v_mov_b32_e32 v45, v0
	v_mov_b32_e32 v46, v0
	v_mov_b32_e32 v47, v0
	v_mov_b32_e32 v56, v0
	v_mov_b32_e32 v57, v0
	v_mov_b32_e32 v58, v0
	v_mov_b32_e32 v59, v0
	v_mov_b32_e32 v60, v0
	v_mov_b32_e32 v61, v0
	v_mov_b32_e32 v62, v0
	v_mov_b32_e32 v63, v0
	v_mov_b32_e32 v64, v0
	v_mov_b32_e32 v65, v0
	v_mov_b32_e32 v66, v0
	v_mov_b32_e32 v67, v0
	v_mov_b32_e32 v68, v0
	v_mov_b32_e32 v69, v0
	v_mov_b32_e32 v70, v0
	v_mov_b32_e32 v71, v0
	v_mov_b32_e32 v80, v0
	v_mov_b32_e32 v81, v0
	v_mov_b32_e32 v82, v0
	v_mov_b32_e32 v83, v0
	v_mov_b32_e32 v84, v0
	v_mov_b32_e32 v85, v0
	v_mov_b32_e32 v86, v0
	v_mov_b32_e32 v87, v0
	v_mov_b32_e32 v96, v0
	v_mov_b32_e32 v97, v0
	v_mov_b32_e32 v98, v0
	v_mov_b32_e32 v99, v0
	v_mov_b32_e32 v100, v0
	v_mov_b32_e32 v101, v0
	v_mov_b32_e32 v102, v0
	v_mov_b32_e32 v103, v0
	v_mov_b32_e32 v112, v0
	v_mov_b32_e32 v113, v0
	v_mov_b32_e32 v114, v0
	v_mov_b32_e32 v115, v0
	v_mov_b32_e32 v116, v0
	v_mov_b32_e32 v117, v0
	v_mov_b32_e32 v118, v0
	v_mov_b32_e32 v119, v0
	v_mov_b32_e32 v72, v0
	v_mov_b32_e32 v73, v0
	v_mov_b32_e32 v74, v0
	v_mov_b32_e32 v75, v0
	v_mov_b32_e32 v76, v0
	v_mov_b32_e32 v77, v0
	v_mov_b32_e32 v78, v0
	v_mov_b32_e32 v79, v0
	v_mov_b32_e32 v88, v0
	v_mov_b32_e32 v89, v0
	v_mov_b32_e32 v90, v0
	v_mov_b32_e32 v91, v0
	v_mov_b32_e32 v92, v0
	v_mov_b32_e32 v93, v0
	v_mov_b32_e32 v94, v0
	v_mov_b32_e32 v95, v0
	v_mov_b32_e32 v104, v0
	v_mov_b32_e32 v105, v0
	v_mov_b32_e32 v106, v0
	v_mov_b32_e32 v107, v0
	v_mov_b32_e32 v108, v0
	v_mov_b32_e32 v109, v0
	v_mov_b32_e32 v110, v0
	v_mov_b32_e32 v111, v0
	v_mov_b32_e32 v120, v0
	v_mov_b32_e32 v121, v0
	v_mov_b32_e32 v122, v0
	v_mov_b32_e32 v123, v0
	v_mov_b32_e32 v124, v0
	v_mov_b32_e32 v125, v0
	v_mov_b32_e32 v126, v0
	v_mov_b32_e32 v127, v0
	v_add_u32_e32 v255, 0x1c000, v189
	v_add_u32_e32 v254, 0x18000, v189
	v_add_u32_e32 v253, 0x80, v164
	v_add_u32_e32 v252, 0x80, v160
	v_add_u32_e32 v251, 0x80, v166
	v_add_u32_e32 v250, 0x80, v162
.LBB0_428:
	ds_read_b128 v[128:131], v201
	ds_read_b128 v[132:135], v201 offset:1024
	ds_read_b128 v[136:139], v201 offset:2048
	ds_read_b128 v[140:143], v201 offset:3072
	ds_read_b128 v[144:147], v205
	ds_read_b128 v[148:151], v205 offset:1024
	ds_read_b128 v[152:155], v205 offset:2048
	ds_read_b128 v[156:159], v205 offset:3072
	s_add_u32 s12, s10, 0xfff80080
	s_addc_u32 s13, s11, -1
	s_cmp_eq_u32 s85, 28
	s_cselect_b32 s61, s55, s13
	s_cselect_b32 s60, s81, s12
	s_cselect_b32 s13, s53, s84
	s_cselect_b32 s12, s82, s83

; #define PG8_STAGE(bufoff, gbase, voff) do { _Pragma("unroll") for (int _i = 0; _i < 2; ++_i) \
;         __builtin_amdgcn_global_load_lds((const unsigned*)((const char*)(gbase) + (voff)[_i]), (PG8_LAS unsigned*)(lds + (bufoff) + ldsw + _i * 8192), 16, 0, 0); } while (0)
; #define PG8_LDA(dst, b, h) do { _Pragma("unroll") for (int m = 0; m < 4; ++m) _Pragma("unroll") for (int k = 0; k < 2; ++k) dst[m][k] = *(const PG8_LAS bf16x8*)(lds + PG8_SA(b, h) + aoff + m * 2048 + k * 1024); } while (0)
; #define PG8_LDB(dst, b, h) do { _Pragma("unroll") for (int n = 0; n < 2; ++n) _Pragma("unroll") for (int k = 0; k < 2; ++k) dst[n][k] = *(const PG8_LAS bf16x8*)(lds + PG8_SB(b, h) + boff + n * 2048 + k * 1024); } while (0)
; #define PG8_SCHED __builtin_amdgcn_sched_barrier(0)
; template <class Epi, class Sched, bool ALIGN_EPI = false, bool SP2 = false>
; __device__ __forceinline__ void gemm_phase(PG8_LAS unsigned char* lds, const Gemm g, const Sched& S, const Epi& E) {
;     ...
;             PG8_LDB(B0, 0, 0); PG8_LDB(B1, 0, 1); PG8_SCHED; PG8_LDA(At, 0, 0); PG8_STAGE(PG8_SA(1, 1), a1 + hstep, voffA);
	s_add_i32 m0, s65, 0xc000
	ds_read_b128 v[176:179], v207
	ds_read_b128 v[184:187], v207 offset:1024
	ds_read_b128 v[190:193], v207 offset:2048
	ds_read_b128 v[210:213], v207 offset:3072
	ds_read_b128 v[214:217], v207 offset:4096
	ds_read_b128 v[218:221], v207 offset:5120
	ds_read_b128 v[222:225], v207 offset:6144
	ds_read_b128 v[226:229], v207 offset:7168
	global_load_lds_dwordx4 v168, s[10:11]

; #define PG8_STAGE(bufoff, gbase, voff) do { _Pragma("unroll") for (int _i = 0; _i < 2; ++_i) \
;         __builtin_amdgcn_global_load_lds((const unsigned*)((const char*)(gbase) + (voff)[_i]), (PG8_LAS unsigned*)(lds + (bufoff) + ldsw + _i * 8192), 16, 0, 0); } while (0)
; #define PG8_LDA(dst, b, h) do { _Pragma("unroll") for (int m = 0; m < 4; ++m) _Pragma("unroll") for (int k = 0; k < 2; ++k) dst[m][k] = *(const PG8_LAS bf16x8*)(lds + PG8_SA(b, h) + aoff + m * 2048 + k * 1024); } while (0)
; #define PG8_LDB(dst, b, h) do { _Pragma("unroll") for (int n = 0; n < 2; ++n) _Pragma("unroll") for (int k = 0; k < 2; ++k) dst[n][k] = *(const PG8_LAS bf16x8*)(lds + PG8_SB(b, h) + boff + n * 2048 + k * 1024); } while (0)
; #define PG8_MMA(ai, bj, At, Bt) do { __builtin_amdgcn_s_setprio(1); _Pragma("unroll") for (int m = 0; m < 4; ++m) _Pragma("unroll") for (int n = 0; n < 2; ++n) _Pragma("unroll") for (int k = 0; k < 2; ++k) \
;         acc[ai][bj][m][n] = __builtin_amdgcn_mfma_f32_16x16x32_bf16(Bt[n][k], At[m][k], acc[ai][bj][m][n], 0, 0, 0); __builtin_amdgcn_s_setprio(0); } while (0)
; #define PG8_WAIT_V(n) asm volatile("s_waitcnt vmcnt(" #n ")" ::: "memory")
; #define PG8_WAIT_L(n) asm volatile("s_waitcnt lgkmcnt(" #n ")" ::: "memory")
; #define PG8_BAR __builtin_amdgcn_s_barrier()
; #define PG8_SCHED __builtin_amdgcn_sched_barrier(0)
; template <class Epi, class Sched, bool ALIGN_EPI = false, bool SP2 = false>
; __device__ __forceinline__ void gemm_phase(PG8_LAS unsigned char* lds, const Gemm g, const Sched& S, const Epi& E) {
;     ...
;             PG8_LDB(B0, 0, 0); PG8_LDB(B1, 0, 1); PG8_SCHED; PG8_LDA(At, 0, 0); PG8_STAGE(PG8_SA(1, 1), a1 + hstep, voffA);
;             PG8_WAIT_V(8); PG8_WAIT_L(0); PG8_BAR; PG8_MMA(0, 0, At, B0); PG8_MMA(0, 1, At, B1); PG8_BAR; PG8_SCHED;
	s_add_i32 m0, s65, 0xe000
	s_nop 0
	global_load_lds_dwordx4 v170, s[10:11]
	s_waitcnt vmcnt(8)
	s_waitcnt lgkmcnt(0)
	s_barrier
	s_setprio 1
	s_waitcnt lgkmcnt(0)
	v_mfma_f32_16x16x32_bf16 v[124:127], v[128:131], v[176:179], v[124:127]
	v_mfma_f32_16x16x32_bf16 v[120:123], v[136:139], v[176:179], v[120:123]
	v_mfma_f32_16x16x32_bf16 v[108:111], v[128:131], v[190:193], v[108:111]
	v_mfma_f32_16x16x32_bf16 v[104:107], v[136:139], v[190:193], v[104:107]
	v_mfma_f32_16x16x32_bf16 v[92:95], v[128:131], v[214:217], v[92:95]
	v_mfma_f32_16x16x32_bf16 v[88:91], v[136:139], v[214:217], v[88:91]
	v_mfma_f32_16x16x32_bf16 v[76:79], v[128:131], v[222:225], v[76:79]
	v_mfma_f32_16x16x32_bf16 v[72:75], v[136:139], v[222:225], v[72:75]
	v_mfma_f32_16x16x32_bf16 v[124:127], v[132:135], v[184:187], v[124:127]
	v_mfma_f32_16x16x32_bf16 v[120:123], v[140:143], v[184:187], v[120:123]
	v_mfma_f32_16x16x32_bf16 v[108:111], v[132:135], v[210:213], v[108:111]
	v_mfma_f32_16x16x32_bf16 v[104:107], v[140:143], v[210:213], v[104:107]
	v_mfma_f32_16x16x32_bf16 v[92:95], v[132:135], v[218:221], v[92:95]
	v_mfma_f32_16x16x32_bf16 v[88:91], v[140:143], v[218:221], v[88:91]
	v_mfma_f32_16x16x32_bf16 v[76:79], v[132:135], v[226:229], v[76:79]
	v_mfma_f32_16x16x32_bf16 v[72:75], v[140:143], v[226:229], v[72:75]


; #define PG8_STAGE(bufoff, gbase, voff) do { _Pragma("unroll") for (int _i = 0; _i < 2; ++_i) \
;         __builtin_amdgcn_global_load_lds((const unsigned*)((const char*)(gbase) + (voff)[_i]), (PG8_LAS unsigned*)(lds + (bufoff) + ldsw + _i * 8192), 16, 0, 0); } while (0)
; #define PG8_LDA(dst, b, h) do { _Pragma("unroll") for (int m = 0; m < 4; ++m) _Pragma("unroll") for (int k = 0; k < 2; ++k) dst[m][k] = *(const PG8_LAS bf16x8*)(lds + PG8_SA(b, h) + aoff + m * 2048 + k * 1024); } while (0)
; #define PG8_MMA(ai, bj, At, Bt) do { __builtin_amdgcn_s_setprio(1); _Pragma("unroll") for (int m = 0; m < 4; ++m) _Pragma("unroll") for (int n = 0; n < 2; ++n) _Pragma("unroll") for (int k = 0; k < 2; ++k) \
;         acc[ai][bj][m][n] = __builtin_amdgcn_mfma_f32_16x16x32_bf16(Bt[n][k], At[m][k], acc[ai][bj][m][n], 0, 0, 0); __builtin_amdgcn_s_setprio(0); } while (0)
; #define PG8_WAIT_V(n) asm volatile("s_waitcnt vmcnt(" #n ")" ::: "memory")
; #define PG8_WAIT_L(n) asm volatile("s_waitcnt lgkmcnt(" #n ")" ::: "memory")
; #define PG8_BAR __builtin_amdgcn_s_barrier()
; #define PG8_SCHED __builtin_amdgcn_sched_barrier(0)
; template <class Epi, class Sched, bool ALIGN_EPI = false, bool SP2 = false>
; __device__ __forceinline__ void gemm_phase(PG8_LAS unsigned char* lds, const Gemm g, const Sched& S, const Epi& E) {
;     ...
;             PG8_WAIT_V(8); PG8_WAIT_L(0); PG8_BAR; PG8_MMA(0, 0, At, B0); PG8_MMA(0, 1, At, B1); PG8_BAR; PG8_SCHED;
;             PG8_LDA(At, 0, 1); PG8_STAGE(PG8_SB(0, 0), b2, voffB); PG8_STAGE(PG8_SB(0, 1), b2 + hstep, voffB); PG8_STAGE(PG8_SA(0, 0), a2, voffA);
	v_mfma_f32_16x16x32_bf16 v[116:119], v[144:147], v[176:179], v[116:119]
	v_mfma_f32_16x16x32_bf16 v[112:115], v[152:155], v[176:179], v[112:115]
	v_mfma_f32_16x16x32_bf16 v[100:103], v[144:147], v[190:193], v[100:103]
	v_mfma_f32_16x16x32_bf16 v[96:99], v[152:155], v[190:193], v[96:99]
	v_mfma_f32_16x16x32_bf16 v[84:87], v[144:147], v[214:217], v[84:87]
	v_mfma_f32_16x16x32_bf16 v[80:83], v[152:155], v[214:217], v[80:83]
	v_mfma_f32_16x16x32_bf16 v[68:71], v[144:147], v[222:225], v[68:71]
	v_mfma_f32_16x16x32_bf16 v[64:67], v[152:155], v[222:225], v[64:67]
	v_mfma_f32_16x16x32_bf16 v[116:119], v[148:151], v[184:187], v[116:119]
	v_mfma_f32_16x16x32_bf16 v[112:115], v[156:159], v[184:187], v[112:115]
	v_mfma_f32_16x16x32_bf16 v[100:103], v[148:151], v[210:213], v[100:103]
	v_mfma_f32_16x16x32_bf16 v[96:99], v[156:159], v[210:213], v[96:99]
	v_mfma_f32_16x16x32_bf16 v[84:87], v[148:151], v[218:221], v[84:87]
	v_mfma_f32_16x16x32_bf16 v[80:83], v[156:159], v[218:221], v[80:83]
	v_mfma_f32_16x16x32_bf16 v[68:71], v[148:151], v[226:229], v[68:71]
	v_mfma_f32_16x16x32_bf16 v[64:67], v[156:159], v[226:229], v[64:67]
	s_setprio 0
	s_barrier
	s_add_i32 s86, s75, s64
	s_mov_b64 s[96:97], s[12:13]

; #define PG8_STAGE(bufoff, gbase, voff) do { _Pragma("unroll") for (int _i = 0; _i < 2; ++_i) \
;         __builtin_amdgcn_global_load_lds((const unsigned*)((const char*)(gbase) + (voff)[_i]), (PG8_LAS unsigned*)(lds + (bufoff) + ldsw + _i * 8192), 16, 0, 0); } while (0)
; #define PG8_LDA(dst, b, h) do { _Pragma("unroll") for (int m = 0; m < 4; ++m) _Pragma("unroll") for (int k = 0; k < 2; ++k) dst[m][k] = *(const PG8_LAS bf16x8*)(lds + PG8_SA(b, h) + aoff + m * 2048 + k * 1024); } while (0)
; template <class Epi, class Sched, bool ALIGN_EPI = false, bool SP2 = false>
; __device__ __forceinline__ void gemm_phase(PG8_LAS unsigned char* lds, const Gemm g, const Sched& S, const Epi& E) {
;     ...
;             PG8_LDA(At, 0, 1); PG8_STAGE(PG8_SB(0, 0), b2, voffB); PG8_STAGE(PG8_SB(0, 1), b2 + hstep, voffB); PG8_STAGE(PG8_SA(0, 0), a2, voffA);
	s_mov_b32 m0, s86
	ds_read_b128 v[176:179], v207 offset:16384
	ds_read_b128 v[184:187], v207 offset:17408
	ds_read_b128 v[190:193], v207 offset:18432
	ds_read_b128 v[210:213], v207 offset:19456
	ds_read_b128 v[214:217], v207 offset:20480
	ds_read_b128 v[218:221], v207 offset:21504
	ds_read_b128 v[222:225], v207 offset:22528
	ds_read_b128 v[226:229], v207 offset:23552
	global_load_lds_dwordx4 v162, s[12:13]
	s_add_i32 m0, s86, 0x2000
	s_add_u32 s86, s12, 0x80000

; #define PG8_STAGE(bufoff, gbase, voff) do { _Pragma("unroll") for (int _i = 0; _i < 2; ++_i) \
;         __builtin_amdgcn_global_load_lds((const unsigned*)((const char*)(gbase) + (voff)[_i]), (PG8_LAS unsigned*)(lds + (bufoff) + ldsw + _i * 8192), 16, 0, 0); } while (0)
; #define PG8_LDA(dst, b, h) do { _Pragma("unroll") for (int m = 0; m < 4; ++m) _Pragma("unroll") for (int k = 0; k < 2; ++k) dst[m][k] = *(const PG8_LAS bf16x8*)(lds + PG8_SA(b, h) + aoff + m * 2048 + k * 1024); } while (0)
; template <class Epi, class Sched, bool ALIGN_EPI = false, bool SP2 = false>
; __device__ __forceinline__ void gemm_phase(PG8_LAS unsigned char* lds, const Gemm g, const Sched& S, const Epi& E) {
;     ...
;             PG8_LDA(At, 0, 1); PG8_STAGE(PG8_SB(0, 0), b2, voffB); PG8_STAGE(PG8_SB(0, 1), b2 + hstep, voffB); PG8_STAGE(PG8_SA(0, 0), a2, voffA);
	s_addc_u32 s87, s13, 0
	s_add_i32 s88, s76, s64
	global_load_lds_dwordx4 v166, s[12:13]

; #define PG8_STAGE(bufoff, gbase, voff) do { _Pragma("unroll") for (int _i = 0; _i < 2; ++_i) \
;         __builtin_amdgcn_global_load_lds((const unsigned*)((const char*)(gbase) + (voff)[_i]), (PG8_LAS unsigned*)(lds + (bufoff) + ldsw + _i * 8192), 16, 0, 0); } while (0)
; #define PG8_LDA(dst, b, h) do { _Pragma("unroll") for (int m = 0; m < 4; ++m) _Pragma("unroll") for (int k = 0; k < 2; ++k) dst[m][k] = *(const PG8_LAS bf16x8*)(lds + PG8_SA(b, h) + aoff + m * 2048 + k * 1024); } while (0)
; template <class Epi, class Sched, bool ALIGN_EPI = false, bool SP2 = false>
; __device__ __forceinline__ void gemm_phase(PG8_LAS unsigned char* lds, const Gemm g, const Sched& S, const Epi& E) {
;     ...
;             PG8_LDA(At, 0, 1); PG8_STAGE(PG8_SB(0, 0), b2, voffB); PG8_STAGE(PG8_SB(0, 1), b2 + hstep, voffB); PG8_STAGE(PG8_SA(0, 0), a2, voffA);
	s_mov_b32 m0, s88
	s_nop 0
	global_load_lds_dwordx4 v162, s[86:87]

; #define PG8_STAGE(bufoff, gbase, voff) do { _Pragma("unroll") for (int _i = 0; _i < 2; ++_i) \
;         __builtin_amdgcn_global_load_lds((const unsigned*)((const char*)(gbase) + (voff)[_i]), (PG8_LAS unsigned*)(lds + (bufoff) + ldsw + _i * 8192), 16, 0, 0); } while (0)
; #define PG8_LDA(dst, b, h) do { _Pragma("unroll") for (int m = 0; m < 4; ++m) _Pragma("unroll") for (int k = 0; k < 2; ++k) dst[m][k] = *(const PG8_LAS bf16x8*)(lds + PG8_SA(b, h) + aoff + m * 2048 + k * 1024); } while (0)
; template <class Epi, class Sched, bool ALIGN_EPI = false, bool SP2 = false>
; __device__ __forceinline__ void gemm_phase(PG8_LAS unsigned char* lds, const Gemm g, const Sched& S, const Epi& E) {
;     ...
;             PG8_LDA(At, 0, 1); PG8_STAGE(PG8_SB(0, 0), b2, voffB); PG8_STAGE(PG8_SB(0, 1), b2 + hstep, voffB); PG8_STAGE(PG8_SA(0, 0), a2, voffA);
	s_add_i32 m0, s88, 0x2000
	s_nop 0
	global_load_lds_dwordx4 v166, s[86:87]
	s_mov_b64 s[98:99], s[60:61]

; #define PG8_STAGE(bufoff, gbase, voff) do { _Pragma("unroll") for (int _i = 0; _i < 2; ++_i) \
;         __builtin_amdgcn_global_load_lds((const unsigned*)((const char*)(gbase) + (voff)[_i]), (PG8_LAS unsigned*)(lds + (bufoff) + ldsw + _i * 8192), 16, 0, 0); } while (0)
; #define PG8_LDA(dst, b, h) do { _Pragma("unroll") for (int m = 0; m < 4; ++m) _Pragma("unroll") for (int k = 0; k < 2; ++k) dst[m][k] = *(const PG8_LAS bf16x8*)(lds + PG8_SA(b, h) + aoff + m * 2048 + k * 1024); } while (0)
; #define PG8_MMA(ai, bj, At, Bt) do { __builtin_amdgcn_s_setprio(1); _Pragma("unroll") for (int m = 0; m < 4; ++m) _Pragma("unroll") for (int n = 0; n < 2; ++n) _Pragma("unroll") for (int k = 0; k < 2; ++k) \
;         acc[ai][bj][m][n] = __builtin_amdgcn_mfma_f32_16x16x32_bf16(Bt[n][k], At[m][k], acc[ai][bj][m][n], 0, 0, 0); __builtin_amdgcn_s_setprio(0); } while (0)
; #define PG8_WAIT_V(n) asm volatile("s_waitcnt vmcnt(" #n ")" ::: "memory")
; #define PG8_WAIT_L(n) asm volatile("s_waitcnt lgkmcnt(" #n ")" ::: "memory")
; #define PG8_BAR __builtin_amdgcn_s_barrier()
; #define PG8_SCHED __builtin_amdgcn_sched_barrier(0)
; template <class Epi, class Sched, bool ALIGN_EPI = false, bool SP2 = false>
; __device__ __forceinline__ void gemm_phase(PG8_LAS unsigned char* lds, const Gemm g, const Sched& S, const Epi& E) {
;     ...
;             PG8_LDA(At, 0, 1); PG8_STAGE(PG8_SB(0, 0), b2, voffB); PG8_STAGE(PG8_SB(0, 1), b2 + hstep, voffB); PG8_STAGE(PG8_SA(0, 0), a2, voffA);
;             PG8_WAIT_V(8); PG8_WAIT_L(0); PG8_BAR; PG8_MMA(1, 0, At, B0); PG8_MMA(1, 1, At, B1); PG8_BAR; PG8_SCHED;
	s_mov_b32 m0, s65
	s_nop 0
	global_load_lds_dwordx4 v160, s[60:61]
	s_mov_b32 m0, s67
	s_nop 0
	global_load_lds_dwordx4 v164, s[60:61]
	s_waitcnt vmcnt(8)
	s_waitcnt lgkmcnt(0)
	s_barrier
	s_setprio 1
	s_waitcnt lgkmcnt(0)
	v_mfma_f32_16x16x32_bf16 v[60:63], v[128:131], v[176:179], v[60:63]
	v_mfma_f32_16x16x32_bf16 v[56:59], v[136:139], v[176:179], v[56:59]
	v_mfma_f32_16x16x32_bf16 v[44:47], v[128:131], v[190:193], v[44:47]
	v_mfma_f32_16x16x32_bf16 v[40:43], v[136:139], v[190:193], v[40:43]
	v_mfma_f32_16x16x32_bf16 v[28:31], v[128:131], v[214:217], v[28:31]
	v_mfma_f32_16x16x32_bf16 v[24:27], v[136:139], v[214:217], v[24:27]
	v_mfma_f32_16x16x32_bf16 v[12:15], v[128:131], v[222:225], v[12:15]
	v_mfma_f32_16x16x32_bf16 v[8:11], v[136:139], v[222:225], v[8:11]
	v_mfma_f32_16x16x32_bf16 v[60:63], v[132:135], v[184:187], v[60:63]
	v_mfma_f32_16x16x32_bf16 v[56:59], v[140:143], v[184:187], v[56:59]
	v_mfma_f32_16x16x32_bf16 v[44:47], v[132:135], v[210:213], v[44:47]
	v_mfma_f32_16x16x32_bf16 v[40:43], v[140:143], v[210:213], v[40:43]
	v_mfma_f32_16x16x32_bf16 v[28:31], v[132:135], v[218:221], v[28:31]
	v_mfma_f32_16x16x32_bf16 v[24:27], v[140:143], v[218:221], v[24:27]
	v_mfma_f32_16x16x32_bf16 v[12:15], v[132:135], v[226:229], v[12:15]
	v_mfma_f32_16x16x32_bf16 v[8:11], v[140:143], v[226:229], v[8:11]


; #define PG8_STAGE(bufoff, gbase, voff) do { _Pragma("unroll") for (int _i = 0; _i < 2; ++_i) \
;         __builtin_amdgcn_global_load_lds((const unsigned*)((const char*)(gbase) + (voff)[_i]), (PG8_LAS unsigned*)(lds + (bufoff) + ldsw + _i * 8192), 16, 0, 0); } while (0)
; #define PG8_LDA(dst, b, h) do { _Pragma("unroll") for (int m = 0; m < 4; ++m) _Pragma("unroll") for (int k = 0; k < 2; ++k) dst[m][k] = *(const PG8_LAS bf16x8*)(lds + PG8_SA(b, h) + aoff + m * 2048 + k * 1024); } while (0)
; #define PG8_LDB(dst, b, h) do { _Pragma("unroll") for (int n = 0; n < 2; ++n) _Pragma("unroll") for (int k = 0; k < 2; ++k) dst[n][k] = *(const PG8_LAS bf16x8*)(lds + PG8_SB(b, h) + boff + n * 2048 + k * 1024); } while (0)
; #define PG8_MMA(ai, bj, At, Bt) do { __builtin_amdgcn_s_setprio(1); _Pragma("unroll") for (int m = 0; m < 4; ++m) _Pragma("unroll") for (int n = 0; n < 2; ++n) _Pragma("unroll") for (int k = 0; k < 2; ++k) \
;         acc[ai][bj][m][n] = __builtin_amdgcn_mfma_f32_16x16x32_bf16(Bt[n][k], At[m][k], acc[ai][bj][m][n], 0, 0, 0); __builtin_amdgcn_s_setprio(0); } while (0)
; #define PG8_WAIT_V(n) asm volatile("s_waitcnt vmcnt(" #n ")" ::: "memory")
; #define PG8_WAIT_L(n) asm volatile("s_waitcnt lgkmcnt(" #n ")" ::: "memory")
; #define PG8_BAR __builtin_amdgcn_s_barrier()
; #define PG8_SCHED __builtin_amdgcn_sched_barrier(0)
; template <class Epi, class Sched, bool ALIGN_EPI = false, bool SP2 = false>
; __device__ __forceinline__ void gemm_phase(PG8_LAS unsigned char* lds, const Gemm g, const Sched& S, const Epi& E) {
;     ...
;             PG8_WAIT_V(8); PG8_WAIT_L(0); PG8_BAR; PG8_MMA(1, 0, At, B0); PG8_MMA(1, 1, At, B1); PG8_BAR; PG8_SCHED;
;             PG8_LDB(B0, 1, 0); PG8_LDB(B1, 1, 1); PG8_SCHED; PG8_LDA(At, 1, 0); PG8_STAGE(PG8_SA(0, 1), a2 + hstep, voffA);
	v_mfma_f32_16x16x32_bf16 v[52:55], v[144:147], v[176:179], v[52:55]
	v_mfma_f32_16x16x32_bf16 v[48:51], v[152:155], v[176:179], v[48:51]
	v_mfma_f32_16x16x32_bf16 v[36:39], v[144:147], v[190:193], v[36:39]
	v_mfma_f32_16x16x32_bf16 v[32:35], v[152:155], v[190:193], v[32:35]
	v_mfma_f32_16x16x32_bf16 v[20:23], v[144:147], v[214:217], v[20:23]
	v_mfma_f32_16x16x32_bf16 v[16:19], v[152:155], v[214:217], v[16:19]
	v_mfma_f32_16x16x32_bf16 v[4:7], v[144:147], v[222:225], v[4:7]
	v_mfma_f32_16x16x32_bf16 v[0:3], v[152:155], v[222:225], v[0:3]
	v_mfma_f32_16x16x32_bf16 v[52:55], v[148:151], v[184:187], v[52:55]
	v_mfma_f32_16x16x32_bf16 v[48:51], v[156:159], v[184:187], v[48:51]
	v_mfma_f32_16x16x32_bf16 v[36:39], v[148:151], v[210:213], v[36:39]
	v_mfma_f32_16x16x32_bf16 v[32:35], v[156:159], v[210:213], v[32:35]
	v_mfma_f32_16x16x32_bf16 v[20:23], v[148:151], v[218:221], v[20:23]
	v_mfma_f32_16x16x32_bf16 v[16:19], v[156:159], v[218:221], v[16:19]
	v_mfma_f32_16x16x32_bf16 v[4:7], v[148:151], v[226:229], v[4:7]
	v_mfma_f32_16x16x32_bf16 v[0:3], v[156:159], v[226:229], v[0:3]
	s_setprio 0
	s_barrier
	s_add_i32 s86, 0, 0x18000
	s_add_i32 s87, 0, 0x1c000


; #define PG8_STAGE(bufoff, gbase, voff) do { _Pragma("unroll") for (int _i = 0; _i < 2; ++_i) \
;         __builtin_amdgcn_global_load_lds((const unsigned*)((const char*)(gbase) + (voff)[_i]), (PG8_LAS unsigned*)(lds + (bufoff) + ldsw + _i * 8192), 16, 0, 0); } while (0)
; #define PG8_LDA(dst, b, h) do { _Pragma("unroll") for (int m = 0; m < 4; ++m) _Pragma("unroll") for (int k = 0; k < 2; ++k) dst[m][k] = *(const PG8_LAS bf16x8*)(lds + PG8_SA(b, h) + aoff + m * 2048 + k * 1024); } while (0)
; #define PG8_LDB(dst, b, h) do { _Pragma("unroll") for (int n = 0; n < 2; ++n) _Pragma("unroll") for (int k = 0; k < 2; ++k) dst[n][k] = *(const PG8_LAS bf16x8*)(lds + PG8_SB(b, h) + boff + n * 2048 + k * 1024); } while (0)
; #define PG8_SCHED __builtin_amdgcn_sched_barrier(0)
; template <class Epi, class Sched, bool ALIGN_EPI = false, bool SP2 = false>
; __device__ __forceinline__ void gemm_phase(PG8_LAS unsigned char* lds, const Gemm g, const Sched& S, const Epi& E) {
;     ...
;             PG8_LDB(B0, 1, 0); PG8_LDB(B1, 1, 1); PG8_SCHED; PG8_LDA(At, 1, 0); PG8_STAGE(PG8_SA(0, 1), a2 + hstep, voffA);
	ds_read_b128 v[128:131], v254
	ds_read_b128 v[132:135], v254 offset:1024
	ds_read_b128 v[136:139], v254 offset:2048
	ds_read_b128 v[140:143], v254 offset:3072
	ds_read_b128 v[144:147], v255
	ds_read_b128 v[148:151], v255 offset:1024
	ds_read_b128 v[152:155], v255 offset:2048
	ds_read_b128 v[156:159], v255 offset:3072
	s_add_u32 s60, s60, 0x80000
	s_addc_u32 s61, s61, 0
	s_mov_b32 m0, s68

; #define PG8_STAGE(bufoff, gbase, voff) do { _Pragma("unroll") for (int _i = 0; _i < 2; ++_i) \
;         __builtin_amdgcn_global_load_lds((const unsigned*)((const char*)(gbase) + (voff)[_i]), (PG8_LAS unsigned*)(lds + (bufoff) + ldsw + _i * 8192), 16, 0, 0); } while (0)
; #define PG8_LDA(dst, b, h) do { _Pragma("unroll") for (int m = 0; m < 4; ++m) _Pragma("unroll") for (int k = 0; k < 2; ++k) dst[m][k] = *(const PG8_LAS bf16x8*)(lds + PG8_SA(b, h) + aoff + m * 2048 + k * 1024); } while (0)
; #define PG8_LDB(dst, b, h) do { _Pragma("unroll") for (int n = 0; n < 2; ++n) _Pragma("unroll") for (int k = 0; k < 2; ++k) dst[n][k] = *(const PG8_LAS bf16x8*)(lds + PG8_SB(b, h) + boff + n * 2048 + k * 1024); } while (0)
; #define PG8_SCHED __builtin_amdgcn_sched_barrier(0)
; template <class Epi, class Sched, bool ALIGN_EPI = false, bool SP2 = false>
; __device__ __forceinline__ void gemm_phase(PG8_LAS unsigned char* lds, const Gemm g, const Sched& S, const Epi& E) {
;     ...
;             PG8_LDB(B0, 1, 0); PG8_LDB(B1, 1, 1); PG8_SCHED; PG8_LDA(At, 1, 0); PG8_STAGE(PG8_SA(0, 1), a2 + hstep, voffA);
	ds_read_b128 v[176:179], v207 offset:32768
	ds_read_b128 v[184:187], v207 offset:33792
	ds_read_b128 v[190:193], v207 offset:34816
	ds_read_b128 v[210:213], v207 offset:35840
	ds_read_b128 v[214:217], v207 offset:36864
	ds_read_b128 v[218:221], v207 offset:37888
	ds_read_b128 v[222:225], v207 offset:38912
	ds_read_b128 v[226:229], v207 offset:39936
	global_load_lds_dwordx4 v160, s[60:61]

; #define PG8_STAGE(bufoff, gbase, voff) do { _Pragma("unroll") for (int _i = 0; _i < 2; ++_i) \
;         __builtin_amdgcn_global_load_lds((const unsigned*)((const char*)(gbase) + (voff)[_i]), (PG8_LAS unsigned*)(lds + (bufoff) + ldsw + _i * 8192), 16, 0, 0); } while (0)
; #define PG8_LDA(dst, b, h) do { _Pragma("unroll") for (int m = 0; m < 4; ++m) _Pragma("unroll") for (int k = 0; k < 2; ++k) dst[m][k] = *(const PG8_LAS bf16x8*)(lds + PG8_SA(b, h) + aoff + m * 2048 + k * 1024); } while (0)
; #define PG8_LDB(dst, b, h) do { _Pragma("unroll") for (int n = 0; n < 2; ++n) _Pragma("unroll") for (int k = 0; k < 2; ++k) dst[n][k] = *(const PG8_LAS bf16x8*)(lds + PG8_SB(b, h) + boff + n * 2048 + k * 1024); } while (0)
; #define PG8_MMA(ai, bj, At, Bt) do { __builtin_amdgcn_s_setprio(1); _Pragma("unroll") for (int m = 0; m < 4; ++m) _Pragma("unroll") for (int n = 0; n < 2; ++n) _Pragma("unroll") for (int k = 0; k < 2; ++k) \
;         acc[ai][bj][m][n] = __builtin_amdgcn_mfma_f32_16x16x32_bf16(Bt[n][k], At[m][k], acc[ai][bj][m][n], 0, 0, 0); __builtin_amdgcn_s_setprio(0); } while (0)
; #define PG8_WAIT_V(n) asm volatile("s_waitcnt vmcnt(" #n ")" ::: "memory")
; #define PG8_WAIT_L(n) asm volatile("s_waitcnt lgkmcnt(" #n ")" ::: "memory")
; #define PG8_BAR __builtin_amdgcn_s_barrier()
; #define PG8_SCHED __builtin_amdgcn_sched_barrier(0)
; template <class Epi, class Sched, bool ALIGN_EPI = false, bool SP2 = false>
; __device__ __forceinline__ void gemm_phase(PG8_LAS unsigned char* lds, const Gemm g, const Sched& S, const Epi& E) {
;     ...
;             PG8_LDB(B0, 1, 0); PG8_LDB(B1, 1, 1); PG8_SCHED; PG8_LDA(At, 1, 0); PG8_STAGE(PG8_SA(0, 1), a2 + hstep, voffA);
;             PG8_WAIT_V(8); PG8_WAIT_L(0); PG8_BAR; PG8_MMA(0, 0, At, B0); PG8_MMA(0, 1, At, B1); PG8_BAR; PG8_SCHED;
	s_mov_b32 m0, s69
	s_nop 0
	global_load_lds_dwordx4 v164, s[60:61]
	s_waitcnt vmcnt(8)
	s_waitcnt lgkmcnt(0)
	s_barrier
	s_setprio 1
	s_waitcnt lgkmcnt(0)
	v_mfma_f32_16x16x32_bf16 v[124:127], v[128:131], v[176:179], v[124:127]
	v_mfma_f32_16x16x32_bf16 v[120:123], v[136:139], v[176:179], v[120:123]
	v_mfma_f32_16x16x32_bf16 v[108:111], v[128:131], v[190:193], v[108:111]
	v_mfma_f32_16x16x32_bf16 v[104:107], v[136:139], v[190:193], v[104:107]
	v_mfma_f32_16x16x32_bf16 v[92:95], v[128:131], v[214:217], v[92:95]
	v_mfma_f32_16x16x32_bf16 v[88:91], v[136:139], v[214:217], v[88:91]
	v_mfma_f32_16x16x32_bf16 v[76:79], v[128:131], v[222:225], v[76:79]
	v_mfma_f32_16x16x32_bf16 v[72:75], v[136:139], v[222:225], v[72:75]
	v_mfma_f32_16x16x32_bf16 v[124:127], v[132:135], v[184:187], v[124:127]
	v_mfma_f32_16x16x32_bf16 v[120:123], v[140:143], v[184:187], v[120:123]
	v_mfma_f32_16x16x32_bf16 v[108:111], v[132:135], v[210:213], v[108:111]
	v_mfma_f32_16x16x32_bf16 v[104:107], v[140:143], v[210:213], v[104:107]
	v_mfma_f32_16x16x32_bf16 v[92:95], v[132:135], v[218:221], v[92:95]
	v_mfma_f32_16x16x32_bf16 v[88:91], v[140:143], v[218:221], v[88:91]
	v_mfma_f32_16x16x32_bf16 v[76:79], v[132:135], v[226:229], v[76:79]
	v_mfma_f32_16x16x32_bf16 v[72:75], v[140:143], v[226:229], v[72:75]


; #define PG8_MMA(ai, bj, At, Bt) do { __builtin_amdgcn_s_setprio(1); _Pragma("unroll") for (int m = 0; m < 4; ++m) _Pragma("unroll") for (int n = 0; n < 2; ++n) _Pragma("unroll") for (int k = 0; k < 2; ++k) \
;         acc[ai][bj][m][n] = __builtin_amdgcn_mfma_f32_16x16x32_bf16(Bt[n][k], At[m][k], acc[ai][bj][m][n], 0, 0, 0); __builtin_amdgcn_s_setprio(0); } while (0)
; #define PG8_WAIT_V(n) asm volatile("s_waitcnt vmcnt(" #n ")" ::: "memory")
; #define PG8_WAIT_L(n) asm volatile("s_waitcnt lgkmcnt(" #n ")" ::: "memory")
; #define PG8_BAR __builtin_amdgcn_s_barrier()
; #define PG8_SCHED __builtin_amdgcn_sched_barrier(0)
; template <class Epi, class Sched, bool ALIGN_EPI = false, bool SP2 = false>
; __device__ __forceinline__ void gemm_phase(PG8_LAS unsigned char* lds, const Gemm g, const Sched& S, const Epi& E) {
;     ...
;             PG8_WAIT_V(8); PG8_WAIT_L(0); PG8_BAR; PG8_MMA(0, 0, At, B0); PG8_MMA(0, 1, At, B1); PG8_BAR; PG8_SCHED;
	v_mfma_f32_16x16x32_bf16 v[116:119], v[144:147], v[176:179], v[116:119]
	v_mfma_f32_16x16x32_bf16 v[112:115], v[152:155], v[176:179], v[112:115]
	v_mfma_f32_16x16x32_bf16 v[100:103], v[144:147], v[190:193], v[100:103]
	v_mfma_f32_16x16x32_bf16 v[96:99], v[152:155], v[190:193], v[96:99]
	v_mfma_f32_16x16x32_bf16 v[84:87], v[144:147], v[214:217], v[84:87]
	v_mfma_f32_16x16x32_bf16 v[80:83], v[152:155], v[214:217], v[80:83]
	v_mfma_f32_16x16x32_bf16 v[68:71], v[144:147], v[222:225], v[68:71]
	v_mfma_f32_16x16x32_bf16 v[64:67], v[152:155], v[222:225], v[64:67]
	v_mfma_f32_16x16x32_bf16 v[116:119], v[148:151], v[184:187], v[116:119]
	v_mfma_f32_16x16x32_bf16 v[112:115], v[156:159], v[184:187], v[112:115]
	v_mfma_f32_16x16x32_bf16 v[100:103], v[148:151], v[210:213], v[100:103]
	v_mfma_f32_16x16x32_bf16 v[96:99], v[156:159], v[210:213], v[96:99]
	v_mfma_f32_16x16x32_bf16 v[84:87], v[148:151], v[218:221], v[84:87]
	v_mfma_f32_16x16x32_bf16 v[80:83], v[156:159], v[218:221], v[80:83]
	v_mfma_f32_16x16x32_bf16 v[68:71], v[148:151], v[226:229], v[68:71]
	v_mfma_f32_16x16x32_bf16 v[64:67], v[156:159], v[226:229], v[64:67]
	s_setprio 0
	s_barrier
	s_add_i32 s60, s86, s64

; #define PG8_STAGE(bufoff, gbase, voff) do { _Pragma("unroll") for (int _i = 0; _i < 2; ++_i) \
;         __builtin_amdgcn_global_load_lds((const unsigned*)((const char*)(gbase) + (voff)[_i]), (PG8_LAS unsigned*)(lds + (bufoff) + ldsw + _i * 8192), 16, 0, 0); } while (0)
; #define PG8_LDA(dst, b, h) do { _Pragma("unroll") for (int m = 0; m < 4; ++m) _Pragma("unroll") for (int k = 0; k < 2; ++k) dst[m][k] = *(const PG8_LAS bf16x8*)(lds + PG8_SA(b, h) + aoff + m * 2048 + k * 1024); } while (0)
; template <class Epi, class Sched, bool ALIGN_EPI = false, bool SP2 = false>
; __device__ __forceinline__ void gemm_phase(PG8_LAS unsigned char* lds, const Gemm g, const Sched& S, const Epi& E) {
;     ...
;             PG8_LDA(At, 1, 1); PG8_STAGE(PG8_SB(1, 0), b3, voffB); PG8_STAGE(PG8_SB(1, 1), b3 + hstep, voffB); PG8_STAGE(PG8_SA(1, 0), a3, voffA);
	s_mov_b32 m0, s60
	ds_read_b128 v[176:179], v207 offset:49152
	ds_read_b128 v[184:187], v207 offset:50176
	ds_read_b128 v[190:193], v207 offset:51200
	ds_read_b128 v[210:213], v207 offset:52224
	ds_read_b128 v[214:217], v207 offset:53248
	ds_read_b128 v[218:221], v207 offset:54272
	ds_read_b128 v[222:225], v207 offset:55296
	ds_read_b128 v[226:229], v207 offset:56320
	global_load_lds_dwordx4 v250, s[96:97]
	s_add_i32 m0, s60, 0x2000
	s_add_u32 s12, s12, 0x80080

; #define PG8_STAGE(bufoff, gbase, voff) do { _Pragma("unroll") for (int _i = 0; _i < 2; ++_i) \
;         __builtin_amdgcn_global_load_lds((const unsigned*)((const char*)(gbase) + (voff)[_i]), (PG8_LAS unsigned*)(lds + (bufoff) + ldsw + _i * 8192), 16, 0, 0); } while (0)
; #define PG8_LDA(dst, b, h) do { _Pragma("unroll") for (int m = 0; m < 4; ++m) _Pragma("unroll") for (int k = 0; k < 2; ++k) dst[m][k] = *(const PG8_LAS bf16x8*)(lds + PG8_SA(b, h) + aoff + m * 2048 + k * 1024); } while (0)
; template <class Epi, class Sched, bool ALIGN_EPI = false, bool SP2 = false>
; __device__ __forceinline__ void gemm_phase(PG8_LAS unsigned char* lds, const Gemm g, const Sched& S, const Epi& E) {
;     ...
;             PG8_LDA(At, 1, 1); PG8_STAGE(PG8_SB(1, 0), b3, voffB); PG8_STAGE(PG8_SB(1, 1), b3 + hstep, voffB); PG8_STAGE(PG8_SA(1, 0), a3, voffA);
	s_addc_u32 s13, s13, 0
	s_add_i32 s60, s87, s64
	global_load_lds_dwordx4 v251, s[96:97]

; #define PG8_STAGE(bufoff, gbase, voff) do { _Pragma("unroll") for (int _i = 0; _i < 2; ++_i) \
;         __builtin_amdgcn_global_load_lds((const unsigned*)((const char*)(gbase) + (voff)[_i]), (PG8_LAS unsigned*)(lds + (bufoff) + ldsw + _i * 8192), 16, 0, 0); } while (0)
; #define PG8_LDA(dst, b, h) do { _Pragma("unroll") for (int m = 0; m < 4; ++m) _Pragma("unroll") for (int k = 0; k < 2; ++k) dst[m][k] = *(const PG8_LAS bf16x8*)(lds + PG8_SA(b, h) + aoff + m * 2048 + k * 1024); } while (0)
; template <class Epi, class Sched, bool ALIGN_EPI = false, bool SP2 = false>
; __device__ __forceinline__ void gemm_phase(PG8_LAS unsigned char* lds, const Gemm g, const Sched& S, const Epi& E) {
;     ...
;             PG8_LDA(At, 1, 1); PG8_STAGE(PG8_SB(1, 0), b3, voffB); PG8_STAGE(PG8_SB(1, 1), b3 + hstep, voffB); PG8_STAGE(PG8_SA(1, 0), a3, voffA);
	s_mov_b32 m0, s60
	s_nop 0
	global_load_lds_dwordx4 v162, s[12:13]

; #define PG8_STAGE(bufoff, gbase, voff) do { _Pragma("unroll") for (int _i = 0; _i < 2; ++_i) \
;         __builtin_amdgcn_global_load_lds((const unsigned*)((const char*)(gbase) + (voff)[_i]), (PG8_LAS unsigned*)(lds + (bufoff) + ldsw + _i * 8192), 16, 0, 0); } while (0)
; #define PG8_LDA(dst, b, h) do { _Pragma("unroll") for (int m = 0; m < 4; ++m) _Pragma("unroll") for (int k = 0; k < 2; ++k) dst[m][k] = *(const PG8_LAS bf16x8*)(lds + PG8_SA(b, h) + aoff + m * 2048 + k * 1024); } while (0)
; template <class Epi, class Sched, bool ALIGN_EPI = false, bool SP2 = false>
; __device__ __forceinline__ void gemm_phase(PG8_LAS unsigned char* lds, const Gemm g, const Sched& S, const Epi& E) {
;     ...
;             PG8_LDA(At, 1, 1); PG8_STAGE(PG8_SB(1, 0), b3, voffB); PG8_STAGE(PG8_SB(1, 1), b3 + hstep, voffB); PG8_STAGE(PG8_SA(1, 0), a3, voffA);
	s_add_i32 m0, s60, 0x2000
	s_nop 0
	global_load_lds_dwordx4 v166, s[12:13]

; #define PG8_STAGE(bufoff, gbase, voff) do { _Pragma("unroll") for (int _i = 0; _i < 2; ++_i) \
;         __builtin_amdgcn_global_load_lds((const unsigned*)((const char*)(gbase) + (voff)[_i]), (PG8_LAS unsigned*)(lds + (bufoff) + ldsw + _i * 8192), 16, 0, 0); } while (0)
; #define PG8_LDA(dst, b, h) do { _Pragma("unroll") for (int m = 0; m < 4; ++m) _Pragma("unroll") for (int k = 0; k < 2; ++k) dst[m][k] = *(const PG8_LAS bf16x8*)(lds + PG8_SA(b, h) + aoff + m * 2048 + k * 1024); } while (0)
; template <class Epi, class Sched, bool ALIGN_EPI = false, bool SP2 = false>
; __device__ __forceinline__ void gemm_phase(PG8_LAS unsigned char* lds, const Gemm g, const Sched& S, const Epi& E) {
;     ...
;             PG8_LDA(At, 1, 1); PG8_STAGE(PG8_SB(1, 0), b3, voffB); PG8_STAGE(PG8_SB(1, 1), b3 + hstep, voffB); PG8_STAGE(PG8_SA(1, 0), a3, voffA);
	s_mov_b32 m0, s71
	s_nop 0
	global_load_lds_dwordx4 v252, s[98:99]

; #define PG8_STAGE(bufoff, gbase, voff) do { _Pragma("unroll") for (int _i = 0; _i < 2; ++_i) \
;         __builtin_amdgcn_global_load_lds((const unsigned*)((const char*)(gbase) + (voff)[_i]), (PG8_LAS unsigned*)(lds + (bufoff) + ldsw + _i * 8192), 16, 0, 0); } while (0)
; #define PG8_LDA(dst, b, h) do { _Pragma("unroll") for (int m = 0; m < 4; ++m) _Pragma("unroll") for (int k = 0; k < 2; ++k) dst[m][k] = *(const PG8_LAS bf16x8*)(lds + PG8_SA(b, h) + aoff + m * 2048 + k * 1024); } while (0)
; #define PG8_MMA(ai, bj, At, Bt) do { __builtin_amdgcn_s_setprio(1); _Pragma("unroll") for (int m = 0; m < 4; ++m) _Pragma("unroll") for (int n = 0; n < 2; ++n) _Pragma("unroll") for (int k = 0; k < 2; ++k) \
;         acc[ai][bj][m][n] = __builtin_amdgcn_mfma_f32_16x16x32_bf16(Bt[n][k], At[m][k], acc[ai][bj][m][n], 0, 0, 0); __builtin_amdgcn_s_setprio(0); } while (0)
; #define PG8_WAIT_V(n) asm volatile("s_waitcnt vmcnt(" #n ")" ::: "memory")
; #define PG8_WAIT_L(n) asm volatile("s_waitcnt lgkmcnt(" #n ")" ::: "memory")
; #define PG8_BAR __builtin_amdgcn_s_barrier()
; #define PG8_SCHED __builtin_amdgcn_sched_barrier(0)
; template <class Epi, class Sched, bool ALIGN_EPI = false, bool SP2 = false>
; __device__ __forceinline__ void gemm_phase(PG8_LAS unsigned char* lds, const Gemm g, const Sched& S, const Epi& E) {
;     ...
;             PG8_LDA(At, 1, 1); PG8_STAGE(PG8_SB(1, 0), b3, voffB); PG8_STAGE(PG8_SB(1, 1), b3 + hstep, voffB); PG8_STAGE(PG8_SA(1, 0), a3, voffA);
;             PG8_WAIT_V(8); PG8_WAIT_L(0); PG8_BAR; PG8_MMA(1, 0, At, B0); PG8_MMA(1, 1, At, B1); PG8_BAR; PG8_SCHED;
	s_mov_b32 m0, s72
	s_nop 0
	global_load_lds_dwordx4 v253, s[98:99]
	s_waitcnt vmcnt(8)
	s_waitcnt lgkmcnt(0)
	s_barrier
	s_setprio 1
	s_waitcnt lgkmcnt(0)
	v_mfma_f32_16x16x32_bf16 v[60:63], v[128:131], v[176:179], v[60:63]
	v_mfma_f32_16x16x32_bf16 v[56:59], v[136:139], v[176:179], v[56:59]
	v_mfma_f32_16x16x32_bf16 v[44:47], v[128:131], v[190:193], v[44:47]
	v_mfma_f32_16x16x32_bf16 v[40:43], v[136:139], v[190:193], v[40:43]
	v_mfma_f32_16x16x32_bf16 v[28:31], v[128:131], v[214:217], v[28:31]
	v_mfma_f32_16x16x32_bf16 v[24:27], v[136:139], v[214:217], v[24:27]
	v_mfma_f32_16x16x32_bf16 v[12:15], v[128:131], v[222:225], v[12:15]
	v_mfma_f32_16x16x32_bf16 v[8:11], v[136:139], v[222:225], v[8:11]
	v_mfma_f32_16x16x32_bf16 v[60:63], v[132:135], v[184:187], v[60:63]
	v_mfma_f32_16x16x32_bf16 v[56:59], v[140:143], v[184:187], v[56:59]
	v_mfma_f32_16x16x32_bf16 v[44:47], v[132:135], v[210:213], v[44:47]
	v_mfma_f32_16x16x32_bf16 v[40:43], v[140:143], v[210:213], v[40:43]
	v_mfma_f32_16x16x32_bf16 v[28:31], v[132:135], v[218:221], v[28:31]
	v_mfma_f32_16x16x32_bf16 v[24:27], v[140:143], v[218:221], v[24:27]
	v_mfma_f32_16x16x32_bf16 v[12:15], v[132:135], v[226:229], v[12:15]
	v_mfma_f32_16x16x32_bf16 v[8:11], v[140:143], v[226:229], v[8:11]


; #define PG8_MMA(ai, bj, At, Bt) do { __builtin_amdgcn_s_setprio(1); _Pragma("unroll") for (int m = 0; m < 4; ++m) _Pragma("unroll") for (int n = 0; n < 2; ++n) _Pragma("unroll") for (int k = 0; k < 2; ++k) \
;         acc[ai][bj][m][n] = __builtin_amdgcn_mfma_f32_16x16x32_bf16(Bt[n][k], At[m][k], acc[ai][bj][m][n], 0, 0, 0); __builtin_amdgcn_s_setprio(0); } while (0)
; #define PG8_WAIT_V(n) asm volatile("s_waitcnt vmcnt(" #n ")" ::: "memory")
; #define PG8_WAIT_L(n) asm volatile("s_waitcnt lgkmcnt(" #n ")" ::: "memory")
; #define PG8_BAR __builtin_amdgcn_s_barrier()
; #define PG8_SCHED __builtin_amdgcn_sched_barrier(0)
; template <class Epi, class Sched, bool ALIGN_EPI = false, bool SP2 = false>
; __device__ __forceinline__ void gemm_phase(PG8_LAS unsigned char* lds, const Gemm g, const Sched& S, const Epi& E) {
;     ...
;         for (int t = 0; t < nt; t += 2) {
;     ...
;             PG8_WAIT_V(8); PG8_WAIT_L(0); PG8_BAR; PG8_MMA(1, 0, At, B0); PG8_MMA(1, 1, At, B1); PG8_BAR; PG8_SCHED;
;     ...
;         if constexpr (ALIGN_EPI) { if (wr == 0) PG8_BAR; }
	v_mfma_f32_16x16x32_bf16 v[52:55], v[144:147], v[176:179], v[52:55]
	v_mfma_f32_16x16x32_bf16 v[48:51], v[152:155], v[176:179], v[48:51]
	v_mfma_f32_16x16x32_bf16 v[36:39], v[144:147], v[190:193], v[36:39]
	v_mfma_f32_16x16x32_bf16 v[32:35], v[152:155], v[190:193], v[32:35]
	v_mfma_f32_16x16x32_bf16 v[20:23], v[144:147], v[214:217], v[20:23]
	v_mfma_f32_16x16x32_bf16 v[16:19], v[152:155], v[214:217], v[16:19]
	v_mfma_f32_16x16x32_bf16 v[4:7], v[144:147], v[222:225], v[4:7]
	v_mfma_f32_16x16x32_bf16 v[0:3], v[152:155], v[222:225], v[0:3]
	v_mfma_f32_16x16x32_bf16 v[52:55], v[148:151], v[184:187], v[52:55]
	v_mfma_f32_16x16x32_bf16 v[48:51], v[156:159], v[184:187], v[48:51]
	v_mfma_f32_16x16x32_bf16 v[36:39], v[148:151], v[210:213], v[36:39]
	v_mfma_f32_16x16x32_bf16 v[32:35], v[156:159], v[210:213], v[32:35]
	v_mfma_f32_16x16x32_bf16 v[20:23], v[148:151], v[218:221], v[20:23]
	v_mfma_f32_16x16x32_bf16 v[16:19], v[156:159], v[218:221], v[16:19]
	v_mfma_f32_16x16x32_bf16 v[4:7], v[148:151], v[226:229], v[4:7]
	v_mfma_f32_16x16x32_bf16 v[0:3], v[156:159], v[226:229], v[0:3]
	s_setprio 0
	s_barrier
	s_add_i32 s85, s85, 2
	s_add_u32 s10, s10, 0x100
	s_addc_u32 s11, s11, 0
	s_add_u32 s83, s83, 0x100
	s_addc_u32 s84, s84, 0
	s_cmp_gt_u32 s85, 29
	s_cbranch_scc0 .LBB0_428
	s_and_b64 vcc, exec, s[42:43]
	s_cbranch_vccz .LBB0_431
	s_barrier

; #define PG8_STAGE(bufoff, gbase, voff) do { _Pragma("unroll") for (int _i = 0; _i < 2; ++_i) \
;         __builtin_amdgcn_global_load_lds((const unsigned*)((const char*)(gbase) + (voff)[_i]), (PG8_LAS unsigned*)(lds + (bufoff) + ldsw + _i * 8192), 16, 0, 0); } while (0)
; #define PG8_LDA(dst, b, h) do { _Pragma("unroll") for (int m = 0; m < 4; ++m) _Pragma("unroll") for (int k = 0; k < 2; ++k) dst[m][k] = *(const PG8_LAS bf16x8*)(lds + PG8_SA(b, h) + aoff + m * 2048 + k * 1024); } while (0)
; #define PG8_LDB(dst, b, h) do { _Pragma("unroll") for (int n = 0; n < 2; ++n) _Pragma("unroll") for (int k = 0; k < 2; ++k) dst[n][k] = *(const PG8_LAS bf16x8*)(lds + PG8_SB(b, h) + boff + n * 2048 + k * 1024); } while (0)
; #define PG8_SCHED __builtin_amdgcn_sched_barrier(0)
; template <class Epi, class Sched, bool ALIGN_EPI = false, bool SP2 = false>
; __device__ __forceinline__ void gemm_phase(PG8_LAS unsigned char* lds, const Gemm g, const Sched& S, const Epi& E) {
;     ...
;         const bool has_next = S.next(ui + 1, nxt);
;         const char* nA = has_next ? (const char*)g.A + (size_t)nxt.pm * tstep : cA; const char* nB = has_next ? (const char*)g.Bt + (size_t)nxt.pn * tstep : cB;
;         for (int t = 0; t < nt; t += 2) {
;             const bool last = (t == nt - 2);
;             const char* a1 = cA + (size_t)(t + 1) * kstep;
;             const char* a2 = last ? nA : cA + (size_t)(t + 2) * kstep; const char* b2 = last ? nB : cB + (size_t)(t + 2) * kstep;
;             const char* a3 = a2 + kstep; const char* b3 = b2 + kstep;
;             if (last && has_next) S.a_ready(nxt);
;             if constexpr (SP2) {
;             PG8_LDB(B0, 0, 0); PG8_LDB(B1, 0, 1); PG8_SCHED; PG8_LDA(At, 0, 0); PG8_STAGE(PG8_SA(1, 1), a1 + hstep, voffA);
;     ...
;         for (int a = 0; a < 2; ++a)
; #pragma unroll
;             for (int b = 0; b < 2; ++b)
; #pragma unroll
;                 for (int m = 0; m < 4; ++m)
; #pragma unroll
;                     for (int n = 0; n < 2; ++n) acc[a][b][m][n] = (f32x4){0.f, 0.f, 0.f, 0.f};
.LBB0_508:
	s_ashr_i32 s51, s50, 31
	s_lshl_b64 s[52:53], s[50:51], 22
	s_add_u32 s52, s22, s52
	s_addc_u32 s53, s23, s53
	s_and_b64 s[54:55], s[6:7], exec
	s_cselect_b32 s11, s53, s59
	s_cselect_b32 s51, s52, s58
	s_ashr_i32 s49, s48, 31
	s_lshl_b64 s[54:55], s[48:49], 22
	s_add_u32 s54, s45, s54
	s_addc_u32 s55, s47, s55
	s_and_b64 s[62:63], s[6:7], exec
	s_cselect_b32 s49, s55, s61
	s_cselect_b32 s78, s54, s60
	s_add_u32 s58, s58, 0x200080
	s_addc_u32 s59, s59, 0
	s_add_u32 s79, s60, 0x100
	v_mov_b32_e32 v0, 0
	s_addc_u32 s80, s61, 0
	s_mov_b32 s81, -2
	v_mov_b32_e32 v1, v0
	s_waitcnt lgkmcnt(0)
	v_mov_b32_e32 v2, v0
	v_mov_b32_e32 v3, v0
	v_mov_b32_e32 v4, v0
	v_mov_b32_e32 v5, v0
	v_mov_b32_e32 v6, v0
	v_mov_b32_e32 v7, v0
	v_mov_b32_e32 v16, v0
	v_mov_b32_e32 v17, v0
	v_mov_b32_e32 v18, v0
	v_mov_b32_e32 v19, v0
	v_mov_b32_e32 v20, v0
	v_mov_b32_e32 v21, v0
	v_mov_b32_e32 v22, v0
	v_mov_b32_e32 v23, v0
	v_mov_b32_e32 v32, v0
	v_mov_b32_e32 v33, v0
	v_mov_b32_e32 v34, v0
	v_mov_b32_e32 v35, v0
	v_mov_b32_e32 v36, v0
	v_mov_b32_e32 v37, v0
	v_mov_b32_e32 v38, v0
	v_mov_b32_e32 v39, v0
	v_mov_b32_e32 v48, v0
	v_mov_b32_e32 v49, v0
	v_mov_b32_e32 v50, v0
	v_mov_b32_e32 v51, v0
	v_mov_b32_e32 v52, v0
	v_mov_b32_e32 v53, v0
	v_mov_b32_e32 v54, v0
	v_mov_b32_e32 v55, v0
	v_mov_b32_e32 v8, v0
	v_mov_b32_e32 v9, v0
	v_mov_b32_e32 v10, v0
	v_mov_b32_e32 v11, v0
	v_mov_b32_e32 v12, v0
	v_mov_b32_e32 v13, v0
	v_mov_b32_e32 v14, v0
	v_mov_b32_e32 v15, v0
	v_mov_b32_e32 v24, v0
	v_mov_b32_e32 v25, v0
	v_mov_b32_e32 v26, v0
	v_mov_b32_e32 v27, v0
	v_mov_b32_e32 v28, v0
	v_mov_b32_e32 v29, v0
	v_mov_b32_e32 v30, v0
	v_mov_b32_e32 v31, v0
	v_mov_b32_e32 v40, v0
	v_mov_b32_e32 v41, v0
	v_mov_b32_e32 v42, v0
	v_mov_b32_e32 v43, v0
	v_mov_b32_e32 v44, v0
	v_mov_b32_e32 v45, v0
	v_mov_b32_e32 v46, v0
	v_mov_b32_e32 v47, v0
	v_mov_b32_e32 v56, v0
	v_mov_b32_e32 v57, v0
	v_mov_b32_e32 v58, v0
	v_mov_b32_e32 v59, v0
	v_mov_b32_e32 v60, v0
	v_mov_b32_e32 v61, v0
	v_mov_b32_e32 v62, v0
	v_mov_b32_e32 v63, v0
	v_mov_b32_e32 v80, v0
	v_mov_b32_e32 v81, v0
	v_mov_b32_e32 v82, v0
	v_mov_b32_e32 v83, v0
	v_mov_b32_e32 v84, v0
	v_mov_b32_e32 v85, v0
	v_mov_b32_e32 v86, v0
	v_mov_b32_e32 v87, v0
	v_mov_b32_e32 v96, v0
	v_mov_b32_e32 v97, v0
	v_mov_b32_e32 v98, v0
	v_mov_b32_e32 v99, v0
	v_mov_b32_e32 v100, v0
	v_mov_b32_e32 v101, v0
	v_mov_b32_e32 v102, v0
	v_mov_b32_e32 v103, v0
	v_mov_b32_e32 v112, v0
	v_mov_b32_e32 v113, v0
	v_mov_b32_e32 v114, v0
	v_mov_b32_e32 v115, v0
	v_mov_b32_e32 v116, v0
	v_mov_b32_e32 v117, v0
	v_mov_b32_e32 v118, v0
	v_mov_b32_e32 v119, v0
	v_mov_b32_e32 v128, v0
	v_mov_b32_e32 v129, v0
	v_mov_b32_e32 v130, v0
	v_mov_b32_e32 v131, v0
	v_mov_b32_e32 v132, v0
	v_mov_b32_e32 v133, v0
	v_mov_b32_e32 v134, v0
	v_mov_b32_e32 v135, v0
	v_mov_b32_e32 v88, v0
	v_mov_b32_e32 v89, v0
	v_mov_b32_e32 v90, v0
	v_mov_b32_e32 v91, v0
	v_mov_b32_e32 v92, v0
	v_mov_b32_e32 v93, v0
	v_mov_b32_e32 v94, v0
	v_mov_b32_e32 v95, v0
	v_mov_b32_e32 v104, v0
	v_mov_b32_e32 v105, v0
	v_mov_b32_e32 v106, v0
	v_mov_b32_e32 v107, v0
	v_mov_b32_e32 v108, v0
	v_mov_b32_e32 v109, v0
	v_mov_b32_e32 v110, v0
	v_mov_b32_e32 v111, v0
	v_mov_b32_e32 v120, v0
	v_mov_b32_e32 v121, v0
	v_mov_b32_e32 v122, v0
	v_mov_b32_e32 v123, v0
	v_mov_b32_e32 v124, v0
	v_mov_b32_e32 v125, v0
	v_mov_b32_e32 v126, v0
	v_mov_b32_e32 v127, v0
	v_mov_b32_e32 v136, v0
	v_mov_b32_e32 v137, v0
	v_mov_b32_e32 v138, v0
	v_mov_b32_e32 v139, v0
	v_mov_b32_e32 v140, v0
	v_mov_b32_e32 v141, v0
	v_mov_b32_e32 v142, v0
	v_mov_b32_e32 v143, v0
	v_add_u32_e32 v255, 0x1c000, v211
	v_add_u32_e32 v254, 0x18000, v211
	v_add_u32_e32 v253, 0x80, v164
	v_add_u32_e32 v252, 0x80, v160
	v_add_u32_e32 v251, 0x80, v166
	v_add_u32_e32 v250, 0x80, v162
.LBB0_509:
	ds_read_b128 v[64:67], v213
	ds_read_b128 v[68:71], v213 offset:1024
	ds_read_b128 v[72:75], v213 offset:2048
	ds_read_b128 v[76:79], v213 offset:3072
	ds_read_b128 v[144:147], v214
	ds_read_b128 v[148:151], v214 offset:1024
	ds_read_b128 v[152:155], v214 offset:2048
	ds_read_b128 v[156:159], v214 offset:3072
	s_add_u32 s60, s58, 0xffe00080
	s_addc_u32 s61, s59, -1
	s_cmpk_eq_i32 s81, 0x7c
	s_cselect_b32 s63, s11, s61
	s_cselect_b32 s62, s51, s60
	s_cselect_b32 s61, s49, s80
	s_cselect_b32 s60, s78, s79

; #define PG8_STAGE(bufoff, gbase, voff) do { _Pragma("unroll") for (int _i = 0; _i < 2; ++_i) \
;         __builtin_amdgcn_global_load_lds((const unsigned*)((const char*)(gbase) + (voff)[_i]), (PG8_LAS unsigned*)(lds + (bufoff) + ldsw + _i * 8192), 16, 0, 0); } while (0)
; #define PG8_LDA(dst, b, h) do { _Pragma("unroll") for (int m = 0; m < 4; ++m) _Pragma("unroll") for (int k = 0; k < 2; ++k) dst[m][k] = *(const PG8_LAS bf16x8*)(lds + PG8_SA(b, h) + aoff + m * 2048 + k * 1024); } while (0)
; #define PG8_LDB(dst, b, h) do { _Pragma("unroll") for (int n = 0; n < 2; ++n) _Pragma("unroll") for (int k = 0; k < 2; ++k) dst[n][k] = *(const PG8_LAS bf16x8*)(lds + PG8_SB(b, h) + boff + n * 2048 + k * 1024); } while (0)
; #define PG8_SCHED __builtin_amdgcn_sched_barrier(0)
; template <class Epi, class Sched, bool ALIGN_EPI = false, bool SP2 = false>
; __device__ __forceinline__ void gemm_phase(PG8_LAS unsigned char* lds, const Gemm g, const Sched& S, const Epi& E) {
;     ...
;             PG8_LDB(B0, 0, 0); PG8_LDB(B1, 0, 1); PG8_SCHED; PG8_LDA(At, 0, 0); PG8_STAGE(PG8_SA(1, 1), a1 + hstep, voffA);
	s_add_i32 m0, s57, 0xc000
	ds_read_b128 v[176:179], v215
	ds_read_b128 v[180:183], v215 offset:1024
	ds_read_b128 v[184:187], v215 offset:2048
	ds_read_b128 v[188:191], v215 offset:3072
	ds_read_b128 v[192:195], v215 offset:4096
	ds_read_b128 v[196:199], v215 offset:5120
	ds_read_b128 v[200:203], v215 offset:6144
	ds_read_b128 v[204:207], v215 offset:7168
	global_load_lds_dwordx4 v168, s[58:59]

; #define PG8_STAGE(bufoff, gbase, voff) do { _Pragma("unroll") for (int _i = 0; _i < 2; ++_i) \
;         __builtin_amdgcn_global_load_lds((const unsigned*)((const char*)(gbase) + (voff)[_i]), (PG8_LAS unsigned*)(lds + (bufoff) + ldsw + _i * 8192), 16, 0, 0); } while (0)
; #define PG8_LDA(dst, b, h) do { _Pragma("unroll") for (int m = 0; m < 4; ++m) _Pragma("unroll") for (int k = 0; k < 2; ++k) dst[m][k] = *(const PG8_LAS bf16x8*)(lds + PG8_SA(b, h) + aoff + m * 2048 + k * 1024); } while (0)
; #define PG8_LDB(dst, b, h) do { _Pragma("unroll") for (int n = 0; n < 2; ++n) _Pragma("unroll") for (int k = 0; k < 2; ++k) dst[n][k] = *(const PG8_LAS bf16x8*)(lds + PG8_SB(b, h) + boff + n * 2048 + k * 1024); } while (0)
; #define PG8_MMA(ai, bj, At, Bt) do { __builtin_amdgcn_s_setprio(1); _Pragma("unroll") for (int m = 0; m < 4; ++m) _Pragma("unroll") for (int n = 0; n < 2; ++n) _Pragma("unroll") for (int k = 0; k < 2; ++k) \
;         acc[ai][bj][m][n] = __builtin_amdgcn_mfma_f32_16x16x32_bf16(Bt[n][k], At[m][k], acc[ai][bj][m][n], 0, 0, 0); __builtin_amdgcn_s_setprio(0); } while (0)
; #define PG8_WAIT_V(n) asm volatile("s_waitcnt vmcnt(" #n ")" ::: "memory")
; #define PG8_WAIT_L(n) asm volatile("s_waitcnt lgkmcnt(" #n ")" ::: "memory")
; #define PG8_BAR __builtin_amdgcn_s_barrier()
; #define PG8_SCHED __builtin_amdgcn_sched_barrier(0)
; template <class Epi, class Sched, bool ALIGN_EPI = false, bool SP2 = false>
; __device__ __forceinline__ void gemm_phase(PG8_LAS unsigned char* lds, const Gemm g, const Sched& S, const Epi& E) {
;     ...
;             PG8_LDB(B0, 0, 0); PG8_LDB(B1, 0, 1); PG8_SCHED; PG8_LDA(At, 0, 0); PG8_STAGE(PG8_SA(1, 1), a1 + hstep, voffA);
;             PG8_WAIT_V(8); PG8_WAIT_L(0); PG8_BAR; PG8_MMA(0, 0, At, B0); PG8_MMA(0, 1, At, B1); PG8_BAR; PG8_SCHED;
	s_add_i32 m0, s57, 0xe000
	s_nop 0
	global_load_lds_dwordx4 v170, s[58:59]
	s_waitcnt vmcnt(8)
	s_waitcnt lgkmcnt(0)
	s_barrier
	s_setprio 1
	s_waitcnt lgkmcnt(0)
	v_mfma_f32_16x16x32_bf16 v[140:143], v[64:67], v[176:179], v[140:143]
	v_mfma_f32_16x16x32_bf16 v[136:139], v[72:75], v[176:179], v[136:139]
	v_mfma_f32_16x16x32_bf16 v[124:127], v[64:67], v[184:187], v[124:127]
	v_mfma_f32_16x16x32_bf16 v[120:123], v[72:75], v[184:187], v[120:123]
	v_mfma_f32_16x16x32_bf16 v[108:111], v[64:67], v[192:195], v[108:111]
	v_mfma_f32_16x16x32_bf16 v[104:107], v[72:75], v[192:195], v[104:107]
	v_mfma_f32_16x16x32_bf16 v[92:95], v[64:67], v[200:203], v[92:95]
	v_mfma_f32_16x16x32_bf16 v[88:91], v[72:75], v[200:203], v[88:91]
	v_mfma_f32_16x16x32_bf16 v[140:143], v[68:71], v[180:183], v[140:143]
	v_mfma_f32_16x16x32_bf16 v[136:139], v[76:79], v[180:183], v[136:139]
	v_mfma_f32_16x16x32_bf16 v[124:127], v[68:71], v[188:191], v[124:127]
	v_mfma_f32_16x16x32_bf16 v[120:123], v[76:79], v[188:191], v[120:123]
	v_mfma_f32_16x16x32_bf16 v[108:111], v[68:71], v[196:199], v[108:111]
	v_mfma_f32_16x16x32_bf16 v[104:107], v[76:79], v[196:199], v[104:107]
	v_mfma_f32_16x16x32_bf16 v[92:95], v[68:71], v[204:207], v[92:95]
	v_mfma_f32_16x16x32_bf16 v[88:91], v[76:79], v[204:207], v[88:91]


; #define PG8_MMA(ai, bj, At, Bt) do { __builtin_amdgcn_s_setprio(1); _Pragma("unroll") for (int m = 0; m < 4; ++m) _Pragma("unroll") for (int n = 0; n < 2; ++n) _Pragma("unroll") for (int k = 0; k < 2; ++k) \
;         acc[ai][bj][m][n] = __builtin_amdgcn_mfma_f32_16x16x32_bf16(Bt[n][k], At[m][k], acc[ai][bj][m][n], 0, 0, 0); __builtin_amdgcn_s_setprio(0); } while (0)
; #define PG8_WAIT_V(n) asm volatile("s_waitcnt vmcnt(" #n ")" ::: "memory")
; #define PG8_WAIT_L(n) asm volatile("s_waitcnt lgkmcnt(" #n ")" ::: "memory")
; #define PG8_BAR __builtin_amdgcn_s_barrier()
; #define PG8_SCHED __builtin_amdgcn_sched_barrier(0)
; template <class Epi, class Sched, bool ALIGN_EPI = false, bool SP2 = false>
; __device__ __forceinline__ void gemm_phase(PG8_LAS unsigned char* lds, const Gemm g, const Sched& S, const Epi& E) {
;     ...
;             PG8_WAIT_V(8); PG8_WAIT_L(0); PG8_BAR; PG8_MMA(0, 0, At, B0); PG8_MMA(0, 1, At, B1); PG8_BAR; PG8_SCHED;
	v_mfma_f32_16x16x32_bf16 v[132:135], v[144:147], v[176:179], v[132:135]
	v_mfma_f32_16x16x32_bf16 v[128:131], v[152:155], v[176:179], v[128:131]
	v_mfma_f32_16x16x32_bf16 v[116:119], v[144:147], v[184:187], v[116:119]
	v_mfma_f32_16x16x32_bf16 v[112:115], v[152:155], v[184:187], v[112:115]
	v_mfma_f32_16x16x32_bf16 v[100:103], v[144:147], v[192:195], v[100:103]
	v_mfma_f32_16x16x32_bf16 v[96:99], v[152:155], v[192:195], v[96:99]
	v_mfma_f32_16x16x32_bf16 v[84:87], v[144:147], v[200:203], v[84:87]
	v_mfma_f32_16x16x32_bf16 v[80:83], v[152:155], v[200:203], v[80:83]
	v_mfma_f32_16x16x32_bf16 v[132:135], v[148:151], v[180:183], v[132:135]
	v_mfma_f32_16x16x32_bf16 v[128:131], v[156:159], v[180:183], v[128:131]
	v_mfma_f32_16x16x32_bf16 v[116:119], v[148:151], v[188:191], v[116:119]
	v_mfma_f32_16x16x32_bf16 v[112:115], v[156:159], v[188:191], v[112:115]
	v_mfma_f32_16x16x32_bf16 v[100:103], v[148:151], v[196:199], v[100:103]
	v_mfma_f32_16x16x32_bf16 v[96:99], v[156:159], v[196:199], v[96:99]
	v_mfma_f32_16x16x32_bf16 v[84:87], v[148:151], v[204:207], v[84:87]
	v_mfma_f32_16x16x32_bf16 v[80:83], v[156:159], v[204:207], v[80:83]
	s_setprio 0
	s_barrier
	s_add_i32 s82, s75, s64
	s_mov_b64 s[96:97], s[60:61]

; #define PG8_STAGE(bufoff, gbase, voff) do { _Pragma("unroll") for (int _i = 0; _i < 2; ++_i) \
;         __builtin_amdgcn_global_load_lds((const unsigned*)((const char*)(gbase) + (voff)[_i]), (PG8_LAS unsigned*)(lds + (bufoff) + ldsw + _i * 8192), 16, 0, 0); } while (0)
; #define PG8_LDA(dst, b, h) do { _Pragma("unroll") for (int m = 0; m < 4; ++m) _Pragma("unroll") for (int k = 0; k < 2; ++k) dst[m][k] = *(const PG8_LAS bf16x8*)(lds + PG8_SA(b, h) + aoff + m * 2048 + k * 1024); } while (0)
; template <class Epi, class Sched, bool ALIGN_EPI = false, bool SP2 = false>
; __device__ __forceinline__ void gemm_phase(PG8_LAS unsigned char* lds, const Gemm g, const Sched& S, const Epi& E) {
;     ...
;             PG8_LDA(At, 0, 1); PG8_STAGE(PG8_SB(0, 0), b2, voffB); PG8_STAGE(PG8_SB(0, 1), b2 + hstep, voffB); PG8_STAGE(PG8_SA(0, 0), a2, voffA);
	s_mov_b32 m0, s82
	ds_read_b128 v[176:179], v215 offset:16384
	ds_read_b128 v[180:183], v215 offset:17408
	ds_read_b128 v[184:187], v215 offset:18432
	ds_read_b128 v[188:191], v215 offset:19456
	ds_read_b128 v[192:195], v215 offset:20480
	ds_read_b128 v[196:199], v215 offset:21504
	ds_read_b128 v[200:203], v215 offset:22528
	ds_read_b128 v[204:207], v215 offset:23552
	global_load_lds_dwordx4 v162, s[60:61]
	s_add_i32 m0, s82, 0x2000
	s_add_u32 s82, s60, 0x200000

; #define PG8_STAGE(bufoff, gbase, voff) do { _Pragma("unroll") for (int _i = 0; _i < 2; ++_i) \
;         __builtin_amdgcn_global_load_lds((const unsigned*)((const char*)(gbase) + (voff)[_i]), (PG8_LAS unsigned*)(lds + (bufoff) + ldsw + _i * 8192), 16, 0, 0); } while (0)
; #define PG8_LDA(dst, b, h) do { _Pragma("unroll") for (int m = 0; m < 4; ++m) _Pragma("unroll") for (int k = 0; k < 2; ++k) dst[m][k] = *(const PG8_LAS bf16x8*)(lds + PG8_SA(b, h) + aoff + m * 2048 + k * 1024); } while (0)
; template <class Epi, class Sched, bool ALIGN_EPI = false, bool SP2 = false>
; __device__ __forceinline__ void gemm_phase(PG8_LAS unsigned char* lds, const Gemm g, const Sched& S, const Epi& E) {
;     ...
;             PG8_LDA(At, 0, 1); PG8_STAGE(PG8_SB(0, 0), b2, voffB); PG8_STAGE(PG8_SB(0, 1), b2 + hstep, voffB); PG8_STAGE(PG8_SA(0, 0), a2, voffA);
	s_addc_u32 s83, s61, 0
	s_add_i32 s84, s76, s64
	global_load_lds_dwordx4 v166, s[60:61]

; #define PG8_STAGE(bufoff, gbase, voff) do { _Pragma("unroll") for (int _i = 0; _i < 2; ++_i) \
;         __builtin_amdgcn_global_load_lds((const unsigned*)((const char*)(gbase) + (voff)[_i]), (PG8_LAS unsigned*)(lds + (bufoff) + ldsw + _i * 8192), 16, 0, 0); } while (0)
; #define PG8_LDA(dst, b, h) do { _Pragma("unroll") for (int m = 0; m < 4; ++m) _Pragma("unroll") for (int k = 0; k < 2; ++k) dst[m][k] = *(const PG8_LAS bf16x8*)(lds + PG8_SA(b, h) + aoff + m * 2048 + k * 1024); } while (0)
; template <class Epi, class Sched, bool ALIGN_EPI = false, bool SP2 = false>
; __device__ __forceinline__ void gemm_phase(PG8_LAS unsigned char* lds, const Gemm g, const Sched& S, const Epi& E) {
;     ...
;             PG8_LDA(At, 0, 1); PG8_STAGE(PG8_SB(0, 0), b2, voffB); PG8_STAGE(PG8_SB(0, 1), b2 + hstep, voffB); PG8_STAGE(PG8_SA(0, 0), a2, voffA);
	s_mov_b32 m0, s84
	s_nop 0
	global_load_lds_dwordx4 v162, s[82:83]

; #define PG8_STAGE(bufoff, gbase, voff) do { _Pragma("unroll") for (int _i = 0; _i < 2; ++_i) \
;         __builtin_amdgcn_global_load_lds((const unsigned*)((const char*)(gbase) + (voff)[_i]), (PG8_LAS unsigned*)(lds + (bufoff) + ldsw + _i * 8192), 16, 0, 0); } while (0)
; #define PG8_LDA(dst, b, h) do { _Pragma("unroll") for (int m = 0; m < 4; ++m) _Pragma("unroll") for (int k = 0; k < 2; ++k) dst[m][k] = *(const PG8_LAS bf16x8*)(lds + PG8_SA(b, h) + aoff + m * 2048 + k * 1024); } while (0)
; template <class Epi, class Sched, bool ALIGN_EPI = false, bool SP2 = false>
; __device__ __forceinline__ void gemm_phase(PG8_LAS unsigned char* lds, const Gemm g, const Sched& S, const Epi& E) {
;     ...
;             PG8_LDA(At, 0, 1); PG8_STAGE(PG8_SB(0, 0), b2, voffB); PG8_STAGE(PG8_SB(0, 1), b2 + hstep, voffB); PG8_STAGE(PG8_SA(0, 0), a2, voffA);
	s_add_i32 m0, s84, 0x2000
	s_nop 0
	global_load_lds_dwordx4 v166, s[82:83]
	s_mov_b64 s[98:99], s[62:63]

; #define PG8_STAGE(bufoff, gbase, voff) do { _Pragma("unroll") for (int _i = 0; _i < 2; ++_i) \
;         __builtin_amdgcn_global_load_lds((const unsigned*)((const char*)(gbase) + (voff)[_i]), (PG8_LAS unsigned*)(lds + (bufoff) + ldsw + _i * 8192), 16, 0, 0); } while (0)
; #define PG8_LDA(dst, b, h) do { _Pragma("unroll") for (int m = 0; m < 4; ++m) _Pragma("unroll") for (int k = 0; k < 2; ++k) dst[m][k] = *(const PG8_LAS bf16x8*)(lds + PG8_SA(b, h) + aoff + m * 2048 + k * 1024); } while (0)
; #define PG8_MMA(ai, bj, At, Bt) do { __builtin_amdgcn_s_setprio(1); _Pragma("unroll") for (int m = 0; m < 4; ++m) _Pragma("unroll") for (int n = 0; n < 2; ++n) _Pragma("unroll") for (int k = 0; k < 2; ++k) \
;         acc[ai][bj][m][n] = __builtin_amdgcn_mfma_f32_16x16x32_bf16(Bt[n][k], At[m][k], acc[ai][bj][m][n], 0, 0, 0); __builtin_amdgcn_s_setprio(0); } while (0)
; #define PG8_WAIT_V(n) asm volatile("s_waitcnt vmcnt(" #n ")" ::: "memory")
; #define PG8_WAIT_L(n) asm volatile("s_waitcnt lgkmcnt(" #n ")" ::: "memory")
; #define PG8_BAR __builtin_amdgcn_s_barrier()
; #define PG8_SCHED __builtin_amdgcn_sched_barrier(0)
; template <class Epi, class Sched, bool ALIGN_EPI = false, bool SP2 = false>
; __device__ __forceinline__ void gemm_phase(PG8_LAS unsigned char* lds, const Gemm g, const Sched& S, const Epi& E) {
;     ...
;             PG8_LDA(At, 0, 1); PG8_STAGE(PG8_SB(0, 0), b2, voffB); PG8_STAGE(PG8_SB(0, 1), b2 + hstep, voffB); PG8_STAGE(PG8_SA(0, 0), a2, voffA);
;             PG8_WAIT_V(8); PG8_WAIT_L(0); PG8_BAR; PG8_MMA(1, 0, At, B0); PG8_MMA(1, 1, At, B1); PG8_BAR; PG8_SCHED;
	s_mov_b32 m0, s57
	s_nop 0
	global_load_lds_dwordx4 v160, s[62:63]
	s_mov_b32 m0, s65
	s_nop 0
	global_load_lds_dwordx4 v164, s[62:63]
	s_waitcnt vmcnt(8)
	s_waitcnt lgkmcnt(0)
	s_barrier
	s_setprio 1
	s_waitcnt lgkmcnt(0)
	v_mfma_f32_16x16x32_bf16 v[60:63], v[64:67], v[176:179], v[60:63]
	v_mfma_f32_16x16x32_bf16 v[56:59], v[72:75], v[176:179], v[56:59]
	v_mfma_f32_16x16x32_bf16 v[44:47], v[64:67], v[184:187], v[44:47]
	v_mfma_f32_16x16x32_bf16 v[40:43], v[72:75], v[184:187], v[40:43]
	v_mfma_f32_16x16x32_bf16 v[28:31], v[64:67], v[192:195], v[28:31]
	v_mfma_f32_16x16x32_bf16 v[24:27], v[72:75], v[192:195], v[24:27]
	v_mfma_f32_16x16x32_bf16 v[12:15], v[64:67], v[200:203], v[12:15]
	v_mfma_f32_16x16x32_bf16 v[8:11], v[72:75], v[200:203], v[8:11]
	v_mfma_f32_16x16x32_bf16 v[60:63], v[68:71], v[180:183], v[60:63]
	v_mfma_f32_16x16x32_bf16 v[56:59], v[76:79], v[180:183], v[56:59]
	v_mfma_f32_16x16x32_bf16 v[44:47], v[68:71], v[188:191], v[44:47]
	v_mfma_f32_16x16x32_bf16 v[40:43], v[76:79], v[188:191], v[40:43]
	v_mfma_f32_16x16x32_bf16 v[28:31], v[68:71], v[196:199], v[28:31]
	v_mfma_f32_16x16x32_bf16 v[24:27], v[76:79], v[196:199], v[24:27]
	v_mfma_f32_16x16x32_bf16 v[12:15], v[68:71], v[204:207], v[12:15]
	v_mfma_f32_16x16x32_bf16 v[8:11], v[76:79], v[204:207], v[8:11]


; #define PG8_STAGE(bufoff, gbase, voff) do { _Pragma("unroll") for (int _i = 0; _i < 2; ++_i) \
;         __builtin_amdgcn_global_load_lds((const unsigned*)((const char*)(gbase) + (voff)[_i]), (PG8_LAS unsigned*)(lds + (bufoff) + ldsw + _i * 8192), 16, 0, 0); } while (0)
; #define PG8_LDA(dst, b, h) do { _Pragma("unroll") for (int m = 0; m < 4; ++m) _Pragma("unroll") for (int k = 0; k < 2; ++k) dst[m][k] = *(const PG8_LAS bf16x8*)(lds + PG8_SA(b, h) + aoff + m * 2048 + k * 1024); } while (0)
; #define PG8_LDB(dst, b, h) do { _Pragma("unroll") for (int n = 0; n < 2; ++n) _Pragma("unroll") for (int k = 0; k < 2; ++k) dst[n][k] = *(const PG8_LAS bf16x8*)(lds + PG8_SB(b, h) + boff + n * 2048 + k * 1024); } while (0)
; #define PG8_MMA(ai, bj, At, Bt) do { __builtin_amdgcn_s_setprio(1); _Pragma("unroll") for (int m = 0; m < 4; ++m) _Pragma("unroll") for (int n = 0; n < 2; ++n) _Pragma("unroll") for (int k = 0; k < 2; ++k) \
;         acc[ai][bj][m][n] = __builtin_amdgcn_mfma_f32_16x16x32_bf16(Bt[n][k], At[m][k], acc[ai][bj][m][n], 0, 0, 0); __builtin_amdgcn_s_setprio(0); } while (0)
; #define PG8_WAIT_V(n) asm volatile("s_waitcnt vmcnt(" #n ")" ::: "memory")
; #define PG8_WAIT_L(n) asm volatile("s_waitcnt lgkmcnt(" #n ")" ::: "memory")
; #define PG8_BAR __builtin_amdgcn_s_barrier()
; #define PG8_SCHED __builtin_amdgcn_sched_barrier(0)
; template <class Epi, class Sched, bool ALIGN_EPI = false, bool SP2 = false>
; __device__ __forceinline__ void gemm_phase(PG8_LAS unsigned char* lds, const Gemm g, const Sched& S, const Epi& E) {
;     ...
;             PG8_WAIT_V(8); PG8_WAIT_L(0); PG8_BAR; PG8_MMA(1, 0, At, B0); PG8_MMA(1, 1, At, B1); PG8_BAR; PG8_SCHED;
;             PG8_LDB(B0, 1, 0); PG8_LDB(B1, 1, 1); PG8_SCHED; PG8_LDA(At, 1, 0); PG8_STAGE(PG8_SA(0, 1), a2 + hstep, voffA);
	v_mfma_f32_16x16x32_bf16 v[52:55], v[144:147], v[176:179], v[52:55]
	v_mfma_f32_16x16x32_bf16 v[48:51], v[152:155], v[176:179], v[48:51]
	v_mfma_f32_16x16x32_bf16 v[36:39], v[144:147], v[184:187], v[36:39]
	v_mfma_f32_16x16x32_bf16 v[32:35], v[152:155], v[184:187], v[32:35]
	v_mfma_f32_16x16x32_bf16 v[20:23], v[144:147], v[192:195], v[20:23]
	v_mfma_f32_16x16x32_bf16 v[16:19], v[152:155], v[192:195], v[16:19]
	v_mfma_f32_16x16x32_bf16 v[4:7], v[144:147], v[200:203], v[4:7]
	v_mfma_f32_16x16x32_bf16 v[0:3], v[152:155], v[200:203], v[0:3]
	v_mfma_f32_16x16x32_bf16 v[52:55], v[148:151], v[180:183], v[52:55]
	v_mfma_f32_16x16x32_bf16 v[48:51], v[156:159], v[180:183], v[48:51]
	v_mfma_f32_16x16x32_bf16 v[36:39], v[148:151], v[188:191], v[36:39]
	v_mfma_f32_16x16x32_bf16 v[32:35], v[156:159], v[188:191], v[32:35]
	v_mfma_f32_16x16x32_bf16 v[20:23], v[148:151], v[196:199], v[20:23]
	v_mfma_f32_16x16x32_bf16 v[16:19], v[156:159], v[196:199], v[16:19]
	v_mfma_f32_16x16x32_bf16 v[4:7], v[148:151], v[204:207], v[4:7]
	v_mfma_f32_16x16x32_bf16 v[0:3], v[156:159], v[204:207], v[0:3]
	s_setprio 0
	s_barrier
	s_add_i32 s82, 0, 0x18000
	s_add_i32 s83, 0, 0x1c000


; #define PG8_STAGE(bufoff, gbase, voff) do { _Pragma("unroll") for (int _i = 0; _i < 2; ++_i) \
;         __builtin_amdgcn_global_load_lds((const unsigned*)((const char*)(gbase) + (voff)[_i]), (PG8_LAS unsigned*)(lds + (bufoff) + ldsw + _i * 8192), 16, 0, 0); } while (0)
; #define PG8_LDA(dst, b, h) do { _Pragma("unroll") for (int m = 0; m < 4; ++m) _Pragma("unroll") for (int k = 0; k < 2; ++k) dst[m][k] = *(const PG8_LAS bf16x8*)(lds + PG8_SA(b, h) + aoff + m * 2048 + k * 1024); } while (0)
; #define PG8_LDB(dst, b, h) do { _Pragma("unroll") for (int n = 0; n < 2; ++n) _Pragma("unroll") for (int k = 0; k < 2; ++k) dst[n][k] = *(const PG8_LAS bf16x8*)(lds + PG8_SB(b, h) + boff + n * 2048 + k * 1024); } while (0)
; #define PG8_SCHED __builtin_amdgcn_sched_barrier(0)
; template <class Epi, class Sched, bool ALIGN_EPI = false, bool SP2 = false>
; __device__ __forceinline__ void gemm_phase(PG8_LAS unsigned char* lds, const Gemm g, const Sched& S, const Epi& E) {
;     ...
;             PG8_LDB(B0, 1, 0); PG8_LDB(B1, 1, 1); PG8_SCHED; PG8_LDA(At, 1, 0); PG8_STAGE(PG8_SA(0, 1), a2 + hstep, voffA);
	ds_read_b128 v[64:67], v254
	ds_read_b128 v[68:71], v254 offset:1024
	ds_read_b128 v[72:75], v254 offset:2048
	ds_read_b128 v[76:79], v254 offset:3072
	ds_read_b128 v[144:147], v255
	ds_read_b128 v[148:151], v255 offset:1024
	ds_read_b128 v[152:155], v255 offset:2048
	ds_read_b128 v[156:159], v255 offset:3072
	s_add_u32 s62, s62, 0x200000
	s_addc_u32 s63, s63, 0
	s_mov_b32 m0, s67

; #define PG8_STAGE(bufoff, gbase, voff) do { _Pragma("unroll") for (int _i = 0; _i < 2; ++_i) \
;         __builtin_amdgcn_global_load_lds((const unsigned*)((const char*)(gbase) + (voff)[_i]), (PG8_LAS unsigned*)(lds + (bufoff) + ldsw + _i * 8192), 16, 0, 0); } while (0)
; #define PG8_LDA(dst, b, h) do { _Pragma("unroll") for (int m = 0; m < 4; ++m) _Pragma("unroll") for (int k = 0; k < 2; ++k) dst[m][k] = *(const PG8_LAS bf16x8*)(lds + PG8_SA(b, h) + aoff + m * 2048 + k * 1024); } while (0)
; #define PG8_LDB(dst, b, h) do { _Pragma("unroll") for (int n = 0; n < 2; ++n) _Pragma("unroll") for (int k = 0; k < 2; ++k) dst[n][k] = *(const PG8_LAS bf16x8*)(lds + PG8_SB(b, h) + boff + n * 2048 + k * 1024); } while (0)
; #define PG8_SCHED __builtin_amdgcn_sched_barrier(0)
; template <class Epi, class Sched, bool ALIGN_EPI = false, bool SP2 = false>
; __device__ __forceinline__ void gemm_phase(PG8_LAS unsigned char* lds, const Gemm g, const Sched& S, const Epi& E) {
;     ...
;             PG8_LDB(B0, 1, 0); PG8_LDB(B1, 1, 1); PG8_SCHED; PG8_LDA(At, 1, 0); PG8_STAGE(PG8_SA(0, 1), a2 + hstep, voffA);
	ds_read_b128 v[176:179], v215 offset:32768
	ds_read_b128 v[180:183], v215 offset:33792
	ds_read_b128 v[184:187], v215 offset:34816
	ds_read_b128 v[188:191], v215 offset:35840
	ds_read_b128 v[192:195], v215 offset:36864
	ds_read_b128 v[196:199], v215 offset:37888
	ds_read_b128 v[200:203], v215 offset:38912
	ds_read_b128 v[204:207], v215 offset:39936
	global_load_lds_dwordx4 v160, s[62:63]

; #define PG8_STAGE(bufoff, gbase, voff) do { _Pragma("unroll") for (int _i = 0; _i < 2; ++_i) \
;         __builtin_amdgcn_global_load_lds((const unsigned*)((const char*)(gbase) + (voff)[_i]), (PG8_LAS unsigned*)(lds + (bufoff) + ldsw + _i * 8192), 16, 0, 0); } while (0)
; #define PG8_LDA(dst, b, h) do { _Pragma("unroll") for (int m = 0; m < 4; ++m) _Pragma("unroll") for (int k = 0; k < 2; ++k) dst[m][k] = *(const PG8_LAS bf16x8*)(lds + PG8_SA(b, h) + aoff + m * 2048 + k * 1024); } while (0)
; #define PG8_LDB(dst, b, h) do { _Pragma("unroll") for (int n = 0; n < 2; ++n) _Pragma("unroll") for (int k = 0; k < 2; ++k) dst[n][k] = *(const PG8_LAS bf16x8*)(lds + PG8_SB(b, h) + boff + n * 2048 + k * 1024); } while (0)
; #define PG8_MMA(ai, bj, At, Bt) do { __builtin_amdgcn_s_setprio(1); _Pragma("unroll") for (int m = 0; m < 4; ++m) _Pragma("unroll") for (int n = 0; n < 2; ++n) _Pragma("unroll") for (int k = 0; k < 2; ++k) \
;         acc[ai][bj][m][n] = __builtin_amdgcn_mfma_f32_16x16x32_bf16(Bt[n][k], At[m][k], acc[ai][bj][m][n], 0, 0, 0); __builtin_amdgcn_s_setprio(0); } while (0)
; #define PG8_WAIT_V(n) asm volatile("s_waitcnt vmcnt(" #n ")" ::: "memory")
; #define PG8_WAIT_L(n) asm volatile("s_waitcnt lgkmcnt(" #n ")" ::: "memory")
; #define PG8_BAR __builtin_amdgcn_s_barrier()
; #define PG8_SCHED __builtin_amdgcn_sched_barrier(0)
; template <class Epi, class Sched, bool ALIGN_EPI = false, bool SP2 = false>
; __device__ __forceinline__ void gemm_phase(PG8_LAS unsigned char* lds, const Gemm g, const Sched& S, const Epi& E) {
;     ...
;             PG8_LDB(B0, 1, 0); PG8_LDB(B1, 1, 1); PG8_SCHED; PG8_LDA(At, 1, 0); PG8_STAGE(PG8_SA(0, 1), a2 + hstep, voffA);
;             PG8_WAIT_V(8); PG8_WAIT_L(0); PG8_BAR; PG8_MMA(0, 0, At, B0); PG8_MMA(0, 1, At, B1); PG8_BAR; PG8_SCHED;
	s_mov_b32 m0, s68
	s_nop 0
	global_load_lds_dwordx4 v164, s[62:63]
	s_waitcnt vmcnt(8)
	s_waitcnt lgkmcnt(0)
	s_barrier
	s_setprio 1
	s_waitcnt lgkmcnt(0)
	v_mfma_f32_16x16x32_bf16 v[140:143], v[64:67], v[176:179], v[140:143]
	v_mfma_f32_16x16x32_bf16 v[136:139], v[72:75], v[176:179], v[136:139]
	v_mfma_f32_16x16x32_bf16 v[124:127], v[64:67], v[184:187], v[124:127]
	v_mfma_f32_16x16x32_bf16 v[120:123], v[72:75], v[184:187], v[120:123]
	v_mfma_f32_16x16x32_bf16 v[108:111], v[64:67], v[192:195], v[108:111]
	v_mfma_f32_16x16x32_bf16 v[104:107], v[72:75], v[192:195], v[104:107]
	v_mfma_f32_16x16x32_bf16 v[92:95], v[64:67], v[200:203], v[92:95]
	v_mfma_f32_16x16x32_bf16 v[88:91], v[72:75], v[200:203], v[88:91]
	v_mfma_f32_16x16x32_bf16 v[140:143], v[68:71], v[180:183], v[140:143]
	v_mfma_f32_16x16x32_bf16 v[136:139], v[76:79], v[180:183], v[136:139]
	v_mfma_f32_16x16x32_bf16 v[124:127], v[68:71], v[188:191], v[124:127]
	v_mfma_f32_16x16x32_bf16 v[120:123], v[76:79], v[188:191], v[120:123]
	v_mfma_f32_16x16x32_bf16 v[108:111], v[68:71], v[196:199], v[108:111]
	v_mfma_f32_16x16x32_bf16 v[104:107], v[76:79], v[196:199], v[104:107]
	v_mfma_f32_16x16x32_bf16 v[92:95], v[68:71], v[204:207], v[92:95]
	v_mfma_f32_16x16x32_bf16 v[88:91], v[76:79], v[204:207], v[88:91]


; #define PG8_MMA(ai, bj, At, Bt) do { __builtin_amdgcn_s_setprio(1); _Pragma("unroll") for (int m = 0; m < 4; ++m) _Pragma("unroll") for (int n = 0; n < 2; ++n) _Pragma("unroll") for (int k = 0; k < 2; ++k) \
;         acc[ai][bj][m][n] = __builtin_amdgcn_mfma_f32_16x16x32_bf16(Bt[n][k], At[m][k], acc[ai][bj][m][n], 0, 0, 0); __builtin_amdgcn_s_setprio(0); } while (0)
; #define PG8_WAIT_V(n) asm volatile("s_waitcnt vmcnt(" #n ")" ::: "memory")
; #define PG8_WAIT_L(n) asm volatile("s_waitcnt lgkmcnt(" #n ")" ::: "memory")
; #define PG8_BAR __builtin_amdgcn_s_barrier()
; #define PG8_SCHED __builtin_amdgcn_sched_barrier(0)
; template <class Epi, class Sched, bool ALIGN_EPI = false, bool SP2 = false>
; __device__ __forceinline__ void gemm_phase(PG8_LAS unsigned char* lds, const Gemm g, const Sched& S, const Epi& E) {
;     ...
;             PG8_WAIT_V(8); PG8_WAIT_L(0); PG8_BAR; PG8_MMA(0, 0, At, B0); PG8_MMA(0, 1, At, B1); PG8_BAR; PG8_SCHED;
	v_mfma_f32_16x16x32_bf16 v[132:135], v[144:147], v[176:179], v[132:135]
	v_mfma_f32_16x16x32_bf16 v[128:131], v[152:155], v[176:179], v[128:131]
	v_mfma_f32_16x16x32_bf16 v[116:119], v[144:147], v[184:187], v[116:119]
	v_mfma_f32_16x16x32_bf16 v[112:115], v[152:155], v[184:187], v[112:115]
	v_mfma_f32_16x16x32_bf16 v[100:103], v[144:147], v[192:195], v[100:103]
	v_mfma_f32_16x16x32_bf16 v[96:99], v[152:155], v[192:195], v[96:99]
	v_mfma_f32_16x16x32_bf16 v[84:87], v[144:147], v[200:203], v[84:87]
	v_mfma_f32_16x16x32_bf16 v[80:83], v[152:155], v[200:203], v[80:83]
	v_mfma_f32_16x16x32_bf16 v[132:135], v[148:151], v[180:183], v[132:135]
	v_mfma_f32_16x16x32_bf16 v[128:131], v[156:159], v[180:183], v[128:131]
	v_mfma_f32_16x16x32_bf16 v[116:119], v[148:151], v[188:191], v[116:119]
	v_mfma_f32_16x16x32_bf16 v[112:115], v[156:159], v[188:191], v[112:115]
	v_mfma_f32_16x16x32_bf16 v[100:103], v[148:151], v[196:199], v[100:103]
	v_mfma_f32_16x16x32_bf16 v[96:99], v[156:159], v[196:199], v[96:99]
	v_mfma_f32_16x16x32_bf16 v[84:87], v[148:151], v[204:207], v[84:87]
	v_mfma_f32_16x16x32_bf16 v[80:83], v[156:159], v[204:207], v[80:83]
	s_setprio 0
	s_barrier
	s_add_i32 s62, s82, s64

; #define PG8_STAGE(bufoff, gbase, voff) do { _Pragma("unroll") for (int _i = 0; _i < 2; ++_i) \
;         __builtin_amdgcn_global_load_lds((const unsigned*)((const char*)(gbase) + (voff)[_i]), (PG8_LAS unsigned*)(lds + (bufoff) + ldsw + _i * 8192), 16, 0, 0); } while (0)
; #define PG8_LDA(dst, b, h) do { _Pragma("unroll") for (int m = 0; m < 4; ++m) _Pragma("unroll") for (int k = 0; k < 2; ++k) dst[m][k] = *(const PG8_LAS bf16x8*)(lds + PG8_SA(b, h) + aoff + m * 2048 + k * 1024); } while (0)
; template <class Epi, class Sched, bool ALIGN_EPI = false, bool SP2 = false>
; __device__ __forceinline__ void gemm_phase(PG8_LAS unsigned char* lds, const Gemm g, const Sched& S, const Epi& E) {
;     ...
;             PG8_LDA(At, 1, 1); PG8_STAGE(PG8_SB(1, 0), b3, voffB); PG8_STAGE(PG8_SB(1, 1), b3 + hstep, voffB); PG8_STAGE(PG8_SA(1, 0), a3, voffA);
	s_mov_b32 m0, s62
	ds_read_b128 v[176:179], v215 offset:49152
	ds_read_b128 v[180:183], v215 offset:50176
	ds_read_b128 v[184:187], v215 offset:51200
	ds_read_b128 v[188:191], v215 offset:52224
	ds_read_b128 v[192:195], v215 offset:53248
	ds_read_b128 v[196:199], v215 offset:54272
	ds_read_b128 v[200:203], v215 offset:55296
	ds_read_b128 v[204:207], v215 offset:56320
	global_load_lds_dwordx4 v250, s[96:97]
	s_add_i32 m0, s62, 0x2000
	s_add_u32 s60, s60, 0x200080

; #define PG8_STAGE(bufoff, gbase, voff) do { _Pragma("unroll") for (int _i = 0; _i < 2; ++_i) \
;         __builtin_amdgcn_global_load_lds((const unsigned*)((const char*)(gbase) + (voff)[_i]), (PG8_LAS unsigned*)(lds + (bufoff) + ldsw + _i * 8192), 16, 0, 0); } while (0)
; #define PG8_LDA(dst, b, h) do { _Pragma("unroll") for (int m = 0; m < 4; ++m) _Pragma("unroll") for (int k = 0; k < 2; ++k) dst[m][k] = *(const PG8_LAS bf16x8*)(lds + PG8_SA(b, h) + aoff + m * 2048 + k * 1024); } while (0)
; template <class Epi, class Sched, bool ALIGN_EPI = false, bool SP2 = false>
; __device__ __forceinline__ void gemm_phase(PG8_LAS unsigned char* lds, const Gemm g, const Sched& S, const Epi& E) {
;     ...
;             PG8_LDA(At, 1, 1); PG8_STAGE(PG8_SB(1, 0), b3, voffB); PG8_STAGE(PG8_SB(1, 1), b3 + hstep, voffB); PG8_STAGE(PG8_SA(1, 0), a3, voffA);
	s_addc_u32 s61, s61, 0
	s_add_i32 s62, s83, s64
	global_load_lds_dwordx4 v251, s[96:97]

; #define PG8_STAGE(bufoff, gbase, voff) do { _Pragma("unroll") for (int _i = 0; _i < 2; ++_i) \
;         __builtin_amdgcn_global_load_lds((const unsigned*)((const char*)(gbase) + (voff)[_i]), (PG8_LAS unsigned*)(lds + (bufoff) + ldsw + _i * 8192), 16, 0, 0); } while (0)
; #define PG8_LDA(dst, b, h) do { _Pragma("unroll") for (int m = 0; m < 4; ++m) _Pragma("unroll") for (int k = 0; k < 2; ++k) dst[m][k] = *(const PG8_LAS bf16x8*)(lds + PG8_SA(b, h) + aoff + m * 2048 + k * 1024); } while (0)
; template <class Epi, class Sched, bool ALIGN_EPI = false, bool SP2 = false>
; __device__ __forceinline__ void gemm_phase(PG8_LAS unsigned char* lds, const Gemm g, const Sched& S, const Epi& E) {
;     ...
;             PG8_LDA(At, 1, 1); PG8_STAGE(PG8_SB(1, 0), b3, voffB); PG8_STAGE(PG8_SB(1, 1), b3 + hstep, voffB); PG8_STAGE(PG8_SA(1, 0), a3, voffA);
	s_mov_b32 m0, s62
	s_nop 0
	global_load_lds_dwordx4 v162, s[60:61]

; #define PG8_STAGE(bufoff, gbase, voff) do { _Pragma("unroll") for (int _i = 0; _i < 2; ++_i) \
;         __builtin_amdgcn_global_load_lds((const unsigned*)((const char*)(gbase) + (voff)[_i]), (PG8_LAS unsigned*)(lds + (bufoff) + ldsw + _i * 8192), 16, 0, 0); } while (0)
; #define PG8_LDA(dst, b, h) do { _Pragma("unroll") for (int m = 0; m < 4; ++m) _Pragma("unroll") for (int k = 0; k < 2; ++k) dst[m][k] = *(const PG8_LAS bf16x8*)(lds + PG8_SA(b, h) + aoff + m * 2048 + k * 1024); } while (0)
; template <class Epi, class Sched, bool ALIGN_EPI = false, bool SP2 = false>
; __device__ __forceinline__ void gemm_phase(PG8_LAS unsigned char* lds, const Gemm g, const Sched& S, const Epi& E) {
;     ...
;             PG8_LDA(At, 1, 1); PG8_STAGE(PG8_SB(1, 0), b3, voffB); PG8_STAGE(PG8_SB(1, 1), b3 + hstep, voffB); PG8_STAGE(PG8_SA(1, 0), a3, voffA);
	s_add_i32 m0, s62, 0x2000
	s_nop 0
	global_load_lds_dwordx4 v166, s[60:61]

; #define PG8_STAGE(bufoff, gbase, voff) do { _Pragma("unroll") for (int _i = 0; _i < 2; ++_i) \
;         __builtin_amdgcn_global_load_lds((const unsigned*)((const char*)(gbase) + (voff)[_i]), (PG8_LAS unsigned*)(lds + (bufoff) + ldsw + _i * 8192), 16, 0, 0); } while (0)
; #define PG8_LDA(dst, b, h) do { _Pragma("unroll") for (int m = 0; m < 4; ++m) _Pragma("unroll") for (int k = 0; k < 2; ++k) dst[m][k] = *(const PG8_LAS bf16x8*)(lds + PG8_SA(b, h) + aoff + m * 2048 + k * 1024); } while (0)
; template <class Epi, class Sched, bool ALIGN_EPI = false, bool SP2 = false>
; __device__ __forceinline__ void gemm_phase(PG8_LAS unsigned char* lds, const Gemm g, const Sched& S, const Epi& E) {
;     ...
;             PG8_LDA(At, 1, 1); PG8_STAGE(PG8_SB(1, 0), b3, voffB); PG8_STAGE(PG8_SB(1, 1), b3 + hstep, voffB); PG8_STAGE(PG8_SA(1, 0), a3, voffA);
	s_mov_b32 m0, s70
	s_nop 0
	global_load_lds_dwordx4 v252, s[98:99]

; #define PG8_STAGE(bufoff, gbase, voff) do { _Pragma("unroll") for (int _i = 0; _i < 2; ++_i) \
;         __builtin_amdgcn_global_load_lds((const unsigned*)((const char*)(gbase) + (voff)[_i]), (PG8_LAS unsigned*)(lds + (bufoff) + ldsw + _i * 8192), 16, 0, 0); } while (0)
; #define PG8_LDA(dst, b, h) do { _Pragma("unroll") for (int m = 0; m < 4; ++m) _Pragma("unroll") for (int k = 0; k < 2; ++k) dst[m][k] = *(const PG8_LAS bf16x8*)(lds + PG8_SA(b, h) + aoff + m * 2048 + k * 1024); } while (0)
; #define PG8_MMA(ai, bj, At, Bt) do { __builtin_amdgcn_s_setprio(1); _Pragma("unroll") for (int m = 0; m < 4; ++m) _Pragma("unroll") for (int n = 0; n < 2; ++n) _Pragma("unroll") for (int k = 0; k < 2; ++k) \
;         acc[ai][bj][m][n] = __builtin_amdgcn_mfma_f32_16x16x32_bf16(Bt[n][k], At[m][k], acc[ai][bj][m][n], 0, 0, 0); __builtin_amdgcn_s_setprio(0); } while (0)
; #define PG8_WAIT_V(n) asm volatile("s_waitcnt vmcnt(" #n ")" ::: "memory")
; #define PG8_WAIT_L(n) asm volatile("s_waitcnt lgkmcnt(" #n ")" ::: "memory")
; #define PG8_BAR __builtin_amdgcn_s_barrier()
; #define PG8_SCHED __builtin_amdgcn_sched_barrier(0)
; template <class Epi, class Sched, bool ALIGN_EPI = false, bool SP2 = false>
; __device__ __forceinline__ void gemm_phase(PG8_LAS unsigned char* lds, const Gemm g, const Sched& S, const Epi& E) {
;     ...
;             PG8_LDA(At, 1, 1); PG8_STAGE(PG8_SB(1, 0), b3, voffB); PG8_STAGE(PG8_SB(1, 1), b3 + hstep, voffB); PG8_STAGE(PG8_SA(1, 0), a3, voffA);
;             PG8_WAIT_V(8); PG8_WAIT_L(0); PG8_BAR; PG8_MMA(1, 0, At, B0); PG8_MMA(1, 1, At, B1); PG8_BAR; PG8_SCHED;
	s_mov_b32 m0, s71
	s_nop 0
	global_load_lds_dwordx4 v253, s[98:99]
	s_waitcnt vmcnt(8)
	s_waitcnt lgkmcnt(0)
	s_barrier
	s_setprio 1
	s_waitcnt lgkmcnt(0)
	v_mfma_f32_16x16x32_bf16 v[60:63], v[64:67], v[176:179], v[60:63]
	v_mfma_f32_16x16x32_bf16 v[56:59], v[72:75], v[176:179], v[56:59]
	v_mfma_f32_16x16x32_bf16 v[44:47], v[64:67], v[184:187], v[44:47]
	v_mfma_f32_16x16x32_bf16 v[40:43], v[72:75], v[184:187], v[40:43]
	v_mfma_f32_16x16x32_bf16 v[28:31], v[64:67], v[192:195], v[28:31]
	v_mfma_f32_16x16x32_bf16 v[24:27], v[72:75], v[192:195], v[24:27]
	v_mfma_f32_16x16x32_bf16 v[12:15], v[64:67], v[200:203], v[12:15]
	v_mfma_f32_16x16x32_bf16 v[8:11], v[72:75], v[200:203], v[8:11]
	v_mfma_f32_16x16x32_bf16 v[60:63], v[68:71], v[180:183], v[60:63]
	v_mfma_f32_16x16x32_bf16 v[56:59], v[76:79], v[180:183], v[56:59]
	v_mfma_f32_16x16x32_bf16 v[44:47], v[68:71], v[188:191], v[44:47]
	v_mfma_f32_16x16x32_bf16 v[40:43], v[76:79], v[188:191], v[40:43]
	v_mfma_f32_16x16x32_bf16 v[28:31], v[68:71], v[196:199], v[28:31]
	v_mfma_f32_16x16x32_bf16 v[24:27], v[76:79], v[196:199], v[24:27]
	v_mfma_f32_16x16x32_bf16 v[12:15], v[68:71], v[204:207], v[12:15]
	v_mfma_f32_16x16x32_bf16 v[8:11], v[76:79], v[204:207], v[8:11]


; #define PG8_MMA(ai, bj, At, Bt) do { __builtin_amdgcn_s_setprio(1); _Pragma("unroll") for (int m = 0; m < 4; ++m) _Pragma("unroll") for (int n = 0; n < 2; ++n) _Pragma("unroll") for (int k = 0; k < 2; ++k) \
;         acc[ai][bj][m][n] = __builtin_amdgcn_mfma_f32_16x16x32_bf16(Bt[n][k], At[m][k], acc[ai][bj][m][n], 0, 0, 0); __builtin_amdgcn_s_setprio(0); } while (0)
; #define PG8_WAIT_V(n) asm volatile("s_waitcnt vmcnt(" #n ")" ::: "memory")
; #define PG8_WAIT_L(n) asm volatile("s_waitcnt lgkmcnt(" #n ")" ::: "memory")
; #define PG8_BAR __builtin_amdgcn_s_barrier()
; #define PG8_SCHED __builtin_amdgcn_sched_barrier(0)
; template <class Epi, class Sched, bool ALIGN_EPI = false, bool SP2 = false>
; __device__ __forceinline__ void gemm_phase(PG8_LAS unsigned char* lds, const Gemm g, const Sched& S, const Epi& E) {
;     ...
;         for (int t = 0; t < nt; t += 2) {
;     ...
;             PG8_WAIT_V(8); PG8_WAIT_L(0); PG8_BAR; PG8_MMA(1, 0, At, B0); PG8_MMA(1, 1, At, B1); PG8_BAR; PG8_SCHED;
;     ...
;         if constexpr (ALIGN_EPI) { if (wr == 0) PG8_BAR; }
	v_mfma_f32_16x16x32_bf16 v[52:55], v[144:147], v[176:179], v[52:55]
	v_mfma_f32_16x16x32_bf16 v[48:51], v[152:155], v[176:179], v[48:51]
	v_mfma_f32_16x16x32_bf16 v[36:39], v[144:147], v[184:187], v[36:39]
	v_mfma_f32_16x16x32_bf16 v[32:35], v[152:155], v[184:187], v[32:35]
	v_mfma_f32_16x16x32_bf16 v[20:23], v[144:147], v[192:195], v[20:23]
	v_mfma_f32_16x16x32_bf16 v[16:19], v[152:155], v[192:195], v[16:19]
	v_mfma_f32_16x16x32_bf16 v[4:7], v[144:147], v[200:203], v[4:7]
	v_mfma_f32_16x16x32_bf16 v[0:3], v[152:155], v[200:203], v[0:3]
	v_mfma_f32_16x16x32_bf16 v[52:55], v[148:151], v[180:183], v[52:55]
	v_mfma_f32_16x16x32_bf16 v[48:51], v[156:159], v[180:183], v[48:51]
	v_mfma_f32_16x16x32_bf16 v[36:39], v[148:151], v[188:191], v[36:39]
	v_mfma_f32_16x16x32_bf16 v[32:35], v[156:159], v[188:191], v[32:35]
	v_mfma_f32_16x16x32_bf16 v[20:23], v[148:151], v[196:199], v[20:23]
	v_mfma_f32_16x16x32_bf16 v[16:19], v[156:159], v[196:199], v[16:19]
	v_mfma_f32_16x16x32_bf16 v[4:7], v[148:151], v[204:207], v[4:7]
	v_mfma_f32_16x16x32_bf16 v[0:3], v[156:159], v[204:207], v[0:3]
	s_setprio 0
	s_barrier
	s_add_i32 s81, s81, 2
	s_add_u32 s58, s58, 0x100
	s_addc_u32 s59, s59, 0
	s_add_u32 s79, s79, 0x100
	s_addc_u32 s80, s80, 0
	s_cmpk_gt_u32 s81, 0x7d
	s_cbranch_scc0 .LBB0_509
	s_and_b64 vcc, exec, s[42:43]
	s_cbranch_vccz .LBB0_512
	s_barrier

; #define PG8_STAGE(bufoff, gbase, voff) do { _Pragma("unroll") for (int _i = 0; _i < 2; ++_i) \
;         __builtin_amdgcn_global_load_lds((const unsigned*)((const char*)(gbase) + (voff)[_i]), (PG8_LAS unsigned*)(lds + (bufoff) + ldsw + _i * 8192), 16, 0, 0); } while (0)
; #define PG8_LDA(dst, b, h) do { _Pragma("unroll") for (int m = 0; m < 4; ++m) _Pragma("unroll") for (int k = 0; k < 2; ++k) dst[m][k] = *(const PG8_LAS bf16x8*)(lds + PG8_SA(b, h) + aoff + m * 2048 + k * 1024); } while (0)
; #define PG8_LDB(dst, b, h) do { _Pragma("unroll") for (int n = 0; n < 2; ++n) _Pragma("unroll") for (int k = 0; k < 2; ++k) dst[n][k] = *(const PG8_LAS bf16x8*)(lds + PG8_SB(b, h) + boff + n * 2048 + k * 1024); } while (0)
; #define PG8_SCHED __builtin_amdgcn_sched_barrier(0)
; template <class Epi, class Sched, bool ALIGN_EPI = false, bool SP2 = false>
; __device__ __forceinline__ void gemm_phase(PG8_LAS unsigned char* lds, const Gemm g, const Sched& S, const Epi& E) {
;     ...
;         const bool has_next = S.next(ui + 1, nxt);
;         const char* nA = has_next ? (const char*)g.A + (size_t)nxt.pm * tstep : cA; const char* nB = has_next ? (const char*)g.Bt + (size_t)nxt.pn * tstep : cB;
;         for (int t = 0; t < nt; t += 2) {
;             const bool last = (t == nt - 2);
;             const char* a1 = cA + (size_t)(t + 1) * kstep;
;             const char* a2 = last ? nA : cA + (size_t)(t + 2) * kstep; const char* b2 = last ? nB : cB + (size_t)(t + 2) * kstep;
;             const char* a3 = a2 + kstep; const char* b3 = b2 + kstep;
;             if (last && has_next) S.a_ready(nxt);
;             if constexpr (SP2) {
;             PG8_LDB(B0, 0, 0); PG8_LDB(B1, 0, 1); PG8_SCHED; PG8_LDA(At, 0, 0); PG8_STAGE(PG8_SA(1, 1), a1 + hstep, voffA);
;     ...
;         for (int a = 0; a < 2; ++a)
; #pragma unroll
;             for (int b = 0; b < 2; ++b)
; #pragma unroll
;                 for (int m = 0; m < 4; ++m)
; #pragma unroll
;                     for (int n = 0; n < 2; ++n) acc[a][b][m][n] = (f32x4){0.f, 0.f, 0.f, 0.f};
.LBB0_678:
	s_ashr_i32 s49, s48, 31
	s_lshl_b64 s[50:51], s[48:49], 20
	s_add_u32 s50, s24, s50
	s_addc_u32 s51, s25, s51
	s_and_b64 s[52:53], s[4:5], exec
	s_cselect_b32 s49, s51, s11
	s_cselect_b32 s74, s50, s10
	s_ashr_i32 s47, s46, 31
	s_lshl_b64 s[52:53], s[46:47], 20
	s_add_u32 s52, s45, s52
	s_addc_u32 s53, s56, s53
	s_and_b64 s[54:55], s[4:5], exec
	s_cselect_b32 s47, s53, s13
	s_cselect_b32 s75, s52, s12
	s_add_u32 s10, s10, 0x80080
	s_addc_u32 s11, s11, 0
	s_add_u32 s76, s12, 0x100
	v_mov_b32_e32 v0, 0
	s_addc_u32 s77, s13, 0
	s_mov_b32 s78, -2
	v_mov_b32_e32 v1, v0
	v_mov_b32_e32 v2, v0
	v_mov_b32_e32 v3, v0
	v_mov_b32_e32 v4, v0
	v_mov_b32_e32 v5, v0
	v_mov_b32_e32 v6, v0
	v_mov_b32_e32 v7, v0
	v_mov_b32_e32 v12, v0
	v_mov_b32_e32 v13, v0
	v_mov_b32_e32 v14, v0
	v_mov_b32_e32 v15, v0
	v_mov_b32_e32 v16, v0
	v_mov_b32_e32 v17, v0
	v_mov_b32_e32 v18, v0
	v_mov_b32_e32 v19, v0
	v_mov_b32_e32 v28, v0
	v_mov_b32_e32 v29, v0
	v_mov_b32_e32 v30, v0
	v_mov_b32_e32 v31, v0
	v_mov_b32_e32 v32, v0
	v_mov_b32_e32 v33, v0
	v_mov_b32_e32 v34, v0
	v_mov_b32_e32 v35, v0
	v_mov_b32_e32 v44, v0
	v_mov_b32_e32 v45, v0
	v_mov_b32_e32 v46, v0
	v_mov_b32_e32 v47, v0
	v_mov_b32_e32 v48, v0
	v_mov_b32_e32 v49, v0
	v_mov_b32_e32 v50, v0
	v_mov_b32_e32 v51, v0
	v_mov_b32_e32 v8, v0
	v_mov_b32_e32 v9, v0
	v_mov_b32_e32 v10, v0
	v_mov_b32_e32 v11, v0
	v_mov_b32_e32 v20, v0
	v_mov_b32_e32 v21, v0
	v_mov_b32_e32 v22, v0
	v_mov_b32_e32 v23, v0
	v_mov_b32_e32 v24, v0
	v_mov_b32_e32 v25, v0
	v_mov_b32_e32 v26, v0
	v_mov_b32_e32 v27, v0
	v_mov_b32_e32 v36, v0
	v_mov_b32_e32 v37, v0
	v_mov_b32_e32 v38, v0
	v_mov_b32_e32 v39, v0
	v_mov_b32_e32 v40, v0
	v_mov_b32_e32 v41, v0
	v_mov_b32_e32 v42, v0
	v_mov_b32_e32 v43, v0
	v_mov_b32_e32 v52, v0
	v_mov_b32_e32 v53, v0
	v_mov_b32_e32 v54, v0
	v_mov_b32_e32 v55, v0
	v_mov_b32_e32 v56, v0
	v_mov_b32_e32 v57, v0
	v_mov_b32_e32 v58, v0
	v_mov_b32_e32 v59, v0
	v_mov_b32_e32 v60, v0
	v_mov_b32_e32 v61, v0
	v_mov_b32_e32 v62, v0
	v_mov_b32_e32 v63, v0
	v_mov_b32_e32 v64, v0
	v_mov_b32_e32 v65, v0
	v_mov_b32_e32 v66, v0
	v_mov_b32_e32 v67, v0
	v_mov_b32_e32 v68, v0
	v_mov_b32_e32 v69, v0
	v_mov_b32_e32 v70, v0
	v_mov_b32_e32 v71, v0
	v_mov_b32_e32 v76, v0
	v_mov_b32_e32 v77, v0
	v_mov_b32_e32 v78, v0
	v_mov_b32_e32 v79, v0
	v_mov_b32_e32 v80, v0
	v_mov_b32_e32 v81, v0
	v_mov_b32_e32 v82, v0
	v_mov_b32_e32 v83, v0
	v_mov_b32_e32 v92, v0
	v_mov_b32_e32 v93, v0
	v_mov_b32_e32 v94, v0
	v_mov_b32_e32 v95, v0
	v_mov_b32_e32 v96, v0
	v_mov_b32_e32 v97, v0
	v_mov_b32_e32 v98, v0
	v_mov_b32_e32 v99, v0
	v_mov_b32_e32 v108, v0
	v_mov_b32_e32 v109, v0
	v_mov_b32_e32 v110, v0
	v_mov_b32_e32 v111, v0
	v_mov_b32_e32 v116, v0
	v_mov_b32_e32 v117, v0
	v_mov_b32_e32 v118, v0
	v_mov_b32_e32 v119, v0
	v_mov_b32_e32 v72, v0
	v_mov_b32_e32 v73, v0
	v_mov_b32_e32 v74, v0
	v_mov_b32_e32 v75, v0
	v_mov_b32_e32 v84, v0
	v_mov_b32_e32 v85, v0
	v_mov_b32_e32 v86, v0
	v_mov_b32_e32 v87, v0
	v_mov_b32_e32 v88, v0
	v_mov_b32_e32 v89, v0
	v_mov_b32_e32 v90, v0
	v_mov_b32_e32 v91, v0
	v_mov_b32_e32 v100, v0
	v_mov_b32_e32 v101, v0
	v_mov_b32_e32 v102, v0
	v_mov_b32_e32 v103, v0
	v_mov_b32_e32 v104, v0
	v_mov_b32_e32 v105, v0
	v_mov_b32_e32 v106, v0
	v_mov_b32_e32 v107, v0
	v_mov_b32_e32 v112, v0
	v_mov_b32_e32 v113, v0
	v_mov_b32_e32 v114, v0
	v_mov_b32_e32 v115, v0
	v_mov_b32_e32 v120, v0
	v_mov_b32_e32 v121, v0
	v_mov_b32_e32 v122, v0
	v_mov_b32_e32 v123, v0
	v_mov_b32_e32 v124, v0
	v_mov_b32_e32 v125, v0
	v_mov_b32_e32 v126, v0
	v_mov_b32_e32 v127, v0
	v_add_u32_e32 v255, 0x1c000, v197
	v_add_u32_e32 v254, 0x18000, v197
	v_add_u32_e32 v253, 0x80, v162
	v_add_u32_e32 v252, 0x80, v166
	v_add_u32_e32 v251, 0x80, v160
	v_add_u32_e32 v250, 0x80, v164
.LBB0_679:
	ds_read_b128 v[128:131], v203
	ds_read_b128 v[132:135], v203 offset:1024
	ds_read_b128 v[136:139], v203 offset:2048
	ds_read_b128 v[140:143], v203 offset:3072
	ds_read_b128 v[144:147], v205
	ds_read_b128 v[148:151], v205 offset:1024
	ds_read_b128 v[152:155], v205 offset:2048
	ds_read_b128 v[156:159], v205 offset:3072
	s_add_u32 s12, s10, 0xfff80080
	s_addc_u32 s13, s11, -1
	s_cmp_eq_u32 s78, 28
	s_cselect_b32 s55, s49, s13
	s_cselect_b32 s54, s74, s12
	s_cselect_b32 s13, s47, s77
	s_cselect_b32 s12, s75, s76

; #define PG8_STAGE(bufoff, gbase, voff) do { _Pragma("unroll") for (int _i = 0; _i < 2; ++_i) \
;         __builtin_amdgcn_global_load_lds((const unsigned*)((const char*)(gbase) + (voff)[_i]), (PG8_LAS unsigned*)(lds + (bufoff) + ldsw + _i * 8192), 16, 0, 0); } while (0)
; #define PG8_LDA(dst, b, h) do { _Pragma("unroll") for (int m = 0; m < 4; ++m) _Pragma("unroll") for (int k = 0; k < 2; ++k) dst[m][k] = *(const PG8_LAS bf16x8*)(lds + PG8_SA(b, h) + aoff + m * 2048 + k * 1024); } while (0)
; #define PG8_LDB(dst, b, h) do { _Pragma("unroll") for (int n = 0; n < 2; ++n) _Pragma("unroll") for (int k = 0; k < 2; ++k) dst[n][k] = *(const PG8_LAS bf16x8*)(lds + PG8_SB(b, h) + boff + n * 2048 + k * 1024); } while (0)
; #define PG8_SCHED __builtin_amdgcn_sched_barrier(0)
; template <class Epi, class Sched, bool ALIGN_EPI = false, bool SP2 = false>
; __device__ __forceinline__ void gemm_phase(PG8_LAS unsigned char* lds, const Gemm g, const Sched& S, const Epi& E) {
;     ...
;             PG8_LDB(B0, 0, 0); PG8_LDB(B1, 0, 1); PG8_SCHED; PG8_LDA(At, 0, 0); PG8_STAGE(PG8_SA(1, 1), a1 + hstep, voffA);
	s_add_i32 m0, s60, 0xc000
	ds_read_b128 v[176:179], v207
	ds_read_b128 v[180:183], v207 offset:1024
	ds_read_b128 v[184:187], v207 offset:2048
	ds_read_b128 v[192:195], v207 offset:3072
	ds_read_b128 v[210:213], v207 offset:4096
	ds_read_b128 v[214:217], v207 offset:5120
	ds_read_b128 v[218:221], v207 offset:6144
	ds_read_b128 v[222:225], v207 offset:7168
	global_load_lds_dwordx4 v168, s[10:11]

; #define PG8_STAGE(bufoff, gbase, voff) do { _Pragma("unroll") for (int _i = 0; _i < 2; ++_i) \
;         __builtin_amdgcn_global_load_lds((const unsigned*)((const char*)(gbase) + (voff)[_i]), (PG8_LAS unsigned*)(lds + (bufoff) + ldsw + _i * 8192), 16, 0, 0); } while (0)
; #define PG8_LDA(dst, b, h) do { _Pragma("unroll") for (int m = 0; m < 4; ++m) _Pragma("unroll") for (int k = 0; k < 2; ++k) dst[m][k] = *(const PG8_LAS bf16x8*)(lds + PG8_SA(b, h) + aoff + m * 2048 + k * 1024); } while (0)
; #define PG8_LDB(dst, b, h) do { _Pragma("unroll") for (int n = 0; n < 2; ++n) _Pragma("unroll") for (int k = 0; k < 2; ++k) dst[n][k] = *(const PG8_LAS bf16x8*)(lds + PG8_SB(b, h) + boff + n * 2048 + k * 1024); } while (0)
; #define PG8_MMA(ai, bj, At, Bt) do { __builtin_amdgcn_s_setprio(1); _Pragma("unroll") for (int m = 0; m < 4; ++m) _Pragma("unroll") for (int n = 0; n < 2; ++n) _Pragma("unroll") for (int k = 0; k < 2; ++k) \
;         acc[ai][bj][m][n] = __builtin_amdgcn_mfma_f32_16x16x32_bf16(Bt[n][k], At[m][k], acc[ai][bj][m][n], 0, 0, 0); __builtin_amdgcn_s_setprio(0); } while (0)
; #define PG8_WAIT_V(n) asm volatile("s_waitcnt vmcnt(" #n ")" ::: "memory")
; #define PG8_WAIT_L(n) asm volatile("s_waitcnt lgkmcnt(" #n ")" ::: "memory")
; #define PG8_BAR __builtin_amdgcn_s_barrier()
; #define PG8_SCHED __builtin_amdgcn_sched_barrier(0)
; template <class Epi, class Sched, bool ALIGN_EPI = false, bool SP2 = false>
; __device__ __forceinline__ void gemm_phase(PG8_LAS unsigned char* lds, const Gemm g, const Sched& S, const Epi& E) {
;     ...
;             PG8_LDB(B0, 0, 0); PG8_LDB(B1, 0, 1); PG8_SCHED; PG8_LDA(At, 0, 0); PG8_STAGE(PG8_SA(1, 1), a1 + hstep, voffA);
;             PG8_WAIT_V(8); PG8_WAIT_L(0); PG8_BAR; PG8_MMA(0, 0, At, B0); PG8_MMA(0, 1, At, B1); PG8_BAR; PG8_SCHED;
	s_add_i32 m0, s60, 0xe000
	s_nop 0
	global_load_lds_dwordx4 v170, s[10:11]
	s_waitcnt vmcnt(8)
	s_waitcnt lgkmcnt(0)
	s_barrier
	s_setprio 1
	s_waitcnt lgkmcnt(0)
	v_mfma_f32_16x16x32_bf16 v[124:127], v[128:131], v[176:179], v[124:127]
	v_mfma_f32_16x16x32_bf16 v[120:123], v[136:139], v[176:179], v[120:123]
	v_mfma_f32_16x16x32_bf16 v[112:115], v[128:131], v[184:187], v[112:115]
	v_mfma_f32_16x16x32_bf16 v[104:107], v[136:139], v[184:187], v[104:107]
	v_mfma_f32_16x16x32_bf16 v[100:103], v[128:131], v[210:213], v[100:103]
	v_mfma_f32_16x16x32_bf16 v[88:91], v[136:139], v[210:213], v[88:91]
	v_mfma_f32_16x16x32_bf16 v[84:87], v[128:131], v[218:221], v[84:87]
	v_mfma_f32_16x16x32_bf16 v[72:75], v[136:139], v[218:221], v[72:75]
	v_mfma_f32_16x16x32_bf16 v[124:127], v[132:135], v[180:183], v[124:127]
	v_mfma_f32_16x16x32_bf16 v[120:123], v[140:143], v[180:183], v[120:123]
	v_mfma_f32_16x16x32_bf16 v[112:115], v[132:135], v[192:195], v[112:115]
	v_mfma_f32_16x16x32_bf16 v[104:107], v[140:143], v[192:195], v[104:107]
	v_mfma_f32_16x16x32_bf16 v[100:103], v[132:135], v[214:217], v[100:103]
	v_mfma_f32_16x16x32_bf16 v[88:91], v[140:143], v[214:217], v[88:91]
	v_mfma_f32_16x16x32_bf16 v[84:87], v[132:135], v[222:225], v[84:87]
	v_mfma_f32_16x16x32_bf16 v[72:75], v[140:143], v[222:225], v[72:75]


; #define PG8_MMA(ai, bj, At, Bt) do { __builtin_amdgcn_s_setprio(1); _Pragma("unroll") for (int m = 0; m < 4; ++m) _Pragma("unroll") for (int n = 0; n < 2; ++n) _Pragma("unroll") for (int k = 0; k < 2; ++k) \
;         acc[ai][bj][m][n] = __builtin_amdgcn_mfma_f32_16x16x32_bf16(Bt[n][k], At[m][k], acc[ai][bj][m][n], 0, 0, 0); __builtin_amdgcn_s_setprio(0); } while (0)
; #define PG8_WAIT_V(n) asm volatile("s_waitcnt vmcnt(" #n ")" ::: "memory")
; #define PG8_WAIT_L(n) asm volatile("s_waitcnt lgkmcnt(" #n ")" ::: "memory")
; #define PG8_BAR __builtin_amdgcn_s_barrier()
; #define PG8_SCHED __builtin_amdgcn_sched_barrier(0)
; template <class Epi, class Sched, bool ALIGN_EPI = false, bool SP2 = false>
; __device__ __forceinline__ void gemm_phase(PG8_LAS unsigned char* lds, const Gemm g, const Sched& S, const Epi& E) {
;     ...
;             PG8_WAIT_V(8); PG8_WAIT_L(0); PG8_BAR; PG8_MMA(0, 0, At, B0); PG8_MMA(0, 1, At, B1); PG8_BAR; PG8_SCHED;
	v_mfma_f32_16x16x32_bf16 v[116:119], v[144:147], v[176:179], v[116:119]
	v_mfma_f32_16x16x32_bf16 v[108:111], v[152:155], v[176:179], v[108:111]
	v_mfma_f32_16x16x32_bf16 v[96:99], v[144:147], v[184:187], v[96:99]
	v_mfma_f32_16x16x32_bf16 v[92:95], v[152:155], v[184:187], v[92:95]
	v_mfma_f32_16x16x32_bf16 v[80:83], v[144:147], v[210:213], v[80:83]
	v_mfma_f32_16x16x32_bf16 v[76:79], v[152:155], v[210:213], v[76:79]
	v_mfma_f32_16x16x32_bf16 v[68:71], v[144:147], v[218:221], v[68:71]
	v_mfma_f32_16x16x32_bf16 v[64:67], v[152:155], v[218:221], v[64:67]
	v_mfma_f32_16x16x32_bf16 v[116:119], v[148:151], v[180:183], v[116:119]
	v_mfma_f32_16x16x32_bf16 v[108:111], v[156:159], v[180:183], v[108:111]
	v_mfma_f32_16x16x32_bf16 v[96:99], v[148:151], v[192:195], v[96:99]
	v_mfma_f32_16x16x32_bf16 v[92:95], v[156:159], v[192:195], v[92:95]
	v_mfma_f32_16x16x32_bf16 v[80:83], v[148:151], v[214:217], v[80:83]
	v_mfma_f32_16x16x32_bf16 v[76:79], v[156:159], v[214:217], v[76:79]
	v_mfma_f32_16x16x32_bf16 v[68:71], v[148:151], v[222:225], v[68:71]
	v_mfma_f32_16x16x32_bf16 v[64:67], v[156:159], v[222:225], v[64:67]
	s_setprio 0
	s_barrier
	s_add_i32 s79, s70, s57
	s_mov_b64 s[96:97], s[12:13]

; #define PG8_STAGE(bufoff, gbase, voff) do { _Pragma("unroll") for (int _i = 0; _i < 2; ++_i) \
;         __builtin_amdgcn_global_load_lds((const unsigned*)((const char*)(gbase) + (voff)[_i]), (PG8_LAS unsigned*)(lds + (bufoff) + ldsw + _i * 8192), 16, 0, 0); } while (0)
; #define PG8_LDA(dst, b, h) do { _Pragma("unroll") for (int m = 0; m < 4; ++m) _Pragma("unroll") for (int k = 0; k < 2; ++k) dst[m][k] = *(const PG8_LAS bf16x8*)(lds + PG8_SA(b, h) + aoff + m * 2048 + k * 1024); } while (0)
; template <class Epi, class Sched, bool ALIGN_EPI = false, bool SP2 = false>
; __device__ __forceinline__ void gemm_phase(PG8_LAS unsigned char* lds, const Gemm g, const Sched& S, const Epi& E) {
;     ...
;             PG8_LDA(At, 0, 1); PG8_STAGE(PG8_SB(0, 0), b2, voffB); PG8_STAGE(PG8_SB(0, 1), b2 + hstep, voffB); PG8_STAGE(PG8_SA(0, 0), a2, voffA);
	s_mov_b32 m0, s79
	ds_read_b128 v[176:179], v207 offset:16384
	ds_read_b128 v[180:183], v207 offset:17408
	ds_read_b128 v[184:187], v207 offset:18432
	ds_read_b128 v[192:195], v207 offset:19456
	ds_read_b128 v[210:213], v207 offset:20480
	ds_read_b128 v[214:217], v207 offset:21504
	ds_read_b128 v[218:221], v207 offset:22528
	ds_read_b128 v[222:225], v207 offset:23552
	global_load_lds_dwordx4 v164, s[12:13]
	s_add_i32 m0, s79, 0x2000
	s_add_u32 s80, s12, 0x80000

; #define PG8_STAGE(bufoff, gbase, voff) do { _Pragma("unroll") for (int _i = 0; _i < 2; ++_i) \
;         __builtin_amdgcn_global_load_lds((const unsigned*)((const char*)(gbase) + (voff)[_i]), (PG8_LAS unsigned*)(lds + (bufoff) + ldsw + _i * 8192), 16, 0, 0); } while (0)
; #define PG8_LDA(dst, b, h) do { _Pragma("unroll") for (int m = 0; m < 4; ++m) _Pragma("unroll") for (int k = 0; k < 2; ++k) dst[m][k] = *(const PG8_LAS bf16x8*)(lds + PG8_SA(b, h) + aoff + m * 2048 + k * 1024); } while (0)
; template <class Epi, class Sched, bool ALIGN_EPI = false, bool SP2 = false>
; __device__ __forceinline__ void gemm_phase(PG8_LAS unsigned char* lds, const Gemm g, const Sched& S, const Epi& E) {
;     ...
;             PG8_LDA(At, 0, 1); PG8_STAGE(PG8_SB(0, 0), b2, voffB); PG8_STAGE(PG8_SB(0, 1), b2 + hstep, voffB); PG8_STAGE(PG8_SA(0, 0), a2, voffA);
	s_addc_u32 s81, s13, 0
	s_add_i32 s79, s71, s57
	global_load_lds_dwordx4 v160, s[12:13]

; #define PG8_STAGE(bufoff, gbase, voff) do { _Pragma("unroll") for (int _i = 0; _i < 2; ++_i) \
;         __builtin_amdgcn_global_load_lds((const unsigned*)((const char*)(gbase) + (voff)[_i]), (PG8_LAS unsigned*)(lds + (bufoff) + ldsw + _i * 8192), 16, 0, 0); } while (0)
; #define PG8_LDA(dst, b, h) do { _Pragma("unroll") for (int m = 0; m < 4; ++m) _Pragma("unroll") for (int k = 0; k < 2; ++k) dst[m][k] = *(const PG8_LAS bf16x8*)(lds + PG8_SA(b, h) + aoff + m * 2048 + k * 1024); } while (0)
; template <class Epi, class Sched, bool ALIGN_EPI = false, bool SP2 = false>
; __device__ __forceinline__ void gemm_phase(PG8_LAS unsigned char* lds, const Gemm g, const Sched& S, const Epi& E) {
;     ...
;             PG8_LDA(At, 0, 1); PG8_STAGE(PG8_SB(0, 0), b2, voffB); PG8_STAGE(PG8_SB(0, 1), b2 + hstep, voffB); PG8_STAGE(PG8_SA(0, 0), a2, voffA);
	s_mov_b32 m0, s79
	s_nop 0
	global_load_lds_dwordx4 v164, s[80:81]

; #define PG8_STAGE(bufoff, gbase, voff) do { _Pragma("unroll") for (int _i = 0; _i < 2; ++_i) \
;         __builtin_amdgcn_global_load_lds((const unsigned*)((const char*)(gbase) + (voff)[_i]), (PG8_LAS unsigned*)(lds + (bufoff) + ldsw + _i * 8192), 16, 0, 0); } while (0)
; #define PG8_LDA(dst, b, h) do { _Pragma("unroll") for (int m = 0; m < 4; ++m) _Pragma("unroll") for (int k = 0; k < 2; ++k) dst[m][k] = *(const PG8_LAS bf16x8*)(lds + PG8_SA(b, h) + aoff + m * 2048 + k * 1024); } while (0)
; template <class Epi, class Sched, bool ALIGN_EPI = false, bool SP2 = false>
; __device__ __forceinline__ void gemm_phase(PG8_LAS unsigned char* lds, const Gemm g, const Sched& S, const Epi& E) {
;     ...
;             PG8_LDA(At, 0, 1); PG8_STAGE(PG8_SB(0, 0), b2, voffB); PG8_STAGE(PG8_SB(0, 1), b2 + hstep, voffB); PG8_STAGE(PG8_SA(0, 0), a2, voffA);
	s_add_i32 m0, s79, 0x2000
	s_nop 0
	global_load_lds_dwordx4 v160, s[80:81]
	s_mov_b64 s[98:99], s[54:55]

; #define PG8_STAGE(bufoff, gbase, voff) do { _Pragma("unroll") for (int _i = 0; _i < 2; ++_i) \
;         __builtin_amdgcn_global_load_lds((const unsigned*)((const char*)(gbase) + (voff)[_i]), (PG8_LAS unsigned*)(lds + (bufoff) + ldsw + _i * 8192), 16, 0, 0); } while (0)
; #define PG8_LDA(dst, b, h) do { _Pragma("unroll") for (int m = 0; m < 4; ++m) _Pragma("unroll") for (int k = 0; k < 2; ++k) dst[m][k] = *(const PG8_LAS bf16x8*)(lds + PG8_SA(b, h) + aoff + m * 2048 + k * 1024); } while (0)
; #define PG8_MMA(ai, bj, At, Bt) do { __builtin_amdgcn_s_setprio(1); _Pragma("unroll") for (int m = 0; m < 4; ++m) _Pragma("unroll") for (int n = 0; n < 2; ++n) _Pragma("unroll") for (int k = 0; k < 2; ++k) \
;         acc[ai][bj][m][n] = __builtin_amdgcn_mfma_f32_16x16x32_bf16(Bt[n][k], At[m][k], acc[ai][bj][m][n], 0, 0, 0); __builtin_amdgcn_s_setprio(0); } while (0)
; #define PG8_WAIT_V(n) asm volatile("s_waitcnt vmcnt(" #n ")" ::: "memory")
; #define PG8_WAIT_L(n) asm volatile("s_waitcnt lgkmcnt(" #n ")" ::: "memory")
; #define PG8_BAR __builtin_amdgcn_s_barrier()
; #define PG8_SCHED __builtin_amdgcn_sched_barrier(0)
; template <class Epi, class Sched, bool ALIGN_EPI = false, bool SP2 = false>
; __device__ __forceinline__ void gemm_phase(PG8_LAS unsigned char* lds, const Gemm g, const Sched& S, const Epi& E) {
;     ...
;             PG8_LDA(At, 0, 1); PG8_STAGE(PG8_SB(0, 0), b2, voffB); PG8_STAGE(PG8_SB(0, 1), b2 + hstep, voffB); PG8_STAGE(PG8_SA(0, 0), a2, voffA);
;             PG8_WAIT_V(8); PG8_WAIT_L(0); PG8_BAR; PG8_MMA(1, 0, At, B0); PG8_MMA(1, 1, At, B1); PG8_BAR; PG8_SCHED;
	s_mov_b32 m0, s60
	s_nop 0
	global_load_lds_dwordx4 v166, s[54:55]
	s_mov_b32 m0, s61
	s_nop 0
	global_load_lds_dwordx4 v162, s[54:55]
	s_waitcnt vmcnt(8)
	s_waitcnt lgkmcnt(0)
	s_barrier
	s_setprio 1
	s_waitcnt lgkmcnt(0)
	v_mfma_f32_16x16x32_bf16 v[60:63], v[128:131], v[176:179], v[60:63]
	v_mfma_f32_16x16x32_bf16 v[56:59], v[136:139], v[176:179], v[56:59]
	v_mfma_f32_16x16x32_bf16 v[52:55], v[128:131], v[184:187], v[52:55]
	v_mfma_f32_16x16x32_bf16 v[40:43], v[136:139], v[184:187], v[40:43]
	v_mfma_f32_16x16x32_bf16 v[36:39], v[128:131], v[210:213], v[36:39]
	v_mfma_f32_16x16x32_bf16 v[24:27], v[136:139], v[210:213], v[24:27]
	v_mfma_f32_16x16x32_bf16 v[20:23], v[128:131], v[218:221], v[20:23]
	v_mfma_f32_16x16x32_bf16 v[8:11], v[136:139], v[218:221], v[8:11]
	v_mfma_f32_16x16x32_bf16 v[60:63], v[132:135], v[180:183], v[60:63]
	v_mfma_f32_16x16x32_bf16 v[56:59], v[140:143], v[180:183], v[56:59]
	v_mfma_f32_16x16x32_bf16 v[52:55], v[132:135], v[192:195], v[52:55]
	v_mfma_f32_16x16x32_bf16 v[40:43], v[140:143], v[192:195], v[40:43]
	v_mfma_f32_16x16x32_bf16 v[36:39], v[132:135], v[214:217], v[36:39]
	v_mfma_f32_16x16x32_bf16 v[24:27], v[140:143], v[214:217], v[24:27]
	v_mfma_f32_16x16x32_bf16 v[20:23], v[132:135], v[222:225], v[20:23]
	v_mfma_f32_16x16x32_bf16 v[8:11], v[140:143], v[222:225], v[8:11]


; #define PG8_STAGE(bufoff, gbase, voff) do { _Pragma("unroll") for (int _i = 0; _i < 2; ++_i) \
;         __builtin_amdgcn_global_load_lds((const unsigned*)((const char*)(gbase) + (voff)[_i]), (PG8_LAS unsigned*)(lds + (bufoff) + ldsw + _i * 8192), 16, 0, 0); } while (0)
; #define PG8_LDA(dst, b, h) do { _Pragma("unroll") for (int m = 0; m < 4; ++m) _Pragma("unroll") for (int k = 0; k < 2; ++k) dst[m][k] = *(const PG8_LAS bf16x8*)(lds + PG8_SA(b, h) + aoff + m * 2048 + k * 1024); } while (0)
; #define PG8_LDB(dst, b, h) do { _Pragma("unroll") for (int n = 0; n < 2; ++n) _Pragma("unroll") for (int k = 0; k < 2; ++k) dst[n][k] = *(const PG8_LAS bf16x8*)(lds + PG8_SB(b, h) + boff + n * 2048 + k * 1024); } while (0)
; #define PG8_MMA(ai, bj, At, Bt) do { __builtin_amdgcn_s_setprio(1); _Pragma("unroll") for (int m = 0; m < 4; ++m) _Pragma("unroll") for (int n = 0; n < 2; ++n) _Pragma("unroll") for (int k = 0; k < 2; ++k) \
;         acc[ai][bj][m][n] = __builtin_amdgcn_mfma_f32_16x16x32_bf16(Bt[n][k], At[m][k], acc[ai][bj][m][n], 0, 0, 0); __builtin_amdgcn_s_setprio(0); } while (0)
; #define PG8_WAIT_V(n) asm volatile("s_waitcnt vmcnt(" #n ")" ::: "memory")
; #define PG8_WAIT_L(n) asm volatile("s_waitcnt lgkmcnt(" #n ")" ::: "memory")
; #define PG8_BAR __builtin_amdgcn_s_barrier()
; #define PG8_SCHED __builtin_amdgcn_sched_barrier(0)
; template <class Epi, class Sched, bool ALIGN_EPI = false, bool SP2 = false>
; __device__ __forceinline__ void gemm_phase(PG8_LAS unsigned char* lds, const Gemm g, const Sched& S, const Epi& E) {
;     ...
;             PG8_WAIT_V(8); PG8_WAIT_L(0); PG8_BAR; PG8_MMA(1, 0, At, B0); PG8_MMA(1, 1, At, B1); PG8_BAR; PG8_SCHED;
;             PG8_LDB(B0, 1, 0); PG8_LDB(B1, 1, 1); PG8_SCHED; PG8_LDA(At, 1, 0); PG8_STAGE(PG8_SA(0, 1), a2 + hstep, voffA);
	v_mfma_f32_16x16x32_bf16 v[48:51], v[144:147], v[176:179], v[48:51]
	v_mfma_f32_16x16x32_bf16 v[44:47], v[152:155], v[176:179], v[44:47]
	v_mfma_f32_16x16x32_bf16 v[32:35], v[144:147], v[184:187], v[32:35]
	v_mfma_f32_16x16x32_bf16 v[28:31], v[152:155], v[184:187], v[28:31]
	v_mfma_f32_16x16x32_bf16 v[16:19], v[144:147], v[210:213], v[16:19]
	v_mfma_f32_16x16x32_bf16 v[12:15], v[152:155], v[210:213], v[12:15]
	v_mfma_f32_16x16x32_bf16 v[4:7], v[144:147], v[218:221], v[4:7]
	v_mfma_f32_16x16x32_bf16 v[0:3], v[152:155], v[218:221], v[0:3]
	v_mfma_f32_16x16x32_bf16 v[48:51], v[148:151], v[180:183], v[48:51]
	v_mfma_f32_16x16x32_bf16 v[44:47], v[156:159], v[180:183], v[44:47]
	v_mfma_f32_16x16x32_bf16 v[32:35], v[148:151], v[192:195], v[32:35]
	v_mfma_f32_16x16x32_bf16 v[28:31], v[156:159], v[192:195], v[28:31]
	v_mfma_f32_16x16x32_bf16 v[16:19], v[148:151], v[214:217], v[16:19]
	v_mfma_f32_16x16x32_bf16 v[12:15], v[156:159], v[214:217], v[12:15]
	v_mfma_f32_16x16x32_bf16 v[4:7], v[148:151], v[222:225], v[4:7]
	v_mfma_f32_16x16x32_bf16 v[0:3], v[156:159], v[222:225], v[0:3]
	s_setprio 0
	s_barrier
	s_add_i32 s79, 0, 0x18000
	s_add_i32 s80, 0, 0x1c000


; #define PG8_STAGE(bufoff, gbase, voff) do { _Pragma("unroll") for (int _i = 0; _i < 2; ++_i) \
;         __builtin_amdgcn_global_load_lds((const unsigned*)((const char*)(gbase) + (voff)[_i]), (PG8_LAS unsigned*)(lds + (bufoff) + ldsw + _i * 8192), 16, 0, 0); } while (0)
; #define PG8_LDA(dst, b, h) do { _Pragma("unroll") for (int m = 0; m < 4; ++m) _Pragma("unroll") for (int k = 0; k < 2; ++k) dst[m][k] = *(const PG8_LAS bf16x8*)(lds + PG8_SA(b, h) + aoff + m * 2048 + k * 1024); } while (0)
; #define PG8_LDB(dst, b, h) do { _Pragma("unroll") for (int n = 0; n < 2; ++n) _Pragma("unroll") for (int k = 0; k < 2; ++k) dst[n][k] = *(const PG8_LAS bf16x8*)(lds + PG8_SB(b, h) + boff + n * 2048 + k * 1024); } while (0)
; #define PG8_SCHED __builtin_amdgcn_sched_barrier(0)
; template <class Epi, class Sched, bool ALIGN_EPI = false, bool SP2 = false>
; __device__ __forceinline__ void gemm_phase(PG8_LAS unsigned char* lds, const Gemm g, const Sched& S, const Epi& E) {
;     ...
;             PG8_LDB(B0, 1, 0); PG8_LDB(B1, 1, 1); PG8_SCHED; PG8_LDA(At, 1, 0); PG8_STAGE(PG8_SA(0, 1), a2 + hstep, voffA);
	ds_read_b128 v[128:131], v254
	ds_read_b128 v[132:135], v254 offset:1024
	ds_read_b128 v[136:139], v254 offset:2048
	ds_read_b128 v[140:143], v254 offset:3072
	ds_read_b128 v[144:147], v255
	ds_read_b128 v[148:151], v255 offset:1024
	ds_read_b128 v[152:155], v255 offset:2048
	ds_read_b128 v[156:159], v255 offset:3072
	s_add_u32 s54, s54, 0x80000
	s_addc_u32 s55, s55, 0
	s_mov_b32 m0, s62

; #define PG8_STAGE(bufoff, gbase, voff) do { _Pragma("unroll") for (int _i = 0; _i < 2; ++_i) \
;         __builtin_amdgcn_global_load_lds((const unsigned*)((const char*)(gbase) + (voff)[_i]), (PG8_LAS unsigned*)(lds + (bufoff) + ldsw + _i * 8192), 16, 0, 0); } while (0)
; #define PG8_LDA(dst, b, h) do { _Pragma("unroll") for (int m = 0; m < 4; ++m) _Pragma("unroll") for (int k = 0; k < 2; ++k) dst[m][k] = *(const PG8_LAS bf16x8*)(lds + PG8_SA(b, h) + aoff + m * 2048 + k * 1024); } while (0)
; #define PG8_LDB(dst, b, h) do { _Pragma("unroll") for (int n = 0; n < 2; ++n) _Pragma("unroll") for (int k = 0; k < 2; ++k) dst[n][k] = *(const PG8_LAS bf16x8*)(lds + PG8_SB(b, h) + boff + n * 2048 + k * 1024); } while (0)
; #define PG8_SCHED __builtin_amdgcn_sched_barrier(0)
; template <class Epi, class Sched, bool ALIGN_EPI = false, bool SP2 = false>
; __device__ __forceinline__ void gemm_phase(PG8_LAS unsigned char* lds, const Gemm g, const Sched& S, const Epi& E) {
;     ...
;             PG8_LDB(B0, 1, 0); PG8_LDB(B1, 1, 1); PG8_SCHED; PG8_LDA(At, 1, 0); PG8_STAGE(PG8_SA(0, 1), a2 + hstep, voffA);
	ds_read_b128 v[176:179], v207 offset:32768
	ds_read_b128 v[180:183], v207 offset:33792
	ds_read_b128 v[184:187], v207 offset:34816
	ds_read_b128 v[192:195], v207 offset:35840
	ds_read_b128 v[210:213], v207 offset:36864
	ds_read_b128 v[214:217], v207 offset:37888
	ds_read_b128 v[218:221], v207 offset:38912
	ds_read_b128 v[222:225], v207 offset:39936
	global_load_lds_dwordx4 v166, s[54:55]

; #define PG8_STAGE(bufoff, gbase, voff) do { _Pragma("unroll") for (int _i = 0; _i < 2; ++_i) \
;         __builtin_amdgcn_global_load_lds((const unsigned*)((const char*)(gbase) + (voff)[_i]), (PG8_LAS unsigned*)(lds + (bufoff) + ldsw + _i * 8192), 16, 0, 0); } while (0)
; #define PG8_LDA(dst, b, h) do { _Pragma("unroll") for (int m = 0; m < 4; ++m) _Pragma("unroll") for (int k = 0; k < 2; ++k) dst[m][k] = *(const PG8_LAS bf16x8*)(lds + PG8_SA(b, h) + aoff + m * 2048 + k * 1024); } while (0)
; #define PG8_LDB(dst, b, h) do { _Pragma("unroll") for (int n = 0; n < 2; ++n) _Pragma("unroll") for (int k = 0; k < 2; ++k) dst[n][k] = *(const PG8_LAS bf16x8*)(lds + PG8_SB(b, h) + boff + n * 2048 + k * 1024); } while (0)
; #define PG8_MMA(ai, bj, At, Bt) do { __builtin_amdgcn_s_setprio(1); _Pragma("unroll") for (int m = 0; m < 4; ++m) _Pragma("unroll") for (int n = 0; n < 2; ++n) _Pragma("unroll") for (int k = 0; k < 2; ++k) \
;         acc[ai][bj][m][n] = __builtin_amdgcn_mfma_f32_16x16x32_bf16(Bt[n][k], At[m][k], acc[ai][bj][m][n], 0, 0, 0); __builtin_amdgcn_s_setprio(0); } while (0)
; #define PG8_WAIT_V(n) asm volatile("s_waitcnt vmcnt(" #n ")" ::: "memory")
; #define PG8_WAIT_L(n) asm volatile("s_waitcnt lgkmcnt(" #n ")" ::: "memory")
; #define PG8_BAR __builtin_amdgcn_s_barrier()
; #define PG8_SCHED __builtin_amdgcn_sched_barrier(0)
; template <class Epi, class Sched, bool ALIGN_EPI = false, bool SP2 = false>
; __device__ __forceinline__ void gemm_phase(PG8_LAS unsigned char* lds, const Gemm g, const Sched& S, const Epi& E) {
;     ...
;             PG8_LDB(B0, 1, 0); PG8_LDB(B1, 1, 1); PG8_SCHED; PG8_LDA(At, 1, 0); PG8_STAGE(PG8_SA(0, 1), a2 + hstep, voffA);
;             PG8_WAIT_V(8); PG8_WAIT_L(0); PG8_BAR; PG8_MMA(0, 0, At, B0); PG8_MMA(0, 1, At, B1); PG8_BAR; PG8_SCHED;
	s_mov_b32 m0, s63
	s_nop 0
	global_load_lds_dwordx4 v162, s[54:55]
	s_waitcnt vmcnt(8)
	s_waitcnt lgkmcnt(0)
	s_barrier
	s_setprio 1
	s_waitcnt lgkmcnt(0)
	v_mfma_f32_16x16x32_bf16 v[124:127], v[128:131], v[176:179], v[124:127]
	v_mfma_f32_16x16x32_bf16 v[120:123], v[136:139], v[176:179], v[120:123]
	v_mfma_f32_16x16x32_bf16 v[112:115], v[128:131], v[184:187], v[112:115]
	v_mfma_f32_16x16x32_bf16 v[104:107], v[136:139], v[184:187], v[104:107]
	v_mfma_f32_16x16x32_bf16 v[100:103], v[128:131], v[210:213], v[100:103]
	v_mfma_f32_16x16x32_bf16 v[88:91], v[136:139], v[210:213], v[88:91]
	v_mfma_f32_16x16x32_bf16 v[84:87], v[128:131], v[218:221], v[84:87]
	v_mfma_f32_16x16x32_bf16 v[72:75], v[136:139], v[218:221], v[72:75]
	v_mfma_f32_16x16x32_bf16 v[124:127], v[132:135], v[180:183], v[124:127]
	v_mfma_f32_16x16x32_bf16 v[120:123], v[140:143], v[180:183], v[120:123]
	v_mfma_f32_16x16x32_bf16 v[112:115], v[132:135], v[192:195], v[112:115]
	v_mfma_f32_16x16x32_bf16 v[104:107], v[140:143], v[192:195], v[104:107]
	v_mfma_f32_16x16x32_bf16 v[100:103], v[132:135], v[214:217], v[100:103]
	v_mfma_f32_16x16x32_bf16 v[88:91], v[140:143], v[214:217], v[88:91]
	v_mfma_f32_16x16x32_bf16 v[84:87], v[132:135], v[222:225], v[84:87]
	v_mfma_f32_16x16x32_bf16 v[72:75], v[140:143], v[222:225], v[72:75]


; #define PG8_MMA(ai, bj, At, Bt) do { __builtin_amdgcn_s_setprio(1); _Pragma("unroll") for (int m = 0; m < 4; ++m) _Pragma("unroll") for (int n = 0; n < 2; ++n) _Pragma("unroll") for (int k = 0; k < 2; ++k) \
;         acc[ai][bj][m][n] = __builtin_amdgcn_mfma_f32_16x16x32_bf16(Bt[n][k], At[m][k], acc[ai][bj][m][n], 0, 0, 0); __builtin_amdgcn_s_setprio(0); } while (0)
; #define PG8_WAIT_V(n) asm volatile("s_waitcnt vmcnt(" #n ")" ::: "memory")
; #define PG8_WAIT_L(n) asm volatile("s_waitcnt lgkmcnt(" #n ")" ::: "memory")
; #define PG8_BAR __builtin_amdgcn_s_barrier()
; #define PG8_SCHED __builtin_amdgcn_sched_barrier(0)
; template <class Epi, class Sched, bool ALIGN_EPI = false, bool SP2 = false>
; __device__ __forceinline__ void gemm_phase(PG8_LAS unsigned char* lds, const Gemm g, const Sched& S, const Epi& E) {
;     ...
;             PG8_WAIT_V(8); PG8_WAIT_L(0); PG8_BAR; PG8_MMA(0, 0, At, B0); PG8_MMA(0, 1, At, B1); PG8_BAR; PG8_SCHED;
	v_mfma_f32_16x16x32_bf16 v[116:119], v[144:147], v[176:179], v[116:119]
	v_mfma_f32_16x16x32_bf16 v[108:111], v[152:155], v[176:179], v[108:111]
	v_mfma_f32_16x16x32_bf16 v[96:99], v[144:147], v[184:187], v[96:99]
	v_mfma_f32_16x16x32_bf16 v[92:95], v[152:155], v[184:187], v[92:95]
	v_mfma_f32_16x16x32_bf16 v[80:83], v[144:147], v[210:213], v[80:83]
	v_mfma_f32_16x16x32_bf16 v[76:79], v[152:155], v[210:213], v[76:79]
	v_mfma_f32_16x16x32_bf16 v[68:71], v[144:147], v[218:221], v[68:71]
	v_mfma_f32_16x16x32_bf16 v[64:67], v[152:155], v[218:221], v[64:67]
	v_mfma_f32_16x16x32_bf16 v[116:119], v[148:151], v[180:183], v[116:119]
	v_mfma_f32_16x16x32_bf16 v[108:111], v[156:159], v[180:183], v[108:111]
	v_mfma_f32_16x16x32_bf16 v[96:99], v[148:151], v[192:195], v[96:99]
	v_mfma_f32_16x16x32_bf16 v[92:95], v[156:159], v[192:195], v[92:95]
	v_mfma_f32_16x16x32_bf16 v[80:83], v[148:151], v[214:217], v[80:83]
	v_mfma_f32_16x16x32_bf16 v[76:79], v[156:159], v[214:217], v[76:79]
	v_mfma_f32_16x16x32_bf16 v[68:71], v[148:151], v[222:225], v[68:71]
	v_mfma_f32_16x16x32_bf16 v[64:67], v[156:159], v[222:225], v[64:67]
	s_setprio 0
	s_barrier
	s_add_i32 s54, s79, s57

; #define PG8_STAGE(bufoff, gbase, voff) do { _Pragma("unroll") for (int _i = 0; _i < 2; ++_i) \
;         __builtin_amdgcn_global_load_lds((const unsigned*)((const char*)(gbase) + (voff)[_i]), (PG8_LAS unsigned*)(lds + (bufoff) + ldsw + _i * 8192), 16, 0, 0); } while (0)
; #define PG8_LDA(dst, b, h) do { _Pragma("unroll") for (int m = 0; m < 4; ++m) _Pragma("unroll") for (int k = 0; k < 2; ++k) dst[m][k] = *(const PG8_LAS bf16x8*)(lds + PG8_SA(b, h) + aoff + m * 2048 + k * 1024); } while (0)
; template <class Epi, class Sched, bool ALIGN_EPI = false, bool SP2 = false>
; __device__ __forceinline__ void gemm_phase(PG8_LAS unsigned char* lds, const Gemm g, const Sched& S, const Epi& E) {
;     ...
;             PG8_LDA(At, 1, 1); PG8_STAGE(PG8_SB(1, 0), b3, voffB); PG8_STAGE(PG8_SB(1, 1), b3 + hstep, voffB); PG8_STAGE(PG8_SA(1, 0), a3, voffA);
	s_mov_b32 m0, s54
	ds_read_b128 v[176:179], v207 offset:49152
	ds_read_b128 v[180:183], v207 offset:50176
	ds_read_b128 v[184:187], v207 offset:51200
	ds_read_b128 v[192:195], v207 offset:52224
	ds_read_b128 v[210:213], v207 offset:53248
	ds_read_b128 v[214:217], v207 offset:54272
	ds_read_b128 v[218:221], v207 offset:55296
	ds_read_b128 v[222:225], v207 offset:56320
	global_load_lds_dwordx4 v250, s[96:97]
	s_add_i32 m0, s54, 0x2000
	s_add_u32 s12, s12, 0x80080

; #define PG8_STAGE(bufoff, gbase, voff) do { _Pragma("unroll") for (int _i = 0; _i < 2; ++_i) \
;         __builtin_amdgcn_global_load_lds((const unsigned*)((const char*)(gbase) + (voff)[_i]), (PG8_LAS unsigned*)(lds + (bufoff) + ldsw + _i * 8192), 16, 0, 0); } while (0)
; #define PG8_LDA(dst, b, h) do { _Pragma("unroll") for (int m = 0; m < 4; ++m) _Pragma("unroll") for (int k = 0; k < 2; ++k) dst[m][k] = *(const PG8_LAS bf16x8*)(lds + PG8_SA(b, h) + aoff + m * 2048 + k * 1024); } while (0)
; template <class Epi, class Sched, bool ALIGN_EPI = false, bool SP2 = false>
; __device__ __forceinline__ void gemm_phase(PG8_LAS unsigned char* lds, const Gemm g, const Sched& S, const Epi& E) {
;     ...
;             PG8_LDA(At, 1, 1); PG8_STAGE(PG8_SB(1, 0), b3, voffB); PG8_STAGE(PG8_SB(1, 1), b3 + hstep, voffB); PG8_STAGE(PG8_SA(1, 0), a3, voffA);
	s_addc_u32 s13, s13, 0
	s_add_i32 s54, s80, s57
	global_load_lds_dwordx4 v251, s[96:97]

; #define PG8_STAGE(bufoff, gbase, voff) do { _Pragma("unroll") for (int _i = 0; _i < 2; ++_i) \
;         __builtin_amdgcn_global_load_lds((const unsigned*)((const char*)(gbase) + (voff)[_i]), (PG8_LAS unsigned*)(lds + (bufoff) + ldsw + _i * 8192), 16, 0, 0); } while (0)
; #define PG8_LDA(dst, b, h) do { _Pragma("unroll") for (int m = 0; m < 4; ++m) _Pragma("unroll") for (int k = 0; k < 2; ++k) dst[m][k] = *(const PG8_LAS bf16x8*)(lds + PG8_SA(b, h) + aoff + m * 2048 + k * 1024); } while (0)
; template <class Epi, class Sched, bool ALIGN_EPI = false, bool SP2 = false>
; __device__ __forceinline__ void gemm_phase(PG8_LAS unsigned char* lds, const Gemm g, const Sched& S, const Epi& E) {
;     ...
;             PG8_LDA(At, 1, 1); PG8_STAGE(PG8_SB(1, 0), b3, voffB); PG8_STAGE(PG8_SB(1, 1), b3 + hstep, voffB); PG8_STAGE(PG8_SA(1, 0), a3, voffA);
	s_mov_b32 m0, s54
	s_nop 0
	global_load_lds_dwordx4 v164, s[12:13]

; #define PG8_STAGE(bufoff, gbase, voff) do { _Pragma("unroll") for (int _i = 0; _i < 2; ++_i) \
;         __builtin_amdgcn_global_load_lds((const unsigned*)((const char*)(gbase) + (voff)[_i]), (PG8_LAS unsigned*)(lds + (bufoff) + ldsw + _i * 8192), 16, 0, 0); } while (0)
; #define PG8_LDA(dst, b, h) do { _Pragma("unroll") for (int m = 0; m < 4; ++m) _Pragma("unroll") for (int k = 0; k < 2; ++k) dst[m][k] = *(const PG8_LAS bf16x8*)(lds + PG8_SA(b, h) + aoff + m * 2048 + k * 1024); } while (0)
; template <class Epi, class Sched, bool ALIGN_EPI = false, bool SP2 = false>
; __device__ __forceinline__ void gemm_phase(PG8_LAS unsigned char* lds, const Gemm g, const Sched& S, const Epi& E) {
;     ...
;             PG8_LDA(At, 1, 1); PG8_STAGE(PG8_SB(1, 0), b3, voffB); PG8_STAGE(PG8_SB(1, 1), b3 + hstep, voffB); PG8_STAGE(PG8_SA(1, 0), a3, voffA);
	s_add_i32 m0, s54, 0x2000
	s_nop 0
	global_load_lds_dwordx4 v160, s[12:13]

; #define PG8_STAGE(bufoff, gbase, voff) do { _Pragma("unroll") for (int _i = 0; _i < 2; ++_i) \
;         __builtin_amdgcn_global_load_lds((const unsigned*)((const char*)(gbase) + (voff)[_i]), (PG8_LAS unsigned*)(lds + (bufoff) + ldsw + _i * 8192), 16, 0, 0); } while (0)
; #define PG8_LDA(dst, b, h) do { _Pragma("unroll") for (int m = 0; m < 4; ++m) _Pragma("unroll") for (int k = 0; k < 2; ++k) dst[m][k] = *(const PG8_LAS bf16x8*)(lds + PG8_SA(b, h) + aoff + m * 2048 + k * 1024); } while (0)
; template <class Epi, class Sched, bool ALIGN_EPI = false, bool SP2 = false>
; __device__ __forceinline__ void gemm_phase(PG8_LAS unsigned char* lds, const Gemm g, const Sched& S, const Epi& E) {
;     ...
;             PG8_LDA(At, 1, 1); PG8_STAGE(PG8_SB(1, 0), b3, voffB); PG8_STAGE(PG8_SB(1, 1), b3 + hstep, voffB); PG8_STAGE(PG8_SA(1, 0), a3, voffA);
	s_mov_b32 m0, s65
	s_nop 0
	global_load_lds_dwordx4 v252, s[98:99]

; #define PG8_STAGE(bufoff, gbase, voff) do { _Pragma("unroll") for (int _i = 0; _i < 2; ++_i) \
;         __builtin_amdgcn_global_load_lds((const unsigned*)((const char*)(gbase) + (voff)[_i]), (PG8_LAS unsigned*)(lds + (bufoff) + ldsw + _i * 8192), 16, 0, 0); } while (0)
; #define PG8_LDA(dst, b, h) do { _Pragma("unroll") for (int m = 0; m < 4; ++m) _Pragma("unroll") for (int k = 0; k < 2; ++k) dst[m][k] = *(const PG8_LAS bf16x8*)(lds + PG8_SA(b, h) + aoff + m * 2048 + k * 1024); } while (0)
; #define PG8_MMA(ai, bj, At, Bt) do { __builtin_amdgcn_s_setprio(1); _Pragma("unroll") for (int m = 0; m < 4; ++m) _Pragma("unroll") for (int n = 0; n < 2; ++n) _Pragma("unroll") for (int k = 0; k < 2; ++k) \
;         acc[ai][bj][m][n] = __builtin_amdgcn_mfma_f32_16x16x32_bf16(Bt[n][k], At[m][k], acc[ai][bj][m][n], 0, 0, 0); __builtin_amdgcn_s_setprio(0); } while (0)
; #define PG8_WAIT_V(n) asm volatile("s_waitcnt vmcnt(" #n ")" ::: "memory")
; #define PG8_WAIT_L(n) asm volatile("s_waitcnt lgkmcnt(" #n ")" ::: "memory")
; #define PG8_BAR __builtin_amdgcn_s_barrier()
; #define PG8_SCHED __builtin_amdgcn_sched_barrier(0)
; template <class Epi, class Sched, bool ALIGN_EPI = false, bool SP2 = false>
; __device__ __forceinline__ void gemm_phase(PG8_LAS unsigned char* lds, const Gemm g, const Sched& S, const Epi& E) {
;     ...
;             PG8_LDA(At, 1, 1); PG8_STAGE(PG8_SB(1, 0), b3, voffB); PG8_STAGE(PG8_SB(1, 1), b3 + hstep, voffB); PG8_STAGE(PG8_SA(1, 0), a3, voffA);
;             PG8_WAIT_V(8); PG8_WAIT_L(0); PG8_BAR; PG8_MMA(1, 0, At, B0); PG8_MMA(1, 1, At, B1); PG8_BAR; PG8_SCHED;
	s_mov_b32 m0, s67
	s_nop 0
	global_load_lds_dwordx4 v253, s[98:99]
	s_waitcnt vmcnt(8)
	s_waitcnt lgkmcnt(0)
	s_barrier
	s_setprio 1
	s_waitcnt lgkmcnt(0)
	v_mfma_f32_16x16x32_bf16 v[60:63], v[128:131], v[176:179], v[60:63]
	v_mfma_f32_16x16x32_bf16 v[56:59], v[136:139], v[176:179], v[56:59]
	v_mfma_f32_16x16x32_bf16 v[52:55], v[128:131], v[184:187], v[52:55]
	v_mfma_f32_16x16x32_bf16 v[40:43], v[136:139], v[184:187], v[40:43]
	v_mfma_f32_16x16x32_bf16 v[36:39], v[128:131], v[210:213], v[36:39]
	v_mfma_f32_16x16x32_bf16 v[24:27], v[136:139], v[210:213], v[24:27]
	v_mfma_f32_16x16x32_bf16 v[20:23], v[128:131], v[218:221], v[20:23]
	v_mfma_f32_16x16x32_bf16 v[8:11], v[136:139], v[218:221], v[8:11]
	v_mfma_f32_16x16x32_bf16 v[60:63], v[132:135], v[180:183], v[60:63]
	v_mfma_f32_16x16x32_bf16 v[56:59], v[140:143], v[180:183], v[56:59]
	v_mfma_f32_16x16x32_bf16 v[52:55], v[132:135], v[192:195], v[52:55]
	v_mfma_f32_16x16x32_bf16 v[40:43], v[140:143], v[192:195], v[40:43]
	v_mfma_f32_16x16x32_bf16 v[36:39], v[132:135], v[214:217], v[36:39]
	v_mfma_f32_16x16x32_bf16 v[24:27], v[140:143], v[214:217], v[24:27]
	v_mfma_f32_16x16x32_bf16 v[20:23], v[132:135], v[222:225], v[20:23]
	v_mfma_f32_16x16x32_bf16 v[8:11], v[140:143], v[222:225], v[8:11]


; #define PG8_MMA(ai, bj, At, Bt) do { __builtin_amdgcn_s_setprio(1); _Pragma("unroll") for (int m = 0; m < 4; ++m) _Pragma("unroll") for (int n = 0; n < 2; ++n) _Pragma("unroll") for (int k = 0; k < 2; ++k) \
;         acc[ai][bj][m][n] = __builtin_amdgcn_mfma_f32_16x16x32_bf16(Bt[n][k], At[m][k], acc[ai][bj][m][n], 0, 0, 0); __builtin_amdgcn_s_setprio(0); } while (0)
; #define PG8_WAIT_V(n) asm volatile("s_waitcnt vmcnt(" #n ")" ::: "memory")
; #define PG8_WAIT_L(n) asm volatile("s_waitcnt lgkmcnt(" #n ")" ::: "memory")
; #define PG8_BAR __builtin_amdgcn_s_barrier()
; #define PG8_SCHED __builtin_amdgcn_sched_barrier(0)
; template <class Epi, class Sched, bool ALIGN_EPI = false, bool SP2 = false>
; __device__ __forceinline__ void gemm_phase(PG8_LAS unsigned char* lds, const Gemm g, const Sched& S, const Epi& E) {
;     ...
;         for (int t = 0; t < nt; t += 2) {
;     ...
;             PG8_WAIT_V(8); PG8_WAIT_L(0); PG8_BAR; PG8_MMA(1, 0, At, B0); PG8_MMA(1, 1, At, B1); PG8_BAR; PG8_SCHED;
;     ...
;         if constexpr (ALIGN_EPI) { if (wr == 0) PG8_BAR; }
	v_mfma_f32_16x16x32_bf16 v[48:51], v[144:147], v[176:179], v[48:51]
	v_mfma_f32_16x16x32_bf16 v[44:47], v[152:155], v[176:179], v[44:47]
	v_mfma_f32_16x16x32_bf16 v[32:35], v[144:147], v[184:187], v[32:35]
	v_mfma_f32_16x16x32_bf16 v[28:31], v[152:155], v[184:187], v[28:31]
	v_mfma_f32_16x16x32_bf16 v[16:19], v[144:147], v[210:213], v[16:19]
	v_mfma_f32_16x16x32_bf16 v[12:15], v[152:155], v[210:213], v[12:15]
	v_mfma_f32_16x16x32_bf16 v[4:7], v[144:147], v[218:221], v[4:7]
	v_mfma_f32_16x16x32_bf16 v[0:3], v[152:155], v[218:221], v[0:3]
	v_mfma_f32_16x16x32_bf16 v[48:51], v[148:151], v[180:183], v[48:51]
	v_mfma_f32_16x16x32_bf16 v[44:47], v[156:159], v[180:183], v[44:47]
	v_mfma_f32_16x16x32_bf16 v[32:35], v[148:151], v[192:195], v[32:35]
	v_mfma_f32_16x16x32_bf16 v[28:31], v[156:159], v[192:195], v[28:31]
	v_mfma_f32_16x16x32_bf16 v[16:19], v[148:151], v[214:217], v[16:19]
	v_mfma_f32_16x16x32_bf16 v[12:15], v[156:159], v[214:217], v[12:15]
	v_mfma_f32_16x16x32_bf16 v[4:7], v[148:151], v[222:225], v[4:7]
	v_mfma_f32_16x16x32_bf16 v[0:3], v[156:159], v[222:225], v[0:3]
	s_setprio 0
	s_barrier
	s_add_i32 s78, s78, 2
	s_add_u32 s10, s10, 0x100
	s_addc_u32 s11, s11, 0
	s_add_u32 s76, s76, 0x100
	s_addc_u32 s77, s77, 0
	s_cmp_gt_u32 s78, 29
	s_cbranch_scc0 .LBB0_679
	s_and_b64 vcc, exec, s[42:43]
	s_cbranch_vccz .LBB0_682
	s_barrier

; #define PG8_STAGE(bufoff, gbase, voff) do { _Pragma("unroll") for (int _i = 0; _i < 2; ++_i) \
;         __builtin_amdgcn_global_load_lds((const unsigned*)((const char*)(gbase) + (voff)[_i]), (PG8_LAS unsigned*)(lds + (bufoff) + ldsw + _i * 8192), 16, 0, 0); } while (0)
; #define PG8_LDA(dst, b, h) do { _Pragma("unroll") for (int m = 0; m < 4; ++m) _Pragma("unroll") for (int k = 0; k < 2; ++k) dst[m][k] = *(const PG8_LAS bf16x8*)(lds + PG8_SA(b, h) + aoff + m * 2048 + k * 1024); } while (0)
; #define PG8_LDB(dst, b, h) do { _Pragma("unroll") for (int n = 0; n < 2; ++n) _Pragma("unroll") for (int k = 0; k < 2; ++k) dst[n][k] = *(const PG8_LAS bf16x8*)(lds + PG8_SB(b, h) + boff + n * 2048 + k * 1024); } while (0)
; #define PG8_SCHED __builtin_amdgcn_sched_barrier(0)
; template <class Epi, class Sched, bool ALIGN_EPI = false, bool SP2 = false>
; __device__ __forceinline__ void gemm_phase(PG8_LAS unsigned char* lds, const Gemm g, const Sched& S, const Epi& E) {
;     ...
;         const bool has_next = S.next(ui + 1, nxt);
;         const char* nA = has_next ? (const char*)g.A + (size_t)nxt.pm * tstep : cA; const char* nB = has_next ? (const char*)g.Bt + (size_t)nxt.pn * tstep : cB;
;         for (int t = 0; t < nt; t += 2) {
;             const bool last = (t == nt - 2);
;             const char* a1 = cA + (size_t)(t + 1) * kstep;
;             const char* a2 = last ? nA : cA + (size_t)(t + 2) * kstep; const char* b2 = last ? nB : cB + (size_t)(t + 2) * kstep;
;             const char* a3 = a2 + kstep; const char* b3 = b2 + kstep;
;             if (last && has_next) S.a_ready(nxt);
;             if constexpr (SP2) {
;             PG8_LDB(B0, 0, 0); PG8_LDB(B1, 0, 1); PG8_SCHED; PG8_LDA(At, 0, 0); PG8_STAGE(PG8_SA(1, 1), a1 + hstep, voffA);
;     ...
;         for (int a = 0; a < 2; ++a)
; #pragma unroll
;             for (int b = 0; b < 2; ++b)
; #pragma unroll
;                 for (int m = 0; m < 4; ++m)
; #pragma unroll
;                     for (int n = 0; n < 2; ++n) acc[a][b][m][n] = (f32x4){0.f, 0.f, 0.f, 0.f};
.LBB0_938:
	s_ashr_i32 s51, s50, 31
	s_lshl_b64 s[52:53], s[50:51], 20
	s_add_u32 s52, s26, s52
	s_addc_u32 s53, s27, s53
	s_and_b64 s[54:55], s[6:7], exec
	s_cselect_b32 s11, s53, s59
	s_cselect_b32 s51, s52, s58
	s_ashr_i32 s49, s48, 31
	s_lshl_b64 s[54:55], s[48:49], 20
	s_add_u32 s54, s45, s54
	s_addc_u32 s55, s47, s55
	s_and_b64 s[62:63], s[6:7], exec
	s_cselect_b32 s49, s55, s61
	s_cselect_b32 s78, s54, s60
	s_add_u32 s58, s58, 0x80080
	s_addc_u32 s59, s59, 0
	s_add_u32 s79, s60, 0x100
	v_mov_b32_e32 v0, 0
	s_addc_u32 s80, s61, 0
	s_mov_b32 s81, -2
	v_mov_b32_e32 v1, v0
	s_waitcnt lgkmcnt(0)
	v_mov_b32_e32 v2, v0
	v_mov_b32_e32 v3, v0
	v_mov_b32_e32 v4, v0
	v_mov_b32_e32 v5, v0
	v_mov_b32_e32 v6, v0
	v_mov_b32_e32 v7, v0
	v_mov_b32_e32 v16, v0
	v_mov_b32_e32 v17, v0
	v_mov_b32_e32 v18, v0
	v_mov_b32_e32 v19, v0
	v_mov_b32_e32 v20, v0
	v_mov_b32_e32 v21, v0
	v_mov_b32_e32 v22, v0
	v_mov_b32_e32 v23, v0
	v_mov_b32_e32 v32, v0
	v_mov_b32_e32 v33, v0
	v_mov_b32_e32 v34, v0
	v_mov_b32_e32 v35, v0
	v_mov_b32_e32 v36, v0
	v_mov_b32_e32 v37, v0
	v_mov_b32_e32 v38, v0
	v_mov_b32_e32 v39, v0
	v_mov_b32_e32 v48, v0
	v_mov_b32_e32 v49, v0
	v_mov_b32_e32 v50, v0
	v_mov_b32_e32 v51, v0
	v_mov_b32_e32 v52, v0
	v_mov_b32_e32 v53, v0
	v_mov_b32_e32 v54, v0
	v_mov_b32_e32 v55, v0
	v_mov_b32_e32 v8, v0
	v_mov_b32_e32 v9, v0
	v_mov_b32_e32 v10, v0
	v_mov_b32_e32 v11, v0
	v_mov_b32_e32 v12, v0
	v_mov_b32_e32 v13, v0
	v_mov_b32_e32 v14, v0
	v_mov_b32_e32 v15, v0
	v_mov_b32_e32 v24, v0
	v_mov_b32_e32 v25, v0
	v_mov_b32_e32 v26, v0
	v_mov_b32_e32 v27, v0
	v_mov_b32_e32 v28, v0
	v_mov_b32_e32 v29, v0
	v_mov_b32_e32 v30, v0
	v_mov_b32_e32 v31, v0
	v_mov_b32_e32 v40, v0
	v_mov_b32_e32 v41, v0
	v_mov_b32_e32 v42, v0
	v_mov_b32_e32 v43, v0
	v_mov_b32_e32 v44, v0
	v_mov_b32_e32 v45, v0
	v_mov_b32_e32 v46, v0
	v_mov_b32_e32 v47, v0
	v_mov_b32_e32 v56, v0
	v_mov_b32_e32 v57, v0
	v_mov_b32_e32 v58, v0
	v_mov_b32_e32 v59, v0
	v_mov_b32_e32 v60, v0
	v_mov_b32_e32 v61, v0
	v_mov_b32_e32 v62, v0
	v_mov_b32_e32 v63, v0
	v_mov_b32_e32 v80, v0
	v_mov_b32_e32 v81, v0
	v_mov_b32_e32 v82, v0
	v_mov_b32_e32 v83, v0
	v_mov_b32_e32 v84, v0
	v_mov_b32_e32 v85, v0
	v_mov_b32_e32 v86, v0
	v_mov_b32_e32 v87, v0
	v_mov_b32_e32 v96, v0
	v_mov_b32_e32 v97, v0
	v_mov_b32_e32 v98, v0
	v_mov_b32_e32 v99, v0
	v_mov_b32_e32 v100, v0
	v_mov_b32_e32 v101, v0
	v_mov_b32_e32 v102, v0
	v_mov_b32_e32 v103, v0
	v_mov_b32_e32 v112, v0
	v_mov_b32_e32 v113, v0
	v_mov_b32_e32 v114, v0
	v_mov_b32_e32 v115, v0
	v_mov_b32_e32 v116, v0
	v_mov_b32_e32 v117, v0
	v_mov_b32_e32 v118, v0
	v_mov_b32_e32 v119, v0
	v_mov_b32_e32 v128, v0
	v_mov_b32_e32 v129, v0
	v_mov_b32_e32 v130, v0
	v_mov_b32_e32 v131, v0
	v_mov_b32_e32 v132, v0
	v_mov_b32_e32 v133, v0
	v_mov_b32_e32 v134, v0
	v_mov_b32_e32 v135, v0
	v_mov_b32_e32 v88, v0
	v_mov_b32_e32 v89, v0
	v_mov_b32_e32 v90, v0
	v_mov_b32_e32 v91, v0
	v_mov_b32_e32 v92, v0
	v_mov_b32_e32 v93, v0
	v_mov_b32_e32 v94, v0
	v_mov_b32_e32 v95, v0
	v_mov_b32_e32 v104, v0
	v_mov_b32_e32 v105, v0
	v_mov_b32_e32 v106, v0
	v_mov_b32_e32 v107, v0
	v_mov_b32_e32 v108, v0
	v_mov_b32_e32 v109, v0
	v_mov_b32_e32 v110, v0
	v_mov_b32_e32 v111, v0
	v_mov_b32_e32 v120, v0
	v_mov_b32_e32 v121, v0
	v_mov_b32_e32 v122, v0
	v_mov_b32_e32 v123, v0
	v_mov_b32_e32 v124, v0
	v_mov_b32_e32 v125, v0
	v_mov_b32_e32 v126, v0
	v_mov_b32_e32 v127, v0
	v_mov_b32_e32 v136, v0
	v_mov_b32_e32 v137, v0
	v_mov_b32_e32 v138, v0
	v_mov_b32_e32 v139, v0
	v_mov_b32_e32 v140, v0
	v_mov_b32_e32 v141, v0
	v_mov_b32_e32 v142, v0
	v_mov_b32_e32 v143, v0
	v_add_u32_e32 v255, 0x1c000, v211
	v_add_u32_e32 v254, 0x18000, v211
	v_add_u32_e32 v253, 0x80, v164
	v_add_u32_e32 v252, 0x80, v160
	v_add_u32_e32 v251, 0x80, v166
	v_add_u32_e32 v250, 0x80, v162
.LBB0_939:
	ds_read_b128 v[64:67], v213
	ds_read_b128 v[68:71], v213 offset:1024
	ds_read_b128 v[72:75], v213 offset:2048
	ds_read_b128 v[76:79], v213 offset:3072
	ds_read_b128 v[144:147], v214
	ds_read_b128 v[148:151], v214 offset:1024
	ds_read_b128 v[152:155], v214 offset:2048
	ds_read_b128 v[156:159], v214 offset:3072
	s_add_u32 s60, s58, 0xfff80080
	s_addc_u32 s61, s59, -1
	s_cmp_eq_u32 s81, 28
	s_cselect_b32 s63, s11, s61
	s_cselect_b32 s62, s51, s60
	s_cselect_b32 s61, s49, s80
	s_cselect_b32 s60, s78, s79

; #define PG8_STAGE(bufoff, gbase, voff) do { _Pragma("unroll") for (int _i = 0; _i < 2; ++_i) \
;         __builtin_amdgcn_global_load_lds((const unsigned*)((const char*)(gbase) + (voff)[_i]), (PG8_LAS unsigned*)(lds + (bufoff) + ldsw + _i * 8192), 16, 0, 0); } while (0)
; #define PG8_LDA(dst, b, h) do { _Pragma("unroll") for (int m = 0; m < 4; ++m) _Pragma("unroll") for (int k = 0; k < 2; ++k) dst[m][k] = *(const PG8_LAS bf16x8*)(lds + PG8_SA(b, h) + aoff + m * 2048 + k * 1024); } while (0)
; #define PG8_LDB(dst, b, h) do { _Pragma("unroll") for (int n = 0; n < 2; ++n) _Pragma("unroll") for (int k = 0; k < 2; ++k) dst[n][k] = *(const PG8_LAS bf16x8*)(lds + PG8_SB(b, h) + boff + n * 2048 + k * 1024); } while (0)
; #define PG8_SCHED __builtin_amdgcn_sched_barrier(0)
; template <class Epi, class Sched, bool ALIGN_EPI = false, bool SP2 = false>
; __device__ __forceinline__ void gemm_phase(PG8_LAS unsigned char* lds, const Gemm g, const Sched& S, const Epi& E) {
;     ...
;             PG8_LDB(B0, 0, 0); PG8_LDB(B1, 0, 1); PG8_SCHED; PG8_LDA(At, 0, 0); PG8_STAGE(PG8_SA(1, 1), a1 + hstep, voffA);
	s_add_i32 m0, s57, 0xc000
	ds_read_b128 v[176:179], v215
	ds_read_b128 v[180:183], v215 offset:1024
	ds_read_b128 v[184:187], v215 offset:2048
	ds_read_b128 v[188:191], v215 offset:3072
	ds_read_b128 v[192:195], v215 offset:4096
	ds_read_b128 v[196:199], v215 offset:5120
	ds_read_b128 v[200:203], v215 offset:6144
	ds_read_b128 v[204:207], v215 offset:7168
	global_load_lds_dwordx4 v168, s[58:59]

; #define PG8_STAGE(bufoff, gbase, voff) do { _Pragma("unroll") for (int _i = 0; _i < 2; ++_i) \
;         __builtin_amdgcn_global_load_lds((const unsigned*)((const char*)(gbase) + (voff)[_i]), (PG8_LAS unsigned*)(lds + (bufoff) + ldsw + _i * 8192), 16, 0, 0); } while (0)
; #define PG8_LDA(dst, b, h) do { _Pragma("unroll") for (int m = 0; m < 4; ++m) _Pragma("unroll") for (int k = 0; k < 2; ++k) dst[m][k] = *(const PG8_LAS bf16x8*)(lds + PG8_SA(b, h) + aoff + m * 2048 + k * 1024); } while (0)
; #define PG8_LDB(dst, b, h) do { _Pragma("unroll") for (int n = 0; n < 2; ++n) _Pragma("unroll") for (int k = 0; k < 2; ++k) dst[n][k] = *(const PG8_LAS bf16x8*)(lds + PG8_SB(b, h) + boff + n * 2048 + k * 1024); } while (0)
; #define PG8_MMA(ai, bj, At, Bt) do { __builtin_amdgcn_s_setprio(1); _Pragma("unroll") for (int m = 0; m < 4; ++m) _Pragma("unroll") for (int n = 0; n < 2; ++n) _Pragma("unroll") for (int k = 0; k < 2; ++k) \
;         acc[ai][bj][m][n] = __builtin_amdgcn_mfma_f32_16x16x32_bf16(Bt[n][k], At[m][k], acc[ai][bj][m][n], 0, 0, 0); __builtin_amdgcn_s_setprio(0); } while (0)
; #define PG8_WAIT_V(n) asm volatile("s_waitcnt vmcnt(" #n ")" ::: "memory")
; #define PG8_WAIT_L(n) asm volatile("s_waitcnt lgkmcnt(" #n ")" ::: "memory")
; #define PG8_BAR __builtin_amdgcn_s_barrier()
; #define PG8_SCHED __builtin_amdgcn_sched_barrier(0)
; template <class Epi, class Sched, bool ALIGN_EPI = false, bool SP2 = false>
; __device__ __forceinline__ void gemm_phase(PG8_LAS unsigned char* lds, const Gemm g, const Sched& S, const Epi& E) {
;     ...
;             PG8_LDB(B0, 0, 0); PG8_LDB(B1, 0, 1); PG8_SCHED; PG8_LDA(At, 0, 0); PG8_STAGE(PG8_SA(1, 1), a1 + hstep, voffA);
;             PG8_WAIT_V(8); PG8_WAIT_L(0); PG8_BAR; PG8_MMA(0, 0, At, B0); PG8_MMA(0, 1, At, B1); PG8_BAR; PG8_SCHED;
	s_add_i32 m0, s57, 0xe000
	s_nop 0
	global_load_lds_dwordx4 v170, s[58:59]
	s_waitcnt vmcnt(8)
	s_waitcnt lgkmcnt(0)
	s_barrier
	s_setprio 1
	s_waitcnt lgkmcnt(0)
	v_mfma_f32_16x16x32_bf16 v[140:143], v[64:67], v[176:179], v[140:143]
	v_mfma_f32_16x16x32_bf16 v[136:139], v[72:75], v[176:179], v[136:139]
	v_mfma_f32_16x16x32_bf16 v[124:127], v[64:67], v[184:187], v[124:127]
	v_mfma_f32_16x16x32_bf16 v[120:123], v[72:75], v[184:187], v[120:123]
	v_mfma_f32_16x16x32_bf16 v[108:111], v[64:67], v[192:195], v[108:111]
	v_mfma_f32_16x16x32_bf16 v[104:107], v[72:75], v[192:195], v[104:107]
	v_mfma_f32_16x16x32_bf16 v[92:95], v[64:67], v[200:203], v[92:95]
	v_mfma_f32_16x16x32_bf16 v[88:91], v[72:75], v[200:203], v[88:91]
	v_mfma_f32_16x16x32_bf16 v[140:143], v[68:71], v[180:183], v[140:143]
	v_mfma_f32_16x16x32_bf16 v[136:139], v[76:79], v[180:183], v[136:139]
	v_mfma_f32_16x16x32_bf16 v[124:127], v[68:71], v[188:191], v[124:127]
	v_mfma_f32_16x16x32_bf16 v[120:123], v[76:79], v[188:191], v[120:123]
	v_mfma_f32_16x16x32_bf16 v[108:111], v[68:71], v[196:199], v[108:111]
	v_mfma_f32_16x16x32_bf16 v[104:107], v[76:79], v[196:199], v[104:107]
	v_mfma_f32_16x16x32_bf16 v[92:95], v[68:71], v[204:207], v[92:95]
	v_mfma_f32_16x16x32_bf16 v[88:91], v[76:79], v[204:207], v[88:91]


; #define PG8_MMA(ai, bj, At, Bt) do { __builtin_amdgcn_s_setprio(1); _Pragma("unroll") for (int m = 0; m < 4; ++m) _Pragma("unroll") for (int n = 0; n < 2; ++n) _Pragma("unroll") for (int k = 0; k < 2; ++k) \
;         acc[ai][bj][m][n] = __builtin_amdgcn_mfma_f32_16x16x32_bf16(Bt[n][k], At[m][k], acc[ai][bj][m][n], 0, 0, 0); __builtin_amdgcn_s_setprio(0); } while (0)
; #define PG8_WAIT_V(n) asm volatile("s_waitcnt vmcnt(" #n ")" ::: "memory")
; #define PG8_WAIT_L(n) asm volatile("s_waitcnt lgkmcnt(" #n ")" ::: "memory")
; #define PG8_BAR __builtin_amdgcn_s_barrier()
; #define PG8_SCHED __builtin_amdgcn_sched_barrier(0)
; template <class Epi, class Sched, bool ALIGN_EPI = false, bool SP2 = false>
; __device__ __forceinline__ void gemm_phase(PG8_LAS unsigned char* lds, const Gemm g, const Sched& S, const Epi& E) {
;     ...
;             PG8_WAIT_V(8); PG8_WAIT_L(0); PG8_BAR; PG8_MMA(0, 0, At, B0); PG8_MMA(0, 1, At, B1); PG8_BAR; PG8_SCHED;
	v_mfma_f32_16x16x32_bf16 v[132:135], v[144:147], v[176:179], v[132:135]
	v_mfma_f32_16x16x32_bf16 v[128:131], v[152:155], v[176:179], v[128:131]
	v_mfma_f32_16x16x32_bf16 v[116:119], v[144:147], v[184:187], v[116:119]
	v_mfma_f32_16x16x32_bf16 v[112:115], v[152:155], v[184:187], v[112:115]
	v_mfma_f32_16x16x32_bf16 v[100:103], v[144:147], v[192:195], v[100:103]
	v_mfma_f32_16x16x32_bf16 v[96:99], v[152:155], v[192:195], v[96:99]
	v_mfma_f32_16x16x32_bf16 v[84:87], v[144:147], v[200:203], v[84:87]
	v_mfma_f32_16x16x32_bf16 v[80:83], v[152:155], v[200:203], v[80:83]
	v_mfma_f32_16x16x32_bf16 v[132:135], v[148:151], v[180:183], v[132:135]
	v_mfma_f32_16x16x32_bf16 v[128:131], v[156:159], v[180:183], v[128:131]
	v_mfma_f32_16x16x32_bf16 v[116:119], v[148:151], v[188:191], v[116:119]
	v_mfma_f32_16x16x32_bf16 v[112:115], v[156:159], v[188:191], v[112:115]
	v_mfma_f32_16x16x32_bf16 v[100:103], v[148:151], v[196:199], v[100:103]
	v_mfma_f32_16x16x32_bf16 v[96:99], v[156:159], v[196:199], v[96:99]
	v_mfma_f32_16x16x32_bf16 v[84:87], v[148:151], v[204:207], v[84:87]
	v_mfma_f32_16x16x32_bf16 v[80:83], v[156:159], v[204:207], v[80:83]
	s_setprio 0
	s_barrier
	s_add_i32 s82, s75, s64
	s_mov_b64 s[96:97], s[60:61]

; #define PG8_STAGE(bufoff, gbase, voff) do { _Pragma("unroll") for (int _i = 0; _i < 2; ++_i) \
;         __builtin_amdgcn_global_load_lds((const unsigned*)((const char*)(gbase) + (voff)[_i]), (PG8_LAS unsigned*)(lds + (bufoff) + ldsw + _i * 8192), 16, 0, 0); } while (0)
; #define PG8_LDA(dst, b, h) do { _Pragma("unroll") for (int m = 0; m < 4; ++m) _Pragma("unroll") for (int k = 0; k < 2; ++k) dst[m][k] = *(const PG8_LAS bf16x8*)(lds + PG8_SA(b, h) + aoff + m * 2048 + k * 1024); } while (0)
; template <class Epi, class Sched, bool ALIGN_EPI = false, bool SP2 = false>
; __device__ __forceinline__ void gemm_phase(PG8_LAS unsigned char* lds, const Gemm g, const Sched& S, const Epi& E) {
;     ...
;             PG8_LDA(At, 0, 1); PG8_STAGE(PG8_SB(0, 0), b2, voffB); PG8_STAGE(PG8_SB(0, 1), b2 + hstep, voffB); PG8_STAGE(PG8_SA(0, 0), a2, voffA);
	s_mov_b32 m0, s82
	ds_read_b128 v[176:179], v215 offset:16384
	ds_read_b128 v[180:183], v215 offset:17408
	ds_read_b128 v[184:187], v215 offset:18432
	ds_read_b128 v[188:191], v215 offset:19456
	ds_read_b128 v[192:195], v215 offset:20480
	ds_read_b128 v[196:199], v215 offset:21504
	ds_read_b128 v[200:203], v215 offset:22528
	ds_read_b128 v[204:207], v215 offset:23552
	global_load_lds_dwordx4 v162, s[60:61]
	s_add_i32 m0, s82, 0x2000
	s_add_u32 s82, s60, 0x80000

; #define PG8_STAGE(bufoff, gbase, voff) do { _Pragma("unroll") for (int _i = 0; _i < 2; ++_i) \
;         __builtin_amdgcn_global_load_lds((const unsigned*)((const char*)(gbase) + (voff)[_i]), (PG8_LAS unsigned*)(lds + (bufoff) + ldsw + _i * 8192), 16, 0, 0); } while (0)
; #define PG8_LDA(dst, b, h) do { _Pragma("unroll") for (int m = 0; m < 4; ++m) _Pragma("unroll") for (int k = 0; k < 2; ++k) dst[m][k] = *(const PG8_LAS bf16x8*)(lds + PG8_SA(b, h) + aoff + m * 2048 + k * 1024); } while (0)
; template <class Epi, class Sched, bool ALIGN_EPI = false, bool SP2 = false>
; __device__ __forceinline__ void gemm_phase(PG8_LAS unsigned char* lds, const Gemm g, const Sched& S, const Epi& E) {
;     ...
;             PG8_LDA(At, 0, 1); PG8_STAGE(PG8_SB(0, 0), b2, voffB); PG8_STAGE(PG8_SB(0, 1), b2 + hstep, voffB); PG8_STAGE(PG8_SA(0, 0), a2, voffA);
	s_addc_u32 s83, s61, 0
	s_add_i32 s84, s76, s64
	global_load_lds_dwordx4 v166, s[60:61]

; #define PG8_STAGE(bufoff, gbase, voff) do { _Pragma("unroll") for (int _i = 0; _i < 2; ++_i) \
;         __builtin_amdgcn_global_load_lds((const unsigned*)((const char*)(gbase) + (voff)[_i]), (PG8_LAS unsigned*)(lds + (bufoff) + ldsw + _i * 8192), 16, 0, 0); } while (0)
; #define PG8_LDA(dst, b, h) do { _Pragma("unroll") for (int m = 0; m < 4; ++m) _Pragma("unroll") for (int k = 0; k < 2; ++k) dst[m][k] = *(const PG8_LAS bf16x8*)(lds + PG8_SA(b, h) + aoff + m * 2048 + k * 1024); } while (0)
; template <class Epi, class Sched, bool ALIGN_EPI = false, bool SP2 = false>
; __device__ __forceinline__ void gemm_phase(PG8_LAS unsigned char* lds, const Gemm g, const Sched& S, const Epi& E) {
;     ...
;             PG8_LDA(At, 0, 1); PG8_STAGE(PG8_SB(0, 0), b2, voffB); PG8_STAGE(PG8_SB(0, 1), b2 + hstep, voffB); PG8_STAGE(PG8_SA(0, 0), a2, voffA);
	s_mov_b32 m0, s84
	s_nop 0
	global_load_lds_dwordx4 v162, s[82:83]

; #define PG8_STAGE(bufoff, gbase, voff) do { _Pragma("unroll") for (int _i = 0; _i < 2; ++_i) \
;         __builtin_amdgcn_global_load_lds((const unsigned*)((const char*)(gbase) + (voff)[_i]), (PG8_LAS unsigned*)(lds + (bufoff) + ldsw + _i * 8192), 16, 0, 0); } while (0)
; #define PG8_LDA(dst, b, h) do { _Pragma("unroll") for (int m = 0; m < 4; ++m) _Pragma("unroll") for (int k = 0; k < 2; ++k) dst[m][k] = *(const PG8_LAS bf16x8*)(lds + PG8_SA(b, h) + aoff + m * 2048 + k * 1024); } while (0)
; template <class Epi, class Sched, bool ALIGN_EPI = false, bool SP2 = false>
; __device__ __forceinline__ void gemm_phase(PG8_LAS unsigned char* lds, const Gemm g, const Sched& S, const Epi& E) {
;     ...
;             PG8_LDA(At, 0, 1); PG8_STAGE(PG8_SB(0, 0), b2, voffB); PG8_STAGE(PG8_SB(0, 1), b2 + hstep, voffB); PG8_STAGE(PG8_SA(0, 0), a2, voffA);
	s_add_i32 m0, s84, 0x2000
	s_nop 0
	global_load_lds_dwordx4 v166, s[82:83]
	s_mov_b64 s[98:99], s[62:63]

; #define PG8_STAGE(bufoff, gbase, voff) do { _Pragma("unroll") for (int _i = 0; _i < 2; ++_i) \
;         __builtin_amdgcn_global_load_lds((const unsigned*)((const char*)(gbase) + (voff)[_i]), (PG8_LAS unsigned*)(lds + (bufoff) + ldsw + _i * 8192), 16, 0, 0); } while (0)
; #define PG8_LDA(dst, b, h) do { _Pragma("unroll") for (int m = 0; m < 4; ++m) _Pragma("unroll") for (int k = 0; k < 2; ++k) dst[m][k] = *(const PG8_LAS bf16x8*)(lds + PG8_SA(b, h) + aoff + m * 2048 + k * 1024); } while (0)
; #define PG8_MMA(ai, bj, At, Bt) do { __builtin_amdgcn_s_setprio(1); _Pragma("unroll") for (int m = 0; m < 4; ++m) _Pragma("unroll") for (int n = 0; n < 2; ++n) _Pragma("unroll") for (int k = 0; k < 2; ++k) \
;         acc[ai][bj][m][n] = __builtin_amdgcn_mfma_f32_16x16x32_bf16(Bt[n][k], At[m][k], acc[ai][bj][m][n], 0, 0, 0); __builtin_amdgcn_s_setprio(0); } while (0)
; #define PG8_WAIT_V(n) asm volatile("s_waitcnt vmcnt(" #n ")" ::: "memory")
; #define PG8_WAIT_L(n) asm volatile("s_waitcnt lgkmcnt(" #n ")" ::: "memory")
; #define PG8_BAR __builtin_amdgcn_s_barrier()
; #define PG8_SCHED __builtin_amdgcn_sched_barrier(0)
; template <class Epi, class Sched, bool ALIGN_EPI = false, bool SP2 = false>
; __device__ __forceinline__ void gemm_phase(PG8_LAS unsigned char* lds, const Gemm g, const Sched& S, const Epi& E) {
;     ...
;             PG8_LDA(At, 0, 1); PG8_STAGE(PG8_SB(0, 0), b2, voffB); PG8_STAGE(PG8_SB(0, 1), b2 + hstep, voffB); PG8_STAGE(PG8_SA(0, 0), a2, voffA);
;             PG8_WAIT_V(8); PG8_WAIT_L(0); PG8_BAR; PG8_MMA(1, 0, At, B0); PG8_MMA(1, 1, At, B1); PG8_BAR; PG8_SCHED;
	s_mov_b32 m0, s57
	s_nop 0
	global_load_lds_dwordx4 v160, s[62:63]
	s_mov_b32 m0, s65
	s_nop 0
	global_load_lds_dwordx4 v164, s[62:63]
	s_waitcnt vmcnt(8)
	s_waitcnt lgkmcnt(0)
	s_barrier
	s_setprio 1
	s_waitcnt lgkmcnt(0)
	v_mfma_f32_16x16x32_bf16 v[60:63], v[64:67], v[176:179], v[60:63]
	v_mfma_f32_16x16x32_bf16 v[56:59], v[72:75], v[176:179], v[56:59]
	v_mfma_f32_16x16x32_bf16 v[44:47], v[64:67], v[184:187], v[44:47]
	v_mfma_f32_16x16x32_bf16 v[40:43], v[72:75], v[184:187], v[40:43]
	v_mfma_f32_16x16x32_bf16 v[28:31], v[64:67], v[192:195], v[28:31]
	v_mfma_f32_16x16x32_bf16 v[24:27], v[72:75], v[192:195], v[24:27]
	v_mfma_f32_16x16x32_bf16 v[12:15], v[64:67], v[200:203], v[12:15]
	v_mfma_f32_16x16x32_bf16 v[8:11], v[72:75], v[200:203], v[8:11]
	v_mfma_f32_16x16x32_bf16 v[60:63], v[68:71], v[180:183], v[60:63]
	v_mfma_f32_16x16x32_bf16 v[56:59], v[76:79], v[180:183], v[56:59]
	v_mfma_f32_16x16x32_bf16 v[44:47], v[68:71], v[188:191], v[44:47]
	v_mfma_f32_16x16x32_bf16 v[40:43], v[76:79], v[188:191], v[40:43]
	v_mfma_f32_16x16x32_bf16 v[28:31], v[68:71], v[196:199], v[28:31]
	v_mfma_f32_16x16x32_bf16 v[24:27], v[76:79], v[196:199], v[24:27]
	v_mfma_f32_16x16x32_bf16 v[12:15], v[68:71], v[204:207], v[12:15]
	v_mfma_f32_16x16x32_bf16 v[8:11], v[76:79], v[204:207], v[8:11]


; #define PG8_STAGE(bufoff, gbase, voff) do { _Pragma("unroll") for (int _i = 0; _i < 2; ++_i) \
;         __builtin_amdgcn_global_load_lds((const unsigned*)((const char*)(gbase) + (voff)[_i]), (PG8_LAS unsigned*)(lds + (bufoff) + ldsw + _i * 8192), 16, 0, 0); } while (0)
; #define PG8_LDA(dst, b, h) do { _Pragma("unroll") for (int m = 0; m < 4; ++m) _Pragma("unroll") for (int k = 0; k < 2; ++k) dst[m][k] = *(const PG8_LAS bf16x8*)(lds + PG8_SA(b, h) + aoff + m * 2048 + k * 1024); } while (0)
; #define PG8_LDB(dst, b, h) do { _Pragma("unroll") for (int n = 0; n < 2; ++n) _Pragma("unroll") for (int k = 0; k < 2; ++k) dst[n][k] = *(const PG8_LAS bf16x8*)(lds + PG8_SB(b, h) + boff + n * 2048 + k * 1024); } while (0)
; #define PG8_MMA(ai, bj, At, Bt) do { __builtin_amdgcn_s_setprio(1); _Pragma("unroll") for (int m = 0; m < 4; ++m) _Pragma("unroll") for (int n = 0; n < 2; ++n) _Pragma("unroll") for (int k = 0; k < 2; ++k) \
;         acc[ai][bj][m][n] = __builtin_amdgcn_mfma_f32_16x16x32_bf16(Bt[n][k], At[m][k], acc[ai][bj][m][n], 0, 0, 0); __builtin_amdgcn_s_setprio(0); } while (0)
; #define PG8_WAIT_V(n) asm volatile("s_waitcnt vmcnt(" #n ")" ::: "memory")
; #define PG8_WAIT_L(n) asm volatile("s_waitcnt lgkmcnt(" #n ")" ::: "memory")
; #define PG8_BAR __builtin_amdgcn_s_barrier()
; #define PG8_SCHED __builtin_amdgcn_sched_barrier(0)
; template <class Epi, class Sched, bool ALIGN_EPI = false, bool SP2 = false>
; __device__ __forceinline__ void gemm_phase(PG8_LAS unsigned char* lds, const Gemm g, const Sched& S, const Epi& E) {
;     ...
;             PG8_WAIT_V(8); PG8_WAIT_L(0); PG8_BAR; PG8_MMA(1, 0, At, B0); PG8_MMA(1, 1, At, B1); PG8_BAR; PG8_SCHED;
;             PG8_LDB(B0, 1, 0); PG8_LDB(B1, 1, 1); PG8_SCHED; PG8_LDA(At, 1, 0); PG8_STAGE(PG8_SA(0, 1), a2 + hstep, voffA);
	v_mfma_f32_16x16x32_bf16 v[52:55], v[144:147], v[176:179], v[52:55]
	v_mfma_f32_16x16x32_bf16 v[48:51], v[152:155], v[176:179], v[48:51]
	v_mfma_f32_16x16x32_bf16 v[36:39], v[144:147], v[184:187], v[36:39]
	v_mfma_f32_16x16x32_bf16 v[32:35], v[152:155], v[184:187], v[32:35]
	v_mfma_f32_16x16x32_bf16 v[20:23], v[144:147], v[192:195], v[20:23]
	v_mfma_f32_16x16x32_bf16 v[16:19], v[152:155], v[192:195], v[16:19]
	v_mfma_f32_16x16x32_bf16 v[4:7], v[144:147], v[200:203], v[4:7]
	v_mfma_f32_16x16x32_bf16 v[0:3], v[152:155], v[200:203], v[0:3]
	v_mfma_f32_16x16x32_bf16 v[52:55], v[148:151], v[180:183], v[52:55]
	v_mfma_f32_16x16x32_bf16 v[48:51], v[156:159], v[180:183], v[48:51]
	v_mfma_f32_16x16x32_bf16 v[36:39], v[148:151], v[188:191], v[36:39]
	v_mfma_f32_16x16x32_bf16 v[32:35], v[156:159], v[188:191], v[32:35]
	v_mfma_f32_16x16x32_bf16 v[20:23], v[148:151], v[196:199], v[20:23]
	v_mfma_f32_16x16x32_bf16 v[16:19], v[156:159], v[196:199], v[16:19]
	v_mfma_f32_16x16x32_bf16 v[4:7], v[148:151], v[204:207], v[4:7]
	v_mfma_f32_16x16x32_bf16 v[0:3], v[156:159], v[204:207], v[0:3]
	s_setprio 0
	s_barrier
	s_add_i32 s82, 0, 0x18000
	s_add_i32 s83, 0, 0x1c000


; #define PG8_STAGE(bufoff, gbase, voff) do { _Pragma("unroll") for (int _i = 0; _i < 2; ++_i) \
;         __builtin_amdgcn_global_load_lds((const unsigned*)((const char*)(gbase) + (voff)[_i]), (PG8_LAS unsigned*)(lds + (bufoff) + ldsw + _i * 8192), 16, 0, 0); } while (0)
; #define PG8_LDA(dst, b, h) do { _Pragma("unroll") for (int m = 0; m < 4; ++m) _Pragma("unroll") for (int k = 0; k < 2; ++k) dst[m][k] = *(const PG8_LAS bf16x8*)(lds + PG8_SA(b, h) + aoff + m * 2048 + k * 1024); } while (0)
; #define PG8_LDB(dst, b, h) do { _Pragma("unroll") for (int n = 0; n < 2; ++n) _Pragma("unroll") for (int k = 0; k < 2; ++k) dst[n][k] = *(const PG8_LAS bf16x8*)(lds + PG8_SB(b, h) + boff + n * 2048 + k * 1024); } while (0)
; #define PG8_SCHED __builtin_amdgcn_sched_barrier(0)
; template <class Epi, class Sched, bool ALIGN_EPI = false, bool SP2 = false>
; __device__ __forceinline__ void gemm_phase(PG8_LAS unsigned char* lds, const Gemm g, const Sched& S, const Epi& E) {
;     ...
;             PG8_LDB(B0, 1, 0); PG8_LDB(B1, 1, 1); PG8_SCHED; PG8_LDA(At, 1, 0); PG8_STAGE(PG8_SA(0, 1), a2 + hstep, voffA);
	ds_read_b128 v[64:67], v254
	ds_read_b128 v[68:71], v254 offset:1024
	ds_read_b128 v[72:75], v254 offset:2048
	ds_read_b128 v[76:79], v254 offset:3072
	ds_read_b128 v[144:147], v255
	ds_read_b128 v[148:151], v255 offset:1024
	ds_read_b128 v[152:155], v255 offset:2048
	ds_read_b128 v[156:159], v255 offset:3072
	s_add_u32 s62, s62, 0x80000
	s_addc_u32 s63, s63, 0
	s_mov_b32 m0, s67

; #define PG8_STAGE(bufoff, gbase, voff) do { _Pragma("unroll") for (int _i = 0; _i < 2; ++_i) \
;         __builtin_amdgcn_global_load_lds((const unsigned*)((const char*)(gbase) + (voff)[_i]), (PG8_LAS unsigned*)(lds + (bufoff) + ldsw + _i * 8192), 16, 0, 0); } while (0)
; #define PG8_LDA(dst, b, h) do { _Pragma("unroll") for (int m = 0; m < 4; ++m) _Pragma("unroll") for (int k = 0; k < 2; ++k) dst[m][k] = *(const PG8_LAS bf16x8*)(lds + PG8_SA(b, h) + aoff + m * 2048 + k * 1024); } while (0)
; #define PG8_LDB(dst, b, h) do { _Pragma("unroll") for (int n = 0; n < 2; ++n) _Pragma("unroll") for (int k = 0; k < 2; ++k) dst[n][k] = *(const PG8_LAS bf16x8*)(lds + PG8_SB(b, h) + boff + n * 2048 + k * 1024); } while (0)
; #define PG8_SCHED __builtin_amdgcn_sched_barrier(0)
; template <class Epi, class Sched, bool ALIGN_EPI = false, bool SP2 = false>
; __device__ __forceinline__ void gemm_phase(PG8_LAS unsigned char* lds, const Gemm g, const Sched& S, const Epi& E) {
;     ...
;             PG8_LDB(B0, 1, 0); PG8_LDB(B1, 1, 1); PG8_SCHED; PG8_LDA(At, 1, 0); PG8_STAGE(PG8_SA(0, 1), a2 + hstep, voffA);
	ds_read_b128 v[176:179], v215 offset:32768
	ds_read_b128 v[180:183], v215 offset:33792
	ds_read_b128 v[184:187], v215 offset:34816
	ds_read_b128 v[188:191], v215 offset:35840
	ds_read_b128 v[192:195], v215 offset:36864
	ds_read_b128 v[196:199], v215 offset:37888
	ds_read_b128 v[200:203], v215 offset:38912
	ds_read_b128 v[204:207], v215 offset:39936
	global_load_lds_dwordx4 v160, s[62:63]

; #define PG8_STAGE(bufoff, gbase, voff) do { _Pragma("unroll") for (int _i = 0; _i < 2; ++_i) \
;         __builtin_amdgcn_global_load_lds((const unsigned*)((const char*)(gbase) + (voff)[_i]), (PG8_LAS unsigned*)(lds + (bufoff) + ldsw + _i * 8192), 16, 0, 0); } while (0)
; #define PG8_LDA(dst, b, h) do { _Pragma("unroll") for (int m = 0; m < 4; ++m) _Pragma("unroll") for (int k = 0; k < 2; ++k) dst[m][k] = *(const PG8_LAS bf16x8*)(lds + PG8_SA(b, h) + aoff + m * 2048 + k * 1024); } while (0)
; #define PG8_LDB(dst, b, h) do { _Pragma("unroll") for (int n = 0; n < 2; ++n) _Pragma("unroll") for (int k = 0; k < 2; ++k) dst[n][k] = *(const PG8_LAS bf16x8*)(lds + PG8_SB(b, h) + boff + n * 2048 + k * 1024); } while (0)
; #define PG8_MMA(ai, bj, At, Bt) do { __builtin_amdgcn_s_setprio(1); _Pragma("unroll") for (int m = 0; m < 4; ++m) _Pragma("unroll") for (int n = 0; n < 2; ++n) _Pragma("unroll") for (int k = 0; k < 2; ++k) \
;         acc[ai][bj][m][n] = __builtin_amdgcn_mfma_f32_16x16x32_bf16(Bt[n][k], At[m][k], acc[ai][bj][m][n], 0, 0, 0); __builtin_amdgcn_s_setprio(0); } while (0)
; #define PG8_WAIT_V(n) asm volatile("s_waitcnt vmcnt(" #n ")" ::: "memory")
; #define PG8_WAIT_L(n) asm volatile("s_waitcnt lgkmcnt(" #n ")" ::: "memory")
; #define PG8_BAR __builtin_amdgcn_s_barrier()
; #define PG8_SCHED __builtin_amdgcn_sched_barrier(0)
; template <class Epi, class Sched, bool ALIGN_EPI = false, bool SP2 = false>
; __device__ __forceinline__ void gemm_phase(PG8_LAS unsigned char* lds, const Gemm g, const Sched& S, const Epi& E) {
;     ...
;             PG8_LDB(B0, 1, 0); PG8_LDB(B1, 1, 1); PG8_SCHED; PG8_LDA(At, 1, 0); PG8_STAGE(PG8_SA(0, 1), a2 + hstep, voffA);
;             PG8_WAIT_V(8); PG8_WAIT_L(0); PG8_BAR; PG8_MMA(0, 0, At, B0); PG8_MMA(0, 1, At, B1); PG8_BAR; PG8_SCHED;
	s_mov_b32 m0, s68
	s_nop 0
	global_load_lds_dwordx4 v164, s[62:63]
	s_waitcnt vmcnt(8)
	s_waitcnt lgkmcnt(0)
	s_barrier
	s_setprio 1
	s_waitcnt lgkmcnt(0)
	v_mfma_f32_16x16x32_bf16 v[140:143], v[64:67], v[176:179], v[140:143]
	v_mfma_f32_16x16x32_bf16 v[136:139], v[72:75], v[176:179], v[136:139]
	v_mfma_f32_16x16x32_bf16 v[124:127], v[64:67], v[184:187], v[124:127]
	v_mfma_f32_16x16x32_bf16 v[120:123], v[72:75], v[184:187], v[120:123]
	v_mfma_f32_16x16x32_bf16 v[108:111], v[64:67], v[192:195], v[108:111]
	v_mfma_f32_16x16x32_bf16 v[104:107], v[72:75], v[192:195], v[104:107]
	v_mfma_f32_16x16x32_bf16 v[92:95], v[64:67], v[200:203], v[92:95]
	v_mfma_f32_16x16x32_bf16 v[88:91], v[72:75], v[200:203], v[88:91]
	v_mfma_f32_16x16x32_bf16 v[140:143], v[68:71], v[180:183], v[140:143]
	v_mfma_f32_16x16x32_bf16 v[136:139], v[76:79], v[180:183], v[136:139]
	v_mfma_f32_16x16x32_bf16 v[124:127], v[68:71], v[188:191], v[124:127]
	v_mfma_f32_16x16x32_bf16 v[120:123], v[76:79], v[188:191], v[120:123]
	v_mfma_f32_16x16x32_bf16 v[108:111], v[68:71], v[196:199], v[108:111]
	v_mfma_f32_16x16x32_bf16 v[104:107], v[76:79], v[196:199], v[104:107]
	v_mfma_f32_16x16x32_bf16 v[92:95], v[68:71], v[204:207], v[92:95]
	v_mfma_f32_16x16x32_bf16 v[88:91], v[76:79], v[204:207], v[88:91]


; #define PG8_STAGE(bufoff, gbase, voff) do { _Pragma("unroll") for (int _i = 0; _i < 2; ++_i) \
;         __builtin_amdgcn_global_load_lds((const unsigned*)((const char*)(gbase) + (voff)[_i]), (PG8_LAS unsigned*)(lds + (bufoff) + ldsw + _i * 8192), 16, 0, 0); } while (0)
; #define PG8_LDA(dst, b, h) do { _Pragma("unroll") for (int m = 0; m < 4; ++m) _Pragma("unroll") for (int k = 0; k < 2; ++k) dst[m][k] = *(const PG8_LAS bf16x8*)(lds + PG8_SA(b, h) + aoff + m * 2048 + k * 1024); } while (0)
; #define PG8_MMA(ai, bj, At, Bt) do { __builtin_amdgcn_s_setprio(1); _Pragma("unroll") for (int m = 0; m < 4; ++m) _Pragma("unroll") for (int n = 0; n < 2; ++n) _Pragma("unroll") for (int k = 0; k < 2; ++k) \
;         acc[ai][bj][m][n] = __builtin_amdgcn_mfma_f32_16x16x32_bf16(Bt[n][k], At[m][k], acc[ai][bj][m][n], 0, 0, 0); __builtin_amdgcn_s_setprio(0); } while (0)
; #define PG8_WAIT_V(n) asm volatile("s_waitcnt vmcnt(" #n ")" ::: "memory")
; #define PG8_WAIT_L(n) asm volatile("s_waitcnt lgkmcnt(" #n ")" ::: "memory")
; #define PG8_BAR __builtin_amdgcn_s_barrier()
; #define PG8_SCHED __builtin_amdgcn_sched_barrier(0)
; template <class Epi, class Sched, bool ALIGN_EPI = false, bool SP2 = false>
; __device__ __forceinline__ void gemm_phase(PG8_LAS unsigned char* lds, const Gemm g, const Sched& S, const Epi& E) {
;     ...
;             PG8_WAIT_V(8); PG8_WAIT_L(0); PG8_BAR; PG8_MMA(0, 0, At, B0); PG8_MMA(0, 1, At, B1); PG8_BAR; PG8_SCHED;
;             PG8_LDA(At, 1, 1); PG8_STAGE(PG8_SB(1, 0), b3, voffB); PG8_STAGE(PG8_SB(1, 1), b3 + hstep, voffB); PG8_STAGE(PG8_SA(1, 0), a3, voffA);
	v_mfma_f32_16x16x32_bf16 v[132:135], v[144:147], v[176:179], v[132:135]
	v_mfma_f32_16x16x32_bf16 v[128:131], v[152:155], v[176:179], v[128:131]
	v_mfma_f32_16x16x32_bf16 v[116:119], v[144:147], v[184:187], v[116:119]
	v_mfma_f32_16x16x32_bf16 v[112:115], v[152:155], v[184:187], v[112:115]
	v_mfma_f32_16x16x32_bf16 v[100:103], v[144:147], v[192:195], v[100:103]
	v_mfma_f32_16x16x32_bf16 v[96:99], v[152:155], v[192:195], v[96:99]
	v_mfma_f32_16x16x32_bf16 v[84:87], v[144:147], v[200:203], v[84:87]
	v_mfma_f32_16x16x32_bf16 v[80:83], v[152:155], v[200:203], v[80:83]
	v_mfma_f32_16x16x32_bf16 v[132:135], v[148:151], v[180:183], v[132:135]
	v_mfma_f32_16x16x32_bf16 v[128:131], v[156:159], v[180:183], v[128:131]
	v_mfma_f32_16x16x32_bf16 v[116:119], v[148:151], v[188:191], v[116:119]
	v_mfma_f32_16x16x32_bf16 v[112:115], v[156:159], v[188:191], v[112:115]
	v_mfma_f32_16x16x32_bf16 v[100:103], v[148:151], v[196:199], v[100:103]
	v_mfma_f32_16x16x32_bf16 v[96:99], v[156:159], v[196:199], v[96:99]
	v_mfma_f32_16x16x32_bf16 v[84:87], v[148:151], v[204:207], v[84:87]
	v_mfma_f32_16x16x32_bf16 v[80:83], v[156:159], v[204:207], v[80:83]
	s_setprio 0
	s_barrier
	s_add_i32 s62, s82, s64

; #define PG8_STAGE(bufoff, gbase, voff) do { _Pragma("unroll") for (int _i = 0; _i < 2; ++_i) \
;         __builtin_amdgcn_global_load_lds((const unsigned*)((const char*)(gbase) + (voff)[_i]), (PG8_LAS unsigned*)(lds + (bufoff) + ldsw + _i * 8192), 16, 0, 0); } while (0)
; #define PG8_LDA(dst, b, h) do { _Pragma("unroll") for (int m = 0; m < 4; ++m) _Pragma("unroll") for (int k = 0; k < 2; ++k) dst[m][k] = *(const PG8_LAS bf16x8*)(lds + PG8_SA(b, h) + aoff + m * 2048 + k * 1024); } while (0)
; template <class Epi, class Sched, bool ALIGN_EPI = false, bool SP2 = false>
; __device__ __forceinline__ void gemm_phase(PG8_LAS unsigned char* lds, const Gemm g, const Sched& S, const Epi& E) {
;     ...
;             PG8_LDA(At, 1, 1); PG8_STAGE(PG8_SB(1, 0), b3, voffB); PG8_STAGE(PG8_SB(1, 1), b3 + hstep, voffB); PG8_STAGE(PG8_SA(1, 0), a3, voffA);
	s_mov_b32 m0, s62
	ds_read_b128 v[176:179], v215 offset:49152
	ds_read_b128 v[180:183], v215 offset:50176
	ds_read_b128 v[184:187], v215 offset:51200
	ds_read_b128 v[188:191], v215 offset:52224
	ds_read_b128 v[192:195], v215 offset:53248
	ds_read_b128 v[196:199], v215 offset:54272
	ds_read_b128 v[200:203], v215 offset:55296
	ds_read_b128 v[204:207], v215 offset:56320
	global_load_lds_dwordx4 v250, s[96:97]
	s_add_i32 m0, s62, 0x2000
	s_add_u32 s60, s60, 0x80080

; #define PG8_STAGE(bufoff, gbase, voff) do { _Pragma("unroll") for (int _i = 0; _i < 2; ++_i) \
;         __builtin_amdgcn_global_load_lds((const unsigned*)((const char*)(gbase) + (voff)[_i]), (PG8_LAS unsigned*)(lds + (bufoff) + ldsw + _i * 8192), 16, 0, 0); } while (0)
; #define PG8_LDA(dst, b, h) do { _Pragma("unroll") for (int m = 0; m < 4; ++m) _Pragma("unroll") for (int k = 0; k < 2; ++k) dst[m][k] = *(const PG8_LAS bf16x8*)(lds + PG8_SA(b, h) + aoff + m * 2048 + k * 1024); } while (0)
; template <class Epi, class Sched, bool ALIGN_EPI = false, bool SP2 = false>
; __device__ __forceinline__ void gemm_phase(PG8_LAS unsigned char* lds, const Gemm g, const Sched& S, const Epi& E) {
;     ...
;             PG8_LDA(At, 1, 1); PG8_STAGE(PG8_SB(1, 0), b3, voffB); PG8_STAGE(PG8_SB(1, 1), b3 + hstep, voffB); PG8_STAGE(PG8_SA(1, 0), a3, voffA);
	s_addc_u32 s61, s61, 0
	s_add_i32 s62, s83, s64
	global_load_lds_dwordx4 v251, s[96:97]

; #define PG8_STAGE(bufoff, gbase, voff) do { _Pragma("unroll") for (int _i = 0; _i < 2; ++_i) \
;         __builtin_amdgcn_global_load_lds((const unsigned*)((const char*)(gbase) + (voff)[_i]), (PG8_LAS unsigned*)(lds + (bufoff) + ldsw + _i * 8192), 16, 0, 0); } while (0)
; #define PG8_LDA(dst, b, h) do { _Pragma("unroll") for (int m = 0; m < 4; ++m) _Pragma("unroll") for (int k = 0; k < 2; ++k) dst[m][k] = *(const PG8_LAS bf16x8*)(lds + PG8_SA(b, h) + aoff + m * 2048 + k * 1024); } while (0)
; template <class Epi, class Sched, bool ALIGN_EPI = false, bool SP2 = false>
; __device__ __forceinline__ void gemm_phase(PG8_LAS unsigned char* lds, const Gemm g, const Sched& S, const Epi& E) {
;     ...
;             PG8_LDA(At, 1, 1); PG8_STAGE(PG8_SB(1, 0), b3, voffB); PG8_STAGE(PG8_SB(1, 1), b3 + hstep, voffB); PG8_STAGE(PG8_SA(1, 0), a3, voffA);
	s_mov_b32 m0, s62
	s_nop 0
	global_load_lds_dwordx4 v162, s[60:61]

; #define PG8_STAGE(bufoff, gbase, voff) do { _Pragma("unroll") for (int _i = 0; _i < 2; ++_i) \
;         __builtin_amdgcn_global_load_lds((const unsigned*)((const char*)(gbase) + (voff)[_i]), (PG8_LAS unsigned*)(lds + (bufoff) + ldsw + _i * 8192), 16, 0, 0); } while (0)
; #define PG8_LDA(dst, b, h) do { _Pragma("unroll") for (int m = 0; m < 4; ++m) _Pragma("unroll") for (int k = 0; k < 2; ++k) dst[m][k] = *(const PG8_LAS bf16x8*)(lds + PG8_SA(b, h) + aoff + m * 2048 + k * 1024); } while (0)
; template <class Epi, class Sched, bool ALIGN_EPI = false, bool SP2 = false>
; __device__ __forceinline__ void gemm_phase(PG8_LAS unsigned char* lds, const Gemm g, const Sched& S, const Epi& E) {
;     ...
;             PG8_LDA(At, 1, 1); PG8_STAGE(PG8_SB(1, 0), b3, voffB); PG8_STAGE(PG8_SB(1, 1), b3 + hstep, voffB); PG8_STAGE(PG8_SA(1, 0), a3, voffA);
	s_add_i32 m0, s62, 0x2000
	s_nop 0
	global_load_lds_dwordx4 v166, s[60:61]

; #define PG8_STAGE(bufoff, gbase, voff) do { _Pragma("unroll") for (int _i = 0; _i < 2; ++_i) \
;         __builtin_amdgcn_global_load_lds((const unsigned*)((const char*)(gbase) + (voff)[_i]), (PG8_LAS unsigned*)(lds + (bufoff) + ldsw + _i * 8192), 16, 0, 0); } while (0)
; #define PG8_LDA(dst, b, h) do { _Pragma("unroll") for (int m = 0; m < 4; ++m) _Pragma("unroll") for (int k = 0; k < 2; ++k) dst[m][k] = *(const PG8_LAS bf16x8*)(lds + PG8_SA(b, h) + aoff + m * 2048 + k * 1024); } while (0)
; template <class Epi, class Sched, bool ALIGN_EPI = false, bool SP2 = false>
; __device__ __forceinline__ void gemm_phase(PG8_LAS unsigned char* lds, const Gemm g, const Sched& S, const Epi& E) {
;     ...
;             PG8_LDA(At, 1, 1); PG8_STAGE(PG8_SB(1, 0), b3, voffB); PG8_STAGE(PG8_SB(1, 1), b3 + hstep, voffB); PG8_STAGE(PG8_SA(1, 0), a3, voffA);
	s_mov_b32 m0, s70
	s_nop 0
	global_load_lds_dwordx4 v252, s[98:99]

; #define PG8_STAGE(bufoff, gbase, voff) do { _Pragma("unroll") for (int _i = 0; _i < 2; ++_i) \
;         __builtin_amdgcn_global_load_lds((const unsigned*)((const char*)(gbase) + (voff)[_i]), (PG8_LAS unsigned*)(lds + (bufoff) + ldsw + _i * 8192), 16, 0, 0); } while (0)
; #define PG8_LDA(dst, b, h) do { _Pragma("unroll") for (int m = 0; m < 4; ++m) _Pragma("unroll") for (int k = 0; k < 2; ++k) dst[m][k] = *(const PG8_LAS bf16x8*)(lds + PG8_SA(b, h) + aoff + m * 2048 + k * 1024); } while (0)
; #define PG8_MMA(ai, bj, At, Bt) do { __builtin_amdgcn_s_setprio(1); _Pragma("unroll") for (int m = 0; m < 4; ++m) _Pragma("unroll") for (int n = 0; n < 2; ++n) _Pragma("unroll") for (int k = 0; k < 2; ++k) \
;         acc[ai][bj][m][n] = __builtin_amdgcn_mfma_f32_16x16x32_bf16(Bt[n][k], At[m][k], acc[ai][bj][m][n], 0, 0, 0); __builtin_amdgcn_s_setprio(0); } while (0)
; #define PG8_WAIT_V(n) asm volatile("s_waitcnt vmcnt(" #n ")" ::: "memory")
; #define PG8_WAIT_L(n) asm volatile("s_waitcnt lgkmcnt(" #n ")" ::: "memory")
; #define PG8_BAR __builtin_amdgcn_s_barrier()
; #define PG8_SCHED __builtin_amdgcn_sched_barrier(0)
; template <class Epi, class Sched, bool ALIGN_EPI = false, bool SP2 = false>
; __device__ __forceinline__ void gemm_phase(PG8_LAS unsigned char* lds, const Gemm g, const Sched& S, const Epi& E) {
;     ...
;             PG8_LDA(At, 1, 1); PG8_STAGE(PG8_SB(1, 0), b3, voffB); PG8_STAGE(PG8_SB(1, 1), b3 + hstep, voffB); PG8_STAGE(PG8_SA(1, 0), a3, voffA);
;             PG8_WAIT_V(8); PG8_WAIT_L(0); PG8_BAR; PG8_MMA(1, 0, At, B0); PG8_MMA(1, 1, At, B1); PG8_BAR; PG8_SCHED;
	s_mov_b32 m0, s71
	s_nop 0
	global_load_lds_dwordx4 v253, s[98:99]
	s_waitcnt vmcnt(8)
	s_waitcnt lgkmcnt(0)
	s_barrier
	s_setprio 1
	s_waitcnt lgkmcnt(0)
	v_mfma_f32_16x16x32_bf16 v[60:63], v[64:67], v[176:179], v[60:63]
	v_mfma_f32_16x16x32_bf16 v[56:59], v[72:75], v[176:179], v[56:59]
	v_mfma_f32_16x16x32_bf16 v[44:47], v[64:67], v[184:187], v[44:47]
	v_mfma_f32_16x16x32_bf16 v[40:43], v[72:75], v[184:187], v[40:43]
	v_mfma_f32_16x16x32_bf16 v[28:31], v[64:67], v[192:195], v[28:31]
	v_mfma_f32_16x16x32_bf16 v[24:27], v[72:75], v[192:195], v[24:27]
	v_mfma_f32_16x16x32_bf16 v[12:15], v[64:67], v[200:203], v[12:15]
	v_mfma_f32_16x16x32_bf16 v[8:11], v[72:75], v[200:203], v[8:11]
	v_mfma_f32_16x16x32_bf16 v[60:63], v[68:71], v[180:183], v[60:63]
	v_mfma_f32_16x16x32_bf16 v[56:59], v[76:79], v[180:183], v[56:59]
	v_mfma_f32_16x16x32_bf16 v[44:47], v[68:71], v[188:191], v[44:47]
	v_mfma_f32_16x16x32_bf16 v[40:43], v[76:79], v[188:191], v[40:43]
	v_mfma_f32_16x16x32_bf16 v[28:31], v[68:71], v[196:199], v[28:31]
	v_mfma_f32_16x16x32_bf16 v[24:27], v[76:79], v[196:199], v[24:27]
	v_mfma_f32_16x16x32_bf16 v[12:15], v[68:71], v[204:207], v[12:15]
	v_mfma_f32_16x16x32_bf16 v[8:11], v[76:79], v[204:207], v[8:11]


; #define PG8_MMA(ai, bj, At, Bt) do { __builtin_amdgcn_s_setprio(1); _Pragma("unroll") for (int m = 0; m < 4; ++m) _Pragma("unroll") for (int n = 0; n < 2; ++n) _Pragma("unroll") for (int k = 0; k < 2; ++k) \
;         acc[ai][bj][m][n] = __builtin_amdgcn_mfma_f32_16x16x32_bf16(Bt[n][k], At[m][k], acc[ai][bj][m][n], 0, 0, 0); __builtin_amdgcn_s_setprio(0); } while (0)
; #define PG8_WAIT_V(n) asm volatile("s_waitcnt vmcnt(" #n ")" ::: "memory")
; #define PG8_WAIT_L(n) asm volatile("s_waitcnt lgkmcnt(" #n ")" ::: "memory")
; #define PG8_BAR __builtin_amdgcn_s_barrier()
; #define PG8_SCHED __builtin_amdgcn_sched_barrier(0)
; template <class Epi, class Sched, bool ALIGN_EPI = false, bool SP2 = false>
; __device__ __forceinline__ void gemm_phase(PG8_LAS unsigned char* lds, const Gemm g, const Sched& S, const Epi& E) {
;     ...
;         for (int t = 0; t < nt; t += 2) {
;     ...
;             PG8_WAIT_V(8); PG8_WAIT_L(0); PG8_BAR; PG8_MMA(1, 0, At, B0); PG8_MMA(1, 1, At, B1); PG8_BAR; PG8_SCHED;
;     ...
;         if constexpr (ALIGN_EPI) { if (wr == 0) PG8_BAR; }
	v_mfma_f32_16x16x32_bf16 v[52:55], v[144:147], v[176:179], v[52:55]
	v_mfma_f32_16x16x32_bf16 v[48:51], v[152:155], v[176:179], v[48:51]
	v_mfma_f32_16x16x32_bf16 v[36:39], v[144:147], v[184:187], v[36:39]
	v_mfma_f32_16x16x32_bf16 v[32:35], v[152:155], v[184:187], v[32:35]
	v_mfma_f32_16x16x32_bf16 v[20:23], v[144:147], v[192:195], v[20:23]
	v_mfma_f32_16x16x32_bf16 v[16:19], v[152:155], v[192:195], v[16:19]
	v_mfma_f32_16x16x32_bf16 v[4:7], v[144:147], v[200:203], v[4:7]
	v_mfma_f32_16x16x32_bf16 v[0:3], v[152:155], v[200:203], v[0:3]
	v_mfma_f32_16x16x32_bf16 v[52:55], v[148:151], v[180:183], v[52:55]
	v_mfma_f32_16x16x32_bf16 v[48:51], v[156:159], v[180:183], v[48:51]
	v_mfma_f32_16x16x32_bf16 v[36:39], v[148:151], v[188:191], v[36:39]
	v_mfma_f32_16x16x32_bf16 v[32:35], v[156:159], v[188:191], v[32:35]
	v_mfma_f32_16x16x32_bf16 v[20:23], v[148:151], v[196:199], v[20:23]
	v_mfma_f32_16x16x32_bf16 v[16:19], v[156:159], v[196:199], v[16:19]
	v_mfma_f32_16x16x32_bf16 v[4:7], v[148:151], v[204:207], v[4:7]
	v_mfma_f32_16x16x32_bf16 v[0:3], v[156:159], v[204:207], v[0:3]
	s_setprio 0
	s_barrier
	s_add_i32 s81, s81, 2
	s_add_u32 s58, s58, 0x100
	s_addc_u32 s59, s59, 0
	s_add_u32 s79, s79, 0x100
	s_addc_u32 s80, s80, 0
	s_cmp_gt_u32 s81, 29
	s_cbranch_scc0 .LBB0_939
	s_and_b64 vcc, exec, s[42:43]
	s_cbranch_vccz .LBB0_942
	s_barrier

; #define PG8_STAGE(bufoff, gbase, voff) do { _Pragma("unroll") for (int _i = 0; _i < 2; ++_i) \
;         __builtin_amdgcn_global_load_lds((const unsigned*)((const char*)(gbase) + (voff)[_i]), (PG8_LAS unsigned*)(lds + (bufoff) + ldsw + _i * 8192), 16, 0, 0); } while (0)
; #define PG8_LDA(dst, b, h) do { _Pragma("unroll") for (int m = 0; m < 4; ++m) _Pragma("unroll") for (int k = 0; k < 2; ++k) dst[m][k] = *(const PG8_LAS bf16x8*)(lds + PG8_SA(b, h) + aoff + m * 2048 + k * 1024); } while (0)
; #define PG8_LDB(dst, b, h) do { _Pragma("unroll") for (int n = 0; n < 2; ++n) _Pragma("unroll") for (int k = 0; k < 2; ++k) dst[n][k] = *(const PG8_LAS bf16x8*)(lds + PG8_SB(b, h) + boff + n * 2048 + k * 1024); } while (0)
; #define PG8_SCHED __builtin_amdgcn_sched_barrier(0)
; template <class Epi, class Sched, bool ALIGN_EPI = false, bool SP2 = false>
; __device__ __forceinline__ void gemm_phase(PG8_LAS unsigned char* lds, const Gemm g, const Sched& S, const Epi& E) {
;     ...
;     for (;;) {
;         const bool has_next = S.next(ui + 1, nxt);
;         const char* nA = has_next ? (const char*)g.A + (size_t)nxt.pm * tstep : cA; const char* nB = has_next ? (const char*)g.Bt + (size_t)nxt.pn * tstep : cB;
;         for (int t = 0; t < nt; t += 2) {
;             const bool last = (t == nt - 2);
;             const char* a1 = cA + (size_t)(t + 1) * kstep;
;             const char* a2 = last ? nA : cA + (size_t)(t + 2) * kstep; const char* b2 = last ? nB : cB + (size_t)(t + 2) * kstep;
;             const char* a3 = a2 + kstep; const char* b3 = b2 + kstep;
;             if (last && has_next) S.a_ready(nxt);
;             if constexpr (SP2) {
;             PG8_LDB(B0, 0, 0); PG8_LDB(B1, 0, 1); PG8_SCHED; PG8_LDA(At, 0, 0); PG8_STAGE(PG8_SA(1, 1), a1 + hstep, voffA);
;     ...
; #pragma unroll
;         for (int a = 0; a < 2; ++a)
; #pragma unroll
;             for (int b = 0; b < 2; ++b)
; #pragma unroll
;                 for (int m = 0; m < 4; ++m)
; #pragma unroll
;                     for (int n = 0; n < 2; ++n) acc[a][b][m][n] = (f32x4){0.f, 0.f, 0.f, 0.f};
;         cur = nxt; cA = nA; cB = nB; ++ui;
.LBB0_1033:
	s_ashr_i32 s53, s52, 31
	s_lshl_b64 s[54:55], s[52:53], 20
	s_add_u32 s54, s24, s54
	s_addc_u32 s55, s25, s55
	s_and_b64 s[56:57], s[4:5], exec
	s_cselect_b32 s53, s55, s11
	s_cselect_b32 s79, s54, s10
	s_ashr_i32 s51, s50, 31
	s_lshl_b64 s[56:57], s[50:51], 20
	s_add_u32 s56, s60, s56
	s_addc_u32 s57, s61, s57
	s_and_b64 s[58:59], s[4:5], exec
	s_cselect_b32 s51, s57, s13
	s_cselect_b32 s80, s56, s12
	s_add_u32 s10, s10, 0x80080
	s_addc_u32 s11, s11, 0
	s_add_u32 s81, s12, 0x100
	v_mov_b32_e32 v0, 0
	s_addc_u32 s82, s13, 0
	s_mov_b32 s83, -2
	v_mov_b32_e32 v1, v0
	v_mov_b32_e32 v2, v0
	v_mov_b32_e32 v3, v0
	v_mov_b32_e32 v4, v0
	v_mov_b32_e32 v5, v0
	v_mov_b32_e32 v6, v0
	v_mov_b32_e32 v7, v0
	v_mov_b32_e32 v16, v0
	v_mov_b32_e32 v17, v0
	v_mov_b32_e32 v18, v0
	v_mov_b32_e32 v19, v0
	v_mov_b32_e32 v20, v0
	v_mov_b32_e32 v21, v0
	v_mov_b32_e32 v22, v0
	v_mov_b32_e32 v23, v0
	v_mov_b32_e32 v32, v0
	v_mov_b32_e32 v33, v0
	v_mov_b32_e32 v34, v0
	v_mov_b32_e32 v35, v0
	v_mov_b32_e32 v36, v0
	v_mov_b32_e32 v37, v0
	v_mov_b32_e32 v38, v0
	v_mov_b32_e32 v39, v0
	v_mov_b32_e32 v48, v0
	v_mov_b32_e32 v49, v0
	v_mov_b32_e32 v50, v0
	v_mov_b32_e32 v51, v0
	v_mov_b32_e32 v52, v0
	v_mov_b32_e32 v53, v0
	v_mov_b32_e32 v54, v0
	v_mov_b32_e32 v55, v0
	v_mov_b32_e32 v8, v0
	v_mov_b32_e32 v9, v0
	v_mov_b32_e32 v10, v0
	v_mov_b32_e32 v11, v0
	v_mov_b32_e32 v12, v0
	v_mov_b32_e32 v13, v0
	v_mov_b32_e32 v14, v0
	v_mov_b32_e32 v15, v0
	v_mov_b32_e32 v24, v0
	v_mov_b32_e32 v25, v0
	v_mov_b32_e32 v26, v0
	v_mov_b32_e32 v27, v0
	v_mov_b32_e32 v28, v0
	v_mov_b32_e32 v29, v0
	v_mov_b32_e32 v30, v0
	v_mov_b32_e32 v31, v0
	v_mov_b32_e32 v40, v0
	v_mov_b32_e32 v41, v0
	v_mov_b32_e32 v42, v0
	v_mov_b32_e32 v43, v0
	v_mov_b32_e32 v44, v0
	v_mov_b32_e32 v45, v0
	v_mov_b32_e32 v46, v0
	v_mov_b32_e32 v47, v0
	v_mov_b32_e32 v56, v0
	v_mov_b32_e32 v57, v0
	v_mov_b32_e32 v58, v0
	v_mov_b32_e32 v59, v0
	v_mov_b32_e32 v60, v0
	v_mov_b32_e32 v61, v0
	v_mov_b32_e32 v62, v0
	v_mov_b32_e32 v63, v0
	v_mov_b32_e32 v64, v0
	v_mov_b32_e32 v65, v0
	v_mov_b32_e32 v66, v0
	v_mov_b32_e32 v67, v0
	v_mov_b32_e32 v68, v0
	v_mov_b32_e32 v69, v0
	v_mov_b32_e32 v70, v0
	v_mov_b32_e32 v71, v0
	v_mov_b32_e32 v80, v0
	v_mov_b32_e32 v81, v0
	v_mov_b32_e32 v82, v0
	v_mov_b32_e32 v83, v0
	v_mov_b32_e32 v84, v0
	v_mov_b32_e32 v85, v0
	v_mov_b32_e32 v86, v0
	v_mov_b32_e32 v87, v0
	v_mov_b32_e32 v96, v0
	v_mov_b32_e32 v97, v0
	v_mov_b32_e32 v98, v0
	v_mov_b32_e32 v99, v0
	v_mov_b32_e32 v100, v0
	v_mov_b32_e32 v101, v0
	v_mov_b32_e32 v102, v0
	v_mov_b32_e32 v103, v0
	v_mov_b32_e32 v112, v0
	v_mov_b32_e32 v113, v0
	v_mov_b32_e32 v114, v0
	v_mov_b32_e32 v115, v0
	v_mov_b32_e32 v116, v0
	v_mov_b32_e32 v117, v0
	v_mov_b32_e32 v118, v0
	v_mov_b32_e32 v119, v0
	v_mov_b32_e32 v72, v0
	v_mov_b32_e32 v73, v0
	v_mov_b32_e32 v74, v0
	v_mov_b32_e32 v75, v0
	v_mov_b32_e32 v76, v0
	v_mov_b32_e32 v77, v0
	v_mov_b32_e32 v78, v0
	v_mov_b32_e32 v79, v0
	v_mov_b32_e32 v88, v0
	v_mov_b32_e32 v89, v0
	v_mov_b32_e32 v90, v0
	v_mov_b32_e32 v91, v0
	v_mov_b32_e32 v92, v0
	v_mov_b32_e32 v93, v0
	v_mov_b32_e32 v94, v0
	v_mov_b32_e32 v95, v0
	v_mov_b32_e32 v104, v0
	v_mov_b32_e32 v105, v0
	v_mov_b32_e32 v106, v0
	v_mov_b32_e32 v107, v0
	v_mov_b32_e32 v108, v0
	v_mov_b32_e32 v109, v0
	v_mov_b32_e32 v110, v0
	v_mov_b32_e32 v111, v0
	v_mov_b32_e32 v120, v0
	v_mov_b32_e32 v121, v0
	v_mov_b32_e32 v122, v0
	v_mov_b32_e32 v123, v0
	v_mov_b32_e32 v124, v0
	v_mov_b32_e32 v125, v0
	v_mov_b32_e32 v126, v0
	v_mov_b32_e32 v127, v0
	v_add_u32_e32 v255, 0x1c000, v189
	v_add_u32_e32 v254, 0x18000, v189
	v_add_u32_e32 v253, 0x80, v164
	v_add_u32_e32 v252, 0x80, v160
	v_add_u32_e32 v251, 0x80, v166
	v_add_u32_e32 v250, 0x80, v162
.LBB0_1034:
	ds_read_b128 v[128:131], v201
	ds_read_b128 v[132:135], v201 offset:1024
	ds_read_b128 v[136:139], v201 offset:2048
	ds_read_b128 v[140:143], v201 offset:3072
	ds_read_b128 v[144:147], v205
	ds_read_b128 v[148:151], v205 offset:1024
	ds_read_b128 v[152:155], v205 offset:2048
	ds_read_b128 v[156:159], v205 offset:3072
	s_add_u32 s12, s10, 0xfff80080
	s_addc_u32 s13, s11, -1
	s_cmp_eq_u32 s83, 28
	s_cselect_b32 s59, s53, s13
	s_cselect_b32 s58, s79, s12
	s_cselect_b32 s13, s51, s82
	s_cselect_b32 s12, s80, s81

; #define PG8_STAGE(bufoff, gbase, voff) do { _Pragma("unroll") for (int _i = 0; _i < 2; ++_i) \
;         __builtin_amdgcn_global_load_lds((const unsigned*)((const char*)(gbase) + (voff)[_i]), (PG8_LAS unsigned*)(lds + (bufoff) + ldsw + _i * 8192), 16, 0, 0); } while (0)
; #define PG8_LDA(dst, b, h) do { _Pragma("unroll") for (int m = 0; m < 4; ++m) _Pragma("unroll") for (int k = 0; k < 2; ++k) dst[m][k] = *(const PG8_LAS bf16x8*)(lds + PG8_SA(b, h) + aoff + m * 2048 + k * 1024); } while (0)
; #define PG8_LDB(dst, b, h) do { _Pragma("unroll") for (int n = 0; n < 2; ++n) _Pragma("unroll") for (int k = 0; k < 2; ++k) dst[n][k] = *(const PG8_LAS bf16x8*)(lds + PG8_SB(b, h) + boff + n * 2048 + k * 1024); } while (0)
; #define PG8_MMA(ai, bj, At, Bt) do { __builtin_amdgcn_s_setprio(1); _Pragma("unroll") for (int m = 0; m < 4; ++m) _Pragma("unroll") for (int n = 0; n < 2; ++n) _Pragma("unroll") for (int k = 0; k < 2; ++k) \
;         acc[ai][bj][m][n] = __builtin_amdgcn_mfma_f32_16x16x32_bf16(Bt[n][k], At[m][k], acc[ai][bj][m][n], 0, 0, 0); __builtin_amdgcn_s_setprio(0); } while (0)
; #define PG8_WAIT_V(n) asm volatile("s_waitcnt vmcnt(" #n ")" ::: "memory")
; #define PG8_WAIT_L(n) asm volatile("s_waitcnt lgkmcnt(" #n ")" ::: "memory")
; #define PG8_BAR __builtin_amdgcn_s_barrier()
; #define PG8_SCHED __builtin_amdgcn_sched_barrier(0)
; template <class Epi, class Sched, bool ALIGN_EPI = false, bool SP2 = false>
; __device__ __forceinline__ void gemm_phase(PG8_LAS unsigned char* lds, const Gemm g, const Sched& S, const Epi& E) {
;     ...
;             PG8_LDB(B0, 0, 0); PG8_LDB(B1, 0, 1); PG8_SCHED; PG8_LDA(At, 0, 0); PG8_STAGE(PG8_SA(1, 1), a1 + hstep, voffA);
;             PG8_WAIT_V(8); PG8_WAIT_L(0); PG8_BAR; PG8_MMA(0, 0, At, B0); PG8_MMA(0, 1, At, B1); PG8_BAR; PG8_SCHED;
	s_add_i32 m0, s63, 0xc000
	ds_read_b128 v[176:179], v207
	ds_read_b128 v[184:187], v207 offset:1024
	ds_read_b128 v[190:193], v207 offset:2048
	ds_read_b128 v[210:213], v207 offset:3072
	ds_read_b128 v[214:217], v207 offset:4096
	ds_read_b128 v[218:221], v207 offset:5120
	ds_read_b128 v[222:225], v207 offset:6144
	ds_read_b128 v[226:229], v207 offset:7168
	global_load_lds_dwordx4 v168, s[10:11]

; #define PG8_STAGE(bufoff, gbase, voff) do { _Pragma("unroll") for (int _i = 0; _i < 2; ++_i) \
;         __builtin_amdgcn_global_load_lds((const unsigned*)((const char*)(gbase) + (voff)[_i]), (PG8_LAS unsigned*)(lds + (bufoff) + ldsw + _i * 8192), 16, 0, 0); } while (0)
; #define PG8_LDA(dst, b, h) do { _Pragma("unroll") for (int m = 0; m < 4; ++m) _Pragma("unroll") for (int k = 0; k < 2; ++k) dst[m][k] = *(const PG8_LAS bf16x8*)(lds + PG8_SA(b, h) + aoff + m * 2048 + k * 1024); } while (0)
; #define PG8_LDB(dst, b, h) do { _Pragma("unroll") for (int n = 0; n < 2; ++n) _Pragma("unroll") for (int k = 0; k < 2; ++k) dst[n][k] = *(const PG8_LAS bf16x8*)(lds + PG8_SB(b, h) + boff + n * 2048 + k * 1024); } while (0)
; #define PG8_MMA(ai, bj, At, Bt) do { __builtin_amdgcn_s_setprio(1); _Pragma("unroll") for (int m = 0; m < 4; ++m) _Pragma("unroll") for (int n = 0; n < 2; ++n) _Pragma("unroll") for (int k = 0; k < 2; ++k) \
;         acc[ai][bj][m][n] = __builtin_amdgcn_mfma_f32_16x16x32_bf16(Bt[n][k], At[m][k], acc[ai][bj][m][n], 0, 0, 0); __builtin_amdgcn_s_setprio(0); } while (0)
; #define PG8_WAIT_V(n) asm volatile("s_waitcnt vmcnt(" #n ")" ::: "memory")
; #define PG8_WAIT_L(n) asm volatile("s_waitcnt lgkmcnt(" #n ")" ::: "memory")
; #define PG8_BAR __builtin_amdgcn_s_barrier()
; #define PG8_SCHED __builtin_amdgcn_sched_barrier(0)
; template <class Epi, class Sched, bool ALIGN_EPI = false, bool SP2 = false>
; __device__ __forceinline__ void gemm_phase(PG8_LAS unsigned char* lds, const Gemm g, const Sched& S, const Epi& E) {
;     ...
;             PG8_LDB(B0, 0, 0); PG8_LDB(B1, 0, 1); PG8_SCHED; PG8_LDA(At, 0, 0); PG8_STAGE(PG8_SA(1, 1), a1 + hstep, voffA);
;             PG8_WAIT_V(8); PG8_WAIT_L(0); PG8_BAR; PG8_MMA(0, 0, At, B0); PG8_MMA(0, 1, At, B1); PG8_BAR; PG8_SCHED;
	s_add_i32 m0, s63, 0xe000
	s_nop 0
	global_load_lds_dwordx4 v170, s[10:11]
	s_waitcnt vmcnt(8)
	s_waitcnt lgkmcnt(0)
	s_barrier
	s_setprio 1
	s_waitcnt lgkmcnt(0)
	v_mfma_f32_16x16x32_bf16 v[124:127], v[128:131], v[176:179], v[124:127]
	v_mfma_f32_16x16x32_bf16 v[120:123], v[136:139], v[176:179], v[120:123]
	v_mfma_f32_16x16x32_bf16 v[108:111], v[128:131], v[190:193], v[108:111]
	v_mfma_f32_16x16x32_bf16 v[104:107], v[136:139], v[190:193], v[104:107]
	v_mfma_f32_16x16x32_bf16 v[92:95], v[128:131], v[214:217], v[92:95]
	v_mfma_f32_16x16x32_bf16 v[88:91], v[136:139], v[214:217], v[88:91]
	v_mfma_f32_16x16x32_bf16 v[76:79], v[128:131], v[222:225], v[76:79]
	v_mfma_f32_16x16x32_bf16 v[72:75], v[136:139], v[222:225], v[72:75]
	v_mfma_f32_16x16x32_bf16 v[124:127], v[132:135], v[184:187], v[124:127]
	v_mfma_f32_16x16x32_bf16 v[120:123], v[140:143], v[184:187], v[120:123]
	v_mfma_f32_16x16x32_bf16 v[108:111], v[132:135], v[210:213], v[108:111]
	v_mfma_f32_16x16x32_bf16 v[104:107], v[140:143], v[210:213], v[104:107]
	v_mfma_f32_16x16x32_bf16 v[92:95], v[132:135], v[218:221], v[92:95]
	v_mfma_f32_16x16x32_bf16 v[88:91], v[140:143], v[218:221], v[88:91]
	v_mfma_f32_16x16x32_bf16 v[76:79], v[132:135], v[226:229], v[76:79]
	v_mfma_f32_16x16x32_bf16 v[72:75], v[140:143], v[226:229], v[72:75]


; #define PG8_STAGE(bufoff, gbase, voff) do { _Pragma("unroll") for (int _i = 0; _i < 2; ++_i) \
;         __builtin_amdgcn_global_load_lds((const unsigned*)((const char*)(gbase) + (voff)[_i]), (PG8_LAS unsigned*)(lds + (bufoff) + ldsw + _i * 8192), 16, 0, 0); } while (0)
; #define PG8_LDA(dst, b, h) do { _Pragma("unroll") for (int m = 0; m < 4; ++m) _Pragma("unroll") for (int k = 0; k < 2; ++k) dst[m][k] = *(const PG8_LAS bf16x8*)(lds + PG8_SA(b, h) + aoff + m * 2048 + k * 1024); } while (0)
; #define PG8_MMA(ai, bj, At, Bt) do { __builtin_amdgcn_s_setprio(1); _Pragma("unroll") for (int m = 0; m < 4; ++m) _Pragma("unroll") for (int n = 0; n < 2; ++n) _Pragma("unroll") for (int k = 0; k < 2; ++k) \
;         acc[ai][bj][m][n] = __builtin_amdgcn_mfma_f32_16x16x32_bf16(Bt[n][k], At[m][k], acc[ai][bj][m][n], 0, 0, 0); __builtin_amdgcn_s_setprio(0); } while (0)
; #define PG8_WAIT_V(n) asm volatile("s_waitcnt vmcnt(" #n ")" ::: "memory")
; #define PG8_WAIT_L(n) asm volatile("s_waitcnt lgkmcnt(" #n ")" ::: "memory")
; #define PG8_BAR __builtin_amdgcn_s_barrier()
; #define PG8_SCHED __builtin_amdgcn_sched_barrier(0)
; template <class Epi, class Sched, bool ALIGN_EPI = false, bool SP2 = false>
; __device__ __forceinline__ void gemm_phase(PG8_LAS unsigned char* lds, const Gemm g, const Sched& S, const Epi& E) {
;     ...
;             PG8_WAIT_V(8); PG8_WAIT_L(0); PG8_BAR; PG8_MMA(0, 0, At, B0); PG8_MMA(0, 1, At, B1); PG8_BAR; PG8_SCHED;
;             PG8_LDA(At, 0, 1); PG8_STAGE(PG8_SB(0, 0), b2, voffB); PG8_STAGE(PG8_SB(0, 1), b2 + hstep, voffB); PG8_STAGE(PG8_SA(0, 0), a2, voffA);
	v_mfma_f32_16x16x32_bf16 v[116:119], v[144:147], v[176:179], v[116:119]
	v_mfma_f32_16x16x32_bf16 v[112:115], v[152:155], v[176:179], v[112:115]
	v_mfma_f32_16x16x32_bf16 v[100:103], v[144:147], v[190:193], v[100:103]
	v_mfma_f32_16x16x32_bf16 v[96:99], v[152:155], v[190:193], v[96:99]
	v_mfma_f32_16x16x32_bf16 v[84:87], v[144:147], v[214:217], v[84:87]
	v_mfma_f32_16x16x32_bf16 v[80:83], v[152:155], v[214:217], v[80:83]
	v_mfma_f32_16x16x32_bf16 v[68:71], v[144:147], v[222:225], v[68:71]
	v_mfma_f32_16x16x32_bf16 v[64:67], v[152:155], v[222:225], v[64:67]
	v_mfma_f32_16x16x32_bf16 v[116:119], v[148:151], v[184:187], v[116:119]
	v_mfma_f32_16x16x32_bf16 v[112:115], v[156:159], v[184:187], v[112:115]
	v_mfma_f32_16x16x32_bf16 v[100:103], v[148:151], v[210:213], v[100:103]
	v_mfma_f32_16x16x32_bf16 v[96:99], v[156:159], v[210:213], v[96:99]
	v_mfma_f32_16x16x32_bf16 v[84:87], v[148:151], v[218:221], v[84:87]
	v_mfma_f32_16x16x32_bf16 v[80:83], v[156:159], v[218:221], v[80:83]
	v_mfma_f32_16x16x32_bf16 v[68:71], v[148:151], v[226:229], v[68:71]
	v_mfma_f32_16x16x32_bf16 v[64:67], v[156:159], v[226:229], v[64:67]
	s_setprio 0
	s_barrier
	s_add_i32 s84, s73, s62
	s_mov_b64 s[96:97], s[12:13]

; #define PG8_STAGE(bufoff, gbase, voff) do { _Pragma("unroll") for (int _i = 0; _i < 2; ++_i) \
;         __builtin_amdgcn_global_load_lds((const unsigned*)((const char*)(gbase) + (voff)[_i]), (PG8_LAS unsigned*)(lds + (bufoff) + ldsw + _i * 8192), 16, 0, 0); } while (0)
; #define PG8_LDA(dst, b, h) do { _Pragma("unroll") for (int m = 0; m < 4; ++m) _Pragma("unroll") for (int k = 0; k < 2; ++k) dst[m][k] = *(const PG8_LAS bf16x8*)(lds + PG8_SA(b, h) + aoff + m * 2048 + k * 1024); } while (0)
; template <class Epi, class Sched, bool ALIGN_EPI = false, bool SP2 = false>
; __device__ __forceinline__ void gemm_phase(PG8_LAS unsigned char* lds, const Gemm g, const Sched& S, const Epi& E) {
;     ...
;             PG8_LDA(At, 0, 1); PG8_STAGE(PG8_SB(0, 0), b2, voffB); PG8_STAGE(PG8_SB(0, 1), b2 + hstep, voffB); PG8_STAGE(PG8_SA(0, 0), a2, voffA);
	s_mov_b32 m0, s84
	ds_read_b128 v[176:179], v207 offset:16384
	ds_read_b128 v[184:187], v207 offset:17408
	ds_read_b128 v[190:193], v207 offset:18432
	ds_read_b128 v[210:213], v207 offset:19456
	ds_read_b128 v[214:217], v207 offset:20480
	ds_read_b128 v[218:221], v207 offset:21504
	ds_read_b128 v[222:225], v207 offset:22528
	ds_read_b128 v[226:229], v207 offset:23552
	global_load_lds_dwordx4 v162, s[12:13]
	s_add_i32 m0, s84, 0x2000
	s_add_u32 s84, s12, 0x80000

; #define PG8_STAGE(bufoff, gbase, voff) do { _Pragma("unroll") for (int _i = 0; _i < 2; ++_i) \
;         __builtin_amdgcn_global_load_lds((const unsigned*)((const char*)(gbase) + (voff)[_i]), (PG8_LAS unsigned*)(lds + (bufoff) + ldsw + _i * 8192), 16, 0, 0); } while (0)
; #define PG8_LDA(dst, b, h) do { _Pragma("unroll") for (int m = 0; m < 4; ++m) _Pragma("unroll") for (int k = 0; k < 2; ++k) dst[m][k] = *(const PG8_LAS bf16x8*)(lds + PG8_SA(b, h) + aoff + m * 2048 + k * 1024); } while (0)
; template <class Epi, class Sched, bool ALIGN_EPI = false, bool SP2 = false>
; __device__ __forceinline__ void gemm_phase(PG8_LAS unsigned char* lds, const Gemm g, const Sched& S, const Epi& E) {
;     ...
;             PG8_LDA(At, 0, 1); PG8_STAGE(PG8_SB(0, 0), b2, voffB); PG8_STAGE(PG8_SB(0, 1), b2 + hstep, voffB); PG8_STAGE(PG8_SA(0, 0), a2, voffA);
	s_addc_u32 s85, s13, 0
	s_add_i32 s86, s74, s62
	global_load_lds_dwordx4 v166, s[12:13]

; #define PG8_STAGE(bufoff, gbase, voff) do { _Pragma("unroll") for (int _i = 0; _i < 2; ++_i) \
;         __builtin_amdgcn_global_load_lds((const unsigned*)((const char*)(gbase) + (voff)[_i]), (PG8_LAS unsigned*)(lds + (bufoff) + ldsw + _i * 8192), 16, 0, 0); } while (0)
; #define PG8_LDA(dst, b, h) do { _Pragma("unroll") for (int m = 0; m < 4; ++m) _Pragma("unroll") for (int k = 0; k < 2; ++k) dst[m][k] = *(const PG8_LAS bf16x8*)(lds + PG8_SA(b, h) + aoff + m * 2048 + k * 1024); } while (0)
; template <class Epi, class Sched, bool ALIGN_EPI = false, bool SP2 = false>
; __device__ __forceinline__ void gemm_phase(PG8_LAS unsigned char* lds, const Gemm g, const Sched& S, const Epi& E) {
;     ...
;             PG8_LDA(At, 0, 1); PG8_STAGE(PG8_SB(0, 0), b2, voffB); PG8_STAGE(PG8_SB(0, 1), b2 + hstep, voffB); PG8_STAGE(PG8_SA(0, 0), a2, voffA);
	s_mov_b32 m0, s86
	s_nop 0
	global_load_lds_dwordx4 v162, s[84:85]

; #define PG8_STAGE(bufoff, gbase, voff) do { _Pragma("unroll") for (int _i = 0; _i < 2; ++_i) \
;         __builtin_amdgcn_global_load_lds((const unsigned*)((const char*)(gbase) + (voff)[_i]), (PG8_LAS unsigned*)(lds + (bufoff) + ldsw + _i * 8192), 16, 0, 0); } while (0)
; #define PG8_LDA(dst, b, h) do { _Pragma("unroll") for (int m = 0; m < 4; ++m) _Pragma("unroll") for (int k = 0; k < 2; ++k) dst[m][k] = *(const PG8_LAS bf16x8*)(lds + PG8_SA(b, h) + aoff + m * 2048 + k * 1024); } while (0)
; template <class Epi, class Sched, bool ALIGN_EPI = false, bool SP2 = false>
; __device__ __forceinline__ void gemm_phase(PG8_LAS unsigned char* lds, const Gemm g, const Sched& S, const Epi& E) {
;     ...
;             PG8_LDA(At, 0, 1); PG8_STAGE(PG8_SB(0, 0), b2, voffB); PG8_STAGE(PG8_SB(0, 1), b2 + hstep, voffB); PG8_STAGE(PG8_SA(0, 0), a2, voffA);
	s_add_i32 m0, s86, 0x2000
	s_nop 0
	global_load_lds_dwordx4 v166, s[84:85]
	s_mov_b64 s[98:99], s[58:59]

; #define PG8_STAGE(bufoff, gbase, voff) do { _Pragma("unroll") for (int _i = 0; _i < 2; ++_i) \
;         __builtin_amdgcn_global_load_lds((const unsigned*)((const char*)(gbase) + (voff)[_i]), (PG8_LAS unsigned*)(lds + (bufoff) + ldsw + _i * 8192), 16, 0, 0); } while (0)
; #define PG8_LDA(dst, b, h) do { _Pragma("unroll") for (int m = 0; m < 4; ++m) _Pragma("unroll") for (int k = 0; k < 2; ++k) dst[m][k] = *(const PG8_LAS bf16x8*)(lds + PG8_SA(b, h) + aoff + m * 2048 + k * 1024); } while (0)
; #define PG8_MMA(ai, bj, At, Bt) do { __builtin_amdgcn_s_setprio(1); _Pragma("unroll") for (int m = 0; m < 4; ++m) _Pragma("unroll") for (int n = 0; n < 2; ++n) _Pragma("unroll") for (int k = 0; k < 2; ++k) \
;         acc[ai][bj][m][n] = __builtin_amdgcn_mfma_f32_16x16x32_bf16(Bt[n][k], At[m][k], acc[ai][bj][m][n], 0, 0, 0); __builtin_amdgcn_s_setprio(0); } while (0)
; #define PG8_WAIT_V(n) asm volatile("s_waitcnt vmcnt(" #n ")" ::: "memory")
; #define PG8_WAIT_L(n) asm volatile("s_waitcnt lgkmcnt(" #n ")" ::: "memory")
; #define PG8_BAR __builtin_amdgcn_s_barrier()
; #define PG8_SCHED __builtin_amdgcn_sched_barrier(0)
; template <class Epi, class Sched, bool ALIGN_EPI = false, bool SP2 = false>
; __device__ __forceinline__ void gemm_phase(PG8_LAS unsigned char* lds, const Gemm g, const Sched& S, const Epi& E) {
;     ...
;             PG8_LDA(At, 0, 1); PG8_STAGE(PG8_SB(0, 0), b2, voffB); PG8_STAGE(PG8_SB(0, 1), b2 + hstep, voffB); PG8_STAGE(PG8_SA(0, 0), a2, voffA);
;             PG8_WAIT_V(8); PG8_WAIT_L(0); PG8_BAR; PG8_MMA(1, 0, At, B0); PG8_MMA(1, 1, At, B1); PG8_BAR; PG8_SCHED;
	s_mov_b32 m0, s63
	s_nop 0
	global_load_lds_dwordx4 v160, s[58:59]
	s_mov_b32 m0, s64
	s_nop 0
	global_load_lds_dwordx4 v164, s[58:59]
	s_waitcnt vmcnt(8)
	s_waitcnt lgkmcnt(0)
	s_barrier
	s_setprio 1
	s_waitcnt lgkmcnt(0)
	v_mfma_f32_16x16x32_bf16 v[60:63], v[128:131], v[176:179], v[60:63]
	v_mfma_f32_16x16x32_bf16 v[56:59], v[136:139], v[176:179], v[56:59]
	v_mfma_f32_16x16x32_bf16 v[44:47], v[128:131], v[190:193], v[44:47]
	v_mfma_f32_16x16x32_bf16 v[40:43], v[136:139], v[190:193], v[40:43]
	v_mfma_f32_16x16x32_bf16 v[28:31], v[128:131], v[214:217], v[28:31]
	v_mfma_f32_16x16x32_bf16 v[24:27], v[136:139], v[214:217], v[24:27]
	v_mfma_f32_16x16x32_bf16 v[12:15], v[128:131], v[222:225], v[12:15]
	v_mfma_f32_16x16x32_bf16 v[8:11], v[136:139], v[222:225], v[8:11]
	v_mfma_f32_16x16x32_bf16 v[60:63], v[132:135], v[184:187], v[60:63]
	v_mfma_f32_16x16x32_bf16 v[56:59], v[140:143], v[184:187], v[56:59]
	v_mfma_f32_16x16x32_bf16 v[44:47], v[132:135], v[210:213], v[44:47]
	v_mfma_f32_16x16x32_bf16 v[40:43], v[140:143], v[210:213], v[40:43]
	v_mfma_f32_16x16x32_bf16 v[28:31], v[132:135], v[218:221], v[28:31]
	v_mfma_f32_16x16x32_bf16 v[24:27], v[140:143], v[218:221], v[24:27]
	v_mfma_f32_16x16x32_bf16 v[12:15], v[132:135], v[226:229], v[12:15]
	v_mfma_f32_16x16x32_bf16 v[8:11], v[140:143], v[226:229], v[8:11]


; #define PG8_STAGE(bufoff, gbase, voff) do { _Pragma("unroll") for (int _i = 0; _i < 2; ++_i) \
;         __builtin_amdgcn_global_load_lds((const unsigned*)((const char*)(gbase) + (voff)[_i]), (PG8_LAS unsigned*)(lds + (bufoff) + ldsw + _i * 8192), 16, 0, 0); } while (0)
; #define PG8_LDA(dst, b, h) do { _Pragma("unroll") for (int m = 0; m < 4; ++m) _Pragma("unroll") for (int k = 0; k < 2; ++k) dst[m][k] = *(const PG8_LAS bf16x8*)(lds + PG8_SA(b, h) + aoff + m * 2048 + k * 1024); } while (0)
; #define PG8_LDB(dst, b, h) do { _Pragma("unroll") for (int n = 0; n < 2; ++n) _Pragma("unroll") for (int k = 0; k < 2; ++k) dst[n][k] = *(const PG8_LAS bf16x8*)(lds + PG8_SB(b, h) + boff + n * 2048 + k * 1024); } while (0)
; #define PG8_MMA(ai, bj, At, Bt) do { __builtin_amdgcn_s_setprio(1); _Pragma("unroll") for (int m = 0; m < 4; ++m) _Pragma("unroll") for (int n = 0; n < 2; ++n) _Pragma("unroll") for (int k = 0; k < 2; ++k) \
;         acc[ai][bj][m][n] = __builtin_amdgcn_mfma_f32_16x16x32_bf16(Bt[n][k], At[m][k], acc[ai][bj][m][n], 0, 0, 0); __builtin_amdgcn_s_setprio(0); } while (0)
; #define PG8_WAIT_V(n) asm volatile("s_waitcnt vmcnt(" #n ")" ::: "memory")
; #define PG8_WAIT_L(n) asm volatile("s_waitcnt lgkmcnt(" #n ")" ::: "memory")
; #define PG8_BAR __builtin_amdgcn_s_barrier()
; #define PG8_SCHED __builtin_amdgcn_sched_barrier(0)
; template <class Epi, class Sched, bool ALIGN_EPI = false, bool SP2 = false>
; __device__ __forceinline__ void gemm_phase(PG8_LAS unsigned char* lds, const Gemm g, const Sched& S, const Epi& E) {
;     ...
;             PG8_WAIT_V(8); PG8_WAIT_L(0); PG8_BAR; PG8_MMA(1, 0, At, B0); PG8_MMA(1, 1, At, B1); PG8_BAR; PG8_SCHED;
;             PG8_LDB(B0, 1, 0); PG8_LDB(B1, 1, 1); PG8_SCHED; PG8_LDA(At, 1, 0); PG8_STAGE(PG8_SA(0, 1), a2 + hstep, voffA);
	v_mfma_f32_16x16x32_bf16 v[52:55], v[144:147], v[176:179], v[52:55]
	v_mfma_f32_16x16x32_bf16 v[48:51], v[152:155], v[176:179], v[48:51]
	v_mfma_f32_16x16x32_bf16 v[36:39], v[144:147], v[190:193], v[36:39]
	v_mfma_f32_16x16x32_bf16 v[32:35], v[152:155], v[190:193], v[32:35]
	v_mfma_f32_16x16x32_bf16 v[20:23], v[144:147], v[214:217], v[20:23]
	v_mfma_f32_16x16x32_bf16 v[16:19], v[152:155], v[214:217], v[16:19]
	v_mfma_f32_16x16x32_bf16 v[4:7], v[144:147], v[222:225], v[4:7]
	v_mfma_f32_16x16x32_bf16 v[0:3], v[152:155], v[222:225], v[0:3]
	v_mfma_f32_16x16x32_bf16 v[52:55], v[148:151], v[184:187], v[52:55]
	v_mfma_f32_16x16x32_bf16 v[48:51], v[156:159], v[184:187], v[48:51]
	v_mfma_f32_16x16x32_bf16 v[36:39], v[148:151], v[210:213], v[36:39]
	v_mfma_f32_16x16x32_bf16 v[32:35], v[156:159], v[210:213], v[32:35]
	v_mfma_f32_16x16x32_bf16 v[20:23], v[148:151], v[218:221], v[20:23]
	v_mfma_f32_16x16x32_bf16 v[16:19], v[156:159], v[218:221], v[16:19]
	v_mfma_f32_16x16x32_bf16 v[4:7], v[148:151], v[226:229], v[4:7]
	v_mfma_f32_16x16x32_bf16 v[0:3], v[156:159], v[226:229], v[0:3]
	s_setprio 0
	s_barrier
	s_add_i32 s84, 0, 0x18000
	s_add_i32 s85, 0, 0x1c000


; #define PG8_STAGE(bufoff, gbase, voff) do { _Pragma("unroll") for (int _i = 0; _i < 2; ++_i) \
;         __builtin_amdgcn_global_load_lds((const unsigned*)((const char*)(gbase) + (voff)[_i]), (PG8_LAS unsigned*)(lds + (bufoff) + ldsw + _i * 8192), 16, 0, 0); } while (0)
; #define PG8_LDA(dst, b, h) do { _Pragma("unroll") for (int m = 0; m < 4; ++m) _Pragma("unroll") for (int k = 0; k < 2; ++k) dst[m][k] = *(const PG8_LAS bf16x8*)(lds + PG8_SA(b, h) + aoff + m * 2048 + k * 1024); } while (0)
; #define PG8_LDB(dst, b, h) do { _Pragma("unroll") for (int n = 0; n < 2; ++n) _Pragma("unroll") for (int k = 0; k < 2; ++k) dst[n][k] = *(const PG8_LAS bf16x8*)(lds + PG8_SB(b, h) + boff + n * 2048 + k * 1024); } while (0)
; #define PG8_SCHED __builtin_amdgcn_sched_barrier(0)
; template <class Epi, class Sched, bool ALIGN_EPI = false, bool SP2 = false>
; __device__ __forceinline__ void gemm_phase(PG8_LAS unsigned char* lds, const Gemm g, const Sched& S, const Epi& E) {
;     ...
;             PG8_LDB(B0, 1, 0); PG8_LDB(B1, 1, 1); PG8_SCHED; PG8_LDA(At, 1, 0); PG8_STAGE(PG8_SA(0, 1), a2 + hstep, voffA);
	ds_read_b128 v[128:131], v254
	ds_read_b128 v[132:135], v254 offset:1024
	ds_read_b128 v[136:139], v254 offset:2048
	ds_read_b128 v[140:143], v254 offset:3072
	ds_read_b128 v[144:147], v255
	ds_read_b128 v[148:151], v255 offset:1024
	ds_read_b128 v[152:155], v255 offset:2048
	ds_read_b128 v[156:159], v255 offset:3072
	s_add_u32 s58, s58, 0x80000
	s_addc_u32 s59, s59, 0
	s_mov_b32 m0, s65

; #define PG8_STAGE(bufoff, gbase, voff) do { _Pragma("unroll") for (int _i = 0; _i < 2; ++_i) \
;         __builtin_amdgcn_global_load_lds((const unsigned*)((const char*)(gbase) + (voff)[_i]), (PG8_LAS unsigned*)(lds + (bufoff) + ldsw + _i * 8192), 16, 0, 0); } while (0)
; #define PG8_LDA(dst, b, h) do { _Pragma("unroll") for (int m = 0; m < 4; ++m) _Pragma("unroll") for (int k = 0; k < 2; ++k) dst[m][k] = *(const PG8_LAS bf16x8*)(lds + PG8_SA(b, h) + aoff + m * 2048 + k * 1024); } while (0)
; #define PG8_LDB(dst, b, h) do { _Pragma("unroll") for (int n = 0; n < 2; ++n) _Pragma("unroll") for (int k = 0; k < 2; ++k) dst[n][k] = *(const PG8_LAS bf16x8*)(lds + PG8_SB(b, h) + boff + n * 2048 + k * 1024); } while (0)
; #define PG8_SCHED __builtin_amdgcn_sched_barrier(0)
; template <class Epi, class Sched, bool ALIGN_EPI = false, bool SP2 = false>
; __device__ __forceinline__ void gemm_phase(PG8_LAS unsigned char* lds, const Gemm g, const Sched& S, const Epi& E) {
;     ...
;             PG8_LDB(B0, 1, 0); PG8_LDB(B1, 1, 1); PG8_SCHED; PG8_LDA(At, 1, 0); PG8_STAGE(PG8_SA(0, 1), a2 + hstep, voffA);
	ds_read_b128 v[176:179], v207 offset:32768
	ds_read_b128 v[184:187], v207 offset:33792
	ds_read_b128 v[190:193], v207 offset:34816
	ds_read_b128 v[210:213], v207 offset:35840
	ds_read_b128 v[214:217], v207 offset:36864
	ds_read_b128 v[218:221], v207 offset:37888
	ds_read_b128 v[222:225], v207 offset:38912
	ds_read_b128 v[226:229], v207 offset:39936
	global_load_lds_dwordx4 v160, s[58:59]

; #define PG8_STAGE(bufoff, gbase, voff) do { _Pragma("unroll") for (int _i = 0; _i < 2; ++_i) \
;         __builtin_amdgcn_global_load_lds((const unsigned*)((const char*)(gbase) + (voff)[_i]), (PG8_LAS unsigned*)(lds + (bufoff) + ldsw + _i * 8192), 16, 0, 0); } while (0)
; #define PG8_LDA(dst, b, h) do { _Pragma("unroll") for (int m = 0; m < 4; ++m) _Pragma("unroll") for (int k = 0; k < 2; ++k) dst[m][k] = *(const PG8_LAS bf16x8*)(lds + PG8_SA(b, h) + aoff + m * 2048 + k * 1024); } while (0)
; #define PG8_LDB(dst, b, h) do { _Pragma("unroll") for (int n = 0; n < 2; ++n) _Pragma("unroll") for (int k = 0; k < 2; ++k) dst[n][k] = *(const PG8_LAS bf16x8*)(lds + PG8_SB(b, h) + boff + n * 2048 + k * 1024); } while (0)
; #define PG8_MMA(ai, bj, At, Bt) do { __builtin_amdgcn_s_setprio(1); _Pragma("unroll") for (int m = 0; m < 4; ++m) _Pragma("unroll") for (int n = 0; n < 2; ++n) _Pragma("unroll") for (int k = 0; k < 2; ++k) \
;         acc[ai][bj][m][n] = __builtin_amdgcn_mfma_f32_16x16x32_bf16(Bt[n][k], At[m][k], acc[ai][bj][m][n], 0, 0, 0); __builtin_amdgcn_s_setprio(0); } while (0)
; #define PG8_WAIT_V(n) asm volatile("s_waitcnt vmcnt(" #n ")" ::: "memory")
; #define PG8_WAIT_L(n) asm volatile("s_waitcnt lgkmcnt(" #n ")" ::: "memory")
; #define PG8_BAR __builtin_amdgcn_s_barrier()
; #define PG8_SCHED __builtin_amdgcn_sched_barrier(0)
; template <class Epi, class Sched, bool ALIGN_EPI = false, bool SP2 = false>
; __device__ __forceinline__ void gemm_phase(PG8_LAS unsigned char* lds, const Gemm g, const Sched& S, const Epi& E) {
;     ...
;             PG8_LDB(B0, 1, 0); PG8_LDB(B1, 1, 1); PG8_SCHED; PG8_LDA(At, 1, 0); PG8_STAGE(PG8_SA(0, 1), a2 + hstep, voffA);
;             PG8_WAIT_V(8); PG8_WAIT_L(0); PG8_BAR; PG8_MMA(0, 0, At, B0); PG8_MMA(0, 1, At, B1); PG8_BAR; PG8_SCHED;
	s_mov_b32 m0, s67
	s_nop 0
	global_load_lds_dwordx4 v164, s[58:59]
	s_waitcnt vmcnt(8)
	s_waitcnt lgkmcnt(0)
	s_barrier
	s_setprio 1
	s_waitcnt lgkmcnt(0)
	v_mfma_f32_16x16x32_bf16 v[124:127], v[128:131], v[176:179], v[124:127]
	v_mfma_f32_16x16x32_bf16 v[120:123], v[136:139], v[176:179], v[120:123]
	v_mfma_f32_16x16x32_bf16 v[108:111], v[128:131], v[190:193], v[108:111]
	v_mfma_f32_16x16x32_bf16 v[104:107], v[136:139], v[190:193], v[104:107]
	v_mfma_f32_16x16x32_bf16 v[92:95], v[128:131], v[214:217], v[92:95]
	v_mfma_f32_16x16x32_bf16 v[88:91], v[136:139], v[214:217], v[88:91]
	v_mfma_f32_16x16x32_bf16 v[76:79], v[128:131], v[222:225], v[76:79]
	v_mfma_f32_16x16x32_bf16 v[72:75], v[136:139], v[222:225], v[72:75]
	v_mfma_f32_16x16x32_bf16 v[124:127], v[132:135], v[184:187], v[124:127]
	v_mfma_f32_16x16x32_bf16 v[120:123], v[140:143], v[184:187], v[120:123]
	v_mfma_f32_16x16x32_bf16 v[108:111], v[132:135], v[210:213], v[108:111]
	v_mfma_f32_16x16x32_bf16 v[104:107], v[140:143], v[210:213], v[104:107]
	v_mfma_f32_16x16x32_bf16 v[92:95], v[132:135], v[218:221], v[92:95]
	v_mfma_f32_16x16x32_bf16 v[88:91], v[140:143], v[218:221], v[88:91]
	v_mfma_f32_16x16x32_bf16 v[76:79], v[132:135], v[226:229], v[76:79]
	v_mfma_f32_16x16x32_bf16 v[72:75], v[140:143], v[226:229], v[72:75]


; #define PG8_STAGE(bufoff, gbase, voff) do { _Pragma("unroll") for (int _i = 0; _i < 2; ++_i) \
;         __builtin_amdgcn_global_load_lds((const unsigned*)((const char*)(gbase) + (voff)[_i]), (PG8_LAS unsigned*)(lds + (bufoff) + ldsw + _i * 8192), 16, 0, 0); } while (0)
; #define PG8_LDA(dst, b, h) do { _Pragma("unroll") for (int m = 0; m < 4; ++m) _Pragma("unroll") for (int k = 0; k < 2; ++k) dst[m][k] = *(const PG8_LAS bf16x8*)(lds + PG8_SA(b, h) + aoff + m * 2048 + k * 1024); } while (0)
; #define PG8_MMA(ai, bj, At, Bt) do { __builtin_amdgcn_s_setprio(1); _Pragma("unroll") for (int m = 0; m < 4; ++m) _Pragma("unroll") for (int n = 0; n < 2; ++n) _Pragma("unroll") for (int k = 0; k < 2; ++k) \
;         acc[ai][bj][m][n] = __builtin_amdgcn_mfma_f32_16x16x32_bf16(Bt[n][k], At[m][k], acc[ai][bj][m][n], 0, 0, 0); __builtin_amdgcn_s_setprio(0); } while (0)
; #define PG8_WAIT_V(n) asm volatile("s_waitcnt vmcnt(" #n ")" ::: "memory")
; #define PG8_WAIT_L(n) asm volatile("s_waitcnt lgkmcnt(" #n ")" ::: "memory")
; #define PG8_BAR __builtin_amdgcn_s_barrier()
; #define PG8_SCHED __builtin_amdgcn_sched_barrier(0)
; template <class Epi, class Sched, bool ALIGN_EPI = false, bool SP2 = false>
; __device__ __forceinline__ void gemm_phase(PG8_LAS unsigned char* lds, const Gemm g, const Sched& S, const Epi& E) {
;     ...
;             PG8_WAIT_V(8); PG8_WAIT_L(0); PG8_BAR; PG8_MMA(0, 0, At, B0); PG8_MMA(0, 1, At, B1); PG8_BAR; PG8_SCHED;
;             PG8_LDA(At, 1, 1); PG8_STAGE(PG8_SB(1, 0), b3, voffB); PG8_STAGE(PG8_SB(1, 1), b3 + hstep, voffB); PG8_STAGE(PG8_SA(1, 0), a3, voffA);
	v_mfma_f32_16x16x32_bf16 v[116:119], v[144:147], v[176:179], v[116:119]
	v_mfma_f32_16x16x32_bf16 v[112:115], v[152:155], v[176:179], v[112:115]
	v_mfma_f32_16x16x32_bf16 v[100:103], v[144:147], v[190:193], v[100:103]
	v_mfma_f32_16x16x32_bf16 v[96:99], v[152:155], v[190:193], v[96:99]
	v_mfma_f32_16x16x32_bf16 v[84:87], v[144:147], v[214:217], v[84:87]
	v_mfma_f32_16x16x32_bf16 v[80:83], v[152:155], v[214:217], v[80:83]
	v_mfma_f32_16x16x32_bf16 v[68:71], v[144:147], v[222:225], v[68:71]
	v_mfma_f32_16x16x32_bf16 v[64:67], v[152:155], v[222:225], v[64:67]
	v_mfma_f32_16x16x32_bf16 v[116:119], v[148:151], v[184:187], v[116:119]
	v_mfma_f32_16x16x32_bf16 v[112:115], v[156:159], v[184:187], v[112:115]
	v_mfma_f32_16x16x32_bf16 v[100:103], v[148:151], v[210:213], v[100:103]
	v_mfma_f32_16x16x32_bf16 v[96:99], v[156:159], v[210:213], v[96:99]
	v_mfma_f32_16x16x32_bf16 v[84:87], v[148:151], v[218:221], v[84:87]
	v_mfma_f32_16x16x32_bf16 v[80:83], v[156:159], v[218:221], v[80:83]
	v_mfma_f32_16x16x32_bf16 v[68:71], v[148:151], v[226:229], v[68:71]
	v_mfma_f32_16x16x32_bf16 v[64:67], v[156:159], v[226:229], v[64:67]
	s_setprio 0
	s_barrier
	s_add_i32 s58, s84, s62

; #define PG8_STAGE(bufoff, gbase, voff) do { _Pragma("unroll") for (int _i = 0; _i < 2; ++_i) \
;         __builtin_amdgcn_global_load_lds((const unsigned*)((const char*)(gbase) + (voff)[_i]), (PG8_LAS unsigned*)(lds + (bufoff) + ldsw + _i * 8192), 16, 0, 0); } while (0)
; #define PG8_LDA(dst, b, h) do { _Pragma("unroll") for (int m = 0; m < 4; ++m) _Pragma("unroll") for (int k = 0; k < 2; ++k) dst[m][k] = *(const PG8_LAS bf16x8*)(lds + PG8_SA(b, h) + aoff + m * 2048 + k * 1024); } while (0)
; template <class Epi, class Sched, bool ALIGN_EPI = false, bool SP2 = false>
; __device__ __forceinline__ void gemm_phase(PG8_LAS unsigned char* lds, const Gemm g, const Sched& S, const Epi& E) {
;     ...
;             PG8_LDA(At, 1, 1); PG8_STAGE(PG8_SB(1, 0), b3, voffB); PG8_STAGE(PG8_SB(1, 1), b3 + hstep, voffB); PG8_STAGE(PG8_SA(1, 0), a3, voffA);
	s_mov_b32 m0, s58
	ds_read_b128 v[176:179], v207 offset:49152
	ds_read_b128 v[184:187], v207 offset:50176
	ds_read_b128 v[190:193], v207 offset:51200
	ds_read_b128 v[210:213], v207 offset:52224
	ds_read_b128 v[214:217], v207 offset:53248
	ds_read_b128 v[218:221], v207 offset:54272
	ds_read_b128 v[222:225], v207 offset:55296
	ds_read_b128 v[226:229], v207 offset:56320
	global_load_lds_dwordx4 v250, s[96:97]
	s_add_i32 m0, s58, 0x2000
	s_add_u32 s12, s12, 0x80080

; #define PG8_STAGE(bufoff, gbase, voff) do { _Pragma("unroll") for (int _i = 0; _i < 2; ++_i) \
;         __builtin_amdgcn_global_load_lds((const unsigned*)((const char*)(gbase) + (voff)[_i]), (PG8_LAS unsigned*)(lds + (bufoff) + ldsw + _i * 8192), 16, 0, 0); } while (0)
; #define PG8_LDA(dst, b, h) do { _Pragma("unroll") for (int m = 0; m < 4; ++m) _Pragma("unroll") for (int k = 0; k < 2; ++k) dst[m][k] = *(const PG8_LAS bf16x8*)(lds + PG8_SA(b, h) + aoff + m * 2048 + k * 1024); } while (0)
; template <class Epi, class Sched, bool ALIGN_EPI = false, bool SP2 = false>
; __device__ __forceinline__ void gemm_phase(PG8_LAS unsigned char* lds, const Gemm g, const Sched& S, const Epi& E) {
;     ...
;             PG8_LDA(At, 1, 1); PG8_STAGE(PG8_SB(1, 0), b3, voffB); PG8_STAGE(PG8_SB(1, 1), b3 + hstep, voffB); PG8_STAGE(PG8_SA(1, 0), a3, voffA);
	s_addc_u32 s13, s13, 0
	s_add_i32 s58, s85, s62
	global_load_lds_dwordx4 v251, s[96:97]

; #define PG8_STAGE(bufoff, gbase, voff) do { _Pragma("unroll") for (int _i = 0; _i < 2; ++_i) \
;         __builtin_amdgcn_global_load_lds((const unsigned*)((const char*)(gbase) + (voff)[_i]), (PG8_LAS unsigned*)(lds + (bufoff) + ldsw + _i * 8192), 16, 0, 0); } while (0)
; #define PG8_LDA(dst, b, h) do { _Pragma("unroll") for (int m = 0; m < 4; ++m) _Pragma("unroll") for (int k = 0; k < 2; ++k) dst[m][k] = *(const PG8_LAS bf16x8*)(lds + PG8_SA(b, h) + aoff + m * 2048 + k * 1024); } while (0)
; template <class Epi, class Sched, bool ALIGN_EPI = false, bool SP2 = false>
; __device__ __forceinline__ void gemm_phase(PG8_LAS unsigned char* lds, const Gemm g, const Sched& S, const Epi& E) {
;     ...
;             PG8_LDA(At, 1, 1); PG8_STAGE(PG8_SB(1, 0), b3, voffB); PG8_STAGE(PG8_SB(1, 1), b3 + hstep, voffB); PG8_STAGE(PG8_SA(1, 0), a3, voffA);
	s_mov_b32 m0, s58
	s_nop 0
	global_load_lds_dwordx4 v162, s[12:13]

; #define PG8_STAGE(bufoff, gbase, voff) do { _Pragma("unroll") for (int _i = 0; _i < 2; ++_i) \
;         __builtin_amdgcn_global_load_lds((const unsigned*)((const char*)(gbase) + (voff)[_i]), (PG8_LAS unsigned*)(lds + (bufoff) + ldsw + _i * 8192), 16, 0, 0); } while (0)
; #define PG8_LDA(dst, b, h) do { _Pragma("unroll") for (int m = 0; m < 4; ++m) _Pragma("unroll") for (int k = 0; k < 2; ++k) dst[m][k] = *(const PG8_LAS bf16x8*)(lds + PG8_SA(b, h) + aoff + m * 2048 + k * 1024); } while (0)
; template <class Epi, class Sched, bool ALIGN_EPI = false, bool SP2 = false>
; __device__ __forceinline__ void gemm_phase(PG8_LAS unsigned char* lds, const Gemm g, const Sched& S, const Epi& E) {
;     ...
;             PG8_LDA(At, 1, 1); PG8_STAGE(PG8_SB(1, 0), b3, voffB); PG8_STAGE(PG8_SB(1, 1), b3 + hstep, voffB); PG8_STAGE(PG8_SA(1, 0), a3, voffA);
	s_add_i32 m0, s58, 0x2000
	s_nop 0
	global_load_lds_dwordx4 v166, s[12:13]

; #define PG8_STAGE(bufoff, gbase, voff) do { _Pragma("unroll") for (int _i = 0; _i < 2; ++_i) \
;         __builtin_amdgcn_global_load_lds((const unsigned*)((const char*)(gbase) + (voff)[_i]), (PG8_LAS unsigned*)(lds + (bufoff) + ldsw + _i * 8192), 16, 0, 0); } while (0)
; #define PG8_LDA(dst, b, h) do { _Pragma("unroll") for (int m = 0; m < 4; ++m) _Pragma("unroll") for (int k = 0; k < 2; ++k) dst[m][k] = *(const PG8_LAS bf16x8*)(lds + PG8_SA(b, h) + aoff + m * 2048 + k * 1024); } while (0)
; template <class Epi, class Sched, bool ALIGN_EPI = false, bool SP2 = false>
; __device__ __forceinline__ void gemm_phase(PG8_LAS unsigned char* lds, const Gemm g, const Sched& S, const Epi& E) {
;     ...
;             PG8_LDA(At, 1, 1); PG8_STAGE(PG8_SB(1, 0), b3, voffB); PG8_STAGE(PG8_SB(1, 1), b3 + hstep, voffB); PG8_STAGE(PG8_SA(1, 0), a3, voffA);
	s_mov_b32 m0, s69
	s_nop 0
	global_load_lds_dwordx4 v252, s[98:99]

; #define PG8_STAGE(bufoff, gbase, voff) do { _Pragma("unroll") for (int _i = 0; _i < 2; ++_i) \
;         __builtin_amdgcn_global_load_lds((const unsigned*)((const char*)(gbase) + (voff)[_i]), (PG8_LAS unsigned*)(lds + (bufoff) + ldsw + _i * 8192), 16, 0, 0); } while (0)
; #define PG8_LDA(dst, b, h) do { _Pragma("unroll") for (int m = 0; m < 4; ++m) _Pragma("unroll") for (int k = 0; k < 2; ++k) dst[m][k] = *(const PG8_LAS bf16x8*)(lds + PG8_SA(b, h) + aoff + m * 2048 + k * 1024); } while (0)
; #define PG8_MMA(ai, bj, At, Bt) do { __builtin_amdgcn_s_setprio(1); _Pragma("unroll") for (int m = 0; m < 4; ++m) _Pragma("unroll") for (int n = 0; n < 2; ++n) _Pragma("unroll") for (int k = 0; k < 2; ++k) \
;         acc[ai][bj][m][n] = __builtin_amdgcn_mfma_f32_16x16x32_bf16(Bt[n][k], At[m][k], acc[ai][bj][m][n], 0, 0, 0); __builtin_amdgcn_s_setprio(0); } while (0)
; #define PG8_WAIT_V(n) asm volatile("s_waitcnt vmcnt(" #n ")" ::: "memory")
; #define PG8_WAIT_L(n) asm volatile("s_waitcnt lgkmcnt(" #n ")" ::: "memory")
; #define PG8_BAR __builtin_amdgcn_s_barrier()
; #define PG8_SCHED __builtin_amdgcn_sched_barrier(0)
; template <class Epi, class Sched, bool ALIGN_EPI = false, bool SP2 = false>
; __device__ __forceinline__ void gemm_phase(PG8_LAS unsigned char* lds, const Gemm g, const Sched& S, const Epi& E) {
;     ...
;             PG8_LDA(At, 1, 1); PG8_STAGE(PG8_SB(1, 0), b3, voffB); PG8_STAGE(PG8_SB(1, 1), b3 + hstep, voffB); PG8_STAGE(PG8_SA(1, 0), a3, voffA);
;             PG8_WAIT_V(8); PG8_WAIT_L(0); PG8_BAR; PG8_MMA(1, 0, At, B0); PG8_MMA(1, 1, At, B1); PG8_BAR; PG8_SCHED;
	s_mov_b32 m0, s70
	s_nop 0
	global_load_lds_dwordx4 v253, s[98:99]
	s_waitcnt vmcnt(8)
	s_waitcnt lgkmcnt(0)
	s_barrier
	s_setprio 1
	s_waitcnt lgkmcnt(0)
	v_mfma_f32_16x16x32_bf16 v[60:63], v[128:131], v[176:179], v[60:63]
	v_mfma_f32_16x16x32_bf16 v[56:59], v[136:139], v[176:179], v[56:59]
	v_mfma_f32_16x16x32_bf16 v[44:47], v[128:131], v[190:193], v[44:47]
	v_mfma_f32_16x16x32_bf16 v[40:43], v[136:139], v[190:193], v[40:43]
	v_mfma_f32_16x16x32_bf16 v[28:31], v[128:131], v[214:217], v[28:31]
	v_mfma_f32_16x16x32_bf16 v[24:27], v[136:139], v[214:217], v[24:27]
	v_mfma_f32_16x16x32_bf16 v[12:15], v[128:131], v[222:225], v[12:15]
	v_mfma_f32_16x16x32_bf16 v[8:11], v[136:139], v[222:225], v[8:11]
	v_mfma_f32_16x16x32_bf16 v[60:63], v[132:135], v[184:187], v[60:63]
	v_mfma_f32_16x16x32_bf16 v[56:59], v[140:143], v[184:187], v[56:59]
	v_mfma_f32_16x16x32_bf16 v[44:47], v[132:135], v[210:213], v[44:47]
	v_mfma_f32_16x16x32_bf16 v[40:43], v[140:143], v[210:213], v[40:43]
	v_mfma_f32_16x16x32_bf16 v[28:31], v[132:135], v[218:221], v[28:31]
	v_mfma_f32_16x16x32_bf16 v[24:27], v[140:143], v[218:221], v[24:27]
	v_mfma_f32_16x16x32_bf16 v[12:15], v[132:135], v[226:229], v[12:15]
	v_mfma_f32_16x16x32_bf16 v[8:11], v[140:143], v[226:229], v[8:11]


; #define PG8_MMA(ai, bj, At, Bt) do { __builtin_amdgcn_s_setprio(1); _Pragma("unroll") for (int m = 0; m < 4; ++m) _Pragma("unroll") for (int n = 0; n < 2; ++n) _Pragma("unroll") for (int k = 0; k < 2; ++k) \
;         acc[ai][bj][m][n] = __builtin_amdgcn_mfma_f32_16x16x32_bf16(Bt[n][k], At[m][k], acc[ai][bj][m][n], 0, 0, 0); __builtin_amdgcn_s_setprio(0); } while (0)
; #define PG8_WAIT_V(n) asm volatile("s_waitcnt vmcnt(" #n ")" ::: "memory")
; #define PG8_WAIT_L(n) asm volatile("s_waitcnt lgkmcnt(" #n ")" ::: "memory")
; #define PG8_BAR __builtin_amdgcn_s_barrier()
; #define PG8_SCHED __builtin_amdgcn_sched_barrier(0)
; template <class Epi, class Sched, bool ALIGN_EPI = false, bool SP2 = false>
; __device__ __forceinline__ void gemm_phase(PG8_LAS unsigned char* lds, const Gemm g, const Sched& S, const Epi& E) {
;     ...
;         for (int t = 0; t < nt; t += 2) {
;     ...
;             PG8_WAIT_V(8); PG8_WAIT_L(0); PG8_BAR; PG8_MMA(1, 0, At, B0); PG8_MMA(1, 1, At, B1); PG8_BAR; PG8_SCHED;
;     ...
;         if constexpr (ALIGN_EPI) { if (wr == 0) PG8_BAR; }
	v_mfma_f32_16x16x32_bf16 v[52:55], v[144:147], v[176:179], v[52:55]
	v_mfma_f32_16x16x32_bf16 v[48:51], v[152:155], v[176:179], v[48:51]
	v_mfma_f32_16x16x32_bf16 v[36:39], v[144:147], v[190:193], v[36:39]
	v_mfma_f32_16x16x32_bf16 v[32:35], v[152:155], v[190:193], v[32:35]
	v_mfma_f32_16x16x32_bf16 v[20:23], v[144:147], v[214:217], v[20:23]
	v_mfma_f32_16x16x32_bf16 v[16:19], v[152:155], v[214:217], v[16:19]
	v_mfma_f32_16x16x32_bf16 v[4:7], v[144:147], v[222:225], v[4:7]
	v_mfma_f32_16x16x32_bf16 v[0:3], v[152:155], v[222:225], v[0:3]
	v_mfma_f32_16x16x32_bf16 v[52:55], v[148:151], v[184:187], v[52:55]
	v_mfma_f32_16x16x32_bf16 v[48:51], v[156:159], v[184:187], v[48:51]
	v_mfma_f32_16x16x32_bf16 v[36:39], v[148:151], v[210:213], v[36:39]
	v_mfma_f32_16x16x32_bf16 v[32:35], v[156:159], v[210:213], v[32:35]
	v_mfma_f32_16x16x32_bf16 v[20:23], v[148:151], v[218:221], v[20:23]
	v_mfma_f32_16x16x32_bf16 v[16:19], v[156:159], v[218:221], v[16:19]
	v_mfma_f32_16x16x32_bf16 v[4:7], v[148:151], v[226:229], v[4:7]
	v_mfma_f32_16x16x32_bf16 v[0:3], v[156:159], v[226:229], v[0:3]
	s_setprio 0
	s_barrier
	s_add_i32 s83, s83, 2
	s_add_u32 s10, s10, 0x100
	s_addc_u32 s11, s11, 0
	s_add_u32 s81, s81, 0x100
	s_addc_u32 s82, s82, 0
	s_cmp_gt_u32 s83, 29
	s_cbranch_scc0 .LBB0_1034
	s_and_b64 vcc, exec, s[40:41]
	s_cbranch_vccz .LBB0_1037
	s_barrier

; #define PG8_STAGE(bufoff, gbase, voff) do { _Pragma("unroll") for (int _i = 0; _i < 2; ++_i) \
;         __builtin_amdgcn_global_load_lds((const unsigned*)((const char*)(gbase) + (voff)[_i]), (PG8_LAS unsigned*)(lds + (bufoff) + ldsw + _i * 8192), 16, 0, 0); } while (0)
; #define PG8_LDA(dst, b, h) do { _Pragma("unroll") for (int m = 0; m < 4; ++m) _Pragma("unroll") for (int k = 0; k < 2; ++k) dst[m][k] = *(const PG8_LAS bf16x8*)(lds + PG8_SA(b, h) + aoff + m * 2048 + k * 1024); } while (0)
; #define PG8_LDB(dst, b, h) do { _Pragma("unroll") for (int n = 0; n < 2; ++n) _Pragma("unroll") for (int k = 0; k < 2; ++k) dst[n][k] = *(const PG8_LAS bf16x8*)(lds + PG8_SB(b, h) + boff + n * 2048 + k * 1024); } while (0)
; #define PG8_SCHED __builtin_amdgcn_sched_barrier(0)
; template <class Epi, class Sched, bool ALIGN_EPI = false, bool SP2 = false>
; __device__ __forceinline__ void gemm_phase(PG8_LAS unsigned char* lds, const Gemm g, const Sched& S, const Epi& E) {
;     ...
;     for (;;) {
;         const bool has_next = S.next(ui + 1, nxt);
;         const char* nA = has_next ? (const char*)g.A + (size_t)nxt.pm * tstep : cA; const char* nB = has_next ? (const char*)g.Bt + (size_t)nxt.pn * tstep : cB;
;         for (int t = 0; t < nt; t += 2) {
;             const bool last = (t == nt - 2);
;             const char* a1 = cA + (size_t)(t + 1) * kstep;
;             const char* a2 = last ? nA : cA + (size_t)(t + 2) * kstep; const char* b2 = last ? nB : cB + (size_t)(t + 2) * kstep;
;             const char* a3 = a2 + kstep; const char* b3 = b2 + kstep;
;             if (last && has_next) S.a_ready(nxt);
;             if constexpr (SP2) {
;             PG8_LDB(B0, 0, 0); PG8_LDB(B1, 0, 1); PG8_SCHED; PG8_LDA(At, 0, 0); PG8_STAGE(PG8_SA(1, 1), a1 + hstep, voffA);
;     ...
; #pragma unroll
;         for (int a = 0; a < 2; ++a)
; #pragma unroll
;             for (int b = 0; b < 2; ++b)
; #pragma unroll
;                 for (int m = 0; m < 4; ++m)
; #pragma unroll
;                     for (int n = 0; n < 2; ++n) acc[a][b][m][n] = (f32x4){0.f, 0.f, 0.f, 0.f};
;         cur = nxt; cA = nA; cB = nB; ++ui;
.LBB0_1113:
	s_ashr_i32 s43, s42, 31
	s_lshl_b64 s[44:45], s[42:43], 22
	s_add_u32 s44, s22, s44
	s_addc_u32 s45, s23, s45
	s_and_b64 s[46:47], s[4:5], exec
	s_cselect_b32 s43, s45, s49
	s_cselect_b32 s69, s44, s48
	s_ashr_i32 s41, s40, 31
	s_lshl_b64 s[46:47], s[40:41], 22
	s_add_u32 s46, s39, s46
	s_addc_u32 s47, s54, s47
	s_and_b64 s[52:53], s[4:5], exec
	s_cselect_b32 s41, s47, s51
	s_cselect_b32 s70, s46, s50
	s_add_u32 s48, s48, 0x200080
	s_addc_u32 s49, s49, 0
	s_add_u32 s71, s50, 0x100
	v_mov_b32_e32 v0, 0
	s_addc_u32 s72, s51, 0
	s_mov_b32 s73, -2
	v_mov_b32_e32 v1, v0
	v_mov_b32_e32 v2, v0
	v_mov_b32_e32 v3, v0
	v_mov_b32_e32 v4, v0
	v_mov_b32_e32 v5, v0
	v_mov_b32_e32 v6, v0
	v_mov_b32_e32 v7, v0
	v_mov_b32_e32 v16, v0
	v_mov_b32_e32 v17, v0
	v_mov_b32_e32 v18, v0
	v_mov_b32_e32 v19, v0
	v_mov_b32_e32 v20, v0
	v_mov_b32_e32 v21, v0
	v_mov_b32_e32 v22, v0
	v_mov_b32_e32 v23, v0
	v_mov_b32_e32 v32, v0
	v_mov_b32_e32 v33, v0
	v_mov_b32_e32 v34, v0
	v_mov_b32_e32 v35, v0
	v_mov_b32_e32 v36, v0
	v_mov_b32_e32 v37, v0
	v_mov_b32_e32 v38, v0
	v_mov_b32_e32 v39, v0
	v_mov_b32_e32 v48, v0
	v_mov_b32_e32 v49, v0
	v_mov_b32_e32 v50, v0
	v_mov_b32_e32 v51, v0
	v_mov_b32_e32 v52, v0
	v_mov_b32_e32 v53, v0
	v_mov_b32_e32 v54, v0
	v_mov_b32_e32 v55, v0
	v_mov_b32_e32 v8, v0
	v_mov_b32_e32 v9, v0
	v_mov_b32_e32 v10, v0
	v_mov_b32_e32 v11, v0
	v_mov_b32_e32 v12, v0
	v_mov_b32_e32 v13, v0
	v_mov_b32_e32 v14, v0
	v_mov_b32_e32 v15, v0
	v_mov_b32_e32 v24, v0
	v_mov_b32_e32 v25, v0
	v_mov_b32_e32 v26, v0
	v_mov_b32_e32 v27, v0
	v_mov_b32_e32 v28, v0
	v_mov_b32_e32 v29, v0
	v_mov_b32_e32 v30, v0
	v_mov_b32_e32 v31, v0
	v_mov_b32_e32 v40, v0
	v_mov_b32_e32 v41, v0
	v_mov_b32_e32 v42, v0
	v_mov_b32_e32 v43, v0
	v_mov_b32_e32 v44, v0
	v_mov_b32_e32 v45, v0
	v_mov_b32_e32 v46, v0
	v_mov_b32_e32 v47, v0
	v_mov_b32_e32 v56, v0
	v_mov_b32_e32 v57, v0
	v_mov_b32_e32 v58, v0
	v_mov_b32_e32 v59, v0
	v_mov_b32_e32 v60, v0
	v_mov_b32_e32 v61, v0
	v_mov_b32_e32 v62, v0
	v_mov_b32_e32 v63, v0
	v_mov_b32_e32 v64, v0
	v_mov_b32_e32 v65, v0
	v_mov_b32_e32 v66, v0
	v_mov_b32_e32 v67, v0
	v_mov_b32_e32 v68, v0
	v_mov_b32_e32 v69, v0
	v_mov_b32_e32 v70, v0
	v_mov_b32_e32 v71, v0
	v_mov_b32_e32 v80, v0
	v_mov_b32_e32 v81, v0
	v_mov_b32_e32 v82, v0
	v_mov_b32_e32 v83, v0
	v_mov_b32_e32 v84, v0
	v_mov_b32_e32 v85, v0
	v_mov_b32_e32 v86, v0
	v_mov_b32_e32 v87, v0
	v_mov_b32_e32 v108, v0
	v_mov_b32_e32 v109, v0
	v_mov_b32_e32 v110, v0
	v_mov_b32_e32 v111, v0
	v_mov_b32_e32 v116, v0
	v_mov_b32_e32 v117, v0
	v_mov_b32_e32 v118, v0
	v_mov_b32_e32 v119, v0
	v_mov_b32_e32 v128, v0
	v_mov_b32_e32 v129, v0
	v_mov_b32_e32 v130, v0
	v_mov_b32_e32 v131, v0
	v_mov_b32_e32 v132, v0
	v_mov_b32_e32 v133, v0
	v_mov_b32_e32 v134, v0
	v_mov_b32_e32 v135, v0
	v_mov_b32_e32 v72, v0
	v_mov_b32_e32 v73, v0
	v_mov_b32_e32 v74, v0
	v_mov_b32_e32 v75, v0
	v_mov_b32_e32 v76, v0
	v_mov_b32_e32 v77, v0
	v_mov_b32_e32 v78, v0
	v_mov_b32_e32 v79, v0
	v_mov_b32_e32 v88, v0
	v_mov_b32_e32 v89, v0
	v_mov_b32_e32 v90, v0
	v_mov_b32_e32 v91, v0
	v_mov_b32_e32 v92, v0
	v_mov_b32_e32 v93, v0
	v_mov_b32_e32 v94, v0
	v_mov_b32_e32 v95, v0
	v_mov_b32_e32 v120, v0
	v_mov_b32_e32 v121, v0
	v_mov_b32_e32 v122, v0
	v_mov_b32_e32 v123, v0
	v_mov_b32_e32 v124, v0
	v_mov_b32_e32 v125, v0
	v_mov_b32_e32 v126, v0
	v_mov_b32_e32 v127, v0
	v_mov_b32_e32 v136, v0
	v_mov_b32_e32 v137, v0
	v_mov_b32_e32 v138, v0
	v_mov_b32_e32 v139, v0
	v_mov_b32_e32 v140, v0
	v_mov_b32_e32 v141, v0
	v_mov_b32_e32 v142, v0
	v_mov_b32_e32 v143, v0
	v_add_u32_e32 v255, 0x1c000, v195
	v_add_u32_e32 v254, 0x18000, v195
	v_add_u32_e32 v253, 0x80, v160
	v_add_u32_e32 v252, 0x80, v156
	v_add_u32_e32 v251, 0x80, v162
	v_add_u32_e32 v250, 0x80, v158
.LBB0_1114:
	ds_read_b128 v[96:99], v197
	ds_read_b128 v[100:103], v197 offset:1024
	ds_read_b128 v[104:107], v197 offset:2048
	ds_read_b128 v[112:115], v197 offset:3072
	ds_read_b128 v[144:147], v198
	ds_read_b128 v[148:151], v198 offset:1024
	ds_read_b128 v[152:155], v198 offset:2048
	ds_read_b128 v[172:175], v198 offset:3072
	s_add_u32 s50, s48, 0xffe00080
	s_addc_u32 s51, s49, -1
	s_cmpk_eq_i32 s73, 0x7c
	s_cselect_b32 s53, s43, s51
	s_cselect_b32 s52, s69, s50
	s_cselect_b32 s51, s41, s72
	s_cselect_b32 s50, s70, s71

; #define PG8_STAGE(bufoff, gbase, voff) do { _Pragma("unroll") for (int _i = 0; _i < 2; ++_i) \
;         __builtin_amdgcn_global_load_lds((const unsigned*)((const char*)(gbase) + (voff)[_i]), (PG8_LAS unsigned*)(lds + (bufoff) + ldsw + _i * 8192), 16, 0, 0); } while (0)
; #define PG8_LDA(dst, b, h) do { _Pragma("unroll") for (int m = 0; m < 4; ++m) _Pragma("unroll") for (int k = 0; k < 2; ++k) dst[m][k] = *(const PG8_LAS bf16x8*)(lds + PG8_SA(b, h) + aoff + m * 2048 + k * 1024); } while (0)
; #define PG8_LDB(dst, b, h) do { _Pragma("unroll") for (int n = 0; n < 2; ++n) _Pragma("unroll") for (int k = 0; k < 2; ++k) dst[n][k] = *(const PG8_LAS bf16x8*)(lds + PG8_SB(b, h) + boff + n * 2048 + k * 1024); } while (0)
; #define PG8_SCHED __builtin_amdgcn_sched_barrier(0)
; template <class Epi, class Sched, bool ALIGN_EPI = false, bool SP2 = false>
; __device__ __forceinline__ void gemm_phase(PG8_LAS unsigned char* lds, const Gemm g, const Sched& S, const Epi& E) {
;     ...
;             PG8_LDB(B0, 0, 0); PG8_LDB(B1, 0, 1); PG8_SCHED; PG8_LDA(At, 0, 0); PG8_STAGE(PG8_SA(1, 1), a1 + hstep, voffA);
	s_add_i32 m0, s56, 0xc000
	ds_read_b128 v[176:179], v199
	ds_read_b128 v[180:183], v199 offset:1024
	ds_read_b128 v[184:187], v199 offset:2048
	ds_read_b128 v[188:191], v199 offset:3072
	ds_read_b128 v[202:205], v199 offset:4096
	ds_read_b128 v[206:209], v199 offset:5120
	ds_read_b128 v[210:213], v199 offset:6144
	ds_read_b128 v[214:217], v199 offset:7168
	global_load_lds_dwordx4 v164, s[48:49]

; #define PG8_STAGE(bufoff, gbase, voff) do { _Pragma("unroll") for (int _i = 0; _i < 2; ++_i) \
;         __builtin_amdgcn_global_load_lds((const unsigned*)((const char*)(gbase) + (voff)[_i]), (PG8_LAS unsigned*)(lds + (bufoff) + ldsw + _i * 8192), 16, 0, 0); } while (0)
; #define PG8_LDA(dst, b, h) do { _Pragma("unroll") for (int m = 0; m < 4; ++m) _Pragma("unroll") for (int k = 0; k < 2; ++k) dst[m][k] = *(const PG8_LAS bf16x8*)(lds + PG8_SA(b, h) + aoff + m * 2048 + k * 1024); } while (0)
; #define PG8_LDB(dst, b, h) do { _Pragma("unroll") for (int n = 0; n < 2; ++n) _Pragma("unroll") for (int k = 0; k < 2; ++k) dst[n][k] = *(const PG8_LAS bf16x8*)(lds + PG8_SB(b, h) + boff + n * 2048 + k * 1024); } while (0)
; #define PG8_MMA(ai, bj, At, Bt) do { __builtin_amdgcn_s_setprio(1); _Pragma("unroll") for (int m = 0; m < 4; ++m) _Pragma("unroll") for (int n = 0; n < 2; ++n) _Pragma("unroll") for (int k = 0; k < 2; ++k) \
;         acc[ai][bj][m][n] = __builtin_amdgcn_mfma_f32_16x16x32_bf16(Bt[n][k], At[m][k], acc[ai][bj][m][n], 0, 0, 0); __builtin_amdgcn_s_setprio(0); } while (0)
; #define PG8_WAIT_V(n) asm volatile("s_waitcnt vmcnt(" #n ")" ::: "memory")
; #define PG8_WAIT_L(n) asm volatile("s_waitcnt lgkmcnt(" #n ")" ::: "memory")
; #define PG8_BAR __builtin_amdgcn_s_barrier()
; #define PG8_SCHED __builtin_amdgcn_sched_barrier(0)
; template <class Epi, class Sched, bool ALIGN_EPI = false, bool SP2 = false>
; __device__ __forceinline__ void gemm_phase(PG8_LAS unsigned char* lds, const Gemm g, const Sched& S, const Epi& E) {
;     ...
;             PG8_LDB(B0, 0, 0); PG8_LDB(B1, 0, 1); PG8_SCHED; PG8_LDA(At, 0, 0); PG8_STAGE(PG8_SA(1, 1), a1 + hstep, voffA);
;             PG8_WAIT_V(8); PG8_WAIT_L(0); PG8_BAR; PG8_MMA(0, 0, At, B0); PG8_MMA(0, 1, At, B1); PG8_BAR; PG8_SCHED;
	s_add_i32 m0, s56, 0xe000
	s_nop 0
	global_load_lds_dwordx4 v166, s[48:49]
	s_waitcnt vmcnt(8)
	s_waitcnt lgkmcnt(0)
	s_barrier
	s_setprio 1
	s_waitcnt lgkmcnt(0)
	v_mfma_f32_16x16x32_bf16 v[140:143], v[96:99], v[176:179], v[140:143]
	v_mfma_f32_16x16x32_bf16 v[136:139], v[104:107], v[176:179], v[136:139]
	v_mfma_f32_16x16x32_bf16 v[124:127], v[96:99], v[184:187], v[124:127]
	v_mfma_f32_16x16x32_bf16 v[120:123], v[104:107], v[184:187], v[120:123]
	v_mfma_f32_16x16x32_bf16 v[92:95], v[96:99], v[202:205], v[92:95]
	v_mfma_f32_16x16x32_bf16 v[88:91], v[104:107], v[202:205], v[88:91]
	v_mfma_f32_16x16x32_bf16 v[76:79], v[96:99], v[210:213], v[76:79]
	v_mfma_f32_16x16x32_bf16 v[72:75], v[104:107], v[210:213], v[72:75]
	v_mfma_f32_16x16x32_bf16 v[140:143], v[100:103], v[180:183], v[140:143]
	v_mfma_f32_16x16x32_bf16 v[136:139], v[112:115], v[180:183], v[136:139]
	v_mfma_f32_16x16x32_bf16 v[124:127], v[100:103], v[188:191], v[124:127]
	v_mfma_f32_16x16x32_bf16 v[120:123], v[112:115], v[188:191], v[120:123]
	v_mfma_f32_16x16x32_bf16 v[92:95], v[100:103], v[206:209], v[92:95]
	v_mfma_f32_16x16x32_bf16 v[88:91], v[112:115], v[206:209], v[88:91]
	v_mfma_f32_16x16x32_bf16 v[76:79], v[100:103], v[214:217], v[76:79]
	v_mfma_f32_16x16x32_bf16 v[72:75], v[112:115], v[214:217], v[72:75]


; #define PG8_STAGE(bufoff, gbase, voff) do { _Pragma("unroll") for (int _i = 0; _i < 2; ++_i) \
;         __builtin_amdgcn_global_load_lds((const unsigned*)((const char*)(gbase) + (voff)[_i]), (PG8_LAS unsigned*)(lds + (bufoff) + ldsw + _i * 8192), 16, 0, 0); } while (0)
; #define PG8_LDA(dst, b, h) do { _Pragma("unroll") for (int m = 0; m < 4; ++m) _Pragma("unroll") for (int k = 0; k < 2; ++k) dst[m][k] = *(const PG8_LAS bf16x8*)(lds + PG8_SA(b, h) + aoff + m * 2048 + k * 1024); } while (0)
; #define PG8_MMA(ai, bj, At, Bt) do { __builtin_amdgcn_s_setprio(1); _Pragma("unroll") for (int m = 0; m < 4; ++m) _Pragma("unroll") for (int n = 0; n < 2; ++n) _Pragma("unroll") for (int k = 0; k < 2; ++k) \
;         acc[ai][bj][m][n] = __builtin_amdgcn_mfma_f32_16x16x32_bf16(Bt[n][k], At[m][k], acc[ai][bj][m][n], 0, 0, 0); __builtin_amdgcn_s_setprio(0); } while (0)
; #define PG8_WAIT_V(n) asm volatile("s_waitcnt vmcnt(" #n ")" ::: "memory")
; #define PG8_WAIT_L(n) asm volatile("s_waitcnt lgkmcnt(" #n ")" ::: "memory")
; #define PG8_BAR __builtin_amdgcn_s_barrier()
; #define PG8_SCHED __builtin_amdgcn_sched_barrier(0)
; template <class Epi, class Sched, bool ALIGN_EPI = false, bool SP2 = false>
; __device__ __forceinline__ void gemm_phase(PG8_LAS unsigned char* lds, const Gemm g, const Sched& S, const Epi& E) {
;     ...
;             PG8_WAIT_V(8); PG8_WAIT_L(0); PG8_BAR; PG8_MMA(0, 0, At, B0); PG8_MMA(0, 1, At, B1); PG8_BAR; PG8_SCHED;
;             PG8_LDA(At, 0, 1); PG8_STAGE(PG8_SB(0, 0), b2, voffB); PG8_STAGE(PG8_SB(0, 1), b2 + hstep, voffB); PG8_STAGE(PG8_SA(0, 0), a2, voffA);
	v_mfma_f32_16x16x32_bf16 v[132:135], v[144:147], v[176:179], v[132:135]
	v_mfma_f32_16x16x32_bf16 v[128:131], v[152:155], v[176:179], v[128:131]
	v_mfma_f32_16x16x32_bf16 v[116:119], v[144:147], v[184:187], v[116:119]
	v_mfma_f32_16x16x32_bf16 v[108:111], v[152:155], v[184:187], v[108:111]
	v_mfma_f32_16x16x32_bf16 v[84:87], v[144:147], v[202:205], v[84:87]
	v_mfma_f32_16x16x32_bf16 v[80:83], v[152:155], v[202:205], v[80:83]
	v_mfma_f32_16x16x32_bf16 v[68:71], v[144:147], v[210:213], v[68:71]
	v_mfma_f32_16x16x32_bf16 v[64:67], v[152:155], v[210:213], v[64:67]
	v_mfma_f32_16x16x32_bf16 v[132:135], v[148:151], v[180:183], v[132:135]
	v_mfma_f32_16x16x32_bf16 v[128:131], v[172:175], v[180:183], v[128:131]
	v_mfma_f32_16x16x32_bf16 v[116:119], v[148:151], v[188:191], v[116:119]
	v_mfma_f32_16x16x32_bf16 v[108:111], v[172:175], v[188:191], v[108:111]
	v_mfma_f32_16x16x32_bf16 v[84:87], v[148:151], v[206:209], v[84:87]
	v_mfma_f32_16x16x32_bf16 v[80:83], v[172:175], v[206:209], v[80:83]
	v_mfma_f32_16x16x32_bf16 v[68:71], v[148:151], v[214:217], v[68:71]
	v_mfma_f32_16x16x32_bf16 v[64:67], v[172:175], v[214:217], v[64:67]
	s_setprio 0
	s_barrier
	s_add_i32 s74, s65, s55
	s_mov_b64 s[96:97], s[50:51]

; #define PG8_STAGE(bufoff, gbase, voff) do { _Pragma("unroll") for (int _i = 0; _i < 2; ++_i) \
;         __builtin_amdgcn_global_load_lds((const unsigned*)((const char*)(gbase) + (voff)[_i]), (PG8_LAS unsigned*)(lds + (bufoff) + ldsw + _i * 8192), 16, 0, 0); } while (0)
; #define PG8_LDA(dst, b, h) do { _Pragma("unroll") for (int m = 0; m < 4; ++m) _Pragma("unroll") for (int k = 0; k < 2; ++k) dst[m][k] = *(const PG8_LAS bf16x8*)(lds + PG8_SA(b, h) + aoff + m * 2048 + k * 1024); } while (0)
; template <class Epi, class Sched, bool ALIGN_EPI = false, bool SP2 = false>
; __device__ __forceinline__ void gemm_phase(PG8_LAS unsigned char* lds, const Gemm g, const Sched& S, const Epi& E) {
;     ...
;             PG8_LDA(At, 0, 1); PG8_STAGE(PG8_SB(0, 0), b2, voffB); PG8_STAGE(PG8_SB(0, 1), b2 + hstep, voffB); PG8_STAGE(PG8_SA(0, 0), a2, voffA);
	s_mov_b32 m0, s74
	ds_read_b128 v[176:179], v199 offset:16384
	ds_read_b128 v[180:183], v199 offset:17408
	ds_read_b128 v[184:187], v199 offset:18432
	ds_read_b128 v[188:191], v199 offset:19456
	ds_read_b128 v[202:205], v199 offset:20480
	ds_read_b128 v[206:209], v199 offset:21504
	ds_read_b128 v[210:213], v199 offset:22528
	ds_read_b128 v[214:217], v199 offset:23552
	global_load_lds_dwordx4 v158, s[50:51]
	s_add_i32 m0, s74, 0x2000
	s_add_u32 s74, s50, 0x200000

; #define PG8_STAGE(bufoff, gbase, voff) do { _Pragma("unroll") for (int _i = 0; _i < 2; ++_i) \
;         __builtin_amdgcn_global_load_lds((const unsigned*)((const char*)(gbase) + (voff)[_i]), (PG8_LAS unsigned*)(lds + (bufoff) + ldsw + _i * 8192), 16, 0, 0); } while (0)
; #define PG8_LDA(dst, b, h) do { _Pragma("unroll") for (int m = 0; m < 4; ++m) _Pragma("unroll") for (int k = 0; k < 2; ++k) dst[m][k] = *(const PG8_LAS bf16x8*)(lds + PG8_SA(b, h) + aoff + m * 2048 + k * 1024); } while (0)
; template <class Epi, class Sched, bool ALIGN_EPI = false, bool SP2 = false>
; __device__ __forceinline__ void gemm_phase(PG8_LAS unsigned char* lds, const Gemm g, const Sched& S, const Epi& E) {
;     ...
;             PG8_LDA(At, 0, 1); PG8_STAGE(PG8_SB(0, 0), b2, voffB); PG8_STAGE(PG8_SB(0, 1), b2 + hstep, voffB); PG8_STAGE(PG8_SA(0, 0), a2, voffA);
	s_addc_u32 s75, s51, 0
	s_add_i32 s76, s67, s55
	global_load_lds_dwordx4 v162, s[50:51]

; #define PG8_STAGE(bufoff, gbase, voff) do { _Pragma("unroll") for (int _i = 0; _i < 2; ++_i) \
;         __builtin_amdgcn_global_load_lds((const unsigned*)((const char*)(gbase) + (voff)[_i]), (PG8_LAS unsigned*)(lds + (bufoff) + ldsw + _i * 8192), 16, 0, 0); } while (0)
; #define PG8_LDA(dst, b, h) do { _Pragma("unroll") for (int m = 0; m < 4; ++m) _Pragma("unroll") for (int k = 0; k < 2; ++k) dst[m][k] = *(const PG8_LAS bf16x8*)(lds + PG8_SA(b, h) + aoff + m * 2048 + k * 1024); } while (0)
; template <class Epi, class Sched, bool ALIGN_EPI = false, bool SP2 = false>
; __device__ __forceinline__ void gemm_phase(PG8_LAS unsigned char* lds, const Gemm g, const Sched& S, const Epi& E) {
;     ...
;             PG8_LDA(At, 0, 1); PG8_STAGE(PG8_SB(0, 0), b2, voffB); PG8_STAGE(PG8_SB(0, 1), b2 + hstep, voffB); PG8_STAGE(PG8_SA(0, 0), a2, voffA);
	s_mov_b32 m0, s76
	s_nop 0
	global_load_lds_dwordx4 v158, s[74:75]

; #define PG8_STAGE(bufoff, gbase, voff) do { _Pragma("unroll") for (int _i = 0; _i < 2; ++_i) \
;         __builtin_amdgcn_global_load_lds((const unsigned*)((const char*)(gbase) + (voff)[_i]), (PG8_LAS unsigned*)(lds + (bufoff) + ldsw + _i * 8192), 16, 0, 0); } while (0)
; #define PG8_LDA(dst, b, h) do { _Pragma("unroll") for (int m = 0; m < 4; ++m) _Pragma("unroll") for (int k = 0; k < 2; ++k) dst[m][k] = *(const PG8_LAS bf16x8*)(lds + PG8_SA(b, h) + aoff + m * 2048 + k * 1024); } while (0)
; template <class Epi, class Sched, bool ALIGN_EPI = false, bool SP2 = false>
; __device__ __forceinline__ void gemm_phase(PG8_LAS unsigned char* lds, const Gemm g, const Sched& S, const Epi& E) {
;     ...
;             PG8_LDA(At, 0, 1); PG8_STAGE(PG8_SB(0, 0), b2, voffB); PG8_STAGE(PG8_SB(0, 1), b2 + hstep, voffB); PG8_STAGE(PG8_SA(0, 0), a2, voffA);
	s_add_i32 m0, s76, 0x2000
	s_nop 0
	global_load_lds_dwordx4 v162, s[74:75]
	s_mov_b64 s[98:99], s[52:53]

; #define PG8_STAGE(bufoff, gbase, voff) do { _Pragma("unroll") for (int _i = 0; _i < 2; ++_i) \
;         __builtin_amdgcn_global_load_lds((const unsigned*)((const char*)(gbase) + (voff)[_i]), (PG8_LAS unsigned*)(lds + (bufoff) + ldsw + _i * 8192), 16, 0, 0); } while (0)
; #define PG8_LDA(dst, b, h) do { _Pragma("unroll") for (int m = 0; m < 4; ++m) _Pragma("unroll") for (int k = 0; k < 2; ++k) dst[m][k] = *(const PG8_LAS bf16x8*)(lds + PG8_SA(b, h) + aoff + m * 2048 + k * 1024); } while (0)
; #define PG8_MMA(ai, bj, At, Bt) do { __builtin_amdgcn_s_setprio(1); _Pragma("unroll") for (int m = 0; m < 4; ++m) _Pragma("unroll") for (int n = 0; n < 2; ++n) _Pragma("unroll") for (int k = 0; k < 2; ++k) \
;         acc[ai][bj][m][n] = __builtin_amdgcn_mfma_f32_16x16x32_bf16(Bt[n][k], At[m][k], acc[ai][bj][m][n], 0, 0, 0); __builtin_amdgcn_s_setprio(0); } while (0)
; #define PG8_WAIT_V(n) asm volatile("s_waitcnt vmcnt(" #n ")" ::: "memory")
; #define PG8_WAIT_L(n) asm volatile("s_waitcnt lgkmcnt(" #n ")" ::: "memory")
; #define PG8_BAR __builtin_amdgcn_s_barrier()
; #define PG8_SCHED __builtin_amdgcn_sched_barrier(0)
; template <class Epi, class Sched, bool ALIGN_EPI = false, bool SP2 = false>
; __device__ __forceinline__ void gemm_phase(PG8_LAS unsigned char* lds, const Gemm g, const Sched& S, const Epi& E) {
;     ...
;             PG8_LDA(At, 0, 1); PG8_STAGE(PG8_SB(0, 0), b2, voffB); PG8_STAGE(PG8_SB(0, 1), b2 + hstep, voffB); PG8_STAGE(PG8_SA(0, 0), a2, voffA);
;             PG8_WAIT_V(8); PG8_WAIT_L(0); PG8_BAR; PG8_MMA(1, 0, At, B0); PG8_MMA(1, 1, At, B1); PG8_BAR; PG8_SCHED;
	s_mov_b32 m0, s56
	s_nop 0
	global_load_lds_dwordx4 v156, s[52:53]
	s_mov_b32 m0, s57
	s_nop 0
	global_load_lds_dwordx4 v160, s[52:53]
	s_waitcnt vmcnt(8)
	s_waitcnt lgkmcnt(0)
	s_barrier
	s_setprio 1
	s_waitcnt lgkmcnt(0)
	v_mfma_f32_16x16x32_bf16 v[60:63], v[96:99], v[176:179], v[60:63]
	v_mfma_f32_16x16x32_bf16 v[56:59], v[104:107], v[176:179], v[56:59]
	v_mfma_f32_16x16x32_bf16 v[44:47], v[96:99], v[184:187], v[44:47]
	v_mfma_f32_16x16x32_bf16 v[40:43], v[104:107], v[184:187], v[40:43]
	v_mfma_f32_16x16x32_bf16 v[28:31], v[96:99], v[202:205], v[28:31]
	v_mfma_f32_16x16x32_bf16 v[24:27], v[104:107], v[202:205], v[24:27]
	v_mfma_f32_16x16x32_bf16 v[12:15], v[96:99], v[210:213], v[12:15]
	v_mfma_f32_16x16x32_bf16 v[8:11], v[104:107], v[210:213], v[8:11]
	v_mfma_f32_16x16x32_bf16 v[60:63], v[100:103], v[180:183], v[60:63]
	v_mfma_f32_16x16x32_bf16 v[56:59], v[112:115], v[180:183], v[56:59]
	v_mfma_f32_16x16x32_bf16 v[44:47], v[100:103], v[188:191], v[44:47]
	v_mfma_f32_16x16x32_bf16 v[40:43], v[112:115], v[188:191], v[40:43]
	v_mfma_f32_16x16x32_bf16 v[28:31], v[100:103], v[206:209], v[28:31]
	v_mfma_f32_16x16x32_bf16 v[24:27], v[112:115], v[206:209], v[24:27]
	v_mfma_f32_16x16x32_bf16 v[12:15], v[100:103], v[214:217], v[12:15]
	v_mfma_f32_16x16x32_bf16 v[8:11], v[112:115], v[214:217], v[8:11]


; #define PG8_STAGE(bufoff, gbase, voff) do { _Pragma("unroll") for (int _i = 0; _i < 2; ++_i) \
;         __builtin_amdgcn_global_load_lds((const unsigned*)((const char*)(gbase) + (voff)[_i]), (PG8_LAS unsigned*)(lds + (bufoff) + ldsw + _i * 8192), 16, 0, 0); } while (0)
; #define PG8_LDA(dst, b, h) do { _Pragma("unroll") for (int m = 0; m < 4; ++m) _Pragma("unroll") for (int k = 0; k < 2; ++k) dst[m][k] = *(const PG8_LAS bf16x8*)(lds + PG8_SA(b, h) + aoff + m * 2048 + k * 1024); } while (0)
; #define PG8_LDB(dst, b, h) do { _Pragma("unroll") for (int n = 0; n < 2; ++n) _Pragma("unroll") for (int k = 0; k < 2; ++k) dst[n][k] = *(const PG8_LAS bf16x8*)(lds + PG8_SB(b, h) + boff + n * 2048 + k * 1024); } while (0)
; #define PG8_MMA(ai, bj, At, Bt) do { __builtin_amdgcn_s_setprio(1); _Pragma("unroll") for (int m = 0; m < 4; ++m) _Pragma("unroll") for (int n = 0; n < 2; ++n) _Pragma("unroll") for (int k = 0; k < 2; ++k) \
;         acc[ai][bj][m][n] = __builtin_amdgcn_mfma_f32_16x16x32_bf16(Bt[n][k], At[m][k], acc[ai][bj][m][n], 0, 0, 0); __builtin_amdgcn_s_setprio(0); } while (0)
; #define PG8_WAIT_V(n) asm volatile("s_waitcnt vmcnt(" #n ")" ::: "memory")
; #define PG8_WAIT_L(n) asm volatile("s_waitcnt lgkmcnt(" #n ")" ::: "memory")
; #define PG8_BAR __builtin_amdgcn_s_barrier()
; #define PG8_SCHED __builtin_amdgcn_sched_barrier(0)
; template <class Epi, class Sched, bool ALIGN_EPI = false, bool SP2 = false>
; __device__ __forceinline__ void gemm_phase(PG8_LAS unsigned char* lds, const Gemm g, const Sched& S, const Epi& E) {
;     ...
;             PG8_WAIT_V(8); PG8_WAIT_L(0); PG8_BAR; PG8_MMA(1, 0, At, B0); PG8_MMA(1, 1, At, B1); PG8_BAR; PG8_SCHED;
;             PG8_LDB(B0, 1, 0); PG8_LDB(B1, 1, 1); PG8_SCHED; PG8_LDA(At, 1, 0); PG8_STAGE(PG8_SA(0, 1), a2 + hstep, voffA);
	v_mfma_f32_16x16x32_bf16 v[52:55], v[144:147], v[176:179], v[52:55]
	v_mfma_f32_16x16x32_bf16 v[48:51], v[152:155], v[176:179], v[48:51]
	v_mfma_f32_16x16x32_bf16 v[36:39], v[144:147], v[184:187], v[36:39]
	v_mfma_f32_16x16x32_bf16 v[32:35], v[152:155], v[184:187], v[32:35]
	v_mfma_f32_16x16x32_bf16 v[20:23], v[144:147], v[202:205], v[20:23]
	v_mfma_f32_16x16x32_bf16 v[16:19], v[152:155], v[202:205], v[16:19]
	v_mfma_f32_16x16x32_bf16 v[4:7], v[144:147], v[210:213], v[4:7]
	v_mfma_f32_16x16x32_bf16 v[0:3], v[152:155], v[210:213], v[0:3]
	v_mfma_f32_16x16x32_bf16 v[52:55], v[148:151], v[180:183], v[52:55]
	v_mfma_f32_16x16x32_bf16 v[48:51], v[172:175], v[180:183], v[48:51]
	v_mfma_f32_16x16x32_bf16 v[36:39], v[148:151], v[188:191], v[36:39]
	v_mfma_f32_16x16x32_bf16 v[32:35], v[172:175], v[188:191], v[32:35]
	v_mfma_f32_16x16x32_bf16 v[20:23], v[148:151], v[206:209], v[20:23]
	v_mfma_f32_16x16x32_bf16 v[16:19], v[172:175], v[206:209], v[16:19]
	v_mfma_f32_16x16x32_bf16 v[4:7], v[148:151], v[214:217], v[4:7]
	v_mfma_f32_16x16x32_bf16 v[0:3], v[172:175], v[214:217], v[0:3]
	s_setprio 0
	s_barrier
	s_add_i32 s74, 0, 0x18000
	s_add_i32 s75, 0, 0x1c000


; #define PG8_STAGE(bufoff, gbase, voff) do { _Pragma("unroll") for (int _i = 0; _i < 2; ++_i) \
;         __builtin_amdgcn_global_load_lds((const unsigned*)((const char*)(gbase) + (voff)[_i]), (PG8_LAS unsigned*)(lds + (bufoff) + ldsw + _i * 8192), 16, 0, 0); } while (0)
; #define PG8_LDA(dst, b, h) do { _Pragma("unroll") for (int m = 0; m < 4; ++m) _Pragma("unroll") for (int k = 0; k < 2; ++k) dst[m][k] = *(const PG8_LAS bf16x8*)(lds + PG8_SA(b, h) + aoff + m * 2048 + k * 1024); } while (0)
; #define PG8_LDB(dst, b, h) do { _Pragma("unroll") for (int n = 0; n < 2; ++n) _Pragma("unroll") for (int k = 0; k < 2; ++k) dst[n][k] = *(const PG8_LAS bf16x8*)(lds + PG8_SB(b, h) + boff + n * 2048 + k * 1024); } while (0)
; #define PG8_SCHED __builtin_amdgcn_sched_barrier(0)
; template <class Epi, class Sched, bool ALIGN_EPI = false, bool SP2 = false>
; __device__ __forceinline__ void gemm_phase(PG8_LAS unsigned char* lds, const Gemm g, const Sched& S, const Epi& E) {
;     ...
;             PG8_LDB(B0, 1, 0); PG8_LDB(B1, 1, 1); PG8_SCHED; PG8_LDA(At, 1, 0); PG8_STAGE(PG8_SA(0, 1), a2 + hstep, voffA);
	ds_read_b128 v[96:99], v254
	ds_read_b128 v[100:103], v254 offset:1024
	ds_read_b128 v[104:107], v254 offset:2048
	ds_read_b128 v[112:115], v254 offset:3072
	ds_read_b128 v[144:147], v255
	ds_read_b128 v[148:151], v255 offset:1024
	ds_read_b128 v[152:155], v255 offset:2048
	ds_read_b128 v[172:175], v255 offset:3072
	s_add_u32 s52, s52, 0x200000
	s_addc_u32 s53, s53, 0
	s_mov_b32 m0, s58

; #define PG8_STAGE(bufoff, gbase, voff) do { _Pragma("unroll") for (int _i = 0; _i < 2; ++_i) \
;         __builtin_amdgcn_global_load_lds((const unsigned*)((const char*)(gbase) + (voff)[_i]), (PG8_LAS unsigned*)(lds + (bufoff) + ldsw + _i * 8192), 16, 0, 0); } while (0)
; #define PG8_LDA(dst, b, h) do { _Pragma("unroll") for (int m = 0; m < 4; ++m) _Pragma("unroll") for (int k = 0; k < 2; ++k) dst[m][k] = *(const PG8_LAS bf16x8*)(lds + PG8_SA(b, h) + aoff + m * 2048 + k * 1024); } while (0)
; #define PG8_LDB(dst, b, h) do { _Pragma("unroll") for (int n = 0; n < 2; ++n) _Pragma("unroll") for (int k = 0; k < 2; ++k) dst[n][k] = *(const PG8_LAS bf16x8*)(lds + PG8_SB(b, h) + boff + n * 2048 + k * 1024); } while (0)
; #define PG8_SCHED __builtin_amdgcn_sched_barrier(0)
; template <class Epi, class Sched, bool ALIGN_EPI = false, bool SP2 = false>
; __device__ __forceinline__ void gemm_phase(PG8_LAS unsigned char* lds, const Gemm g, const Sched& S, const Epi& E) {
;     ...
;             PG8_LDB(B0, 1, 0); PG8_LDB(B1, 1, 1); PG8_SCHED; PG8_LDA(At, 1, 0); PG8_STAGE(PG8_SA(0, 1), a2 + hstep, voffA);
	ds_read_b128 v[176:179], v199 offset:32768
	ds_read_b128 v[180:183], v199 offset:33792
	ds_read_b128 v[184:187], v199 offset:34816
	ds_read_b128 v[188:191], v199 offset:35840
	ds_read_b128 v[202:205], v199 offset:36864
	ds_read_b128 v[206:209], v199 offset:37888
	ds_read_b128 v[210:213], v199 offset:38912
	ds_read_b128 v[214:217], v199 offset:39936
	global_load_lds_dwordx4 v156, s[52:53]

; #define PG8_STAGE(bufoff, gbase, voff) do { _Pragma("unroll") for (int _i = 0; _i < 2; ++_i) \
;         __builtin_amdgcn_global_load_lds((const unsigned*)((const char*)(gbase) + (voff)[_i]), (PG8_LAS unsigned*)(lds + (bufoff) + ldsw + _i * 8192), 16, 0, 0); } while (0)
; #define PG8_LDA(dst, b, h) do { _Pragma("unroll") for (int m = 0; m < 4; ++m) _Pragma("unroll") for (int k = 0; k < 2; ++k) dst[m][k] = *(const PG8_LAS bf16x8*)(lds + PG8_SA(b, h) + aoff + m * 2048 + k * 1024); } while (0)
; #define PG8_LDB(dst, b, h) do { _Pragma("unroll") for (int n = 0; n < 2; ++n) _Pragma("unroll") for (int k = 0; k < 2; ++k) dst[n][k] = *(const PG8_LAS bf16x8*)(lds + PG8_SB(b, h) + boff + n * 2048 + k * 1024); } while (0)
; #define PG8_MMA(ai, bj, At, Bt) do { __builtin_amdgcn_s_setprio(1); _Pragma("unroll") for (int m = 0; m < 4; ++m) _Pragma("unroll") for (int n = 0; n < 2; ++n) _Pragma("unroll") for (int k = 0; k < 2; ++k) \
;         acc[ai][bj][m][n] = __builtin_amdgcn_mfma_f32_16x16x32_bf16(Bt[n][k], At[m][k], acc[ai][bj][m][n], 0, 0, 0); __builtin_amdgcn_s_setprio(0); } while (0)
; #define PG8_WAIT_V(n) asm volatile("s_waitcnt vmcnt(" #n ")" ::: "memory")
; #define PG8_WAIT_L(n) asm volatile("s_waitcnt lgkmcnt(" #n ")" ::: "memory")
; #define PG8_BAR __builtin_amdgcn_s_barrier()
; #define PG8_SCHED __builtin_amdgcn_sched_barrier(0)
; template <class Epi, class Sched, bool ALIGN_EPI = false, bool SP2 = false>
; __device__ __forceinline__ void gemm_phase(PG8_LAS unsigned char* lds, const Gemm g, const Sched& S, const Epi& E) {
;     ...
;             PG8_LDB(B0, 1, 0); PG8_LDB(B1, 1, 1); PG8_SCHED; PG8_LDA(At, 1, 0); PG8_STAGE(PG8_SA(0, 1), a2 + hstep, voffA);
;             PG8_WAIT_V(8); PG8_WAIT_L(0); PG8_BAR; PG8_MMA(0, 0, At, B0); PG8_MMA(0, 1, At, B1); PG8_BAR; PG8_SCHED;
	s_mov_b32 m0, s59
	s_nop 0
	global_load_lds_dwordx4 v160, s[52:53]
	s_waitcnt vmcnt(8)
	s_waitcnt lgkmcnt(0)
	s_barrier
	s_setprio 1
	s_waitcnt lgkmcnt(0)
	v_mfma_f32_16x16x32_bf16 v[140:143], v[96:99], v[176:179], v[140:143]
	v_mfma_f32_16x16x32_bf16 v[136:139], v[104:107], v[176:179], v[136:139]
	v_mfma_f32_16x16x32_bf16 v[124:127], v[96:99], v[184:187], v[124:127]
	v_mfma_f32_16x16x32_bf16 v[120:123], v[104:107], v[184:187], v[120:123]
	v_mfma_f32_16x16x32_bf16 v[92:95], v[96:99], v[202:205], v[92:95]
	v_mfma_f32_16x16x32_bf16 v[88:91], v[104:107], v[202:205], v[88:91]
	v_mfma_f32_16x16x32_bf16 v[76:79], v[96:99], v[210:213], v[76:79]
	v_mfma_f32_16x16x32_bf16 v[72:75], v[104:107], v[210:213], v[72:75]
	v_mfma_f32_16x16x32_bf16 v[140:143], v[100:103], v[180:183], v[140:143]
	v_mfma_f32_16x16x32_bf16 v[136:139], v[112:115], v[180:183], v[136:139]
	v_mfma_f32_16x16x32_bf16 v[124:127], v[100:103], v[188:191], v[124:127]
	v_mfma_f32_16x16x32_bf16 v[120:123], v[112:115], v[188:191], v[120:123]
	v_mfma_f32_16x16x32_bf16 v[92:95], v[100:103], v[206:209], v[92:95]
	v_mfma_f32_16x16x32_bf16 v[88:91], v[112:115], v[206:209], v[88:91]
	v_mfma_f32_16x16x32_bf16 v[76:79], v[100:103], v[214:217], v[76:79]
	v_mfma_f32_16x16x32_bf16 v[72:75], v[112:115], v[214:217], v[72:75]


; #define PG8_STAGE(bufoff, gbase, voff) do { _Pragma("unroll") for (int _i = 0; _i < 2; ++_i) \
;         __builtin_amdgcn_global_load_lds((const unsigned*)((const char*)(gbase) + (voff)[_i]), (PG8_LAS unsigned*)(lds + (bufoff) + ldsw + _i * 8192), 16, 0, 0); } while (0)
; #define PG8_LDA(dst, b, h) do { _Pragma("unroll") for (int m = 0; m < 4; ++m) _Pragma("unroll") for (int k = 0; k < 2; ++k) dst[m][k] = *(const PG8_LAS bf16x8*)(lds + PG8_SA(b, h) + aoff + m * 2048 + k * 1024); } while (0)
; #define PG8_MMA(ai, bj, At, Bt) do { __builtin_amdgcn_s_setprio(1); _Pragma("unroll") for (int m = 0; m < 4; ++m) _Pragma("unroll") for (int n = 0; n < 2; ++n) _Pragma("unroll") for (int k = 0; k < 2; ++k) \
;         acc[ai][bj][m][n] = __builtin_amdgcn_mfma_f32_16x16x32_bf16(Bt[n][k], At[m][k], acc[ai][bj][m][n], 0, 0, 0); __builtin_amdgcn_s_setprio(0); } while (0)
; #define PG8_WAIT_V(n) asm volatile("s_waitcnt vmcnt(" #n ")" ::: "memory")
; #define PG8_WAIT_L(n) asm volatile("s_waitcnt lgkmcnt(" #n ")" ::: "memory")
; #define PG8_BAR __builtin_amdgcn_s_barrier()
; #define PG8_SCHED __builtin_amdgcn_sched_barrier(0)
; template <class Epi, class Sched, bool ALIGN_EPI = false, bool SP2 = false>
; __device__ __forceinline__ void gemm_phase(PG8_LAS unsigned char* lds, const Gemm g, const Sched& S, const Epi& E) {
;     ...
;             PG8_WAIT_V(8); PG8_WAIT_L(0); PG8_BAR; PG8_MMA(0, 0, At, B0); PG8_MMA(0, 1, At, B1); PG8_BAR; PG8_SCHED;
;             PG8_LDA(At, 1, 1); PG8_STAGE(PG8_SB(1, 0), b3, voffB); PG8_STAGE(PG8_SB(1, 1), b3 + hstep, voffB); PG8_STAGE(PG8_SA(1, 0), a3, voffA);
	v_mfma_f32_16x16x32_bf16 v[132:135], v[144:147], v[176:179], v[132:135]
	v_mfma_f32_16x16x32_bf16 v[128:131], v[152:155], v[176:179], v[128:131]
	v_mfma_f32_16x16x32_bf16 v[116:119], v[144:147], v[184:187], v[116:119]
	v_mfma_f32_16x16x32_bf16 v[108:111], v[152:155], v[184:187], v[108:111]
	v_mfma_f32_16x16x32_bf16 v[84:87], v[144:147], v[202:205], v[84:87]
	v_mfma_f32_16x16x32_bf16 v[80:83], v[152:155], v[202:205], v[80:83]
	v_mfma_f32_16x16x32_bf16 v[68:71], v[144:147], v[210:213], v[68:71]
	v_mfma_f32_16x16x32_bf16 v[64:67], v[152:155], v[210:213], v[64:67]
	v_mfma_f32_16x16x32_bf16 v[132:135], v[148:151], v[180:183], v[132:135]
	v_mfma_f32_16x16x32_bf16 v[128:131], v[172:175], v[180:183], v[128:131]
	v_mfma_f32_16x16x32_bf16 v[116:119], v[148:151], v[188:191], v[116:119]
	v_mfma_f32_16x16x32_bf16 v[108:111], v[172:175], v[188:191], v[108:111]
	v_mfma_f32_16x16x32_bf16 v[84:87], v[148:151], v[206:209], v[84:87]
	v_mfma_f32_16x16x32_bf16 v[80:83], v[172:175], v[206:209], v[80:83]
	v_mfma_f32_16x16x32_bf16 v[68:71], v[148:151], v[214:217], v[68:71]
	v_mfma_f32_16x16x32_bf16 v[64:67], v[172:175], v[214:217], v[64:67]
	s_setprio 0
	s_barrier
	s_add_i32 s52, s74, s55

; #define PG8_STAGE(bufoff, gbase, voff) do { _Pragma("unroll") for (int _i = 0; _i < 2; ++_i) \
;         __builtin_amdgcn_global_load_lds((const unsigned*)((const char*)(gbase) + (voff)[_i]), (PG8_LAS unsigned*)(lds + (bufoff) + ldsw + _i * 8192), 16, 0, 0); } while (0)
; #define PG8_LDA(dst, b, h) do { _Pragma("unroll") for (int m = 0; m < 4; ++m) _Pragma("unroll") for (int k = 0; k < 2; ++k) dst[m][k] = *(const PG8_LAS bf16x8*)(lds + PG8_SA(b, h) + aoff + m * 2048 + k * 1024); } while (0)
; template <class Epi, class Sched, bool ALIGN_EPI = false, bool SP2 = false>
; __device__ __forceinline__ void gemm_phase(PG8_LAS unsigned char* lds, const Gemm g, const Sched& S, const Epi& E) {
;     ...
;             PG8_LDA(At, 1, 1); PG8_STAGE(PG8_SB(1, 0), b3, voffB); PG8_STAGE(PG8_SB(1, 1), b3 + hstep, voffB); PG8_STAGE(PG8_SA(1, 0), a3, voffA);
	s_mov_b32 m0, s52
	ds_read_b128 v[176:179], v199 offset:49152
	ds_read_b128 v[180:183], v199 offset:50176
	ds_read_b128 v[184:187], v199 offset:51200
	ds_read_b128 v[188:191], v199 offset:52224
	ds_read_b128 v[202:205], v199 offset:53248
	ds_read_b128 v[206:209], v199 offset:54272
	ds_read_b128 v[210:213], v199 offset:55296
	ds_read_b128 v[214:217], v199 offset:56320
	global_load_lds_dwordx4 v250, s[96:97]
	s_add_i32 m0, s52, 0x2000
	s_add_u32 s50, s50, 0x200080

; #define PG8_STAGE(bufoff, gbase, voff) do { _Pragma("unroll") for (int _i = 0; _i < 2; ++_i) \
;         __builtin_amdgcn_global_load_lds((const unsigned*)((const char*)(gbase) + (voff)[_i]), (PG8_LAS unsigned*)(lds + (bufoff) + ldsw + _i * 8192), 16, 0, 0); } while (0)
; #define PG8_LDA(dst, b, h) do { _Pragma("unroll") for (int m = 0; m < 4; ++m) _Pragma("unroll") for (int k = 0; k < 2; ++k) dst[m][k] = *(const PG8_LAS bf16x8*)(lds + PG8_SA(b, h) + aoff + m * 2048 + k * 1024); } while (0)
; template <class Epi, class Sched, bool ALIGN_EPI = false, bool SP2 = false>
; __device__ __forceinline__ void gemm_phase(PG8_LAS unsigned char* lds, const Gemm g, const Sched& S, const Epi& E) {
;     ...
;             PG8_LDA(At, 1, 1); PG8_STAGE(PG8_SB(1, 0), b3, voffB); PG8_STAGE(PG8_SB(1, 1), b3 + hstep, voffB); PG8_STAGE(PG8_SA(1, 0), a3, voffA);
	s_addc_u32 s51, s51, 0
	s_add_i32 s52, s75, s55
	global_load_lds_dwordx4 v251, s[96:97]

; #define PG8_STAGE(bufoff, gbase, voff) do { _Pragma("unroll") for (int _i = 0; _i < 2; ++_i) \
;         __builtin_amdgcn_global_load_lds((const unsigned*)((const char*)(gbase) + (voff)[_i]), (PG8_LAS unsigned*)(lds + (bufoff) + ldsw + _i * 8192), 16, 0, 0); } while (0)
; #define PG8_LDA(dst, b, h) do { _Pragma("unroll") for (int m = 0; m < 4; ++m) _Pragma("unroll") for (int k = 0; k < 2; ++k) dst[m][k] = *(const PG8_LAS bf16x8*)(lds + PG8_SA(b, h) + aoff + m * 2048 + k * 1024); } while (0)
; template <class Epi, class Sched, bool ALIGN_EPI = false, bool SP2 = false>
; __device__ __forceinline__ void gemm_phase(PG8_LAS unsigned char* lds, const Gemm g, const Sched& S, const Epi& E) {
;     ...
;             PG8_LDA(At, 1, 1); PG8_STAGE(PG8_SB(1, 0), b3, voffB); PG8_STAGE(PG8_SB(1, 1), b3 + hstep, voffB); PG8_STAGE(PG8_SA(1, 0), a3, voffA);
	s_mov_b32 m0, s52
	s_nop 0
	global_load_lds_dwordx4 v158, s[50:51]

; #define PG8_STAGE(bufoff, gbase, voff) do { _Pragma("unroll") for (int _i = 0; _i < 2; ++_i) \
;         __builtin_amdgcn_global_load_lds((const unsigned*)((const char*)(gbase) + (voff)[_i]), (PG8_LAS unsigned*)(lds + (bufoff) + ldsw + _i * 8192), 16, 0, 0); } while (0)
; #define PG8_LDA(dst, b, h) do { _Pragma("unroll") for (int m = 0; m < 4; ++m) _Pragma("unroll") for (int k = 0; k < 2; ++k) dst[m][k] = *(const PG8_LAS bf16x8*)(lds + PG8_SA(b, h) + aoff + m * 2048 + k * 1024); } while (0)
; template <class Epi, class Sched, bool ALIGN_EPI = false, bool SP2 = false>
; __device__ __forceinline__ void gemm_phase(PG8_LAS unsigned char* lds, const Gemm g, const Sched& S, const Epi& E) {
;     ...
;             PG8_LDA(At, 1, 1); PG8_STAGE(PG8_SB(1, 0), b3, voffB); PG8_STAGE(PG8_SB(1, 1), b3 + hstep, voffB); PG8_STAGE(PG8_SA(1, 0), a3, voffA);
	s_add_i32 m0, s52, 0x2000
	s_nop 0
	global_load_lds_dwordx4 v162, s[50:51]

; #define PG8_STAGE(bufoff, gbase, voff) do { _Pragma("unroll") for (int _i = 0; _i < 2; ++_i) \
;         __builtin_amdgcn_global_load_lds((const unsigned*)((const char*)(gbase) + (voff)[_i]), (PG8_LAS unsigned*)(lds + (bufoff) + ldsw + _i * 8192), 16, 0, 0); } while (0)
; #define PG8_LDA(dst, b, h) do { _Pragma("unroll") for (int m = 0; m < 4; ++m) _Pragma("unroll") for (int k = 0; k < 2; ++k) dst[m][k] = *(const PG8_LAS bf16x8*)(lds + PG8_SA(b, h) + aoff + m * 2048 + k * 1024); } while (0)
; template <class Epi, class Sched, bool ALIGN_EPI = false, bool SP2 = false>
; __device__ __forceinline__ void gemm_phase(PG8_LAS unsigned char* lds, const Gemm g, const Sched& S, const Epi& E) {
;     ...
;             PG8_LDA(At, 1, 1); PG8_STAGE(PG8_SB(1, 0), b3, voffB); PG8_STAGE(PG8_SB(1, 1), b3 + hstep, voffB); PG8_STAGE(PG8_SA(1, 0), a3, voffA);
	s_mov_b32 m0, s61
	s_nop 0
	global_load_lds_dwordx4 v252, s[98:99]

; #define PG8_STAGE(bufoff, gbase, voff) do { _Pragma("unroll") for (int _i = 0; _i < 2; ++_i) \
;         __builtin_amdgcn_global_load_lds((const unsigned*)((const char*)(gbase) + (voff)[_i]), (PG8_LAS unsigned*)(lds + (bufoff) + ldsw + _i * 8192), 16, 0, 0); } while (0)
; #define PG8_LDA(dst, b, h) do { _Pragma("unroll") for (int m = 0; m < 4; ++m) _Pragma("unroll") for (int k = 0; k < 2; ++k) dst[m][k] = *(const PG8_LAS bf16x8*)(lds + PG8_SA(b, h) + aoff + m * 2048 + k * 1024); } while (0)
; #define PG8_MMA(ai, bj, At, Bt) do { __builtin_amdgcn_s_setprio(1); _Pragma("unroll") for (int m = 0; m < 4; ++m) _Pragma("unroll") for (int n = 0; n < 2; ++n) _Pragma("unroll") for (int k = 0; k < 2; ++k) \
;         acc[ai][bj][m][n] = __builtin_amdgcn_mfma_f32_16x16x32_bf16(Bt[n][k], At[m][k], acc[ai][bj][m][n], 0, 0, 0); __builtin_amdgcn_s_setprio(0); } while (0)
; #define PG8_WAIT_V(n) asm volatile("s_waitcnt vmcnt(" #n ")" ::: "memory")
; #define PG8_WAIT_L(n) asm volatile("s_waitcnt lgkmcnt(" #n ")" ::: "memory")
; #define PG8_BAR __builtin_amdgcn_s_barrier()
; #define PG8_SCHED __builtin_amdgcn_sched_barrier(0)
; template <class Epi, class Sched, bool ALIGN_EPI = false, bool SP2 = false>
; __device__ __forceinline__ void gemm_phase(PG8_LAS unsigned char* lds, const Gemm g, const Sched& S, const Epi& E) {
;     ...
;             PG8_LDA(At, 1, 1); PG8_STAGE(PG8_SB(1, 0), b3, voffB); PG8_STAGE(PG8_SB(1, 1), b3 + hstep, voffB); PG8_STAGE(PG8_SA(1, 0), a3, voffA);
;             PG8_WAIT_V(8); PG8_WAIT_L(0); PG8_BAR; PG8_MMA(1, 0, At, B0); PG8_MMA(1, 1, At, B1); PG8_BAR; PG8_SCHED;
	s_mov_b32 m0, s62
	s_nop 0
	global_load_lds_dwordx4 v253, s[98:99]
	s_waitcnt vmcnt(8)
	s_waitcnt lgkmcnt(0)
	s_barrier
	s_setprio 1
	s_waitcnt lgkmcnt(0)
	v_mfma_f32_16x16x32_bf16 v[60:63], v[96:99], v[176:179], v[60:63]
	v_mfma_f32_16x16x32_bf16 v[56:59], v[104:107], v[176:179], v[56:59]
	v_mfma_f32_16x16x32_bf16 v[44:47], v[96:99], v[184:187], v[44:47]
	v_mfma_f32_16x16x32_bf16 v[40:43], v[104:107], v[184:187], v[40:43]
	v_mfma_f32_16x16x32_bf16 v[28:31], v[96:99], v[202:205], v[28:31]
	v_mfma_f32_16x16x32_bf16 v[24:27], v[104:107], v[202:205], v[24:27]
	v_mfma_f32_16x16x32_bf16 v[12:15], v[96:99], v[210:213], v[12:15]
	v_mfma_f32_16x16x32_bf16 v[8:11], v[104:107], v[210:213], v[8:11]
	v_mfma_f32_16x16x32_bf16 v[60:63], v[100:103], v[180:183], v[60:63]
	v_mfma_f32_16x16x32_bf16 v[56:59], v[112:115], v[180:183], v[56:59]
	v_mfma_f32_16x16x32_bf16 v[44:47], v[100:103], v[188:191], v[44:47]
	v_mfma_f32_16x16x32_bf16 v[40:43], v[112:115], v[188:191], v[40:43]
	v_mfma_f32_16x16x32_bf16 v[28:31], v[100:103], v[206:209], v[28:31]
	v_mfma_f32_16x16x32_bf16 v[24:27], v[112:115], v[206:209], v[24:27]
	v_mfma_f32_16x16x32_bf16 v[12:15], v[100:103], v[214:217], v[12:15]
	v_mfma_f32_16x16x32_bf16 v[8:11], v[112:115], v[214:217], v[8:11]


; #define PG8_MMA(ai, bj, At, Bt) do { __builtin_amdgcn_s_setprio(1); _Pragma("unroll") for (int m = 0; m < 4; ++m) _Pragma("unroll") for (int n = 0; n < 2; ++n) _Pragma("unroll") for (int k = 0; k < 2; ++k) \
;         acc[ai][bj][m][n] = __builtin_amdgcn_mfma_f32_16x16x32_bf16(Bt[n][k], At[m][k], acc[ai][bj][m][n], 0, 0, 0); __builtin_amdgcn_s_setprio(0); } while (0)
; #define PG8_WAIT_V(n) asm volatile("s_waitcnt vmcnt(" #n ")" ::: "memory")
; #define PG8_WAIT_L(n) asm volatile("s_waitcnt lgkmcnt(" #n ")" ::: "memory")
; #define PG8_BAR __builtin_amdgcn_s_barrier()
; #define PG8_SCHED __builtin_amdgcn_sched_barrier(0)
; template <class Epi, class Sched, bool ALIGN_EPI = false, bool SP2 = false>
; __device__ __forceinline__ void gemm_phase(PG8_LAS unsigned char* lds, const Gemm g, const Sched& S, const Epi& E) {
;     ...
;         for (int t = 0; t < nt; t += 2) {
;     ...
;             PG8_WAIT_V(8); PG8_WAIT_L(0); PG8_BAR; PG8_MMA(1, 0, At, B0); PG8_MMA(1, 1, At, B1); PG8_BAR; PG8_SCHED;
;     ...
;         if constexpr (ALIGN_EPI) { if (wr == 0) PG8_BAR; }
	v_mfma_f32_16x16x32_bf16 v[52:55], v[144:147], v[176:179], v[52:55]
	v_mfma_f32_16x16x32_bf16 v[48:51], v[152:155], v[176:179], v[48:51]
	v_mfma_f32_16x16x32_bf16 v[36:39], v[144:147], v[184:187], v[36:39]
	v_mfma_f32_16x16x32_bf16 v[32:35], v[152:155], v[184:187], v[32:35]
	v_mfma_f32_16x16x32_bf16 v[20:23], v[144:147], v[202:205], v[20:23]
	v_mfma_f32_16x16x32_bf16 v[16:19], v[152:155], v[202:205], v[16:19]
	v_mfma_f32_16x16x32_bf16 v[4:7], v[144:147], v[210:213], v[4:7]
	v_mfma_f32_16x16x32_bf16 v[0:3], v[152:155], v[210:213], v[0:3]
	v_mfma_f32_16x16x32_bf16 v[52:55], v[148:151], v[180:183], v[52:55]
	v_mfma_f32_16x16x32_bf16 v[48:51], v[172:175], v[180:183], v[48:51]
	v_mfma_f32_16x16x32_bf16 v[36:39], v[148:151], v[188:191], v[36:39]
	v_mfma_f32_16x16x32_bf16 v[32:35], v[172:175], v[188:191], v[32:35]
	v_mfma_f32_16x16x32_bf16 v[20:23], v[148:151], v[206:209], v[20:23]
	v_mfma_f32_16x16x32_bf16 v[16:19], v[172:175], v[206:209], v[16:19]
	v_mfma_f32_16x16x32_bf16 v[4:7], v[148:151], v[214:217], v[4:7]
	v_mfma_f32_16x16x32_bf16 v[0:3], v[172:175], v[214:217], v[0:3]
	s_setprio 0
	s_barrier
	s_add_i32 s73, s73, 2
	s_add_u32 s48, s48, 0x100
	s_addc_u32 s49, s49, 0
	s_add_u32 s71, s71, 0x100
	s_addc_u32 s72, s72, 0
	s_cmpk_gt_u32 s73, 0x7d
	s_cbranch_scc0 .LBB0_1114
	s_and_b64 vcc, exec, s[34:35]
	s_cbranch_vccz .LBB0_1117
	s_barrier

; __global__ void __launch_bounds__(512, 2) fwd_mega(Args a) {
	.amdhsa_kernel _Z8fwd_mega4Args
		.amdhsa_group_segment_fixed_size 0
		.amdhsa_private_segment_fixed_size 0
		.amdhsa_kernarg_size 424
		.amdhsa_user_sgpr_count 2
		.amdhsa_user_sgpr_dispatch_ptr 0
		.amdhsa_user_sgpr_queue_ptr 0
		.amdhsa_user_sgpr_kernarg_segment_ptr 1
		.amdhsa_user_sgpr_dispatch_id 0
		.amdhsa_user_sgpr_kernarg_preload_length 0
		.amdhsa_user_sgpr_kernarg_preload_offset 0
		.amdhsa_user_sgpr_private_segment_size 0
		.amdhsa_uses_dynamic_stack 0
		.amdhsa_enable_private_segment 0
		.amdhsa_system_sgpr_workgroup_id_x 1
		.amdhsa_system_sgpr_workgroup_id_y 0
		.amdhsa_system_sgpr_workgroup_id_z 0
		.amdhsa_system_sgpr_workgroup_info 0
		.amdhsa_system_vgpr_workitem_id 2
		.amdhsa_next_free_vgpr 256
		.amdhsa_next_free_sgpr 102
		.amdhsa_accum_offset 256
		.amdhsa_reserve_vcc 1
		.amdhsa_float_round_mode_32 0
		.amdhsa_float_round_mode_16_64 0
		.amdhsa_float_denorm_mode_32 3
		.amdhsa_float_denorm_mode_16_64 3
		.amdhsa_dx10_clamp 1
		.amdhsa_ieee_mode 1
		.amdhsa_fp16_overflow 0
		.amdhsa_tg_split 0
		.amdhsa_exception_fp_ieee_invalid_op 0
		.amdhsa_exception_fp_denorm_src 0
		.amdhsa_exception_fp_ieee_div_zero 0
		.amdhsa_exception_fp_ieee_overflow 0
		.amdhsa_exception_fp_ieee_underflow 0
		.amdhsa_exception_fp_ieee_inexact 0
		.amdhsa_exception_int_div_zero 0
	.end_amdhsa_kernel

; __global__ void __launch_bounds__(512, 2) fwd_mega(Args a) {
amdhsa.kernels:
  - .agpr_count:     0
    .args:
      - .offset:         0
        .size:           168
        .value_kind:     by_value
      - .offset:         168
        .size:           4
        .value_kind:     hidden_block_count_x
      - .offset:         172
        .size:           4
        .value_kind:     hidden_block_count_y
      - .offset:         176
        .size:           4
        .value_kind:     hidden_block_count_z
      - .offset:         180
        .size:           2
        .value_kind:     hidden_group_size_x
      - .offset:         182
        .size:           2
        .value_kind:     hidden_group_size_y
      - .offset:         184
        .size:           2
        .value_kind:     hidden_group_size_z
      - .offset:         186
        .size:           2
        .value_kind:     hidden_remainder_x
      - .offset:         188
        .size:           2
        .value_kind:     hidden_remainder_y
      - .offset:         190
        .size:           2
        .value_kind:     hidden_remainder_z
      - .offset:         208
        .size:           8
        .value_kind:     hidden_global_offset_x
      - .offset:         216
        .size:           8
        .value_kind:     hidden_global_offset_y
      - .offset:         224
        .size:           8
        .value_kind:     hidden_global_offset_z
      - .offset:         232
        .size:           2
        .value_kind:     hidden_grid_dims
      - .offset:         256
        .size:           8
        .value_kind:     hidden_multigrid_sync_arg
      - .offset:         288
        .size:           4
        .value_kind:     hidden_dynamic_lds_size
    .group_segment_fixed_size: 0
    .kernarg_segment_align: 8
    .kernarg_segment_size: 424
    .language:       OpenCL C
    .language_version:
      - 2
      - 0
    .max_flat_workgroup_size: 512
    .name:           _Z8fwd_mega4Args
    .private_segment_fixed_size: 0
    .sgpr_count:     108
    .sgpr_spill_count: 0
    .symbol:         _Z8fwd_mega4Args.kd
    .uniform_work_group_size: 1
    .uses_dynamic_stack: false
    .vgpr_count:     256
    .vgpr_spill_count: 0
    .wavefront_size: 64
